# k17 plus: write-through (sc1) dwordx4 stores in the GEMM epilogues so the grid barrier's L2 write-back has less to flush
# baseline (speedup 1.0000x reference)
; __device__ __forceinline__ float rstd_of(float ss, float inv_n) { return __builtin_amdgcn_rsqf(ss * inv_n + 1e-6f); }
; __device__ __forceinline__ float sigmoid_f(float v) { return __builtin_amdgcn_rcpf(1.0f + __builtin_amdgcn_exp2f(-1.4426950408889634f * v)); }
; __device__ __forceinline__ u32x4 pack8(const f32x4 a, const f32x4 b) { u32x4 w; w.x = cvt_pk_bf16(a[0], a[1]); w.y = cvt_pk_bf16(a[2], a[3]); w.z = cvt_pk_bf16(b[0], b[1]); w.w = cvt_pk_bf16(b[2], b[3]); return w; }
;     __device__ __forceinline__ void operator()(f32x4 (&acc)[2][2][4][2], const Unit& u_, int wr, int wc, int fr, int fq) const {
;         Unit u = u_; if constexpr (OPQ) { unsigned o1_ = ~0u; asm volatile("" : "+s"(u.pm), "+s"(u.pn), "+s"(o1_)); const int l_ = (int)__builtin_amdgcn_mbcnt_hi(o1_, __builtin_amdgcn_mbcnt_lo(o1_, 0u)); fr = l_ & 15; fq = l_ >> 4; }
;         const int row0 = u.pm * BM + wr * 64 + fr, col0 = u.pn * HALF + wc * 32 + 8 * fq;
; #pragma unroll
;         for (int ai = 0; ai < 2; ++ai)
; #pragma unroll
;             for (int m = 0; m < 4; ++m) {
;                 const int row = row0 + ai * HALF + m * 16; const float r = rstd_of(sl[u.par * 256 + ai * HALF + wr * 64 + m * 16 + fr], 1.0f / 2048.0f) * ascale;
;                 f32x4 o[2];
; #pragma unroll
;                 for (int n = 0; n < 2; ++n) { const f32x4 g = acc[ai][0][m][n] * r, uu = acc[ai][1][m][n] * r;
; #pragma unroll
;                     for (int e = 0; e < 4; ++e) o[n][e] = g[e] * uu[e] * sigmoid_f(g[e]); }
;                 if constexpr (F8OUT) {
;                     typedef unsigned u32x2 __attribute__((ext_vector_type(2))); u32x2 w8; w8.x = pack4_fp8(o[0][0] * F8_ACT_SCALE, o[0][1] * F8_ACT_SCALE, o[0][2] * F8_ACT_SCALE, o[0][3] * F8_ACT_SCALE);
;                     w8.y = pack4_fp8(o[1][0] * F8_ACT_SCALE, o[1][1] * F8_ACT_SCALE, o[1][2] * F8_ACT_SCALE, o[1][3] * F8_ACT_SCALE);
;                     *(u32x2*)((unsigned char*)O + (((size_t)u.pm * (ldo / 128) + (col0 >> 7)) * BM + (ai * HALF + wr * 64 + m * 16 + fr)) * 128 + (col0 & 127)) = w8;
;                 } else
;                 *(u32x4*)(O + (((size_t)u.pm * (ldo / 64) + (col0 >> 6)) * BM + (ai * HALF + wr * 64 + m * 16 + fr)) * 64 + (col0 & 63)) = pack8(o[0], o[1]);
;             }
;     }
.LBB0_228:
	v_lshl_add_u32 v166, s76, 10, v162
	ds_read_b32 v172, v166
	ds_read_b32 v173, v166 offset:64
	ds_read_b32 v174, v166 offset:128
	ds_read_b32 v175, v166 offset:192
	ds_read_b32 v176, v166 offset:512
	ds_read_b32 v177, v166 offset:576
	ds_read_b32 v178, v166 offset:640
	ds_read_b32 v179, v166 offset:704
	v_lshl_add_u32 v167, s56, 7, v161
	s_andn2_b64 vcc, exec, s[6:7]
	s_mov_b64 s[6:7], -1
	v_ashrrev_i32_e32 v168, 6, v167
	v_ashrrev_i32_e32 v169, 31, v168
	v_mad_i64_i32 v[180:181], s[8:9], s54, v165, v[168:169]
	v_mov_b32_e32 v170, v152
	v_mov_b32_e32 v171, v129
	v_lshlrev_b64 v[180:181], 15, v[180:181]
	v_mov_b32_e32 v182, 1.0
	v_lshl_add_u64 v[180:181], s[34:35], 0, v[180:181]
	v_lshl_add_u64 v[180:181], v[180:181], 0, v[170:171]
	s_waitcnt lgkmcnt(0)
	v_fmamk_f32 v184, v172, 0x3a000000, v164
	v_rsq_f32_e32 v184, v184
	v_lshl_add_u64 v[202:203], v[180:181], 0, v[130:131]
	v_mul_f32_e32 v186, 0xbfb8aa3b, v184
	v_mul_f32_e32 v188, v184, v184
	v_pk_mul_f32 v[190:191], v[124:125], v[186:187] op_sel_hi:[1,0]
	v_pk_mul_f32 v[192:193], v[126:127], v[186:187] op_sel_hi:[1,0]
	v_pk_mul_f32 v[124:125], v[124:125], v[120:121]
	v_exp_f32_e32 v190, v190
	v_exp_f32_e32 v191, v191
	v_exp_f32_e32 v192, v192
	v_exp_f32_e32 v193, v193
	v_pk_mul_f32 v[126:127], v[126:127], v[122:123]
	v_pk_add_f32 v[190:191], v[190:191], v[182:183] op_sel_hi:[1,0]
	v_pk_add_f32 v[192:193], v[192:193], v[182:183] op_sel_hi:[1,0]
	v_pk_mul_f32 v[124:125], v[124:125], v[188:189] op_sel_hi:[1,0]
	v_rcp_f32_e32 v190, v190
	v_rcp_f32_e32 v191, v191
	v_rcp_f32_e32 v192, v192
	v_rcp_f32_e32 v193, v193
	v_pk_mul_f32 v[126:127], v[126:127], v[188:189] op_sel_hi:[1,0]
	v_pk_mul_f32 v[124:125], v[124:125], v[190:191]
	v_pk_mul_f32 v[126:127], v[126:127], v[192:193]
	v_pk_mul_f32 v[190:191], v[116:117], v[186:187] op_sel_hi:[1,0]
	v_pk_mul_f32 v[192:193], v[118:119], v[186:187] op_sel_hi:[1,0]
	v_pk_mul_f32 v[116:117], v[116:117], v[112:113]
	v_exp_f32_e32 v190, v190
	v_exp_f32_e32 v191, v191
	v_exp_f32_e32 v192, v192
	v_exp_f32_e32 v193, v193
	v_pk_mul_f32 v[118:119], v[118:119], v[114:115]
	v_pk_add_f32 v[190:191], v[190:191], v[182:183] op_sel_hi:[1,0]
	v_pk_add_f32 v[192:193], v[192:193], v[182:183] op_sel_hi:[1,0]
	v_pk_mul_f32 v[116:117], v[116:117], v[188:189] op_sel_hi:[1,0]
	v_rcp_f32_e32 v190, v190
	v_rcp_f32_e32 v191, v191
	v_rcp_f32_e32 v192, v192
	v_rcp_f32_e32 v193, v193
	v_pk_mul_f32 v[118:119], v[118:119], v[188:189] op_sel_hi:[1,0]
	v_pk_mul_f32 v[116:117], v[116:117], v[190:191]
	v_pk_mul_f32 v[118:119], v[118:119], v[192:193]
	v_cvt_pk_bf16_f32 v194, v124, v125
	v_cvt_pk_bf16_f32 v195, v126, v127
	v_cvt_pk_bf16_f32 v196, v116, v117
	v_cvt_pk_bf16_f32 v197, v118, v119
	global_store_dwordx4 v[202:203], v[194:197], off sc1
	v_fmamk_f32 v184, v173, 0x3a000000, v164
	v_rsq_f32_e32 v184, v184
	v_lshl_add_u64 v[202:203], v[180:181], 0, v[132:133]
	v_mul_f32_e32 v186, 0xbfb8aa3b, v184
	v_mul_f32_e32 v188, v184, v184
	v_pk_mul_f32 v[190:191], v[108:109], v[186:187] op_sel_hi:[1,0]
	v_pk_mul_f32 v[192:193], v[110:111], v[186:187] op_sel_hi:[1,0]
	v_pk_mul_f32 v[108:109], v[108:109], v[104:105]
	v_exp_f32_e32 v190, v190
	v_exp_f32_e32 v191, v191
	v_exp_f32_e32 v192, v192
	v_exp_f32_e32 v193, v193
	v_pk_mul_f32 v[110:111], v[110:111], v[106:107]
	v_pk_add_f32 v[190:191], v[190:191], v[182:183] op_sel_hi:[1,0]
	v_pk_add_f32 v[192:193], v[192:193], v[182:183] op_sel_hi:[1,0]
	v_pk_mul_f32 v[108:109], v[108:109], v[188:189] op_sel_hi:[1,0]
	v_rcp_f32_e32 v190, v190
	v_rcp_f32_e32 v191, v191
	v_rcp_f32_e32 v192, v192
	v_rcp_f32_e32 v193, v193
	v_pk_mul_f32 v[110:111], v[110:111], v[188:189] op_sel_hi:[1,0]
	v_pk_mul_f32 v[108:109], v[108:109], v[190:191]
	v_pk_mul_f32 v[110:111], v[110:111], v[192:193]
	v_pk_mul_f32 v[190:191], v[100:101], v[186:187] op_sel_hi:[1,0]
	v_pk_mul_f32 v[192:193], v[102:103], v[186:187] op_sel_hi:[1,0]
	v_pk_mul_f32 v[100:101], v[100:101], v[96:97]
	v_exp_f32_e32 v190, v190
	v_exp_f32_e32 v191, v191
	v_exp_f32_e32 v192, v192
	v_exp_f32_e32 v193, v193
	v_pk_mul_f32 v[102:103], v[102:103], v[98:99]
	v_pk_add_f32 v[190:191], v[190:191], v[182:183] op_sel_hi:[1,0]
	v_pk_add_f32 v[192:193], v[192:193], v[182:183] op_sel_hi:[1,0]
	v_pk_mul_f32 v[100:101], v[100:101], v[188:189] op_sel_hi:[1,0]
	v_rcp_f32_e32 v190, v190
	v_rcp_f32_e32 v191, v191
	v_rcp_f32_e32 v192, v192
	v_rcp_f32_e32 v193, v193
	v_pk_mul_f32 v[102:103], v[102:103], v[188:189] op_sel_hi:[1,0]
	v_pk_mul_f32 v[100:101], v[100:101], v[190:191]
	v_pk_mul_f32 v[102:103], v[102:103], v[192:193]
	v_cvt_pk_bf16_f32 v198, v108, v109
	v_cvt_pk_bf16_f32 v199, v110, v111
	v_cvt_pk_bf16_f32 v200, v100, v101
	v_cvt_pk_bf16_f32 v201, v102, v103
	global_store_dwordx4 v[202:203], v[198:201], off sc1
	v_fmamk_f32 v184, v174, 0x3a000000, v164
	v_rsq_f32_e32 v184, v184
	v_lshl_add_u64 v[202:203], v[180:181], 0, v[134:135]
	v_mul_f32_e32 v186, 0xbfb8aa3b, v184
	v_mul_f32_e32 v188, v184, v184
	v_pk_mul_f32 v[190:191], v[92:93], v[186:187] op_sel_hi:[1,0]
	v_pk_mul_f32 v[192:193], v[94:95], v[186:187] op_sel_hi:[1,0]
	v_pk_mul_f32 v[92:93], v[92:93], v[88:89]
	v_exp_f32_e32 v190, v190
	v_exp_f32_e32 v191, v191
	v_exp_f32_e32 v192, v192
	v_exp_f32_e32 v193, v193
	v_pk_mul_f32 v[94:95], v[94:95], v[90:91]
	v_pk_add_f32 v[190:191], v[190:191], v[182:183] op_sel_hi:[1,0]
	v_pk_add_f32 v[192:193], v[192:193], v[182:183] op_sel_hi:[1,0]
	v_pk_mul_f32 v[92:93], v[92:93], v[188:189] op_sel_hi:[1,0]
	v_rcp_f32_e32 v190, v190
	v_rcp_f32_e32 v191, v191
	v_rcp_f32_e32 v192, v192
	v_rcp_f32_e32 v193, v193
	v_pk_mul_f32 v[94:95], v[94:95], v[188:189] op_sel_hi:[1,0]
	v_pk_mul_f32 v[92:93], v[92:93], v[190:191]
; __device__ __forceinline__ float rstd_of(float ss, float inv_n) { return __builtin_amdgcn_rsqf(ss * inv_n + 1e-6f); }
; __device__ __forceinline__ float sigmoid_f(float v) { return __builtin_amdgcn_rcpf(1.0f + __builtin_amdgcn_exp2f(-1.4426950408889634f * v)); }
; __device__ __forceinline__ u32x4 pack8(const f32x4 a, const f32x4 b) { u32x4 w; w.x = cvt_pk_bf16(a[0], a[1]); w.y = cvt_pk_bf16(a[2], a[3]); w.z = cvt_pk_bf16(b[0], b[1]); w.w = cvt_pk_bf16(b[2], b[3]); return w; }
;     __device__ __forceinline__ void operator()(f32x4 (&acc)[2][2][4][2], const Unit& u_, int wr, int wc, int fr, int fq) const {
;         Unit u = u_; if constexpr (OPQ) { unsigned o1_ = ~0u; asm volatile("" : "+s"(u.pm), "+s"(u.pn), "+s"(o1_)); const int l_ = (int)__builtin_amdgcn_mbcnt_hi(o1_, __builtin_amdgcn_mbcnt_lo(o1_, 0u)); fr = l_ & 15; fq = l_ >> 4; }
;         const int row0 = u.pm * BM + wr * 64 + fr, col0 = u.pn * HALF + wc * 32 + 8 * fq;
; #pragma unroll
;         for (int ai = 0; ai < 2; ++ai)
; #pragma unroll
;             for (int m = 0; m < 4; ++m) {
;                 const int row = row0 + ai * HALF + m * 16; const float r = rstd_of(sl[u.par * 256 + ai * HALF + wr * 64 + m * 16 + fr], 1.0f / 2048.0f) * ascale;
;                 f32x4 o[2];
; #pragma unroll
;                 for (int n = 0; n < 2; ++n) { const f32x4 g = acc[ai][0][m][n] * r, uu = acc[ai][1][m][n] * r;
; #pragma unroll
;                     for (int e = 0; e < 4; ++e) o[n][e] = g[e] * uu[e] * sigmoid_f(g[e]); }
;                 if constexpr (F8OUT) {
;                     typedef unsigned u32x2 __attribute__((ext_vector_type(2))); u32x2 w8; w8.x = pack4_fp8(o[0][0] * F8_ACT_SCALE, o[0][1] * F8_ACT_SCALE, o[0][2] * F8_ACT_SCALE, o[0][3] * F8_ACT_SCALE);
;                     w8.y = pack4_fp8(o[1][0] * F8_ACT_SCALE, o[1][1] * F8_ACT_SCALE, o[1][2] * F8_ACT_SCALE, o[1][3] * F8_ACT_SCALE);
;                     *(u32x2*)((unsigned char*)O + (((size_t)u.pm * (ldo / 128) + (col0 >> 7)) * BM + (ai * HALF + wr * 64 + m * 16 + fr)) * 128 + (col0 & 127)) = w8;
;                 } else
;                 *(u32x4*)(O + (((size_t)u.pm * (ldo / 64) + (col0 >> 6)) * BM + (ai * HALF + wr * 64 + m * 16 + fr)) * 64 + (col0 & 63)) = pack8(o[0], o[1]);
;             }
;     }
	v_pk_mul_f32 v[94:95], v[94:95], v[192:193]
	v_pk_mul_f32 v[190:191], v[84:85], v[186:187] op_sel_hi:[1,0]
	v_pk_mul_f32 v[192:193], v[86:87], v[186:187] op_sel_hi:[1,0]
	v_pk_mul_f32 v[84:85], v[84:85], v[80:81]
	v_exp_f32_e32 v190, v190
	v_exp_f32_e32 v191, v191
	v_exp_f32_e32 v192, v192
	v_exp_f32_e32 v193, v193
	v_pk_mul_f32 v[86:87], v[86:87], v[82:83]
	v_pk_add_f32 v[190:191], v[190:191], v[182:183] op_sel_hi:[1,0]
	v_pk_add_f32 v[192:193], v[192:193], v[182:183] op_sel_hi:[1,0]
	v_pk_mul_f32 v[84:85], v[84:85], v[188:189] op_sel_hi:[1,0]
	v_rcp_f32_e32 v190, v190
	v_rcp_f32_e32 v191, v191
	v_rcp_f32_e32 v192, v192
	v_rcp_f32_e32 v193, v193
	v_pk_mul_f32 v[86:87], v[86:87], v[188:189] op_sel_hi:[1,0]
	v_pk_mul_f32 v[84:85], v[84:85], v[190:191]
	v_pk_mul_f32 v[86:87], v[86:87], v[192:193]
	v_cvt_pk_bf16_f32 v194, v92, v93
	v_cvt_pk_bf16_f32 v195, v94, v95
	v_cvt_pk_bf16_f32 v196, v84, v85
	v_cvt_pk_bf16_f32 v197, v86, v87
	global_store_dwordx4 v[202:203], v[194:197], off sc1
	v_fmamk_f32 v184, v175, 0x3a000000, v164
	v_rsq_f32_e32 v184, v184
	v_lshl_add_u64 v[202:203], v[180:181], 0, v[136:137]
	v_mul_f32_e32 v186, 0xbfb8aa3b, v184
	v_mul_f32_e32 v188, v184, v184
	v_pk_mul_f32 v[190:191], v[76:77], v[186:187] op_sel_hi:[1,0]
	v_pk_mul_f32 v[192:193], v[78:79], v[186:187] op_sel_hi:[1,0]
	v_pk_mul_f32 v[76:77], v[76:77], v[72:73]
	v_exp_f32_e32 v190, v190
	v_exp_f32_e32 v191, v191
	v_exp_f32_e32 v192, v192
	v_exp_f32_e32 v193, v193
	v_pk_mul_f32 v[78:79], v[78:79], v[74:75]
	v_pk_add_f32 v[190:191], v[190:191], v[182:183] op_sel_hi:[1,0]
	v_pk_add_f32 v[192:193], v[192:193], v[182:183] op_sel_hi:[1,0]
	v_pk_mul_f32 v[76:77], v[76:77], v[188:189] op_sel_hi:[1,0]
	v_rcp_f32_e32 v190, v190
	v_rcp_f32_e32 v191, v191
	v_rcp_f32_e32 v192, v192
	v_rcp_f32_e32 v193, v193
	v_pk_mul_f32 v[78:79], v[78:79], v[188:189] op_sel_hi:[1,0]
	v_pk_mul_f32 v[76:77], v[76:77], v[190:191]
	v_pk_mul_f32 v[78:79], v[78:79], v[192:193]
	v_pk_mul_f32 v[190:191], v[68:69], v[186:187] op_sel_hi:[1,0]
	v_pk_mul_f32 v[192:193], v[70:71], v[186:187] op_sel_hi:[1,0]
	v_pk_mul_f32 v[68:69], v[68:69], v[64:65]
	v_exp_f32_e32 v190, v190
	v_exp_f32_e32 v191, v191
	v_exp_f32_e32 v192, v192
	v_exp_f32_e32 v193, v193
	v_pk_mul_f32 v[70:71], v[70:71], v[66:67]
	v_pk_add_f32 v[190:191], v[190:191], v[182:183] op_sel_hi:[1,0]
	v_pk_add_f32 v[192:193], v[192:193], v[182:183] op_sel_hi:[1,0]
	v_pk_mul_f32 v[68:69], v[68:69], v[188:189] op_sel_hi:[1,0]
	v_rcp_f32_e32 v190, v190
	v_rcp_f32_e32 v191, v191
	v_rcp_f32_e32 v192, v192
	v_rcp_f32_e32 v193, v193
	v_pk_mul_f32 v[70:71], v[70:71], v[188:189] op_sel_hi:[1,0]
	v_pk_mul_f32 v[68:69], v[68:69], v[190:191]
	v_pk_mul_f32 v[70:71], v[70:71], v[192:193]
	v_cvt_pk_bf16_f32 v198, v76, v77
	v_cvt_pk_bf16_f32 v199, v78, v79
	v_cvt_pk_bf16_f32 v200, v68, v69
	v_cvt_pk_bf16_f32 v201, v70, v71
	global_store_dwordx4 v[202:203], v[198:201], off sc1
	v_fmamk_f32 v184, v176, 0x3a000000, v164
	v_rsq_f32_e32 v184, v184
	v_lshl_add_u64 v[202:203], v[180:181], 0, v[138:139]
	v_mul_f32_e32 v186, 0xbfb8aa3b, v184
	v_mul_f32_e32 v188, v184, v184
	v_pk_mul_f32 v[190:191], v[60:61], v[186:187] op_sel_hi:[1,0]
	v_pk_mul_f32 v[192:193], v[62:63], v[186:187] op_sel_hi:[1,0]
	v_pk_mul_f32 v[60:61], v[60:61], v[56:57]
	v_exp_f32_e32 v190, v190
	v_exp_f32_e32 v191, v191
	v_exp_f32_e32 v192, v192
	v_exp_f32_e32 v193, v193
	v_pk_mul_f32 v[62:63], v[62:63], v[58:59]
	v_pk_add_f32 v[190:191], v[190:191], v[182:183] op_sel_hi:[1,0]
	v_pk_add_f32 v[192:193], v[192:193], v[182:183] op_sel_hi:[1,0]
	v_pk_mul_f32 v[60:61], v[60:61], v[188:189] op_sel_hi:[1,0]
	v_rcp_f32_e32 v190, v190
	v_rcp_f32_e32 v191, v191
	v_rcp_f32_e32 v192, v192
	v_rcp_f32_e32 v193, v193
	v_pk_mul_f32 v[62:63], v[62:63], v[188:189] op_sel_hi:[1,0]
	v_pk_mul_f32 v[60:61], v[60:61], v[190:191]
	v_pk_mul_f32 v[62:63], v[62:63], v[192:193]
	v_pk_mul_f32 v[190:191], v[52:53], v[186:187] op_sel_hi:[1,0]
	v_pk_mul_f32 v[192:193], v[54:55], v[186:187] op_sel_hi:[1,0]
	v_pk_mul_f32 v[52:53], v[52:53], v[48:49]
	v_exp_f32_e32 v190, v190
	v_exp_f32_e32 v191, v191
	v_exp_f32_e32 v192, v192
	v_exp_f32_e32 v193, v193
	v_pk_mul_f32 v[54:55], v[54:55], v[50:51]
	v_pk_add_f32 v[190:191], v[190:191], v[182:183] op_sel_hi:[1,0]
	v_pk_add_f32 v[192:193], v[192:193], v[182:183] op_sel_hi:[1,0]
	v_pk_mul_f32 v[52:53], v[52:53], v[188:189] op_sel_hi:[1,0]
	v_rcp_f32_e32 v190, v190
	v_rcp_f32_e32 v191, v191
	v_rcp_f32_e32 v192, v192
	v_rcp_f32_e32 v193, v193
	v_pk_mul_f32 v[54:55], v[54:55], v[188:189] op_sel_hi:[1,0]
	v_pk_mul_f32 v[52:53], v[52:53], v[190:191]
	v_pk_mul_f32 v[54:55], v[54:55], v[192:193]
	v_cvt_pk_bf16_f32 v194, v60, v61
	v_cvt_pk_bf16_f32 v195, v62, v63
	v_cvt_pk_bf16_f32 v196, v52, v53
	v_cvt_pk_bf16_f32 v197, v54, v55
	global_store_dwordx4 v[202:203], v[194:197], off sc1
	v_fmamk_f32 v184, v177, 0x3a000000, v164
	v_rsq_f32_e32 v184, v184
	v_lshl_add_u64 v[202:203], v[180:181], 0, v[140:141]
	v_mul_f32_e32 v186, 0xbfb8aa3b, v184
	v_mul_f32_e32 v188, v184, v184
	v_pk_mul_f32 v[190:191], v[44:45], v[186:187] op_sel_hi:[1,0]
	v_pk_mul_f32 v[192:193], v[46:47], v[186:187] op_sel_hi:[1,0]
	v_pk_mul_f32 v[44:45], v[44:45], v[40:41]
	v_exp_f32_e32 v190, v190
	v_exp_f32_e32 v191, v191
	v_exp_f32_e32 v192, v192
	v_exp_f32_e32 v193, v193
	v_pk_mul_f32 v[46:47], v[46:47], v[42:43]
; __device__ __forceinline__ float rstd_of(float ss, float inv_n) { return __builtin_amdgcn_rsqf(ss * inv_n + 1e-6f); }
; __device__ __forceinline__ float sigmoid_f(float v) { return __builtin_amdgcn_rcpf(1.0f + __builtin_amdgcn_exp2f(-1.4426950408889634f * v)); }
; __device__ __forceinline__ u32x4 pack8(const f32x4 a, const f32x4 b) { u32x4 w; w.x = cvt_pk_bf16(a[0], a[1]); w.y = cvt_pk_bf16(a[2], a[3]); w.z = cvt_pk_bf16(b[0], b[1]); w.w = cvt_pk_bf16(b[2], b[3]); return w; }
;     __device__ __forceinline__ void operator()(f32x4 (&acc)[2][2][4][2], const Unit& u_, int wr, int wc, int fr, int fq) const {
;         Unit u = u_; if constexpr (OPQ) { unsigned o1_ = ~0u; asm volatile("" : "+s"(u.pm), "+s"(u.pn), "+s"(o1_)); const int l_ = (int)__builtin_amdgcn_mbcnt_hi(o1_, __builtin_amdgcn_mbcnt_lo(o1_, 0u)); fr = l_ & 15; fq = l_ >> 4; }
;         const int row0 = u.pm * BM + wr * 64 + fr, col0 = u.pn * HALF + wc * 32 + 8 * fq;
; #pragma unroll
;         for (int ai = 0; ai < 2; ++ai)
; #pragma unroll
;             for (int m = 0; m < 4; ++m) {
;                 const int row = row0 + ai * HALF + m * 16; const float r = rstd_of(sl[u.par * 256 + ai * HALF + wr * 64 + m * 16 + fr], 1.0f / 2048.0f) * ascale;
;                 f32x4 o[2];
; #pragma unroll
;                 for (int n = 0; n < 2; ++n) { const f32x4 g = acc[ai][0][m][n] * r, uu = acc[ai][1][m][n] * r;
; #pragma unroll
;                     for (int e = 0; e < 4; ++e) o[n][e] = g[e] * uu[e] * sigmoid_f(g[e]); }
;                 if constexpr (F8OUT) {
;                     typedef unsigned u32x2 __attribute__((ext_vector_type(2))); u32x2 w8; w8.x = pack4_fp8(o[0][0] * F8_ACT_SCALE, o[0][1] * F8_ACT_SCALE, o[0][2] * F8_ACT_SCALE, o[0][3] * F8_ACT_SCALE);
;                     w8.y = pack4_fp8(o[1][0] * F8_ACT_SCALE, o[1][1] * F8_ACT_SCALE, o[1][2] * F8_ACT_SCALE, o[1][3] * F8_ACT_SCALE);
;                     *(u32x2*)((unsigned char*)O + (((size_t)u.pm * (ldo / 128) + (col0 >> 7)) * BM + (ai * HALF + wr * 64 + m * 16 + fr)) * 128 + (col0 & 127)) = w8;
;                 } else
;                 *(u32x4*)(O + (((size_t)u.pm * (ldo / 64) + (col0 >> 6)) * BM + (ai * HALF + wr * 64 + m * 16 + fr)) * 64 + (col0 & 63)) = pack8(o[0], o[1]);
;             }
;     }
	v_pk_add_f32 v[190:191], v[190:191], v[182:183] op_sel_hi:[1,0]
	v_pk_add_f32 v[192:193], v[192:193], v[182:183] op_sel_hi:[1,0]
	v_pk_mul_f32 v[44:45], v[44:45], v[188:189] op_sel_hi:[1,0]
	v_rcp_f32_e32 v190, v190
	v_rcp_f32_e32 v191, v191
	v_rcp_f32_e32 v192, v192
	v_rcp_f32_e32 v193, v193
	v_pk_mul_f32 v[46:47], v[46:47], v[188:189] op_sel_hi:[1,0]
	v_pk_mul_f32 v[44:45], v[44:45], v[190:191]
	v_pk_mul_f32 v[46:47], v[46:47], v[192:193]
	v_pk_mul_f32 v[190:191], v[36:37], v[186:187] op_sel_hi:[1,0]
	v_pk_mul_f32 v[192:193], v[38:39], v[186:187] op_sel_hi:[1,0]
	v_pk_mul_f32 v[36:37], v[36:37], v[32:33]
	v_exp_f32_e32 v190, v190
	v_exp_f32_e32 v191, v191
	v_exp_f32_e32 v192, v192
	v_exp_f32_e32 v193, v193
	v_pk_mul_f32 v[38:39], v[38:39], v[34:35]
	v_pk_add_f32 v[190:191], v[190:191], v[182:183] op_sel_hi:[1,0]
	v_pk_add_f32 v[192:193], v[192:193], v[182:183] op_sel_hi:[1,0]
	v_pk_mul_f32 v[36:37], v[36:37], v[188:189] op_sel_hi:[1,0]
	v_rcp_f32_e32 v190, v190
	v_rcp_f32_e32 v191, v191
	v_rcp_f32_e32 v192, v192
	v_rcp_f32_e32 v193, v193
	v_pk_mul_f32 v[38:39], v[38:39], v[188:189] op_sel_hi:[1,0]
	v_pk_mul_f32 v[36:37], v[36:37], v[190:191]
	v_pk_mul_f32 v[38:39], v[38:39], v[192:193]
	v_cvt_pk_bf16_f32 v198, v44, v45
	v_cvt_pk_bf16_f32 v199, v46, v47
	v_cvt_pk_bf16_f32 v200, v36, v37
	v_cvt_pk_bf16_f32 v201, v38, v39
	global_store_dwordx4 v[202:203], v[198:201], off sc1
	v_fmamk_f32 v184, v178, 0x3a000000, v164
	v_rsq_f32_e32 v184, v184
	v_lshl_add_u64 v[202:203], v[180:181], 0, v[142:143]
	v_mul_f32_e32 v186, 0xbfb8aa3b, v184
	v_mul_f32_e32 v188, v184, v184
	v_pk_mul_f32 v[190:191], v[28:29], v[186:187] op_sel_hi:[1,0]
	v_pk_mul_f32 v[192:193], v[30:31], v[186:187] op_sel_hi:[1,0]
	v_pk_mul_f32 v[28:29], v[28:29], v[24:25]
	v_exp_f32_e32 v190, v190
	v_exp_f32_e32 v191, v191
	v_exp_f32_e32 v192, v192
	v_exp_f32_e32 v193, v193
	v_pk_mul_f32 v[30:31], v[30:31], v[26:27]
	v_pk_add_f32 v[190:191], v[190:191], v[182:183] op_sel_hi:[1,0]
	v_pk_add_f32 v[192:193], v[192:193], v[182:183] op_sel_hi:[1,0]
	v_pk_mul_f32 v[28:29], v[28:29], v[188:189] op_sel_hi:[1,0]
	v_rcp_f32_e32 v190, v190
	v_rcp_f32_e32 v191, v191
	v_rcp_f32_e32 v192, v192
	v_rcp_f32_e32 v193, v193
	v_pk_mul_f32 v[30:31], v[30:31], v[188:189] op_sel_hi:[1,0]
	v_pk_mul_f32 v[28:29], v[28:29], v[190:191]
	v_pk_mul_f32 v[30:31], v[30:31], v[192:193]
	v_pk_mul_f32 v[190:191], v[20:21], v[186:187] op_sel_hi:[1,0]
	v_pk_mul_f32 v[192:193], v[22:23], v[186:187] op_sel_hi:[1,0]
	v_pk_mul_f32 v[20:21], v[20:21], v[16:17]
	v_exp_f32_e32 v190, v190
	v_exp_f32_e32 v191, v191
	v_exp_f32_e32 v192, v192
	v_exp_f32_e32 v193, v193
	v_pk_mul_f32 v[22:23], v[22:23], v[18:19]
	v_pk_add_f32 v[190:191], v[190:191], v[182:183] op_sel_hi:[1,0]
	v_pk_add_f32 v[192:193], v[192:193], v[182:183] op_sel_hi:[1,0]
	v_pk_mul_f32 v[20:21], v[20:21], v[188:189] op_sel_hi:[1,0]
	v_rcp_f32_e32 v190, v190
	v_rcp_f32_e32 v191, v191
	v_rcp_f32_e32 v192, v192
	v_rcp_f32_e32 v193, v193
	v_pk_mul_f32 v[22:23], v[22:23], v[188:189] op_sel_hi:[1,0]
	v_pk_mul_f32 v[20:21], v[20:21], v[190:191]
	v_pk_mul_f32 v[22:23], v[22:23], v[192:193]
	v_cvt_pk_bf16_f32 v194, v28, v29
	v_cvt_pk_bf16_f32 v195, v30, v31
	v_cvt_pk_bf16_f32 v196, v20, v21
	v_cvt_pk_bf16_f32 v197, v22, v23
	global_store_dwordx4 v[202:203], v[194:197], off sc1
	v_fmamk_f32 v184, v179, 0x3a000000, v164
	v_rsq_f32_e32 v184, v184
	v_lshl_add_u64 v[202:203], v[180:181], 0, v[144:145]
	v_mul_f32_e32 v186, 0xbfb8aa3b, v184
	v_mul_f32_e32 v188, v184, v184
	v_pk_mul_f32 v[190:191], v[12:13], v[186:187] op_sel_hi:[1,0]
	v_pk_mul_f32 v[192:193], v[14:15], v[186:187] op_sel_hi:[1,0]
	v_pk_mul_f32 v[12:13], v[12:13], v[8:9]
	v_exp_f32_e32 v190, v190
	v_exp_f32_e32 v191, v191
	v_exp_f32_e32 v192, v192
	v_exp_f32_e32 v193, v193
	v_pk_mul_f32 v[14:15], v[14:15], v[10:11]
	v_pk_add_f32 v[190:191], v[190:191], v[182:183] op_sel_hi:[1,0]
	v_pk_add_f32 v[192:193], v[192:193], v[182:183] op_sel_hi:[1,0]
	v_pk_mul_f32 v[12:13], v[12:13], v[188:189] op_sel_hi:[1,0]
	v_rcp_f32_e32 v190, v190
	v_rcp_f32_e32 v191, v191
	v_rcp_f32_e32 v192, v192
	v_rcp_f32_e32 v193, v193
	v_pk_mul_f32 v[14:15], v[14:15], v[188:189] op_sel_hi:[1,0]
	v_pk_mul_f32 v[12:13], v[12:13], v[190:191]
	v_pk_mul_f32 v[14:15], v[14:15], v[192:193]
	v_pk_mul_f32 v[190:191], v[4:5], v[186:187] op_sel_hi:[1,0]
	v_pk_mul_f32 v[192:193], v[6:7], v[186:187] op_sel_hi:[1,0]
	v_pk_mul_f32 v[4:5], v[4:5], v[0:1]
	v_exp_f32_e32 v190, v190
	v_exp_f32_e32 v191, v191
	v_exp_f32_e32 v192, v192
	v_exp_f32_e32 v193, v193
	v_pk_mul_f32 v[6:7], v[6:7], v[2:3]
	v_pk_add_f32 v[190:191], v[190:191], v[182:183] op_sel_hi:[1,0]
	v_pk_add_f32 v[192:193], v[192:193], v[182:183] op_sel_hi:[1,0]
	v_pk_mul_f32 v[4:5], v[4:5], v[188:189] op_sel_hi:[1,0]
	v_rcp_f32_e32 v190, v190
	v_rcp_f32_e32 v191, v191
	v_rcp_f32_e32 v192, v192
	v_rcp_f32_e32 v193, v193
	v_pk_mul_f32 v[6:7], v[6:7], v[188:189] op_sel_hi:[1,0]
	v_pk_mul_f32 v[4:5], v[4:5], v[190:191]
	v_pk_mul_f32 v[6:7], v[6:7], v[192:193]
	v_cvt_pk_bf16_f32 v198, v12, v13
	v_cvt_pk_bf16_f32 v199, v14, v15
	v_cvt_pk_bf16_f32 v200, v4, v5
	v_cvt_pk_bf16_f32 v201, v6, v7
	global_store_dwordx4 v[202:203], v[198:201], off sc1
	s_cbranch_vccnz .LBB0_219
	s_and_b64 vcc, exec, s[10:11]
	s_cbranch_vccnz .LBB0_218
	s_barrier
	s_branch .LBB0_218

;     __device__ __forceinline__ void operator()(f32x4 (&acc)[2][2][4][2], const Unit& u_, int wr, int wc, int fr, int fq) const {
;     ...
;         const int row0 = u.pm * BM + wr * 64 + fr, col0 = u.pn * BM + wc * 32 + 8 * fq;
;         u32x4 xw[2][4][2]; f32x4 xf[XF32 ? 16 : 1][2];
; #pragma unroll
;         for (int ai = 0; ai < 2; ++ai)
; #pragma unroll
;             for (int m = 0; m < 4; ++m)
; #pragma unroll
;                 for (int bj = 0; bj < 2; ++bj) { const size_t off = (size_t)(row0 + ai * HALF + m * 16) * 2048 + col0 + bj * HALF;
;                     if constexpr (XF32) { xf[(ai * 4 + m) * 2 + bj][0] = *(const f32x4*)(xin + off); xf[(ai * 4 + m) * 2 + bj][1] = *(const f32x4*)(xin + off + 4); }
;                     else if constexpr (BATCH) xw[ai][m][bj] = *(const u32x4*)(xb + off); }
; #pragma unroll
;         for (int ai = 0; ai < 2; ++ai)
; #pragma unroll
;             for (int m = 0; m < 4; ++m) {
;                 const int row = row0 + ai * HALF + m * 16; const size_t off = (size_t)row * 2048 + col0;
;                 float sc = alpha; if constexpr (MODE == 1) sc = rstd_of(ssb[row], 1.0f / 1024.0f);
;                 float q = 0.f;
; #pragma unroll
;                 for (int bj = 0; bj < 2; ++bj) {
;                     f32x4 x0, x1;
;                     if constexpr (XF32) { x0 = xf[(ai * 4 + m) * 2 + bj][0]; x1 = xf[(ai * 4 + m) * 2 + bj][1]; }
;                     else { const u32x4 w = BATCH ? xw[ai][m][bj] : *(const u32x4*)(xb + off + bj * HALF); x0 = (f32x4){bf_lo(w.x), bf_hi(w.x), bf_lo(w.y), bf_hi(w.y)}; x1 = (f32x4){bf_lo(w.z), bf_hi(w.z), bf_lo(w.w), bf_hi(w.w)}; }
;                     const f32x4 v0 = x0 + acc[ai][bj][m][0] * sc, v1 = x1 + acc[ai][bj][m][1] * sc;
;                     *(u32x4*)(xb + off + bj * HALF) = pack8(v0, v1);
;                     if (x8) { typedef unsigned u32x2 __attribute__((ext_vector_type(2))); u32x2 w8; w8.x = pack4_fp8(v0[0] * F8_X_SCALE, v0[1] * F8_X_SCALE, v0[2] * F8_X_SCALE, v0[3] * F8_X_SCALE);
;                         w8.y = pack4_fp8(v1[0] * F8_X_SCALE, v1[1] * F8_X_SCALE, v1[2] * F8_X_SCALE, v1[3] * F8_X_SCALE); *(u32x2*)(x8 + off + bj * HALF) = w8; }
;                     q += sumsq4(v0) + sumsq4(v1);
;                 }
;                 q += __shfl_xor(q, 16); q += __shfl_xor(q, 32);
;                 if (fq == 0 && ssout) atomicAdd(ssout + row, q);
.LBB0_307:
	v_lshl_add_u32 v190, s65, 8, v229
	v_lshl_add_u32 v220, s66, 8, v226
	v_ashrrev_i32_e32 v191, 31, v190
	v_lshlrev_b64 v[242:243], 1, v[190:191]
	v_ashrrev_i32_e32 v221, 31, v220
	v_lshl_add_u64 v[104:105], s[28:29], 0, v[242:243]
	v_lshlrev_b64 v[244:245], 12, v[220:221]
	v_lshl_add_u64 v[106:107], v[104:105], 0, v[244:245]
	global_load_dwordx4 v[234:237], v[106:107], off
	global_load_dwordx4 v[238:241], v[106:107], off offset:256
	v_or_b32_e32 v216, 16, v220
	v_or_b32_e32 v212, 32, v220
	v_or_b32_e32 v208, 48, v220
	v_add_u32_e32 v204, 0x80, v220
	v_add_u32_e32 v200, 0x90, v220
	v_add_u32_e32 v196, 0xa0, v220
	v_add_u32_e32 v192, 0xb0, v220
	v_ashrrev_i32_e32 v217, 31, v216
	v_ashrrev_i32_e32 v213, 31, v212
	v_ashrrev_i32_e32 v209, 31, v208
	v_ashrrev_i32_e32 v205, 31, v204
	v_ashrrev_i32_e32 v201, 31, v200
	v_ashrrev_i32_e32 v197, 31, v196
	v_ashrrev_i32_e32 v193, 31, v192
	v_lshlrev_b64 v[218:219], 12, v[216:217]
	v_lshlrev_b64 v[214:215], 12, v[212:213]
	v_lshlrev_b64 v[210:211], 12, v[208:209]
	v_lshlrev_b64 v[206:207], 12, v[204:205]
	v_lshlrev_b64 v[202:203], 12, v[200:201]
	v_lshlrev_b64 v[198:199], 12, v[196:197]
	v_lshlrev_b64 v[194:195], 12, v[192:193]
	v_lshl_add_u64 v[106:107], v[104:105], 0, v[218:219]
	v_lshl_add_u64 v[116:117], v[104:105], 0, v[214:215]
	v_lshl_add_u64 v[118:119], v[104:105], 0, v[210:211]
	v_lshl_add_u64 v[128:129], v[104:105], 0, v[206:207]
	v_lshl_add_u64 v[130:131], v[104:105], 0, v[202:203]
	v_lshl_add_u64 v[246:247], v[104:105], 0, v[198:199]
	v_lshl_add_u64 v[104:105], v[104:105], 0, v[194:195]
	global_load_dwordx4 v[180:183], v[106:107], off
	global_load_dwordx4 v[176:179], v[106:107], off offset:256
	global_load_dwordx4 v[172:175], v[116:117], off
	global_load_dwordx4 v[168:171], v[116:117], off offset:256
	global_load_dwordx4 v[164:167], v[118:119], off
	global_load_dwordx4 v[160:163], v[118:119], off offset:256
	global_load_dwordx4 v[156:159], v[128:129], off
	global_load_dwordx4 v[152:155], v[128:129], off offset:256
	global_load_dwordx4 v[148:151], v[130:131], off
	global_load_dwordx4 v[144:147], v[130:131], off offset:256
	global_load_dwordx4 v[140:143], v[246:247], off
	s_nop 0
	global_load_dwordx4 v[128:131], v[246:247], off offset:256
	global_load_dwordx4 v[116:119], v[104:105], off
	s_nop 0
	global_load_dwordx4 v[104:107], v[104:105], off offset:256
	s_waitcnt vmcnt(0)
	v_lshlrev_b32_e32 v246, 16, v234
	v_and_b32_e32 v247, 0xffff0000, v234
	v_lshlrev_b32_e32 v234, 16, v235
	v_and_b32_e32 v235, 0xffff0000, v235
	v_lshlrev_b32_e32 v248, 16, v236
	v_and_b32_e32 v249, 0xffff0000, v236
	v_lshlrev_b32_e32 v236, 16, v237
	v_and_b32_e32 v237, 0xffff0000, v237
	v_lshlrev_b32_e32 v250, 16, v238
	v_and_b32_e32 v251, 0xffff0000, v238
	v_lshlrev_b32_e32 v238, 16, v239
	v_and_b32_e32 v239, 0xffff0000, v239
	v_lshlrev_b32_e32 v252, 16, v240
	v_and_b32_e32 v253, 0xffff0000, v240
	v_lshlrev_b32_e32 v240, 16, v241
	v_and_b32_e32 v241, 0xffff0000, v241
	v_pk_fma_f32 v[138:139], v[138:139], 0.5, v[234:235] op_sel_hi:[1,0,1]
	v_pk_fma_f32 v[136:137], v[136:137], 0.5, v[246:247] op_sel_hi:[1,0,1]
	v_pk_fma_f32 v[134:135], v[134:135], 0.5, v[236:237] op_sel_hi:[1,0,1]
	v_pk_fma_f32 v[132:133], v[132:133], 0.5, v[248:249] op_sel_hi:[1,0,1]
	v_pk_fma_f32 v[126:127], v[126:127], 0.5, v[238:239] op_sel_hi:[1,0,1]
	v_pk_fma_f32 v[234:235], v[124:125], 0.5, v[250:251] op_sel_hi:[1,0,1]
	v_pk_fma_f32 v[236:237], v[122:123], 0.5, v[240:241] op_sel_hi:[1,0,1]
	v_pk_fma_f32 v[238:239], v[120:121], 0.5, v[252:253] op_sel_hi:[1,0,1]
	v_cvt_pk_bf16_f32 v122, v136, v137
	v_cvt_pk_bf16_f32 v123, v138, v139
	v_cvt_pk_bf16_f32 v124, v132, v133
	v_cvt_pk_bf16_f32 v125, v134, v135
	v_mul_f32_e32 v120, v137, v137
	v_mul_f32_e32 v121, v139, v139
	v_mul_f32_e32 v133, v133, v133
	v_mul_f32_e32 v135, v135, v135
	v_fmac_f32_e32 v120, v136, v136
	v_fmac_f32_e32 v121, v138, v138
	v_fmac_f32_e32 v133, v132, v132
	v_fmac_f32_e32 v135, v134, v134
	v_add_f32_e32 v120, v120, v121
	v_add_f32_e32 v121, v133, v135
	v_add_f32_e32 v120, v120, v121
	v_mul_f32_e32 v121, v235, v235
	v_mul_f32_e32 v132, v127, v127
	v_fmac_f32_e32 v121, v234, v234
	v_fmac_f32_e32 v132, v126, v126
	v_add_f32_e32 v121, v121, v132
	v_mul_f32_e32 v132, v239, v239
	v_mul_f32_e32 v133, v237, v237
	v_fmac_f32_e32 v132, v238, v238
	v_fmac_f32_e32 v133, v236, v236
	v_add_f32_e32 v132, v132, v133
	v_add_f32_e32 v121, v121, v132
	v_and_b32_e32 v132, 64, v233
	v_add_f32_e32 v121, v120, v121
	v_xor_b32_e32 v120, 16, v233
	v_add_u32_e32 v134, 64, v132
	v_cmp_lt_i32_e32 vcc, v120, v134
	v_lshl_add_u64 v[132:133], s[28:29], 0, v[244:245]
	v_lshl_add_u64 v[132:133], v[132:133], 0, v[242:243]
	v_cndmask_b32_e32 v120, v233, v120, vcc
	v_lshlrev_b32_e32 v120, 2, v120
	ds_bpermute_b32 v135, v120, v121
	global_store_dwordx4 v[132:133], v[122:125], off sc1
	s_nop 1
	v_cvt_pk_bf16_f32 v124, v234, v235
	s_waitcnt lgkmcnt(0)
	v_add_f32_e32 v122, v121, v135
	v_xor_b32_e32 v121, 32, v233
	v_cmp_lt_i32_e32 vcc, v121, v134
	v_cvt_pk_bf16_f32 v125, v126, v127
	v_cvt_pk_bf16_f32 v126, v238, v239
	v_cvt_pk_bf16_f32 v127, v236, v237
	global_store_dwordx4 v[132:133], v[124:127], off offset:256 sc1
	s_nop 0
	v_cndmask_b32_e32 v121, v233, v121, vcc
	v_lshlrev_b32_e32 v121, 2, v121
	ds_bpermute_b32 v123, v121, v122
	s_and_saveexec_b64 s[50:51], s[8:9]
	s_cbranch_execz .LBB0_309
	s_waitcnt lgkmcnt(0)
	v_add_f32_e32 v124, v122, v123
	v_lshl_add_u64 v[122:123], v[220:221], 2, s[74:75]
	global_atomic_add_f32 v[122:123], v124, off
; __device__ __forceinline__ float rstd_of(float ss, float inv_n) { return __builtin_amdgcn_rsqf(ss * inv_n + 1e-6f); }
; __device__ __forceinline__ float bf_lo(unsigned w) { return __uint_as_float(w << 16); }
; __device__ __forceinline__ float bf_hi(unsigned w) { return __uint_as_float(w & 0xffff0000u); }
; __device__ __forceinline__ u32x4 pack8(const f32x4 a, const f32x4 b) { u32x4 w; w.x = cvt_pk_bf16(a[0], a[1]); w.y = cvt_pk_bf16(a[2], a[3]); w.z = cvt_pk_bf16(b[0], b[1]); w.w = cvt_pk_bf16(b[2], b[3]); return w; }
; __device__ __forceinline__ float sumsq4(const f32x4 a) { return (a[0] * a[0] + a[1] * a[1]) + (a[2] * a[2] + a[3] * a[3]); }
;     __device__ __forceinline__ void operator()(f32x4 (&acc)[2][2][4][2], const Unit& u_, int wr, int wc, int fr, int fq) const {
;     ...
;         for (int ai = 0; ai < 2; ++ai)
; #pragma unroll
;             for (int m = 0; m < 4; ++m) {
;                 const int row = row0 + ai * HALF + m * 16; const size_t off = (size_t)row * 2048 + col0;
;                 float sc = alpha; if constexpr (MODE == 1) sc = rstd_of(ssb[row], 1.0f / 1024.0f);
;                 float q = 0.f;
; #pragma unroll
;                 for (int bj = 0; bj < 2; ++bj) {
;                     f32x4 x0, x1;
;                     if constexpr (XF32) { x0 = xf[(ai * 4 + m) * 2 + bj][0]; x1 = xf[(ai * 4 + m) * 2 + bj][1]; }
;                     else { const u32x4 w = BATCH ? xw[ai][m][bj] : *(const u32x4*)(xb + off + bj * HALF); x0 = (f32x4){bf_lo(w.x), bf_hi(w.x), bf_lo(w.y), bf_hi(w.y)}; x1 = (f32x4){bf_lo(w.z), bf_hi(w.z), bf_lo(w.w), bf_hi(w.w)}; }
;                     const f32x4 v0 = x0 + acc[ai][bj][m][0] * sc, v1 = x1 + acc[ai][bj][m][1] * sc;
;                     *(u32x4*)(xb + off + bj * HALF) = pack8(v0, v1);
;                     if (x8) { typedef unsigned u32x2 __attribute__((ext_vector_type(2))); u32x2 w8; w8.x = pack4_fp8(v0[0] * F8_X_SCALE, v0[1] * F8_X_SCALE, v0[2] * F8_X_SCALE, v0[3] * F8_X_SCALE);
;                         w8.y = pack4_fp8(v1[0] * F8_X_SCALE, v1[1] * F8_X_SCALE, v1[2] * F8_X_SCALE, v1[3] * F8_X_SCALE); *(u32x2*)(x8 + off + bj * HALF) = w8; }
;                     q += sumsq4(v0) + sumsq4(v1);
;                 }
;                 q += __shfl_xor(q, 16); q += __shfl_xor(q, 32);
;                 if (fq == 0 && ssout) atomicAdd(ssout + row, q);
.LBB0_309:
	s_or_b64 exec, exec, s[50:51]
	v_lshlrev_b32_e32 v122, 16, v180
	s_waitcnt lgkmcnt(0)
	v_and_b32_e32 v123, 0xffff0000, v180
	v_lshlrev_b32_e32 v124, 16, v181
	v_and_b32_e32 v125, 0xffff0000, v181
	v_lshlrev_b32_e32 v126, 16, v182
	v_and_b32_e32 v127, 0xffff0000, v182
	v_pk_fma_f32 v[112:113], v[112:113], 0.5, v[122:123] op_sel_hi:[1,0,1]
	v_pk_fma_f32 v[114:115], v[114:115], 0.5, v[124:125] op_sel_hi:[1,0,1]
	v_pk_fma_f32 v[124:125], v[108:109], 0.5, v[126:127] op_sel_hi:[1,0,1]
	v_cvt_pk_bf16_f32 v108, v112, v113
	v_mul_f32_e32 v113, v113, v113
	v_lshlrev_b32_e32 v132, 16, v183
	v_and_b32_e32 v133, 0xffff0000, v183
	v_fmac_f32_e32 v113, v112, v112
	v_mul_f32_e32 v112, v115, v115
	v_pk_fma_f32 v[122:123], v[110:111], 0.5, v[132:133] op_sel_hi:[1,0,1]
	v_fmac_f32_e32 v112, v114, v114
	v_cvt_pk_bf16_f32 v109, v114, v115
	v_add_f32_e32 v112, v113, v112
	v_mul_f32_e32 v113, v125, v125
	v_mul_f32_e32 v114, v123, v123
	v_fmac_f32_e32 v113, v124, v124
	v_fmac_f32_e32 v114, v122, v122
	v_add_f32_e32 v113, v113, v114
	v_add_f32_e32 v126, v112, v113
	v_lshlrev_b32_e32 v112, 16, v176
	v_and_b32_e32 v113, 0xffff0000, v176
	v_lshlrev_b32_e32 v114, 16, v177
	v_and_b32_e32 v115, 0xffff0000, v177
	v_cvt_pk_bf16_f32 v110, v124, v125
	v_cvt_pk_bf16_f32 v111, v122, v123
	v_lshlrev_b32_e32 v122, 16, v178
	v_and_b32_e32 v123, 0xffff0000, v178
	v_pk_fma_f32 v[102:103], v[102:103], 0.5, v[114:115] op_sel_hi:[1,0,1]
	v_pk_fma_f32 v[100:101], v[100:101], 0.5, v[112:113] op_sel_hi:[1,0,1]
	v_lshlrev_b32_e32 v124, 16, v179
	v_and_b32_e32 v125, 0xffff0000, v179
	v_pk_fma_f32 v[114:115], v[96:97], 0.5, v[122:123] op_sel_hi:[1,0,1]
	v_mul_f32_e32 v96, v101, v101
	v_mul_f32_e32 v97, v103, v103
	v_pk_fma_f32 v[112:113], v[98:99], 0.5, v[124:125] op_sel_hi:[1,0,1]
	v_fmac_f32_e32 v96, v100, v100
	v_fmac_f32_e32 v97, v102, v102
	v_add_f32_e32 v96, v96, v97
	v_mul_f32_e32 v97, v115, v115
	v_mul_f32_e32 v98, v113, v113
	v_fmac_f32_e32 v97, v114, v114
	v_fmac_f32_e32 v98, v112, v112
	v_add_f32_e32 v97, v97, v98
	v_add_f32_e32 v96, v96, v97
	v_add_f32_e32 v99, v126, v96
	ds_bpermute_b32 v124, v120, v99
	v_lshl_add_u64 v[96:97], s[28:29], 0, v[218:219]
	v_lshl_add_u64 v[122:123], v[190:191], 1, v[96:97]
	global_store_dwordx4 v[122:123], v[108:111], off sc1
	v_cvt_pk_bf16_f32 v98, v100, v101
	s_waitcnt lgkmcnt(0)
	v_add_f32_e32 v96, v99, v124
	ds_bpermute_b32 v97, v121, v96
	v_cvt_pk_bf16_f32 v99, v102, v103
	v_cvt_pk_bf16_f32 v100, v114, v115
	v_cvt_pk_bf16_f32 v101, v112, v113
	global_store_dwordx4 v[122:123], v[98:101], off offset:256 sc1
	s_and_saveexec_b64 s[50:51], s[8:9]
	s_cbranch_execz .LBB0_311
	s_waitcnt lgkmcnt(0)
	v_add_f32_e32 v98, v96, v97
	v_lshl_add_u64 v[96:97], v[216:217], 2, s[74:75]
	global_atomic_add_f32 v[96:97], v98, off
.LBB0_311:
	s_or_b64 exec, exec, s[50:51]
	v_lshlrev_b32_e32 v96, 16, v172
	s_waitcnt lgkmcnt(0)
	v_and_b32_e32 v97, 0xffff0000, v172
	v_lshlrev_b32_e32 v98, 16, v173
	v_and_b32_e32 v99, 0xffff0000, v173
	v_lshlrev_b32_e32 v100, 16, v174
	v_and_b32_e32 v101, 0xffff0000, v174
	v_pk_fma_f32 v[92:93], v[92:93], 0.5, v[96:97] op_sel_hi:[1,0,1]
	v_pk_fma_f32 v[94:95], v[94:95], 0.5, v[98:99] op_sel_hi:[1,0,1]
	v_pk_fma_f32 v[98:99], v[88:89], 0.5, v[100:101] op_sel_hi:[1,0,1]
	v_cvt_pk_bf16_f32 v88, v92, v93
	v_mul_f32_e32 v93, v93, v93
	v_lshlrev_b32_e32 v102, 16, v175
	v_and_b32_e32 v103, 0xffff0000, v175
	v_fmac_f32_e32 v93, v92, v92
	v_mul_f32_e32 v92, v95, v95
	v_pk_fma_f32 v[96:97], v[90:91], 0.5, v[102:103] op_sel_hi:[1,0,1]
	v_fmac_f32_e32 v92, v94, v94
	v_cvt_pk_bf16_f32 v89, v94, v95
	v_add_f32_e32 v92, v93, v92
	v_mul_f32_e32 v93, v99, v99
	v_mul_f32_e32 v94, v97, v97
	v_fmac_f32_e32 v93, v98, v98
	v_fmac_f32_e32 v94, v96, v96
	v_add_f32_e32 v93, v93, v94
	v_add_f32_e32 v100, v92, v93
	v_lshlrev_b32_e32 v92, 16, v168
	v_and_b32_e32 v93, 0xffff0000, v168
	v_lshlrev_b32_e32 v94, 16, v169
	v_and_b32_e32 v95, 0xffff0000, v169
	v_cvt_pk_bf16_f32 v90, v98, v99
	v_cvt_pk_bf16_f32 v91, v96, v97
	v_lshlrev_b32_e32 v96, 16, v170
	v_and_b32_e32 v97, 0xffff0000, v170
	v_pk_fma_f32 v[86:87], v[86:87], 0.5, v[94:95] op_sel_hi:[1,0,1]
	v_pk_fma_f32 v[84:85], v[84:85], 0.5, v[92:93] op_sel_hi:[1,0,1]
	v_lshlrev_b32_e32 v98, 16, v171
	v_and_b32_e32 v99, 0xffff0000, v171
	v_pk_fma_f32 v[94:95], v[80:81], 0.5, v[96:97] op_sel_hi:[1,0,1]
	v_mul_f32_e32 v80, v85, v85
	v_mul_f32_e32 v81, v87, v87
	v_pk_fma_f32 v[92:93], v[82:83], 0.5, v[98:99] op_sel_hi:[1,0,1]
	v_fmac_f32_e32 v80, v84, v84
	v_fmac_f32_e32 v81, v86, v86
	v_add_f32_e32 v80, v80, v81
	v_mul_f32_e32 v81, v95, v95
	v_mul_f32_e32 v82, v93, v93
	v_fmac_f32_e32 v81, v94, v94
	v_fmac_f32_e32 v82, v92, v92
	v_add_f32_e32 v81, v81, v82
	v_add_f32_e32 v80, v80, v81
	v_add_f32_e32 v83, v100, v80
	ds_bpermute_b32 v98, v120, v83
	v_lshl_add_u64 v[80:81], s[28:29], 0, v[214:215]
	v_lshl_add_u64 v[96:97], v[190:191], 1, v[80:81]
	global_store_dwordx4 v[96:97], v[88:91], off sc1
	v_cvt_pk_bf16_f32 v82, v84, v85
	s_waitcnt lgkmcnt(0)
	v_add_f32_e32 v80, v83, v98
	ds_bpermute_b32 v81, v121, v80
	v_cvt_pk_bf16_f32 v83, v86, v87
	v_cvt_pk_bf16_f32 v84, v94, v95
	v_cvt_pk_bf16_f32 v85, v92, v93
	global_store_dwordx4 v[96:97], v[82:85], off offset:256 sc1
	s_and_saveexec_b64 s[50:51], s[8:9]
	s_cbranch_execz .LBB0_313
	s_waitcnt lgkmcnt(0)
	v_add_f32_e32 v82, v80, v81
	v_lshl_add_u64 v[80:81], v[212:213], 2, s[74:75]
	global_atomic_add_f32 v[80:81], v82, off
; __device__ __forceinline__ float rstd_of(float ss, float inv_n) { return __builtin_amdgcn_rsqf(ss * inv_n + 1e-6f); }
; __device__ __forceinline__ float bf_lo(unsigned w) { return __uint_as_float(w << 16); }
; __device__ __forceinline__ float bf_hi(unsigned w) { return __uint_as_float(w & 0xffff0000u); }
; __device__ __forceinline__ u32x4 pack8(const f32x4 a, const f32x4 b) { u32x4 w; w.x = cvt_pk_bf16(a[0], a[1]); w.y = cvt_pk_bf16(a[2], a[3]); w.z = cvt_pk_bf16(b[0], b[1]); w.w = cvt_pk_bf16(b[2], b[3]); return w; }
; __device__ __forceinline__ float sumsq4(const f32x4 a) { return (a[0] * a[0] + a[1] * a[1]) + (a[2] * a[2] + a[3] * a[3]); }
;     __device__ __forceinline__ void operator()(f32x4 (&acc)[2][2][4][2], const Unit& u_, int wr, int wc, int fr, int fq) const {
;     ...
;         for (int ai = 0; ai < 2; ++ai)
; #pragma unroll
;             for (int m = 0; m < 4; ++m) {
;                 const int row = row0 + ai * HALF + m * 16; const size_t off = (size_t)row * 2048 + col0;
;                 float sc = alpha; if constexpr (MODE == 1) sc = rstd_of(ssb[row], 1.0f / 1024.0f);
;                 float q = 0.f;
; #pragma unroll
;                 for (int bj = 0; bj < 2; ++bj) {
;                     f32x4 x0, x1;
;                     if constexpr (XF32) { x0 = xf[(ai * 4 + m) * 2 + bj][0]; x1 = xf[(ai * 4 + m) * 2 + bj][1]; }
;                     else { const u32x4 w = BATCH ? xw[ai][m][bj] : *(const u32x4*)(xb + off + bj * HALF); x0 = (f32x4){bf_lo(w.x), bf_hi(w.x), bf_lo(w.y), bf_hi(w.y)}; x1 = (f32x4){bf_lo(w.z), bf_hi(w.z), bf_lo(w.w), bf_hi(w.w)}; }
;                     const f32x4 v0 = x0 + acc[ai][bj][m][0] * sc, v1 = x1 + acc[ai][bj][m][1] * sc;
;                     *(u32x4*)(xb + off + bj * HALF) = pack8(v0, v1);
;                     if (x8) { typedef unsigned u32x2 __attribute__((ext_vector_type(2))); u32x2 w8; w8.x = pack4_fp8(v0[0] * F8_X_SCALE, v0[1] * F8_X_SCALE, v0[2] * F8_X_SCALE, v0[3] * F8_X_SCALE);
;                         w8.y = pack4_fp8(v1[0] * F8_X_SCALE, v1[1] * F8_X_SCALE, v1[2] * F8_X_SCALE, v1[3] * F8_X_SCALE); *(u32x2*)(x8 + off + bj * HALF) = w8; }
;                     q += sumsq4(v0) + sumsq4(v1);
;                 }
;                 q += __shfl_xor(q, 16); q += __shfl_xor(q, 32);
;                 if (fq == 0 && ssout) atomicAdd(ssout + row, q);
.LBB0_313:
	s_or_b64 exec, exec, s[50:51]
	v_lshlrev_b32_e32 v80, 16, v164
	s_waitcnt lgkmcnt(0)
	v_and_b32_e32 v81, 0xffff0000, v164
	v_lshlrev_b32_e32 v82, 16, v165
	v_and_b32_e32 v83, 0xffff0000, v165
	v_lshlrev_b32_e32 v84, 16, v166
	v_and_b32_e32 v85, 0xffff0000, v166
	v_pk_fma_f32 v[76:77], v[76:77], 0.5, v[80:81] op_sel_hi:[1,0,1]
	v_pk_fma_f32 v[78:79], v[78:79], 0.5, v[82:83] op_sel_hi:[1,0,1]
	v_pk_fma_f32 v[82:83], v[72:73], 0.5, v[84:85] op_sel_hi:[1,0,1]
	v_cvt_pk_bf16_f32 v72, v76, v77
	v_mul_f32_e32 v77, v77, v77
	v_lshlrev_b32_e32 v86, 16, v167
	v_and_b32_e32 v87, 0xffff0000, v167
	v_fmac_f32_e32 v77, v76, v76
	v_mul_f32_e32 v76, v79, v79
	v_pk_fma_f32 v[80:81], v[74:75], 0.5, v[86:87] op_sel_hi:[1,0,1]
	v_fmac_f32_e32 v76, v78, v78
	v_cvt_pk_bf16_f32 v73, v78, v79
	v_add_f32_e32 v76, v77, v76
	v_mul_f32_e32 v77, v83, v83
	v_mul_f32_e32 v78, v81, v81
	v_fmac_f32_e32 v77, v82, v82
	v_fmac_f32_e32 v78, v80, v80
	v_add_f32_e32 v77, v77, v78
	v_add_f32_e32 v84, v76, v77
	v_lshlrev_b32_e32 v76, 16, v160
	v_and_b32_e32 v77, 0xffff0000, v160
	v_lshlrev_b32_e32 v78, 16, v161
	v_and_b32_e32 v79, 0xffff0000, v161
	v_cvt_pk_bf16_f32 v74, v82, v83
	v_cvt_pk_bf16_f32 v75, v80, v81
	v_lshlrev_b32_e32 v80, 16, v162
	v_and_b32_e32 v81, 0xffff0000, v162
	v_pk_fma_f32 v[70:71], v[70:71], 0.5, v[78:79] op_sel_hi:[1,0,1]
	v_pk_fma_f32 v[68:69], v[68:69], 0.5, v[76:77] op_sel_hi:[1,0,1]
	v_lshlrev_b32_e32 v82, 16, v163
	v_and_b32_e32 v83, 0xffff0000, v163
	v_pk_fma_f32 v[78:79], v[64:65], 0.5, v[80:81] op_sel_hi:[1,0,1]
	v_mul_f32_e32 v64, v69, v69
	v_mul_f32_e32 v65, v71, v71
	v_pk_fma_f32 v[76:77], v[66:67], 0.5, v[82:83] op_sel_hi:[1,0,1]
	v_fmac_f32_e32 v64, v68, v68
	v_fmac_f32_e32 v65, v70, v70
	v_add_f32_e32 v64, v64, v65
	v_mul_f32_e32 v65, v79, v79
	v_mul_f32_e32 v66, v77, v77
	v_fmac_f32_e32 v65, v78, v78
	v_fmac_f32_e32 v66, v76, v76
	v_add_f32_e32 v65, v65, v66
	v_add_f32_e32 v64, v64, v65
	v_add_f32_e32 v67, v84, v64
	ds_bpermute_b32 v82, v120, v67
	v_lshl_add_u64 v[64:65], s[28:29], 0, v[210:211]
	v_lshl_add_u64 v[80:81], v[190:191], 1, v[64:65]
	global_store_dwordx4 v[80:81], v[72:75], off sc1
	v_cvt_pk_bf16_f32 v66, v68, v69
	s_waitcnt lgkmcnt(0)
	v_add_f32_e32 v64, v67, v82
	ds_bpermute_b32 v65, v121, v64
	v_cvt_pk_bf16_f32 v67, v70, v71
	v_cvt_pk_bf16_f32 v68, v78, v79
	v_cvt_pk_bf16_f32 v69, v76, v77
	global_store_dwordx4 v[80:81], v[66:69], off offset:256 sc1
	s_and_saveexec_b64 s[50:51], s[8:9]
	s_cbranch_execz .LBB0_315
	s_waitcnt lgkmcnt(0)
	v_add_f32_e32 v66, v64, v65
	v_lshl_add_u64 v[64:65], v[208:209], 2, s[74:75]
	global_atomic_add_f32 v[64:65], v66, off
.LBB0_315:
	s_or_b64 exec, exec, s[50:51]
	v_lshlrev_b32_e32 v64, 16, v156
	s_waitcnt lgkmcnt(0)
	v_and_b32_e32 v65, 0xffff0000, v156
	v_lshlrev_b32_e32 v66, 16, v157
	v_and_b32_e32 v67, 0xffff0000, v157
	v_lshlrev_b32_e32 v68, 16, v158
	v_and_b32_e32 v69, 0xffff0000, v158
	v_pk_fma_f32 v[60:61], v[60:61], 0.5, v[64:65] op_sel_hi:[1,0,1]
	v_pk_fma_f32 v[62:63], v[62:63], 0.5, v[66:67] op_sel_hi:[1,0,1]
	v_pk_fma_f32 v[66:67], v[56:57], 0.5, v[68:69] op_sel_hi:[1,0,1]
	v_cvt_pk_bf16_f32 v56, v60, v61
	v_mul_f32_e32 v61, v61, v61
	v_lshlrev_b32_e32 v70, 16, v159
	v_and_b32_e32 v71, 0xffff0000, v159
	v_fmac_f32_e32 v61, v60, v60
	v_mul_f32_e32 v60, v63, v63
	v_pk_fma_f32 v[64:65], v[58:59], 0.5, v[70:71] op_sel_hi:[1,0,1]
	v_fmac_f32_e32 v60, v62, v62
	v_cvt_pk_bf16_f32 v57, v62, v63
	v_add_f32_e32 v60, v61, v60
	v_mul_f32_e32 v61, v67, v67
	v_mul_f32_e32 v62, v65, v65
	v_fmac_f32_e32 v61, v66, v66
	v_fmac_f32_e32 v62, v64, v64
	v_add_f32_e32 v61, v61, v62
	v_add_f32_e32 v68, v60, v61
	v_lshlrev_b32_e32 v60, 16, v152
	v_and_b32_e32 v61, 0xffff0000, v152
	v_lshlrev_b32_e32 v62, 16, v153
	v_and_b32_e32 v63, 0xffff0000, v153
	v_cvt_pk_bf16_f32 v58, v66, v67
	v_cvt_pk_bf16_f32 v59, v64, v65
	v_lshlrev_b32_e32 v64, 16, v154
	v_and_b32_e32 v65, 0xffff0000, v154
	v_pk_fma_f32 v[54:55], v[54:55], 0.5, v[62:63] op_sel_hi:[1,0,1]
	v_pk_fma_f32 v[52:53], v[52:53], 0.5, v[60:61] op_sel_hi:[1,0,1]
	v_lshlrev_b32_e32 v66, 16, v155
	v_and_b32_e32 v67, 0xffff0000, v155
	v_pk_fma_f32 v[62:63], v[48:49], 0.5, v[64:65] op_sel_hi:[1,0,1]
	v_mul_f32_e32 v48, v53, v53
	v_mul_f32_e32 v49, v55, v55
	v_pk_fma_f32 v[60:61], v[50:51], 0.5, v[66:67] op_sel_hi:[1,0,1]
	v_fmac_f32_e32 v48, v52, v52
	v_fmac_f32_e32 v49, v54, v54
	v_add_f32_e32 v48, v48, v49
	v_mul_f32_e32 v49, v63, v63
	v_mul_f32_e32 v50, v61, v61
	v_fmac_f32_e32 v49, v62, v62
	v_fmac_f32_e32 v50, v60, v60
	v_add_f32_e32 v49, v49, v50
	v_add_f32_e32 v48, v48, v49
	v_add_f32_e32 v51, v68, v48
	ds_bpermute_b32 v66, v120, v51
	v_lshl_add_u64 v[48:49], s[28:29], 0, v[206:207]
	v_lshl_add_u64 v[64:65], v[190:191], 1, v[48:49]
	global_store_dwordx4 v[64:65], v[56:59], off sc1
	v_cvt_pk_bf16_f32 v50, v52, v53
	s_waitcnt lgkmcnt(0)
	v_add_f32_e32 v48, v51, v66
	ds_bpermute_b32 v49, v121, v48
	v_cvt_pk_bf16_f32 v51, v54, v55
	v_cvt_pk_bf16_f32 v52, v62, v63
	v_cvt_pk_bf16_f32 v53, v60, v61
	global_store_dwordx4 v[64:65], v[50:53], off offset:256 sc1
	s_and_saveexec_b64 s[50:51], s[8:9]
	s_cbranch_execz .LBB0_317
	s_waitcnt lgkmcnt(0)
	v_add_f32_e32 v50, v48, v49
	v_lshl_add_u64 v[48:49], v[204:205], 2, s[74:75]
	global_atomic_add_f32 v[48:49], v50, off
; __device__ __forceinline__ float rstd_of(float ss, float inv_n) { return __builtin_amdgcn_rsqf(ss * inv_n + 1e-6f); }
; __device__ __forceinline__ float bf_lo(unsigned w) { return __uint_as_float(w << 16); }
; __device__ __forceinline__ float bf_hi(unsigned w) { return __uint_as_float(w & 0xffff0000u); }
; __device__ __forceinline__ u32x4 pack8(const f32x4 a, const f32x4 b) { u32x4 w; w.x = cvt_pk_bf16(a[0], a[1]); w.y = cvt_pk_bf16(a[2], a[3]); w.z = cvt_pk_bf16(b[0], b[1]); w.w = cvt_pk_bf16(b[2], b[3]); return w; }
; __device__ __forceinline__ float sumsq4(const f32x4 a) { return (a[0] * a[0] + a[1] * a[1]) + (a[2] * a[2] + a[3] * a[3]); }
;     __device__ __forceinline__ void operator()(f32x4 (&acc)[2][2][4][2], const Unit& u_, int wr, int wc, int fr, int fq) const {
;     ...
;             for (int m = 0; m < 4; ++m) {
;                 const int row = row0 + ai * HALF + m * 16; const size_t off = (size_t)row * 2048 + col0;
;                 float sc = alpha; if constexpr (MODE == 1) sc = rstd_of(ssb[row], 1.0f / 1024.0f);
;                 float q = 0.f;
; #pragma unroll
;                 for (int bj = 0; bj < 2; ++bj) {
;                     f32x4 x0, x1;
;                     if constexpr (XF32) { x0 = xf[(ai * 4 + m) * 2 + bj][0]; x1 = xf[(ai * 4 + m) * 2 + bj][1]; }
;                     else { const u32x4 w = BATCH ? xw[ai][m][bj] : *(const u32x4*)(xb + off + bj * HALF); x0 = (f32x4){bf_lo(w.x), bf_hi(w.x), bf_lo(w.y), bf_hi(w.y)}; x1 = (f32x4){bf_lo(w.z), bf_hi(w.z), bf_lo(w.w), bf_hi(w.w)}; }
;                     const f32x4 v0 = x0 + acc[ai][bj][m][0] * sc, v1 = x1 + acc[ai][bj][m][1] * sc;
;                     *(u32x4*)(xb + off + bj * HALF) = pack8(v0, v1);
;                     if (x8) { typedef unsigned u32x2 __attribute__((ext_vector_type(2))); u32x2 w8; w8.x = pack4_fp8(v0[0] * F8_X_SCALE, v0[1] * F8_X_SCALE, v0[2] * F8_X_SCALE, v0[3] * F8_X_SCALE);
;                         w8.y = pack4_fp8(v1[0] * F8_X_SCALE, v1[1] * F8_X_SCALE, v1[2] * F8_X_SCALE, v1[3] * F8_X_SCALE); *(u32x2*)(x8 + off + bj * HALF) = w8; }
;                     q += sumsq4(v0) + sumsq4(v1);
;                 }
;                 q += __shfl_xor(q, 16); q += __shfl_xor(q, 32);
;                 if (fq == 0 && ssout) atomicAdd(ssout + row, q);
.LBB0_317:
	s_or_b64 exec, exec, s[50:51]
	v_lshlrev_b32_e32 v48, 16, v148
	s_waitcnt lgkmcnt(0)
	v_and_b32_e32 v49, 0xffff0000, v148
	v_lshlrev_b32_e32 v50, 16, v149
	v_and_b32_e32 v51, 0xffff0000, v149
	v_lshlrev_b32_e32 v52, 16, v150
	v_and_b32_e32 v53, 0xffff0000, v150
	v_pk_fma_f32 v[44:45], v[44:45], 0.5, v[48:49] op_sel_hi:[1,0,1]
	v_pk_fma_f32 v[46:47], v[46:47], 0.5, v[50:51] op_sel_hi:[1,0,1]
	v_pk_fma_f32 v[50:51], v[40:41], 0.5, v[52:53] op_sel_hi:[1,0,1]
	v_cvt_pk_bf16_f32 v40, v44, v45
	v_mul_f32_e32 v45, v45, v45
	v_lshlrev_b32_e32 v54, 16, v151
	v_and_b32_e32 v55, 0xffff0000, v151
	v_fmac_f32_e32 v45, v44, v44
	v_mul_f32_e32 v44, v47, v47
	v_pk_fma_f32 v[48:49], v[42:43], 0.5, v[54:55] op_sel_hi:[1,0,1]
	v_fmac_f32_e32 v44, v46, v46
	v_cvt_pk_bf16_f32 v41, v46, v47
	v_add_f32_e32 v44, v45, v44
	v_mul_f32_e32 v45, v51, v51
	v_mul_f32_e32 v46, v49, v49
	v_fmac_f32_e32 v45, v50, v50
	v_fmac_f32_e32 v46, v48, v48
	v_add_f32_e32 v45, v45, v46
	v_add_f32_e32 v52, v44, v45
	v_lshlrev_b32_e32 v44, 16, v144
	v_and_b32_e32 v45, 0xffff0000, v144
	v_lshlrev_b32_e32 v46, 16, v145
	v_and_b32_e32 v47, 0xffff0000, v145
	v_cvt_pk_bf16_f32 v42, v50, v51
	v_cvt_pk_bf16_f32 v43, v48, v49
	v_lshlrev_b32_e32 v48, 16, v146
	v_and_b32_e32 v49, 0xffff0000, v146
	v_pk_fma_f32 v[38:39], v[38:39], 0.5, v[46:47] op_sel_hi:[1,0,1]
	v_pk_fma_f32 v[36:37], v[36:37], 0.5, v[44:45] op_sel_hi:[1,0,1]
	v_lshlrev_b32_e32 v50, 16, v147
	v_and_b32_e32 v51, 0xffff0000, v147
	v_pk_fma_f32 v[46:47], v[32:33], 0.5, v[48:49] op_sel_hi:[1,0,1]
	v_mul_f32_e32 v32, v37, v37
	v_mul_f32_e32 v33, v39, v39
	v_pk_fma_f32 v[44:45], v[34:35], 0.5, v[50:51] op_sel_hi:[1,0,1]
	v_fmac_f32_e32 v32, v36, v36
	v_fmac_f32_e32 v33, v38, v38
	v_add_f32_e32 v32, v32, v33
	v_mul_f32_e32 v33, v47, v47
	v_mul_f32_e32 v34, v45, v45
	v_fmac_f32_e32 v33, v46, v46
	v_fmac_f32_e32 v34, v44, v44
	v_add_f32_e32 v33, v33, v34
	v_add_f32_e32 v32, v32, v33
	v_add_f32_e32 v35, v52, v32
	ds_bpermute_b32 v50, v120, v35
	v_lshl_add_u64 v[32:33], s[28:29], 0, v[202:203]
	v_lshl_add_u64 v[48:49], v[190:191], 1, v[32:33]
	global_store_dwordx4 v[48:49], v[40:43], off sc1
	v_cvt_pk_bf16_f32 v34, v36, v37
	s_waitcnt lgkmcnt(0)
	v_add_f32_e32 v32, v35, v50
	ds_bpermute_b32 v33, v121, v32
	v_cvt_pk_bf16_f32 v35, v38, v39
	v_cvt_pk_bf16_f32 v36, v46, v47
	v_cvt_pk_bf16_f32 v37, v44, v45
	global_store_dwordx4 v[48:49], v[34:37], off offset:256 sc1
	s_and_saveexec_b64 s[50:51], s[8:9]
	s_cbranch_execz .LBB0_319
	s_waitcnt lgkmcnt(0)
	v_add_f32_e32 v34, v32, v33
	v_lshl_add_u64 v[32:33], v[200:201], 2, s[74:75]
	global_atomic_add_f32 v[32:33], v34, off
; __device__ __forceinline__ float rstd_of(float ss, float inv_n) { return __builtin_amdgcn_rsqf(ss * inv_n + 1e-6f); }
; __device__ __forceinline__ float bf_lo(unsigned w) { return __uint_as_float(w << 16); }
; __device__ __forceinline__ float bf_hi(unsigned w) { return __uint_as_float(w & 0xffff0000u); }
; __device__ __forceinline__ u32x4 pack8(const f32x4 a, const f32x4 b) { u32x4 w; w.x = cvt_pk_bf16(a[0], a[1]); w.y = cvt_pk_bf16(a[2], a[3]); w.z = cvt_pk_bf16(b[0], b[1]); w.w = cvt_pk_bf16(b[2], b[3]); return w; }
; __device__ __forceinline__ float sumsq4(const f32x4 a) { return (a[0] * a[0] + a[1] * a[1]) + (a[2] * a[2] + a[3] * a[3]); }
;     __device__ __forceinline__ void operator()(f32x4 (&acc)[2][2][4][2], const Unit& u_, int wr, int wc, int fr, int fq) const {
;     ...
;             for (int m = 0; m < 4; ++m) {
;                 const int row = row0 + ai * HALF + m * 16; const size_t off = (size_t)row * 2048 + col0;
;                 float sc = alpha; if constexpr (MODE == 1) sc = rstd_of(ssb[row], 1.0f / 1024.0f);
;                 float q = 0.f;
; #pragma unroll
;                 for (int bj = 0; bj < 2; ++bj) {
;                     f32x4 x0, x1;
;                     if constexpr (XF32) { x0 = xf[(ai * 4 + m) * 2 + bj][0]; x1 = xf[(ai * 4 + m) * 2 + bj][1]; }
;                     else { const u32x4 w = BATCH ? xw[ai][m][bj] : *(const u32x4*)(xb + off + bj * HALF); x0 = (f32x4){bf_lo(w.x), bf_hi(w.x), bf_lo(w.y), bf_hi(w.y)}; x1 = (f32x4){bf_lo(w.z), bf_hi(w.z), bf_lo(w.w), bf_hi(w.w)}; }
;                     const f32x4 v0 = x0 + acc[ai][bj][m][0] * sc, v1 = x1 + acc[ai][bj][m][1] * sc;
;                     *(u32x4*)(xb + off + bj * HALF) = pack8(v0, v1);
;                     if (x8) { typedef unsigned u32x2 __attribute__((ext_vector_type(2))); u32x2 w8; w8.x = pack4_fp8(v0[0] * F8_X_SCALE, v0[1] * F8_X_SCALE, v0[2] * F8_X_SCALE, v0[3] * F8_X_SCALE);
;                         w8.y = pack4_fp8(v1[0] * F8_X_SCALE, v1[1] * F8_X_SCALE, v1[2] * F8_X_SCALE, v1[3] * F8_X_SCALE); *(u32x2*)(x8 + off + bj * HALF) = w8; }
;                     q += sumsq4(v0) + sumsq4(v1);
;                 }
;                 q += __shfl_xor(q, 16); q += __shfl_xor(q, 32);
;                 if (fq == 0 && ssout) atomicAdd(ssout + row, q);
.LBB0_319:
	s_or_b64 exec, exec, s[50:51]
	v_lshlrev_b32_e32 v32, 16, v140
	s_waitcnt lgkmcnt(0)
	v_and_b32_e32 v33, 0xffff0000, v140
	v_lshlrev_b32_e32 v34, 16, v141
	v_and_b32_e32 v35, 0xffff0000, v141
	v_lshlrev_b32_e32 v36, 16, v142
	v_and_b32_e32 v37, 0xffff0000, v142
	v_pk_fma_f32 v[28:29], v[28:29], 0.5, v[32:33] op_sel_hi:[1,0,1]
	v_pk_fma_f32 v[30:31], v[30:31], 0.5, v[34:35] op_sel_hi:[1,0,1]
	v_pk_fma_f32 v[34:35], v[24:25], 0.5, v[36:37] op_sel_hi:[1,0,1]
	v_cvt_pk_bf16_f32 v24, v28, v29
	v_mul_f32_e32 v29, v29, v29
	v_lshlrev_b32_e32 v38, 16, v143
	v_and_b32_e32 v39, 0xffff0000, v143
	v_fmac_f32_e32 v29, v28, v28
	v_mul_f32_e32 v28, v31, v31
	v_pk_fma_f32 v[32:33], v[26:27], 0.5, v[38:39] op_sel_hi:[1,0,1]
	v_fmac_f32_e32 v28, v30, v30
	v_cvt_pk_bf16_f32 v25, v30, v31
	v_add_f32_e32 v28, v29, v28
	v_mul_f32_e32 v29, v35, v35
	v_mul_f32_e32 v30, v33, v33
	v_fmac_f32_e32 v29, v34, v34
	v_fmac_f32_e32 v30, v32, v32
	v_add_f32_e32 v29, v29, v30
	v_add_f32_e32 v36, v28, v29
	v_lshlrev_b32_e32 v28, 16, v128
	v_and_b32_e32 v29, 0xffff0000, v128
	v_lshlrev_b32_e32 v30, 16, v129
	v_and_b32_e32 v31, 0xffff0000, v129
	v_cvt_pk_bf16_f32 v26, v34, v35
	v_cvt_pk_bf16_f32 v27, v32, v33
	v_lshlrev_b32_e32 v32, 16, v130
	v_and_b32_e32 v33, 0xffff0000, v130
	v_pk_fma_f32 v[22:23], v[22:23], 0.5, v[30:31] op_sel_hi:[1,0,1]
	v_pk_fma_f32 v[20:21], v[20:21], 0.5, v[28:29] op_sel_hi:[1,0,1]
	v_lshlrev_b32_e32 v34, 16, v131
	v_and_b32_e32 v35, 0xffff0000, v131
	v_pk_fma_f32 v[30:31], v[16:17], 0.5, v[32:33] op_sel_hi:[1,0,1]
	v_mul_f32_e32 v16, v21, v21
	v_mul_f32_e32 v17, v23, v23
	v_pk_fma_f32 v[28:29], v[18:19], 0.5, v[34:35] op_sel_hi:[1,0,1]
	v_fmac_f32_e32 v16, v20, v20
	v_fmac_f32_e32 v17, v22, v22
	v_add_f32_e32 v16, v16, v17
	v_mul_f32_e32 v17, v31, v31
	v_mul_f32_e32 v18, v29, v29
	v_fmac_f32_e32 v17, v30, v30
	v_fmac_f32_e32 v18, v28, v28
	v_add_f32_e32 v17, v17, v18
	v_add_f32_e32 v16, v16, v17
	v_add_f32_e32 v19, v36, v16
	ds_bpermute_b32 v34, v120, v19
	v_lshl_add_u64 v[16:17], s[28:29], 0, v[198:199]
	v_lshl_add_u64 v[32:33], v[190:191], 1, v[16:17]
	global_store_dwordx4 v[32:33], v[24:27], off sc1
	v_cvt_pk_bf16_f32 v18, v20, v21
	s_waitcnt lgkmcnt(0)
	v_add_f32_e32 v16, v19, v34
	ds_bpermute_b32 v17, v121, v16
	v_cvt_pk_bf16_f32 v19, v22, v23
	v_cvt_pk_bf16_f32 v20, v30, v31
	v_cvt_pk_bf16_f32 v21, v28, v29
	global_store_dwordx4 v[32:33], v[18:21], off offset:256 sc1
	s_and_saveexec_b64 s[50:51], s[8:9]
	s_cbranch_execz .LBB0_321
	s_waitcnt lgkmcnt(0)
	v_add_f32_e32 v18, v16, v17
	v_lshl_add_u64 v[16:17], v[196:197], 2, s[74:75]
	global_atomic_add_f32 v[16:17], v18, off
.LBB0_321:
	s_or_b64 exec, exec, s[50:51]
	v_lshlrev_b32_e32 v16, 16, v116
	s_waitcnt lgkmcnt(0)
	v_and_b32_e32 v17, 0xffff0000, v116
	v_lshlrev_b32_e32 v18, 16, v117
	v_and_b32_e32 v19, 0xffff0000, v117
	v_lshlrev_b32_e32 v20, 16, v118
	v_and_b32_e32 v21, 0xffff0000, v118
	v_pk_fma_f32 v[12:13], v[12:13], 0.5, v[16:17] op_sel_hi:[1,0,1]
	v_pk_fma_f32 v[14:15], v[14:15], 0.5, v[18:19] op_sel_hi:[1,0,1]
	v_pk_fma_f32 v[18:19], v[8:9], 0.5, v[20:21] op_sel_hi:[1,0,1]
	v_cvt_pk_bf16_f32 v8, v12, v13
	v_mul_f32_e32 v13, v13, v13
	v_lshlrev_b32_e32 v22, 16, v119
	v_and_b32_e32 v23, 0xffff0000, v119
	v_fmac_f32_e32 v13, v12, v12
	v_mul_f32_e32 v12, v15, v15
	v_pk_fma_f32 v[16:17], v[10:11], 0.5, v[22:23] op_sel_hi:[1,0,1]
	v_fmac_f32_e32 v12, v14, v14
	v_cvt_pk_bf16_f32 v9, v14, v15
	v_add_f32_e32 v12, v13, v12
	v_mul_f32_e32 v13, v19, v19
	v_mul_f32_e32 v14, v17, v17
	v_fmac_f32_e32 v13, v18, v18
	v_fmac_f32_e32 v14, v16, v16
	v_add_f32_e32 v13, v13, v14
	v_add_f32_e32 v20, v12, v13
	v_lshlrev_b32_e32 v12, 16, v104
	v_and_b32_e32 v13, 0xffff0000, v104
	v_lshlrev_b32_e32 v14, 16, v105
	v_and_b32_e32 v15, 0xffff0000, v105
	v_cvt_pk_bf16_f32 v10, v18, v19
	v_cvt_pk_bf16_f32 v11, v16, v17
	v_lshlrev_b32_e32 v16, 16, v106
	v_and_b32_e32 v17, 0xffff0000, v106
	v_pk_fma_f32 v[6:7], v[6:7], 0.5, v[14:15] op_sel_hi:[1,0,1]
	v_pk_fma_f32 v[4:5], v[4:5], 0.5, v[12:13] op_sel_hi:[1,0,1]
	v_lshlrev_b32_e32 v18, 16, v107
	v_and_b32_e32 v19, 0xffff0000, v107
	v_pk_fma_f32 v[14:15], v[0:1], 0.5, v[16:17] op_sel_hi:[1,0,1]
	v_mul_f32_e32 v0, v5, v5
	v_mul_f32_e32 v1, v7, v7
	v_pk_fma_f32 v[12:13], v[2:3], 0.5, v[18:19] op_sel_hi:[1,0,1]
	v_fmac_f32_e32 v0, v4, v4
	v_fmac_f32_e32 v1, v6, v6
	v_add_f32_e32 v0, v0, v1
	v_mul_f32_e32 v1, v15, v15
	v_mul_f32_e32 v2, v13, v13
	v_fmac_f32_e32 v1, v14, v14
	v_fmac_f32_e32 v2, v12, v12
	v_add_f32_e32 v1, v1, v2
	v_add_f32_e32 v0, v0, v1
	v_add_f32_e32 v3, v20, v0
	ds_bpermute_b32 v18, v120, v3
	v_lshl_add_u64 v[0:1], s[28:29], 0, v[194:195]
	v_lshl_add_u64 v[16:17], v[190:191], 1, v[0:1]
	global_store_dwordx4 v[16:17], v[8:11], off sc1
	v_cvt_pk_bf16_f32 v2, v4, v5
	s_waitcnt lgkmcnt(0)
	v_add_f32_e32 v0, v3, v18
	ds_bpermute_b32 v1, v121, v0
	v_cvt_pk_bf16_f32 v3, v6, v7
	v_cvt_pk_bf16_f32 v4, v14, v15
	v_cvt_pk_bf16_f32 v5, v12, v13
	global_store_dwordx4 v[16:17], v[2:5], off offset:256 sc1
	s_and_saveexec_b64 s[50:51], s[8:9]
	s_cbranch_execz .LBB0_323
	s_waitcnt lgkmcnt(0)
	v_add_f32_e32 v2, v0, v1
	v_lshl_add_u64 v[0:1], v[192:193], 2, s[74:75]
	global_atomic_add_f32 v[0:1], v2, off

; #define PG8_LAS __attribute__((address_space(3)))
; __device__ __forceinline__ u32x4 pack8(const f32x4 a, const f32x4 b) { u32x4 w; w.x = cvt_pk_bf16(a[0], a[1]); w.y = cvt_pk_bf16(a[2], a[3]); w.z = cvt_pk_bf16(b[0], b[1]); w.w = cvt_pk_bf16(b[2], b[3]); return w; }
;     __device__ __forceinline__ void operator()(f32x4 (&acc)[2][2][4][2], const Unit& u, int wr, int wc, int fr, int fq) const {
;     ...
;             asm volatile("s_waitcnt lgkmcnt(0)" ::: "memory"); __builtin_amdgcn_s_barrier(); asm volatile("" ::: "memory");
;             const float* gain = (seg == 1) ? gq : gk; bf16_t* dst = (seg == 1) ? Q : K;
;             const float osc = (seg == 1) ? (0.08838834764831845f * 1.4426950408889634f) : 1.0f;
;             const int d0 = wc * 32 + 8 * fq;
;             const f32x4 g0 = *(const f32x4*)(gain + d0) * osc, g1 = *(const f32x4*)(gain + d0 + 4) * osc;
; #pragma unroll
;             for (int ai = 0; ai < 2; ++ai)
; #pragma unroll
;                 for (int m = 0; m < 4; ++m) { const int rl = ai * HALF + wr * 64 + m * 16 + fr, row = u.pm * BM + rl;
;                     const float epr = 1e-6f * (ssr[ai * HALF + m * 16] * (1.0f / 2048.0f) + 1e-6f);
; #pragma unroll
;                     for (int bj = 0; bj < 2; ++bj) { const f32x4 p = *(const PG8_LAS f32x4*)(xch + rl * 8 + bj * 4);
;                         const float rq = __builtin_amdgcn_rsqf(((p[0] + p[1]) + (p[2] + p[3])) * (1.0f / 128.0f) + epr);
;                         *(u32x4*)(dst + (size_t)row * 1024 + lc0 + bj * HALF) = pack8(acc[ai][bj][m][0] * g0 * rq, acc[ai][bj][m][1] * g1 * rq); } }
.LBB0_432:
	s_or_b64 exec, exec, s[58:59]
	s_cmp_eq_u32 s51, 1
	s_cselect_b64 vcc, -1, 0
	s_and_b64 s[58:59], vcc, exec
	s_cselect_b32 s51, s41, s43
	s_cselect_b32 s53, s40, s42
	v_mov_b32_e32 v146, s53
	v_mov_b32_e32 v147, s51
	s_waitcnt lgkmcnt(0)
	s_barrier
	v_lshl_add_u64 v[146:147], v[130:131], 2, v[146:147]
	global_load_dwordx4 v[154:157], v[146:147], off offset:16
	s_nop 0
	global_load_dwordx4 v[146:149], v[146:147], off
	v_cndmask_b32_e32 v128, 1.0, v180, vcc
	ds_read_b128 v[188:191], v174
	s_brev_b32 s51, 4
	s_cselect_b32 s51, s51, 0x24000000
	s_add_u32 s58, s68, s51
	s_addc_u32 s59, s69, 0
	s_waitcnt lgkmcnt(0)
	v_add_f32_e32 v193, v188, v189
	v_add_f32_e32 v139, v190, v191
	v_ashrrev_i32_e32 v145, 31, v144
	s_waitcnt vmcnt(0)
	v_pk_mul_f32 v[150:151], v[128:129], v[148:149] op_sel_hi:[0,1]
	v_pk_mul_f32 v[152:153], v[128:129], v[146:147] op_sel_hi:[0,1]
	v_pk_mul_f32 v[146:147], v[128:129], v[156:157] op_sel_hi:[0,1]
	v_pk_mul_f32 v[148:149], v[128:129], v[154:155] op_sel_hi:[0,1]
	global_load_dword v128, v[140:141], off
	v_add_u32_e32 v156, s23, v163
	v_pk_mul_f32 v[190:191], v[124:125], v[152:153]
	v_ashrrev_i32_e32 v157, 31, v156
	v_pk_mul_f32 v[196:197], v[120:121], v[148:149]
	v_lshl_add_u64 v[154:155], v[144:145], 1, s[58:59]
	v_lshlrev_b64 v[156:157], 11, v[156:157]
	v_lshl_add_u64 v[156:157], v[154:155], 0, v[156:157]
	s_mov_b64 s[58:59], 0
	s_waitcnt vmcnt(0)
	v_mul_f32_e32 v192, 0x3a000000, v128
	v_pk_add_f32 v[188:189], v[192:193], v[138:139]
	s_nop 0
	v_pk_mul_f32 v[192:193], v[188:189], s[14:15]
	v_pk_mul_f32 v[188:189], v[126:127], v[150:151]
	v_add_f32_e32 v128, v192, v193
	v_rsq_f32_e32 v128, v128
	s_nop 0
	v_pk_mul_f32 v[194:195], v[188:189], v[128:129] op_sel_hi:[1,0]
	v_pk_mul_f32 v[188:189], v[190:191], v[128:129] op_sel_hi:[1,0]
	v_pk_mul_f32 v[190:191], v[122:123], v[146:147]
	v_cvt_pk_bf16_f32 v188, v188, v189
	v_cvt_pk_bf16_f32 v189, v194, v195
	s_nop 0
	v_pk_mul_f32 v[198:199], v[190:191], v[128:129] op_sel_hi:[1,0]
	v_pk_mul_f32 v[190:191], v[196:197], v[128:129] op_sel_hi:[1,0]
	s_nop 0
	v_cvt_pk_bf16_f32 v190, v190, v191
	v_cvt_pk_bf16_f32 v191, v198, v199
	global_store_dwordx4 v[156:157], v[188:191], off sc1
	ds_read_b128 v[188:191], v174 offset:16
	s_waitcnt lgkmcnt(0)
	v_mov_b32_e32 v194, v189
	v_mov_b32_e32 v195, v190
	v_mov_b32_e32 v189, v191
	v_pk_add_f32 v[188:189], v[194:195], v[188:189]
	v_pk_mul_f32 v[190:191], v[116:117], v[152:153]
	v_add_f32_e32 v128, v188, v189
	v_fmac_f32_e32 v192, 0x3c000000, v128
	v_rsq_f32_e32 v128, v192
	v_pk_mul_f32 v[188:189], v[118:119], v[150:151]
	v_pk_mul_f32 v[194:195], v[112:113], v[148:149]
	v_pk_mul_f32 v[192:193], v[188:189], v[128:129] op_sel_hi:[1,0]
	v_pk_mul_f32 v[188:189], v[190:191], v[128:129] op_sel_hi:[1,0]
	v_pk_mul_f32 v[190:191], v[114:115], v[146:147]
	v_cvt_pk_bf16_f32 v188, v188, v189
	v_cvt_pk_bf16_f32 v189, v192, v193
	s_nop 0
	v_pk_mul_f32 v[196:197], v[190:191], v[128:129] op_sel_hi:[1,0]
	v_pk_mul_f32 v[190:191], v[194:195], v[128:129] op_sel_hi:[1,0]
	s_nop 0
	v_cvt_pk_bf16_f32 v190, v190, v191
	v_cvt_pk_bf16_f32 v191, v196, v197
	global_store_dwordx4 v[156:157], v[188:191], off offset:256 sc1
	global_load_dword v128, v[140:141], off offset:64
	ds_read_b128 v[188:191], v181
	v_add_u32_e32 v156, s23, v167
	v_ashrrev_i32_e32 v157, 31, v156
	v_pk_mul_f32 v[196:197], v[104:105], v[148:149]
	v_lshlrev_b64 v[156:157], 11, v[156:157]
	s_waitcnt lgkmcnt(0)
	v_add_f32_e32 v193, v188, v189
	v_add_f32_e32 v139, v190, v191
	v_pk_mul_f32 v[190:191], v[108:109], v[152:153]
	v_lshl_add_u64 v[156:157], v[154:155], 0, v[156:157]
	s_waitcnt vmcnt(0)
	v_mul_f32_e32 v192, 0x3a000000, v128
	v_pk_add_f32 v[188:189], v[192:193], v[138:139]
	s_nop 0
	v_pk_mul_f32 v[192:193], v[188:189], s[14:15]
	v_pk_mul_f32 v[188:189], v[110:111], v[150:151]
	v_add_f32_e32 v128, v192, v193
	v_rsq_f32_e32 v128, v128
	s_nop 0
	v_pk_mul_f32 v[194:195], v[188:189], v[128:129] op_sel_hi:[1,0]
	v_pk_mul_f32 v[188:189], v[190:191], v[128:129] op_sel_hi:[1,0]
	v_pk_mul_f32 v[190:191], v[106:107], v[146:147]
	v_cvt_pk_bf16_f32 v188, v188, v189
	v_cvt_pk_bf16_f32 v189, v194, v195
	s_nop 0
	v_pk_mul_f32 v[198:199], v[190:191], v[128:129] op_sel_hi:[1,0]
	v_pk_mul_f32 v[190:191], v[196:197], v[128:129] op_sel_hi:[1,0]
	s_nop 0
	v_cvt_pk_bf16_f32 v190, v190, v191
	v_cvt_pk_bf16_f32 v191, v198, v199
	global_store_dwordx4 v[156:157], v[188:191], off sc1
	ds_read_b128 v[188:191], v181 offset:16
	s_waitcnt lgkmcnt(0)
	v_mov_b32_e32 v194, v189
	v_mov_b32_e32 v195, v190
	v_mov_b32_e32 v189, v191
	v_pk_add_f32 v[188:189], v[194:195], v[188:189]
	v_pk_mul_f32 v[190:191], v[100:101], v[152:153]
	v_add_f32_e32 v128, v188, v189
	v_fmac_f32_e32 v192, 0x3c000000, v128
	v_rsq_f32_e32 v128, v192
	v_pk_mul_f32 v[188:189], v[102:103], v[150:151]
	v_pk_mul_f32 v[194:195], v[96:97], v[148:149]
	v_pk_mul_f32 v[192:193], v[188:189], v[128:129] op_sel_hi:[1,0]
	v_pk_mul_f32 v[188:189], v[190:191], v[128:129] op_sel_hi:[1,0]
	v_pk_mul_f32 v[190:191], v[98:99], v[146:147]
	v_cvt_pk_bf16_f32 v188, v188, v189
	v_cvt_pk_bf16_f32 v189, v192, v193
	s_nop 0
	v_pk_mul_f32 v[196:197], v[190:191], v[128:129] op_sel_hi:[1,0]
	v_pk_mul_f32 v[190:191], v[194:195], v[128:129] op_sel_hi:[1,0]
	s_nop 0
	v_cvt_pk_bf16_f32 v190, v190, v191
	v_cvt_pk_bf16_f32 v191, v196, v197
	global_store_dwordx4 v[156:157], v[188:191], off offset:256 sc1
	global_load_dword v128, v[140:141], off offset:128
	ds_read_b128 v[188:191], v182
	v_add_u32_e32 v156, s23, v168
	v_ashrrev_i32_e32 v157, 31, v156
	v_pk_mul_f32 v[196:197], v[88:89], v[148:149]
	v_lshlrev_b64 v[156:157], 11, v[156:157]
	s_waitcnt lgkmcnt(0)
; #define PG8_LAS __attribute__((address_space(3)))
; __device__ __forceinline__ u32x4 pack8(const f32x4 a, const f32x4 b) { u32x4 w; w.x = cvt_pk_bf16(a[0], a[1]); w.y = cvt_pk_bf16(a[2], a[3]); w.z = cvt_pk_bf16(b[0], b[1]); w.w = cvt_pk_bf16(b[2], b[3]); return w; }
;     __device__ __forceinline__ void operator()(f32x4 (&acc)[2][2][4][2], const Unit& u, int wr, int wc, int fr, int fq) const {
;     ...
;             for (int ai = 0; ai < 2; ++ai)
; #pragma unroll
;                 for (int m = 0; m < 4; ++m) { const int rl = ai * HALF + wr * 64 + m * 16 + fr, row = u.pm * BM + rl;
;                     const float epr = 1e-6f * (ssr[ai * HALF + m * 16] * (1.0f / 2048.0f) + 1e-6f);
; #pragma unroll
;                     for (int bj = 0; bj < 2; ++bj) { const f32x4 p = *(const PG8_LAS f32x4*)(xch + rl * 8 + bj * 4);
;                         const float rq = __builtin_amdgcn_rsqf(((p[0] + p[1]) + (p[2] + p[3])) * (1.0f / 128.0f) + epr);
;                         *(u32x4*)(dst + (size_t)row * 1024 + lc0 + bj * HALF) = pack8(acc[ai][bj][m][0] * g0 * rq, acc[ai][bj][m][1] * g1 * rq); } }
	v_add_f32_e32 v193, v188, v189
	v_add_f32_e32 v139, v190, v191
	v_pk_mul_f32 v[190:191], v[92:93], v[152:153]
	v_lshl_add_u64 v[156:157], v[154:155], 0, v[156:157]
	s_waitcnt vmcnt(0)
	v_mul_f32_e32 v192, 0x3a000000, v128
	v_pk_add_f32 v[188:189], v[192:193], v[138:139]
	s_nop 0
	v_pk_mul_f32 v[192:193], v[188:189], s[14:15]
	v_pk_mul_f32 v[188:189], v[94:95], v[150:151]
	v_add_f32_e32 v128, v192, v193
	v_rsq_f32_e32 v128, v128
	s_nop 0
	v_pk_mul_f32 v[194:195], v[188:189], v[128:129] op_sel_hi:[1,0]
	v_pk_mul_f32 v[188:189], v[190:191], v[128:129] op_sel_hi:[1,0]
	v_pk_mul_f32 v[190:191], v[90:91], v[146:147]
	v_cvt_pk_bf16_f32 v188, v188, v189
	v_cvt_pk_bf16_f32 v189, v194, v195
	s_nop 0
	v_pk_mul_f32 v[198:199], v[190:191], v[128:129] op_sel_hi:[1,0]
	v_pk_mul_f32 v[190:191], v[196:197], v[128:129] op_sel_hi:[1,0]
	s_nop 0
	v_cvt_pk_bf16_f32 v190, v190, v191
	v_cvt_pk_bf16_f32 v191, v198, v199
	global_store_dwordx4 v[156:157], v[188:191], off sc1
	ds_read_b128 v[188:191], v182 offset:16
	s_waitcnt lgkmcnt(0)
	v_mov_b32_e32 v194, v189
	v_mov_b32_e32 v195, v190
	v_mov_b32_e32 v189, v191
	v_pk_add_f32 v[188:189], v[194:195], v[188:189]
	v_pk_mul_f32 v[190:191], v[84:85], v[152:153]
	v_add_f32_e32 v128, v188, v189
	v_fmac_f32_e32 v192, 0x3c000000, v128
	v_rsq_f32_e32 v128, v192
	v_pk_mul_f32 v[188:189], v[86:87], v[150:151]
	v_pk_mul_f32 v[194:195], v[80:81], v[148:149]
	v_pk_mul_f32 v[192:193], v[188:189], v[128:129] op_sel_hi:[1,0]
	v_pk_mul_f32 v[188:189], v[190:191], v[128:129] op_sel_hi:[1,0]
	v_pk_mul_f32 v[190:191], v[82:83], v[146:147]
	v_cvt_pk_bf16_f32 v188, v188, v189
	v_cvt_pk_bf16_f32 v189, v192, v193
	s_nop 0
	v_pk_mul_f32 v[196:197], v[190:191], v[128:129] op_sel_hi:[1,0]
	v_pk_mul_f32 v[190:191], v[194:195], v[128:129] op_sel_hi:[1,0]
	s_nop 0
	v_cvt_pk_bf16_f32 v190, v190, v191
	v_cvt_pk_bf16_f32 v191, v196, v197
	global_store_dwordx4 v[156:157], v[188:191], off offset:256 sc1
	global_load_dword v128, v[140:141], off offset:192
	ds_read_b128 v[188:191], v183
	v_add_u32_e32 v156, s23, v169
	v_ashrrev_i32_e32 v157, 31, v156
	v_pk_mul_f32 v[196:197], v[72:73], v[148:149]
	v_lshlrev_b64 v[156:157], 11, v[156:157]
	s_waitcnt lgkmcnt(0)
	v_add_f32_e32 v193, v188, v189
	v_add_f32_e32 v139, v190, v191
	v_pk_mul_f32 v[190:191], v[76:77], v[152:153]
	v_lshl_add_u64 v[156:157], v[154:155], 0, v[156:157]
	s_waitcnt vmcnt(0)
	v_mul_f32_e32 v192, 0x3a000000, v128
	v_pk_add_f32 v[188:189], v[192:193], v[138:139]
	s_nop 0
	v_pk_mul_f32 v[192:193], v[188:189], s[14:15]
	v_pk_mul_f32 v[188:189], v[78:79], v[150:151]
	v_add_f32_e32 v128, v192, v193
	v_rsq_f32_e32 v128, v128
	s_nop 0
	v_pk_mul_f32 v[194:195], v[188:189], v[128:129] op_sel_hi:[1,0]
	v_pk_mul_f32 v[188:189], v[190:191], v[128:129] op_sel_hi:[1,0]
	v_pk_mul_f32 v[190:191], v[74:75], v[146:147]
	v_cvt_pk_bf16_f32 v188, v188, v189
	v_cvt_pk_bf16_f32 v189, v194, v195
	s_nop 0
	v_pk_mul_f32 v[198:199], v[190:191], v[128:129] op_sel_hi:[1,0]
	v_pk_mul_f32 v[190:191], v[196:197], v[128:129] op_sel_hi:[1,0]
	s_nop 0
	v_cvt_pk_bf16_f32 v190, v190, v191
	v_cvt_pk_bf16_f32 v191, v198, v199
	global_store_dwordx4 v[156:157], v[188:191], off sc1
	ds_read_b128 v[188:191], v183 offset:16
	s_waitcnt lgkmcnt(0)
	v_mov_b32_e32 v194, v189
	v_mov_b32_e32 v195, v190
	v_mov_b32_e32 v189, v191
	v_pk_add_f32 v[188:189], v[194:195], v[188:189]
	v_pk_mul_f32 v[190:191], v[68:69], v[152:153]
	v_add_f32_e32 v128, v188, v189
	v_fmac_f32_e32 v192, 0x3c000000, v128
	v_rsq_f32_e32 v128, v192
	v_pk_mul_f32 v[188:189], v[70:71], v[150:151]
	v_pk_mul_f32 v[194:195], v[64:65], v[148:149]
	v_pk_mul_f32 v[192:193], v[188:189], v[128:129] op_sel_hi:[1,0]
	v_pk_mul_f32 v[188:189], v[190:191], v[128:129] op_sel_hi:[1,0]
	v_pk_mul_f32 v[190:191], v[66:67], v[146:147]
	v_cvt_pk_bf16_f32 v188, v188, v189
	v_cvt_pk_bf16_f32 v189, v192, v193
	s_nop 0
	v_pk_mul_f32 v[196:197], v[190:191], v[128:129] op_sel_hi:[1,0]
	v_pk_mul_f32 v[190:191], v[194:195], v[128:129] op_sel_hi:[1,0]
	s_nop 0
	v_cvt_pk_bf16_f32 v190, v190, v191
	v_cvt_pk_bf16_f32 v191, v196, v197
	global_store_dwordx4 v[156:157], v[188:191], off offset:256 sc1
	global_load_dword v128, v[140:141], off offset:512
	ds_read_b128 v[188:191], v184
	v_add_u32_e32 v156, s23, v170
	v_ashrrev_i32_e32 v157, 31, v156
	v_pk_mul_f32 v[196:197], v[56:57], v[148:149]
	v_lshlrev_b64 v[156:157], 11, v[156:157]
	s_waitcnt lgkmcnt(0)
	v_add_f32_e32 v193, v188, v189
	v_add_f32_e32 v139, v190, v191
	v_pk_mul_f32 v[190:191], v[60:61], v[152:153]
	v_lshl_add_u64 v[156:157], v[154:155], 0, v[156:157]
	s_waitcnt vmcnt(0)
	v_mul_f32_e32 v192, 0x3a000000, v128
	v_pk_add_f32 v[188:189], v[192:193], v[138:139]
	s_nop 0
	v_pk_mul_f32 v[192:193], v[188:189], s[14:15]
	v_pk_mul_f32 v[188:189], v[62:63], v[150:151]
	v_add_f32_e32 v128, v192, v193
	v_rsq_f32_e32 v128, v128
	s_nop 0
	v_pk_mul_f32 v[194:195], v[188:189], v[128:129] op_sel_hi:[1,0]
	v_pk_mul_f32 v[188:189], v[190:191], v[128:129] op_sel_hi:[1,0]
	v_pk_mul_f32 v[190:191], v[58:59], v[146:147]
	v_cvt_pk_bf16_f32 v188, v188, v189
	v_cvt_pk_bf16_f32 v189, v194, v195
	s_nop 0
	v_pk_mul_f32 v[198:199], v[190:191], v[128:129] op_sel_hi:[1,0]
	v_pk_mul_f32 v[190:191], v[196:197], v[128:129] op_sel_hi:[1,0]
	s_nop 0
	v_cvt_pk_bf16_f32 v190, v190, v191
	v_cvt_pk_bf16_f32 v191, v198, v199
	global_store_dwordx4 v[156:157], v[188:191], off sc1
	ds_read_b128 v[188:191], v184 offset:16
	s_waitcnt lgkmcnt(0)
; #define PG8_LAS __attribute__((address_space(3)))
; __device__ __forceinline__ u32x4 pack8(const f32x4 a, const f32x4 b) { u32x4 w; w.x = cvt_pk_bf16(a[0], a[1]); w.y = cvt_pk_bf16(a[2], a[3]); w.z = cvt_pk_bf16(b[0], b[1]); w.w = cvt_pk_bf16(b[2], b[3]); return w; }
;     __device__ __forceinline__ void operator()(f32x4 (&acc)[2][2][4][2], const Unit& u, int wr, int wc, int fr, int fq) const {
;     ...
;             for (int ai = 0; ai < 2; ++ai)
; #pragma unroll
;                 for (int m = 0; m < 4; ++m) { const int rl = ai * HALF + wr * 64 + m * 16 + fr, row = u.pm * BM + rl;
;                     const float epr = 1e-6f * (ssr[ai * HALF + m * 16] * (1.0f / 2048.0f) + 1e-6f);
; #pragma unroll
;                     for (int bj = 0; bj < 2; ++bj) { const f32x4 p = *(const PG8_LAS f32x4*)(xch + rl * 8 + bj * 4);
;                         const float rq = __builtin_amdgcn_rsqf(((p[0] + p[1]) + (p[2] + p[3])) * (1.0f / 128.0f) + epr);
;                         *(u32x4*)(dst + (size_t)row * 1024 + lc0 + bj * HALF) = pack8(acc[ai][bj][m][0] * g0 * rq, acc[ai][bj][m][1] * g1 * rq); } }
	v_mov_b32_e32 v194, v189
	v_mov_b32_e32 v195, v190
	v_mov_b32_e32 v189, v191
	v_pk_add_f32 v[188:189], v[194:195], v[188:189]
	v_pk_mul_f32 v[190:191], v[52:53], v[152:153]
	v_add_f32_e32 v128, v188, v189
	v_fmac_f32_e32 v192, 0x3c000000, v128
	v_rsq_f32_e32 v128, v192
	v_pk_mul_f32 v[188:189], v[54:55], v[150:151]
	v_pk_mul_f32 v[194:195], v[48:49], v[148:149]
	v_pk_mul_f32 v[192:193], v[188:189], v[128:129] op_sel_hi:[1,0]
	v_pk_mul_f32 v[188:189], v[190:191], v[128:129] op_sel_hi:[1,0]
	v_pk_mul_f32 v[190:191], v[50:51], v[146:147]
	v_cvt_pk_bf16_f32 v188, v188, v189
	v_cvt_pk_bf16_f32 v189, v192, v193
	s_nop 0
	v_pk_mul_f32 v[196:197], v[190:191], v[128:129] op_sel_hi:[1,0]
	v_pk_mul_f32 v[190:191], v[194:195], v[128:129] op_sel_hi:[1,0]
	s_nop 0
	v_cvt_pk_bf16_f32 v190, v190, v191
	v_cvt_pk_bf16_f32 v191, v196, v197
	global_store_dwordx4 v[156:157], v[188:191], off offset:256 sc1
	global_load_dword v128, v[140:141], off offset:576
	ds_read_b128 v[188:191], v185
	v_add_u32_e32 v156, s23, v171
	v_ashrrev_i32_e32 v157, 31, v156
	v_pk_mul_f32 v[196:197], v[40:41], v[148:149]
	v_lshlrev_b64 v[156:157], 11, v[156:157]
	s_waitcnt lgkmcnt(0)
	v_add_f32_e32 v193, v188, v189
	v_add_f32_e32 v139, v190, v191
	v_pk_mul_f32 v[190:191], v[44:45], v[152:153]
	v_lshl_add_u64 v[156:157], v[154:155], 0, v[156:157]
	s_waitcnt vmcnt(0)
	v_mul_f32_e32 v192, 0x3a000000, v128
	v_pk_add_f32 v[188:189], v[192:193], v[138:139]
	s_nop 0
	v_pk_mul_f32 v[192:193], v[188:189], s[14:15]
	v_pk_mul_f32 v[188:189], v[46:47], v[150:151]
	v_add_f32_e32 v128, v192, v193
	v_rsq_f32_e32 v128, v128
	s_nop 0
	v_pk_mul_f32 v[194:195], v[188:189], v[128:129] op_sel_hi:[1,0]
	v_pk_mul_f32 v[188:189], v[190:191], v[128:129] op_sel_hi:[1,0]
	v_pk_mul_f32 v[190:191], v[42:43], v[146:147]
	v_cvt_pk_bf16_f32 v188, v188, v189
	v_cvt_pk_bf16_f32 v189, v194, v195
	s_nop 0
	v_pk_mul_f32 v[198:199], v[190:191], v[128:129] op_sel_hi:[1,0]
	v_pk_mul_f32 v[190:191], v[196:197], v[128:129] op_sel_hi:[1,0]
	s_nop 0
	v_cvt_pk_bf16_f32 v190, v190, v191
	v_cvt_pk_bf16_f32 v191, v198, v199
	global_store_dwordx4 v[156:157], v[188:191], off sc1
	ds_read_b128 v[188:191], v185 offset:16
	s_waitcnt lgkmcnt(0)
	v_mov_b32_e32 v194, v189
	v_mov_b32_e32 v195, v190
	v_mov_b32_e32 v189, v191
	v_pk_add_f32 v[188:189], v[194:195], v[188:189]
	v_pk_mul_f32 v[190:191], v[36:37], v[152:153]
	v_add_f32_e32 v128, v188, v189
	v_fmac_f32_e32 v192, 0x3c000000, v128
	v_rsq_f32_e32 v128, v192
	v_pk_mul_f32 v[188:189], v[38:39], v[150:151]
	v_pk_mul_f32 v[194:195], v[32:33], v[148:149]
	v_pk_mul_f32 v[192:193], v[188:189], v[128:129] op_sel_hi:[1,0]
	v_pk_mul_f32 v[188:189], v[190:191], v[128:129] op_sel_hi:[1,0]
	v_pk_mul_f32 v[190:191], v[34:35], v[146:147]
	v_cvt_pk_bf16_f32 v188, v188, v189
	v_cvt_pk_bf16_f32 v189, v192, v193
	s_nop 0
	v_pk_mul_f32 v[196:197], v[190:191], v[128:129] op_sel_hi:[1,0]
	v_pk_mul_f32 v[190:191], v[194:195], v[128:129] op_sel_hi:[1,0]
	s_nop 0
	v_cvt_pk_bf16_f32 v190, v190, v191
	v_cvt_pk_bf16_f32 v191, v196, v197
	global_store_dwordx4 v[156:157], v[188:191], off offset:256 sc1
	global_load_dword v128, v[140:141], off offset:640
	ds_read_b128 v[188:191], v186
	v_add_u32_e32 v156, s23, v172
	v_ashrrev_i32_e32 v157, 31, v156
	v_pk_mul_f32 v[196:197], v[24:25], v[148:149]
	v_lshlrev_b64 v[156:157], 11, v[156:157]
	s_waitcnt lgkmcnt(0)
	v_add_f32_e32 v193, v188, v189
	v_add_f32_e32 v139, v190, v191
	v_pk_mul_f32 v[190:191], v[28:29], v[152:153]
	v_lshl_add_u64 v[156:157], v[154:155], 0, v[156:157]
	s_waitcnt vmcnt(0)
	v_mul_f32_e32 v192, 0x3a000000, v128
	v_pk_add_f32 v[188:189], v[192:193], v[138:139]
	s_nop 0
	v_pk_mul_f32 v[192:193], v[188:189], s[14:15]
	v_pk_mul_f32 v[188:189], v[30:31], v[150:151]
	v_add_f32_e32 v128, v192, v193
	v_rsq_f32_e32 v128, v128
	s_nop 0
	v_pk_mul_f32 v[194:195], v[188:189], v[128:129] op_sel_hi:[1,0]
	v_pk_mul_f32 v[188:189], v[190:191], v[128:129] op_sel_hi:[1,0]
	v_pk_mul_f32 v[190:191], v[26:27], v[146:147]
	v_cvt_pk_bf16_f32 v188, v188, v189
	v_cvt_pk_bf16_f32 v189, v194, v195
	s_nop 0
	v_pk_mul_f32 v[198:199], v[190:191], v[128:129] op_sel_hi:[1,0]
	v_pk_mul_f32 v[190:191], v[196:197], v[128:129] op_sel_hi:[1,0]
	s_nop 0
	v_cvt_pk_bf16_f32 v190, v190, v191
	v_cvt_pk_bf16_f32 v191, v198, v199
	global_store_dwordx4 v[156:157], v[188:191], off sc1
	ds_read_b128 v[188:191], v186 offset:16
	s_waitcnt lgkmcnt(0)
	v_mov_b32_e32 v194, v189
	v_mov_b32_e32 v195, v190
	v_mov_b32_e32 v189, v191
	v_pk_add_f32 v[188:189], v[194:195], v[188:189]
	v_pk_mul_f32 v[190:191], v[20:21], v[152:153]
	v_add_f32_e32 v128, v188, v189
	v_fmac_f32_e32 v192, 0x3c000000, v128
	v_rsq_f32_e32 v128, v192
	v_pk_mul_f32 v[188:189], v[22:23], v[150:151]
	v_pk_mul_f32 v[194:195], v[16:17], v[148:149]
	v_pk_mul_f32 v[192:193], v[188:189], v[128:129] op_sel_hi:[1,0]
	v_pk_mul_f32 v[188:189], v[190:191], v[128:129] op_sel_hi:[1,0]
	v_pk_mul_f32 v[190:191], v[18:19], v[146:147]
	v_cvt_pk_bf16_f32 v188, v188, v189
	v_cvt_pk_bf16_f32 v189, v192, v193
	s_nop 0
	v_pk_mul_f32 v[196:197], v[190:191], v[128:129] op_sel_hi:[1,0]
	v_pk_mul_f32 v[190:191], v[194:195], v[128:129] op_sel_hi:[1,0]
	v_pk_mul_f32 v[194:195], v[8:9], v[148:149]
	v_cvt_pk_bf16_f32 v190, v190, v191
	v_cvt_pk_bf16_f32 v191, v196, v197
	global_store_dwordx4 v[156:157], v[188:191], off offset:256 sc1
	global_load_dword v128, v[140:141], off offset:704
	ds_read_b128 v[188:191], v187
	v_add_u32_e32 v156, s23, v173
	v_ashrrev_i32_e32 v157, 31, v156
	v_lshlrev_b64 v[156:157], 11, v[156:157]
	v_lshl_add_u64 v[154:155], v[154:155], 0, v[156:157]
	s_waitcnt lgkmcnt(0)
; #define PG8_LAS __attribute__((address_space(3)))
; __device__ __forceinline__ float rstd_of(float ss, float inv_n) { return __builtin_amdgcn_rsqf(ss * inv_n + 1e-6f); }
; __device__ __forceinline__ u32x4 pack8(const f32x4 a, const f32x4 b) { u32x4 w; w.x = cvt_pk_bf16(a[0], a[1]); w.y = cvt_pk_bf16(a[2], a[3]); w.z = cvt_pk_bf16(b[0], b[1]); w.w = cvt_pk_bf16(b[2], b[3]); return w; }
;     __device__ __forceinline__ void operator()(f32x4 (&acc)[2][2][4][2], const Unit& u, int wr, int wc, int fr, int fq) const {
;     ...
;                 for (int m = 0; m < 4; ++m) { const float r = rstd_of(ssr[ai * HALF + m * 16], 1.0f / 2048.0f); const int row = row0 + ai * HALF + m * 16;
; #pragma unroll
;                     for (int bj = 0; bj < 2; ++bj) *(u32x4*)(V + (size_t)row * 1024 + lc0 + bj * HALF) = pack8(acc[ai][bj][m][0] * r, acc[ai][bj][m][1] * r); }
;     ...
;             for (int ai = 0; ai < 2; ++ai)
; #pragma unroll
;                 for (int m = 0; m < 4; ++m) { const int rl = ai * HALF + wr * 64 + m * 16 + fr, row = u.pm * BM + rl;
;                     const float epr = 1e-6f * (ssr[ai * HALF + m * 16] * (1.0f / 2048.0f) + 1e-6f);
; #pragma unroll
;                     for (int bj = 0; bj < 2; ++bj) { const f32x4 p = *(const PG8_LAS f32x4*)(xch + rl * 8 + bj * 4);
;                         const float rq = __builtin_amdgcn_rsqf(((p[0] + p[1]) + (p[2] + p[3])) * (1.0f / 128.0f) + epr);
;                         *(u32x4*)(dst + (size_t)row * 1024 + lc0 + bj * HALF) = pack8(acc[ai][bj][m][0] * g0 * rq, acc[ai][bj][m][1] * g1 * rq); } }
	v_add_f32_e32 v193, v188, v189
	v_add_f32_e32 v139, v190, v191
	v_pk_mul_f32 v[188:189], v[14:15], v[150:151]
	v_pk_mul_f32 v[190:191], v[12:13], v[152:153]
	v_pk_mul_f32 v[148:149], v[0:1], v[148:149]
	v_pk_mul_f32 v[150:151], v[6:7], v[150:151]
	v_pk_mul_f32 v[152:153], v[4:5], v[152:153]
	s_waitcnt vmcnt(0)
	v_mul_f32_e32 v192, 0x3a000000, v128
	v_pk_add_f32 v[156:157], v[192:193], v[138:139]
	s_nop 0
	v_pk_mul_f32 v[156:157], v[156:157], s[14:15]
	s_nop 0
	v_add_f32_e32 v128, v156, v157
	v_rsq_f32_e32 v128, v128
	s_nop 0
	v_pk_mul_f32 v[192:193], v[188:189], v[128:129] op_sel_hi:[1,0]
	v_pk_mul_f32 v[188:189], v[190:191], v[128:129] op_sel_hi:[1,0]
	v_pk_mul_f32 v[190:191], v[10:11], v[146:147]
	v_cvt_pk_bf16_f32 v188, v188, v189
	v_cvt_pk_bf16_f32 v189, v192, v193
	v_pk_mul_f32 v[146:147], v[2:3], v[146:147]
	v_pk_mul_f32 v[196:197], v[190:191], v[128:129] op_sel_hi:[1,0]
	v_pk_mul_f32 v[190:191], v[194:195], v[128:129] op_sel_hi:[1,0]
	s_nop 0
	v_cvt_pk_bf16_f32 v190, v190, v191
	v_cvt_pk_bf16_f32 v191, v196, v197
	global_store_dwordx4 v[154:155], v[188:191], off sc1
	ds_read_b128 v[188:191], v187 offset:16
	s_waitcnt lgkmcnt(0)
	v_mov_b32_e32 v192, v189
	v_mov_b32_e32 v193, v190
	v_mov_b32_e32 v189, v191
	v_pk_add_f32 v[188:189], v[192:193], v[188:189]
	s_nop 0
	v_add_f32_e32 v128, v188, v189
	v_fmac_f32_e32 v156, 0x3c000000, v128
	v_rsq_f32_e32 v128, v156
	s_nop 0
	v_pk_mul_f32 v[148:149], v[148:149], v[128:129] op_sel_hi:[1,0]
	v_pk_mul_f32 v[150:151], v[150:151], v[128:129] op_sel_hi:[1,0]
	v_pk_mul_f32 v[152:153], v[152:153], v[128:129] op_sel_hi:[1,0]
	v_pk_mul_f32 v[156:157], v[146:147], v[128:129] op_sel_hi:[1,0]
	v_cvt_pk_bf16_f32 v146, v152, v153
	v_cvt_pk_bf16_f32 v147, v150, v151
	v_cvt_pk_bf16_f32 v148, v148, v149
	s_nop 0
	v_cvt_pk_bf16_f32 v149, v156, v157
	global_store_dwordx4 v[154:155], v[146:149], off offset:256 sc1
.LBB0_433:
	s_and_b64 vcc, exec, s[58:59]
	s_cbranch_vccz .LBB0_435
	global_load_dword v128, v[140:141], off
	v_ashrrev_i32_e32 v145, 31, v144
	v_lshlrev_b64 v[146:147], 11, v[142:143]
	v_lshl_add_u64 v[146:147], s[48:49], 0, v[146:147]
	s_mov_b32 s23, 0x40000
	s_mov_b64 s[58:59], 0x40000
	s_waitcnt vmcnt(0)
	v_fmamk_f32 v128, v128, 0x3a000000, v138
	v_rsq_f32_e32 v128, v128
	s_nop 0
	v_pk_mul_f32 v[148:149], v[126:127], v[128:129] op_sel_hi:[1,0]
	v_pk_mul_f32 v[150:151], v[124:125], v[128:129] op_sel_hi:[1,0]
	v_pk_mul_f32 v[152:153], v[120:121], v[128:129] op_sel_hi:[1,0]
	v_cvt_pk_bf16_f32 v150, v150, v151
	v_cvt_pk_bf16_f32 v151, v148, v149
	v_lshlrev_b64 v[148:149], 1, v[144:145]
	v_pk_mul_f32 v[154:155], v[122:123], v[128:129] op_sel_hi:[1,0]
	v_cvt_pk_bf16_f32 v152, v152, v153
	v_lshl_add_u64 v[146:147], v[146:147], 0, v[148:149]
	v_cvt_pk_bf16_f32 v153, v154, v155
	global_store_dwordx4 v[146:147], v[150:153], off sc1
	v_pk_mul_f32 v[154:155], v[114:115], v[128:129] op_sel_hi:[1,0]
	v_pk_mul_f32 v[156:157], v[112:113], v[128:129] op_sel_hi:[1,0]
	v_pk_mul_f32 v[152:153], v[118:119], v[128:129] op_sel_hi:[1,0]
	v_pk_mul_f32 v[150:151], v[116:117], v[128:129] op_sel_hi:[1,0]
	s_nop 0
	v_cvt_pk_bf16_f32 v150, v150, v151
	v_cvt_pk_bf16_f32 v151, v152, v153
	v_cvt_pk_bf16_f32 v152, v156, v157
	v_cvt_pk_bf16_f32 v153, v154, v155
	global_store_dwordx4 v[146:147], v[150:153], off offset:256 sc1
	global_load_dword v128, v[140:141], off offset:64
	s_waitcnt vmcnt(0)
	v_fmamk_f32 v128, v128, 0x3a000000, v138
	v_rsq_f32_e32 v128, v128
	v_or_b32_e32 v150, 16, v142
	v_ashrrev_i32_e32 v151, 31, v150
	v_lshlrev_b64 v[154:155], 11, v[150:151]
	v_pk_mul_f32 v[152:153], v[110:111], v[128:129] op_sel_hi:[1,0]
	v_pk_mul_f32 v[150:151], v[108:109], v[128:129] op_sel_hi:[1,0]
	v_lshl_add_u64 v[154:155], s[48:49], 0, v[154:155]
	v_pk_mul_f32 v[156:157], v[106:107], v[128:129] op_sel_hi:[1,0]
	v_pk_mul_f32 v[188:189], v[104:105], v[128:129] op_sel_hi:[1,0]
	v_cvt_pk_bf16_f32 v150, v150, v151
	v_cvt_pk_bf16_f32 v151, v152, v153
	v_lshl_add_u64 v[154:155], v[154:155], 0, v[148:149]
	v_cvt_pk_bf16_f32 v152, v188, v189
	v_cvt_pk_bf16_f32 v153, v156, v157
	global_store_dwordx4 v[154:155], v[150:153], off sc1
	v_pk_mul_f32 v[156:157], v[98:99], v[128:129] op_sel_hi:[1,0]
	v_pk_mul_f32 v[188:189], v[96:97], v[128:129] op_sel_hi:[1,0]
	v_pk_mul_f32 v[152:153], v[102:103], v[128:129] op_sel_hi:[1,0]
	v_pk_mul_f32 v[150:151], v[100:101], v[128:129] op_sel_hi:[1,0]
	s_nop 0
	v_cvt_pk_bf16_f32 v150, v150, v151
	v_cvt_pk_bf16_f32 v151, v152, v153
	v_cvt_pk_bf16_f32 v152, v188, v189
	v_cvt_pk_bf16_f32 v153, v156, v157
	global_store_dwordx4 v[154:155], v[150:153], off offset:256 sc1
	global_load_dword v128, v[140:141], off offset:128
	s_waitcnt vmcnt(0)
	v_fmamk_f32 v128, v128, 0x3a000000, v138
	v_rsq_f32_e32 v128, v128
	v_or_b32_e32 v150, 32, v142
	v_ashrrev_i32_e32 v151, 31, v150
	v_lshlrev_b64 v[154:155], 11, v[150:151]
	v_pk_mul_f32 v[152:153], v[94:95], v[128:129] op_sel_hi:[1,0]
	v_pk_mul_f32 v[150:151], v[92:93], v[128:129] op_sel_hi:[1,0]
	v_lshl_add_u64 v[154:155], s[48:49], 0, v[154:155]
	v_pk_mul_f32 v[156:157], v[90:91], v[128:129] op_sel_hi:[1,0]
	v_pk_mul_f32 v[188:189], v[88:89], v[128:129] op_sel_hi:[1,0]
	v_cvt_pk_bf16_f32 v150, v150, v151
	v_cvt_pk_bf16_f32 v151, v152, v153
	v_lshl_add_u64 v[154:155], v[154:155], 0, v[148:149]
	v_cvt_pk_bf16_f32 v152, v188, v189
	v_cvt_pk_bf16_f32 v153, v156, v157
	global_store_dwordx4 v[154:155], v[150:153], off sc1
	v_pk_mul_f32 v[156:157], v[82:83], v[128:129] op_sel_hi:[1,0]
	v_pk_mul_f32 v[188:189], v[80:81], v[128:129] op_sel_hi:[1,0]
	v_pk_mul_f32 v[152:153], v[86:87], v[128:129] op_sel_hi:[1,0]
	v_pk_mul_f32 v[150:151], v[84:85], v[128:129] op_sel_hi:[1,0]
	s_nop 0
	v_cvt_pk_bf16_f32 v150, v150, v151
	v_cvt_pk_bf16_f32 v151, v152, v153
	v_cvt_pk_bf16_f32 v152, v188, v189
	v_cvt_pk_bf16_f32 v153, v156, v157
	global_store_dwordx4 v[154:155], v[150:153], off offset:256 sc1
	global_load_dword v128, v[140:141], off offset:192
	s_waitcnt vmcnt(0)
; __device__ __forceinline__ float rstd_of(float ss, float inv_n) { return __builtin_amdgcn_rsqf(ss * inv_n + 1e-6f); }
; __device__ __forceinline__ u32x4 pack8(const f32x4 a, const f32x4 b) { u32x4 w; w.x = cvt_pk_bf16(a[0], a[1]); w.y = cvt_pk_bf16(a[2], a[3]); w.z = cvt_pk_bf16(b[0], b[1]); w.w = cvt_pk_bf16(b[2], b[3]); return w; }
;     __device__ __forceinline__ void operator()(f32x4 (&acc)[2][2][4][2], const Unit& u, int wr, int wc, int fr, int fq) const {
;     ...
;                 for (int m = 0; m < 4; ++m) { const float r = rstd_of(ssr[ai * HALF + m * 16], 1.0f / 2048.0f); const int row = row0 + ai * HALF + m * 16;
; #pragma unroll
;                     for (int bj = 0; bj < 2; ++bj) *(u32x4*)(V + (size_t)row * 1024 + lc0 + bj * HALF) = pack8(acc[ai][bj][m][0] * r, acc[ai][bj][m][1] * r); }
	v_fmamk_f32 v128, v128, 0x3a000000, v138
	v_rsq_f32_e32 v128, v128
	v_or_b32_e32 v150, 48, v142
	v_ashrrev_i32_e32 v151, 31, v150
	v_lshlrev_b64 v[154:155], 11, v[150:151]
	v_pk_mul_f32 v[150:151], v[76:77], v[128:129] op_sel_hi:[1,0]
	v_lshl_add_u64 v[154:155], s[48:49], 0, v[154:155]
	v_pk_mul_f32 v[152:153], v[78:79], v[128:129] op_sel_hi:[1,0]
	v_cvt_pk_bf16_f32 v150, v150, v151
	v_lshl_add_u64 v[154:155], v[154:155], 0, v[148:149]
	v_cvt_pk_bf16_f32 v151, v152, v153
	v_pk_mul_f32 v[156:157], v[74:75], v[128:129] op_sel_hi:[1,0]
	v_pk_mul_f32 v[188:189], v[72:73], v[128:129] op_sel_hi:[1,0]
	v_pk_mul_f32 v[148:149], v[68:69], v[128:129] op_sel_hi:[1,0]
	v_cvt_pk_bf16_f32 v152, v188, v189
	v_cvt_pk_bf16_f32 v153, v156, v157
	global_store_dwordx4 v[154:155], v[150:153], off sc1
	v_pk_mul_f32 v[156:157], v[64:65], v[128:129] op_sel_hi:[1,0]
	v_cvt_pk_bf16_f32 v148, v148, v149
	s_nop 0
	v_pk_mul_f32 v[150:151], v[70:71], v[128:129] op_sel_hi:[1,0]
	v_pk_mul_f32 v[152:153], v[66:67], v[128:129] op_sel_hi:[1,0]
	v_cvt_pk_bf16_f32 v149, v150, v151
	v_cvt_pk_bf16_f32 v150, v156, v157
	s_nop 0
	v_cvt_pk_bf16_f32 v151, v152, v153
	global_store_dwordx4 v[154:155], v[148:151], off offset:256 sc1
	global_load_dword v128, v[140:141], off offset:512
	s_waitcnt vmcnt(0)
	v_fmamk_f32 v128, v128, 0x3a000000, v138
	v_rsq_f32_e32 v128, v128
	s_nop 0
	v_pk_mul_f32 v[150:151], v[62:63], v[128:129] op_sel_hi:[1,0]
	v_pk_mul_f32 v[148:149], v[60:61], v[128:129] op_sel_hi:[1,0]
	v_pk_mul_f32 v[154:155], v[56:57], v[128:129] op_sel_hi:[1,0]
	v_cvt_pk_bf16_f32 v148, v148, v149
	v_cvt_pk_bf16_f32 v149, v150, v151
	v_pk_mul_f32 v[152:153], v[58:59], v[128:129] op_sel_hi:[1,0]
	v_cvt_pk_bf16_f32 v150, v154, v155
	v_add_co_u32_e32 v154, vcc, s23, v146
	v_cvt_pk_bf16_f32 v151, v152, v153
	v_lshl_add_u64 v[152:153], v[146:147], 0, s[58:59]
	s_nop 0
	v_addc_co_u32_e32 v155, vcc, 0, v147, vcc
	global_store_dwordx4 v[154:155], v[148:151], off sc1
	v_pk_mul_f32 v[154:155], v[50:51], v[128:129] op_sel_hi:[1,0]
	v_pk_mul_f32 v[156:157], v[48:49], v[128:129] op_sel_hi:[1,0]
	v_pk_mul_f32 v[150:151], v[54:55], v[128:129] op_sel_hi:[1,0]
	v_pk_mul_f32 v[148:149], v[52:53], v[128:129] op_sel_hi:[1,0]
	s_mov_b32 s23, 0x48000
	v_cvt_pk_bf16_f32 v148, v148, v149
	v_cvt_pk_bf16_f32 v149, v150, v151
	v_cvt_pk_bf16_f32 v150, v156, v157
	v_cvt_pk_bf16_f32 v151, v154, v155
	global_store_dwordx4 v[152:153], v[148:151], off offset:256 sc1
	global_load_dword v128, v[140:141], off offset:576
	s_mov_b64 s[58:59], 0x48000
	s_waitcnt vmcnt(0)
	v_fmamk_f32 v128, v128, 0x3a000000, v138
	v_rsq_f32_e32 v128, v128
	s_nop 0
	v_pk_mul_f32 v[150:151], v[46:47], v[128:129] op_sel_hi:[1,0]
	v_pk_mul_f32 v[148:149], v[44:45], v[128:129] op_sel_hi:[1,0]
	v_pk_mul_f32 v[154:155], v[40:41], v[128:129] op_sel_hi:[1,0]
	v_cvt_pk_bf16_f32 v148, v148, v149
	v_cvt_pk_bf16_f32 v149, v150, v151
	v_pk_mul_f32 v[152:153], v[42:43], v[128:129] op_sel_hi:[1,0]
	v_cvt_pk_bf16_f32 v150, v154, v155
	v_add_co_u32_e32 v154, vcc, s23, v146
	v_cvt_pk_bf16_f32 v151, v152, v153
	v_lshl_add_u64 v[152:153], v[146:147], 0, s[58:59]
	s_nop 0
	v_addc_co_u32_e32 v155, vcc, 0, v147, vcc
	global_store_dwordx4 v[154:155], v[148:151], off sc1
	v_pk_mul_f32 v[154:155], v[34:35], v[128:129] op_sel_hi:[1,0]
	v_pk_mul_f32 v[156:157], v[32:33], v[128:129] op_sel_hi:[1,0]
	v_pk_mul_f32 v[150:151], v[38:39], v[128:129] op_sel_hi:[1,0]
	v_pk_mul_f32 v[148:149], v[36:37], v[128:129] op_sel_hi:[1,0]
	s_mov_b32 s23, 0x50000
	v_cvt_pk_bf16_f32 v148, v148, v149
	v_cvt_pk_bf16_f32 v149, v150, v151
	v_cvt_pk_bf16_f32 v150, v156, v157
	v_cvt_pk_bf16_f32 v151, v154, v155
	global_store_dwordx4 v[152:153], v[148:151], off offset:256 sc1
	global_load_dword v128, v[140:141], off offset:640
	s_mov_b64 s[58:59], 0x50000
	s_waitcnt vmcnt(0)
	v_fmamk_f32 v128, v128, 0x3a000000, v138
	v_rsq_f32_e32 v128, v128
	s_nop 0
	v_pk_mul_f32 v[150:151], v[30:31], v[128:129] op_sel_hi:[1,0]
	v_pk_mul_f32 v[148:149], v[28:29], v[128:129] op_sel_hi:[1,0]
	v_pk_mul_f32 v[154:155], v[24:25], v[128:129] op_sel_hi:[1,0]
	v_cvt_pk_bf16_f32 v148, v148, v149
	v_cvt_pk_bf16_f32 v149, v150, v151
	v_pk_mul_f32 v[152:153], v[26:27], v[128:129] op_sel_hi:[1,0]
	v_cvt_pk_bf16_f32 v150, v154, v155
	v_add_co_u32_e32 v154, vcc, s23, v146
	v_cvt_pk_bf16_f32 v151, v152, v153
	v_lshl_add_u64 v[152:153], v[146:147], 0, s[58:59]
	s_nop 0
	v_addc_co_u32_e32 v155, vcc, 0, v147, vcc
	global_store_dwordx4 v[154:155], v[148:151], off sc1
	v_pk_mul_f32 v[154:155], v[18:19], v[128:129] op_sel_hi:[1,0]
	v_pk_mul_f32 v[156:157], v[16:17], v[128:129] op_sel_hi:[1,0]
	v_pk_mul_f32 v[150:151], v[22:23], v[128:129] op_sel_hi:[1,0]
	v_pk_mul_f32 v[148:149], v[20:21], v[128:129] op_sel_hi:[1,0]
	s_mov_b64 s[58:59], 0x58000
	v_cvt_pk_bf16_f32 v148, v148, v149
	v_cvt_pk_bf16_f32 v149, v150, v151
	v_cvt_pk_bf16_f32 v150, v156, v157
	v_cvt_pk_bf16_f32 v151, v154, v155
	global_store_dwordx4 v[152:153], v[148:151], off offset:256 sc1
	global_load_dword v128, v[140:141], off offset:704
	s_mov_b32 s23, 0x58000
	s_waitcnt vmcnt(0)
	v_fmamk_f32 v128, v128, 0x3a000000, v138
	v_rsq_f32_e32 v128, v128
	s_nop 0
	v_pk_mul_f32 v[150:151], v[14:15], v[128:129] op_sel_hi:[1,0]
	v_pk_mul_f32 v[148:149], v[12:13], v[128:129] op_sel_hi:[1,0]
	v_pk_mul_f32 v[152:153], v[10:11], v[128:129] op_sel_hi:[1,0]
	v_pk_mul_f32 v[154:155], v[8:9], v[128:129] op_sel_hi:[1,0]
	v_cvt_pk_bf16_f32 v148, v148, v149
	v_cvt_pk_bf16_f32 v149, v150, v151
	s_nop 0
	v_cvt_pk_bf16_f32 v150, v154, v155
	v_cvt_pk_bf16_f32 v151, v152, v153
	v_lshl_add_u64 v[152:153], v[146:147], 0, s[58:59]
	v_add_co_u32_e32 v146, vcc, s23, v146
	v_pk_mul_f32 v[154:155], v[0:1], v[128:129] op_sel_hi:[1,0]
	s_nop 0
	v_addc_co_u32_e32 v147, vcc, 0, v147, vcc
	global_store_dwordx4 v[146:147], v[148:151], off sc1
	v_pk_mul_f32 v[146:147], v[4:5], v[128:129] op_sel_hi:[1,0]
	s_nop 0
	v_pk_mul_f32 v[148:149], v[6:7], v[128:129] op_sel_hi:[1,0]
	v_pk_mul_f32 v[150:151], v[2:3], v[128:129] op_sel_hi:[1,0]
	v_cvt_pk_bf16_f32 v146, v146, v147
	v_cvt_pk_bf16_f32 v147, v148, v149
	v_cvt_pk_bf16_f32 v148, v154, v155
	s_nop 0
	v_cvt_pk_bf16_f32 v149, v150, v151
	global_store_dwordx4 v[152:153], v[146:149], off offset:256 sc1

; __device__ __forceinline__ float rstd_of(float ss, float inv_n) { return __builtin_amdgcn_rsqf(ss * inv_n + 1e-6f); }
; __device__ __forceinline__ u32x4 pack8(const f32x4 a, const f32x4 b) { u32x4 w; w.x = cvt_pk_bf16(a[0], a[1]); w.y = cvt_pk_bf16(a[2], a[3]); w.z = cvt_pk_bf16(b[0], b[1]); w.w = cvt_pk_bf16(b[2], b[3]); return w; }
;     __device__ __forceinline__ void operator()(f32x4 (&acc)[2][2][4][2], const Unit& u, int wr, int wc, int fr, int fq) const {
;     ...
;         if (seg == 0) {
; #pragma unroll
;             for (int ai = 0; ai < 2; ++ai)
; #pragma unroll
;                 for (int m = 0; m < 4; ++m) { const float r = rstd_of(ssr[ai * HALF + m * 16], 1.0f / 2048.0f); const int row = row0 + ai * HALF + m * 16, b = row >> 12, t = row & 4095;
; #pragma unroll
;                     for (int bj = 0; bj < 2; ++bj) { const int col = lc0 + bj * HALF, g = col >> 4, half = (col >> 3) & 1;
;                         *(u32x4*)(UG + ((size_t)((b * 64 + g) * 4096 + t) * 16 + 8 * half)) = pack8(acc[ai][bj][m][0] * r, acc[ai][bj][m][1] * r); } }
.LBB0_438:
	global_load_dword v150, v[140:141], off
	s_ashr_i32 s20, s20, 6
	v_add_u32_e32 v139, 0x80, v144
	v_ashrrev_i32_e32 v128, 4, v144
	s_andn2_b32 s20, s20, 63
	v_ashrrev_i32_e32 v139, 4, v139
	v_and_b32_e32 v143, 0xfcf, v142
	v_add_lshl_u32 v145, v128, s20, 12
	v_add_lshl_u32 v144, v139, s20, 12
	v_or_b32_e32 v146, v145, v143
	v_or_b32_e32 v148, v144, v143
	v_ashrrev_i32_e32 v147, 31, v146
	v_ashrrev_i32_e32 v149, 31, v148
	v_lshlrev_b64 v[146:147], 5, v[146:147]
	v_lshlrev_b64 v[148:149], 5, v[148:149]
	v_lshl_add_u64 v[146:147], v[132:133], 0, v[146:147]
	v_lshl_add_u64 v[148:149], v[132:133], 0, v[148:149]
	s_waitcnt vmcnt(0)
	v_fmamk_f32 v150, v150, 0x3a000000, v138
	v_rsq_f32_e32 v150, v150
	s_nop 0
	v_pk_mul_f32 v[126:127], v[126:127], v[150:151] op_sel_hi:[1,0]
	v_pk_mul_f32 v[124:125], v[124:125], v[150:151] op_sel_hi:[1,0]
	v_pk_mul_f32 v[122:123], v[122:123], v[150:151] op_sel_hi:[1,0]
	v_pk_mul_f32 v[120:121], v[120:121], v[150:151] op_sel_hi:[1,0]
	v_pk_mul_f32 v[118:119], v[118:119], v[150:151] op_sel_hi:[1,0]
	v_pk_mul_f32 v[116:117], v[116:117], v[150:151] op_sel_hi:[1,0]
	v_pk_mul_f32 v[152:153], v[114:115], v[150:151] op_sel_hi:[1,0]
	v_pk_mul_f32 v[150:151], v[112:113], v[150:151] op_sel_hi:[1,0]
	v_cvt_pk_bf16_f32 v112, v124, v125
	v_cvt_pk_bf16_f32 v113, v126, v127
	v_cvt_pk_bf16_f32 v114, v120, v121
	v_cvt_pk_bf16_f32 v115, v122, v123
	global_store_dwordx4 v[146:147], v[112:115], off sc1
	s_nop 1
	v_cvt_pk_bf16_f32 v112, v116, v117
	v_cvt_pk_bf16_f32 v113, v118, v119
	v_cvt_pk_bf16_f32 v114, v150, v151
	v_cvt_pk_bf16_f32 v115, v152, v153
	global_store_dwordx4 v[148:149], v[112:115], off sc1
	global_load_dword v116, v[140:141], off offset:64
	s_waitcnt vmcnt(0)
	v_fmamk_f32 v116, v116, 0x3a000000, v138
	v_or_b32_e32 v113, 16, v143
	v_rsq_f32_e32 v116, v116
	v_or_b32_e32 v112, v145, v113
	v_or_b32_e32 v114, v144, v113
	v_ashrrev_i32_e32 v113, 31, v112
	v_ashrrev_i32_e32 v115, 31, v114
	v_lshlrev_b64 v[112:113], 5, v[112:113]
	v_lshlrev_b64 v[114:115], 5, v[114:115]
	v_lshl_add_u64 v[112:113], v[132:133], 0, v[112:113]
	v_lshl_add_u64 v[114:115], v[132:133], 0, v[114:115]
	v_pk_mul_f32 v[110:111], v[110:111], v[116:117] op_sel_hi:[1,0]
	v_pk_mul_f32 v[108:109], v[108:109], v[116:117] op_sel_hi:[1,0]
	v_pk_mul_f32 v[106:107], v[106:107], v[116:117] op_sel_hi:[1,0]
	v_pk_mul_f32 v[104:105], v[104:105], v[116:117] op_sel_hi:[1,0]
	v_pk_mul_f32 v[102:103], v[102:103], v[116:117] op_sel_hi:[1,0]
	v_pk_mul_f32 v[100:101], v[100:101], v[116:117] op_sel_hi:[1,0]
	v_pk_mul_f32 v[118:119], v[98:99], v[116:117] op_sel_hi:[1,0]
	v_pk_mul_f32 v[116:117], v[96:97], v[116:117] op_sel_hi:[1,0]
	v_cvt_pk_bf16_f32 v96, v108, v109
	v_cvt_pk_bf16_f32 v97, v110, v111
	v_cvt_pk_bf16_f32 v98, v104, v105
	v_cvt_pk_bf16_f32 v99, v106, v107
	global_store_dwordx4 v[112:113], v[96:99], off sc1
	s_nop 1
	v_cvt_pk_bf16_f32 v96, v100, v101
	v_cvt_pk_bf16_f32 v97, v102, v103
	v_cvt_pk_bf16_f32 v98, v116, v117
	v_cvt_pk_bf16_f32 v99, v118, v119
	global_store_dwordx4 v[114:115], v[96:99], off sc1
	global_load_dword v100, v[140:141], off offset:128
	s_waitcnt vmcnt(0)
	v_fmamk_f32 v100, v100, 0x3a000000, v138
	v_or_b32_e32 v97, 32, v143
	v_rsq_f32_e32 v100, v100
	v_or_b32_e32 v96, v145, v97
	v_or_b32_e32 v98, v144, v97
	v_ashrrev_i32_e32 v97, 31, v96
	v_ashrrev_i32_e32 v99, 31, v98
	v_lshlrev_b64 v[96:97], 5, v[96:97]
	v_lshlrev_b64 v[98:99], 5, v[98:99]
	v_lshl_add_u64 v[96:97], v[132:133], 0, v[96:97]
	v_lshl_add_u64 v[98:99], v[132:133], 0, v[98:99]
	v_pk_mul_f32 v[94:95], v[94:95], v[100:101] op_sel_hi:[1,0]
	v_pk_mul_f32 v[92:93], v[92:93], v[100:101] op_sel_hi:[1,0]
	v_pk_mul_f32 v[90:91], v[90:91], v[100:101] op_sel_hi:[1,0]
	v_pk_mul_f32 v[88:89], v[88:89], v[100:101] op_sel_hi:[1,0]
	v_pk_mul_f32 v[86:87], v[86:87], v[100:101] op_sel_hi:[1,0]
	v_pk_mul_f32 v[84:85], v[84:85], v[100:101] op_sel_hi:[1,0]
	v_pk_mul_f32 v[102:103], v[82:83], v[100:101] op_sel_hi:[1,0]
	v_pk_mul_f32 v[100:101], v[80:81], v[100:101] op_sel_hi:[1,0]
	v_cvt_pk_bf16_f32 v80, v92, v93
	v_cvt_pk_bf16_f32 v81, v94, v95
	v_cvt_pk_bf16_f32 v82, v88, v89
	v_cvt_pk_bf16_f32 v83, v90, v91
	global_store_dwordx4 v[96:97], v[80:83], off sc1
	s_nop 1
	v_cvt_pk_bf16_f32 v80, v84, v85
	v_cvt_pk_bf16_f32 v81, v86, v87
	v_cvt_pk_bf16_f32 v82, v100, v101
	v_cvt_pk_bf16_f32 v83, v102, v103
	global_store_dwordx4 v[98:99], v[80:83], off sc1
	global_load_dword v84, v[140:141], off offset:192
	s_waitcnt vmcnt(0)
	v_fmamk_f32 v84, v84, 0x3a000000, v138
	v_or_b32_e32 v81, 48, v143
	v_rsq_f32_e32 v84, v84
	v_or_b32_e32 v80, v145, v81
	v_or_b32_e32 v82, v144, v81
	v_ashrrev_i32_e32 v81, 31, v80
	v_ashrrev_i32_e32 v83, 31, v82
	v_lshlrev_b64 v[80:81], 5, v[80:81]
	v_lshlrev_b64 v[82:83], 5, v[82:83]
	v_lshl_add_u64 v[80:81], v[132:133], 0, v[80:81]
	v_lshl_add_u64 v[82:83], v[132:133], 0, v[82:83]
	v_pk_mul_f32 v[78:79], v[78:79], v[84:85] op_sel_hi:[1,0]
	v_pk_mul_f32 v[76:77], v[76:77], v[84:85] op_sel_hi:[1,0]
	v_pk_mul_f32 v[74:75], v[74:75], v[84:85] op_sel_hi:[1,0]
	v_pk_mul_f32 v[72:73], v[72:73], v[84:85] op_sel_hi:[1,0]
	v_pk_mul_f32 v[70:71], v[70:71], v[84:85] op_sel_hi:[1,0]
	v_pk_mul_f32 v[68:69], v[68:69], v[84:85] op_sel_hi:[1,0]
	v_pk_mul_f32 v[86:87], v[66:67], v[84:85] op_sel_hi:[1,0]
	v_pk_mul_f32 v[84:85], v[64:65], v[84:85] op_sel_hi:[1,0]
	v_cvt_pk_bf16_f32 v64, v76, v77
	v_cvt_pk_bf16_f32 v65, v78, v79
	v_cvt_pk_bf16_f32 v66, v72, v73
	v_cvt_pk_bf16_f32 v67, v74, v75
	global_store_dwordx4 v[80:81], v[64:67], off sc1
	s_nop 1
	v_cvt_pk_bf16_f32 v64, v68, v69
	v_cvt_pk_bf16_f32 v65, v70, v71
	v_cvt_pk_bf16_f32 v66, v84, v85
	v_cvt_pk_bf16_f32 v67, v86, v87
	global_store_dwordx4 v[82:83], v[64:67], off sc1
	global_load_dword v67, v[140:141], off offset:512
	s_nop 0
	v_add_u32_e32 v65, 0x80, v142
	v_and_b32_e32 v64, 0xfcf, v65
	v_ashrrev_i32_e32 v65, 6, v65
	v_and_b32_e32 v66, 0xffffffc0, v65
	v_add_lshl_u32 v65, v66, v128, 12
	v_add_lshl_u32 v66, v66, v139, 12
	v_or_b32_e32 v68, v65, v64
	v_or_b32_e32 v70, v66, v64
	v_ashrrev_i32_e32 v69, 31, v68
	v_ashrrev_i32_e32 v71, 31, v70
	v_lshlrev_b64 v[68:69], 5, v[68:69]
	v_lshlrev_b64 v[70:71], 5, v[70:71]
	v_lshl_add_u64 v[68:69], v[132:133], 0, v[68:69]
	v_lshl_add_u64 v[70:71], v[132:133], 0, v[70:71]
	s_waitcnt vmcnt(0)
; __device__ __forceinline__ float rstd_of(float ss, float inv_n) { return __builtin_amdgcn_rsqf(ss * inv_n + 1e-6f); }
; __device__ __forceinline__ u32x4 pack8(const f32x4 a, const f32x4 b) { u32x4 w; w.x = cvt_pk_bf16(a[0], a[1]); w.y = cvt_pk_bf16(a[2], a[3]); w.z = cvt_pk_bf16(b[0], b[1]); w.w = cvt_pk_bf16(b[2], b[3]); return w; }
;     __device__ __forceinline__ void operator()(f32x4 (&acc)[2][2][4][2], const Unit& u, int wr, int wc, int fr, int fq) const {
;     ...
;                 for (int m = 0; m < 4; ++m) { const float r = rstd_of(ssr[ai * HALF + m * 16], 1.0f / 2048.0f); const int row = row0 + ai * HALF + m * 16, b = row >> 12, t = row & 4095;
; #pragma unroll
;                     for (int bj = 0; bj < 2; ++bj) { const int col = lc0 + bj * HALF, g = col >> 4, half = (col >> 3) & 1;
;                         *(u32x4*)(UG + ((size_t)((b * 64 + g) * 4096 + t) * 16 + 8 * half)) = pack8(acc[ai][bj][m][0] * r, acc[ai][bj][m][1] * r); } }
	v_fmamk_f32 v67, v67, 0x3a000000, v138
	v_rsq_f32_e32 v72, v67
	s_nop 0
	v_pk_mul_f32 v[62:63], v[62:63], v[72:73] op_sel_hi:[1,0]
	v_pk_mul_f32 v[60:61], v[60:61], v[72:73] op_sel_hi:[1,0]
	v_pk_mul_f32 v[58:59], v[58:59], v[72:73] op_sel_hi:[1,0]
	v_pk_mul_f32 v[56:57], v[56:57], v[72:73] op_sel_hi:[1,0]
	v_pk_mul_f32 v[54:55], v[54:55], v[72:73] op_sel_hi:[1,0]
	v_pk_mul_f32 v[52:53], v[52:53], v[72:73] op_sel_hi:[1,0]
	v_pk_mul_f32 v[74:75], v[50:51], v[72:73] op_sel_hi:[1,0]
	v_pk_mul_f32 v[72:73], v[48:49], v[72:73] op_sel_hi:[1,0]
	v_cvt_pk_bf16_f32 v48, v60, v61
	v_cvt_pk_bf16_f32 v49, v62, v63
	v_cvt_pk_bf16_f32 v50, v56, v57
	v_cvt_pk_bf16_f32 v51, v58, v59
	global_store_dwordx4 v[68:69], v[48:51], off sc1
	s_nop 1
	v_cvt_pk_bf16_f32 v48, v52, v53
	v_cvt_pk_bf16_f32 v49, v54, v55
	v_cvt_pk_bf16_f32 v50, v72, v73
	v_cvt_pk_bf16_f32 v51, v74, v75
	global_store_dwordx4 v[70:71], v[48:51], off sc1
	global_load_dword v52, v[140:141], off offset:576
	s_waitcnt vmcnt(0)
	v_fmamk_f32 v52, v52, 0x3a000000, v138
	v_or_b32_e32 v49, 16, v64
	v_rsq_f32_e32 v52, v52
	v_or_b32_e32 v48, v65, v49
	v_or_b32_e32 v50, v66, v49
	v_ashrrev_i32_e32 v49, 31, v48
	v_ashrrev_i32_e32 v51, 31, v50
	v_lshlrev_b64 v[48:49], 5, v[48:49]
	v_lshlrev_b64 v[50:51], 5, v[50:51]
	v_lshl_add_u64 v[48:49], v[132:133], 0, v[48:49]
	v_lshl_add_u64 v[50:51], v[132:133], 0, v[50:51]
	v_pk_mul_f32 v[46:47], v[46:47], v[52:53] op_sel_hi:[1,0]
	v_pk_mul_f32 v[44:45], v[44:45], v[52:53] op_sel_hi:[1,0]
	v_pk_mul_f32 v[42:43], v[42:43], v[52:53] op_sel_hi:[1,0]
	v_pk_mul_f32 v[40:41], v[40:41], v[52:53] op_sel_hi:[1,0]
	v_pk_mul_f32 v[38:39], v[38:39], v[52:53] op_sel_hi:[1,0]
	v_pk_mul_f32 v[36:37], v[36:37], v[52:53] op_sel_hi:[1,0]
	v_pk_mul_f32 v[54:55], v[34:35], v[52:53] op_sel_hi:[1,0]
	v_pk_mul_f32 v[52:53], v[32:33], v[52:53] op_sel_hi:[1,0]
	v_cvt_pk_bf16_f32 v32, v44, v45
	v_cvt_pk_bf16_f32 v33, v46, v47
	v_cvt_pk_bf16_f32 v34, v40, v41
	v_cvt_pk_bf16_f32 v35, v42, v43
	global_store_dwordx4 v[48:49], v[32:35], off sc1
	s_nop 1
	v_cvt_pk_bf16_f32 v32, v36, v37
	v_cvt_pk_bf16_f32 v33, v38, v39
	v_cvt_pk_bf16_f32 v34, v52, v53
	v_cvt_pk_bf16_f32 v35, v54, v55
	global_store_dwordx4 v[50:51], v[32:35], off sc1
	global_load_dword v36, v[140:141], off offset:640
	s_waitcnt vmcnt(0)
	v_fmamk_f32 v36, v36, 0x3a000000, v138
	v_or_b32_e32 v33, 32, v64
	v_rsq_f32_e32 v36, v36
	v_or_b32_e32 v32, v65, v33
	v_or_b32_e32 v34, v66, v33
	v_ashrrev_i32_e32 v33, 31, v32
	v_ashrrev_i32_e32 v35, 31, v34
	v_lshlrev_b64 v[32:33], 5, v[32:33]
	v_lshlrev_b64 v[34:35], 5, v[34:35]
	v_lshl_add_u64 v[32:33], v[132:133], 0, v[32:33]
	v_lshl_add_u64 v[34:35], v[132:133], 0, v[34:35]
	v_pk_mul_f32 v[30:31], v[30:31], v[36:37] op_sel_hi:[1,0]
	v_pk_mul_f32 v[28:29], v[28:29], v[36:37] op_sel_hi:[1,0]
	v_pk_mul_f32 v[26:27], v[26:27], v[36:37] op_sel_hi:[1,0]
	v_pk_mul_f32 v[24:25], v[24:25], v[36:37] op_sel_hi:[1,0]
	v_pk_mul_f32 v[22:23], v[22:23], v[36:37] op_sel_hi:[1,0]
	v_pk_mul_f32 v[20:21], v[20:21], v[36:37] op_sel_hi:[1,0]
	v_pk_mul_f32 v[38:39], v[18:19], v[36:37] op_sel_hi:[1,0]
	v_pk_mul_f32 v[36:37], v[16:17], v[36:37] op_sel_hi:[1,0]
	v_cvt_pk_bf16_f32 v16, v28, v29
	v_cvt_pk_bf16_f32 v17, v30, v31
	v_cvt_pk_bf16_f32 v18, v24, v25
	v_cvt_pk_bf16_f32 v19, v26, v27
	global_store_dwordx4 v[32:33], v[16:19], off sc1
	s_nop 1
	v_cvt_pk_bf16_f32 v16, v20, v21
	v_cvt_pk_bf16_f32 v17, v22, v23
	v_cvt_pk_bf16_f32 v18, v36, v37
	v_cvt_pk_bf16_f32 v19, v38, v39
	global_store_dwordx4 v[34:35], v[16:19], off sc1
	global_load_dword v20, v[140:141], off offset:704
	s_waitcnt vmcnt(0)
	v_fmamk_f32 v20, v20, 0x3a000000, v138
	v_or_b32_e32 v17, 48, v64
	v_rsq_f32_e32 v20, v20
	v_or_b32_e32 v16, v65, v17
	v_or_b32_e32 v18, v66, v17
	v_ashrrev_i32_e32 v17, 31, v16
	v_ashrrev_i32_e32 v19, 31, v18
	v_lshlrev_b64 v[16:17], 5, v[16:17]
	v_lshlrev_b64 v[18:19], 5, v[18:19]
	v_lshl_add_u64 v[16:17], v[132:133], 0, v[16:17]
	v_pk_mul_f32 v[14:15], v[14:15], v[20:21] op_sel_hi:[1,0]
	v_pk_mul_f32 v[12:13], v[12:13], v[20:21] op_sel_hi:[1,0]
	v_pk_mul_f32 v[10:11], v[10:11], v[20:21] op_sel_hi:[1,0]
	v_pk_mul_f32 v[8:9], v[8:9], v[20:21] op_sel_hi:[1,0]
	v_pk_mul_f32 v[6:7], v[6:7], v[20:21] op_sel_hi:[1,0]
	v_pk_mul_f32 v[4:5], v[4:5], v[20:21] op_sel_hi:[1,0]
	v_pk_mul_f32 v[22:23], v[2:3], v[20:21] op_sel_hi:[1,0]
	v_pk_mul_f32 v[20:21], v[0:1], v[20:21] op_sel_hi:[1,0]
	v_cvt_pk_bf16_f32 v0, v12, v13
	v_cvt_pk_bf16_f32 v1, v14, v15
	v_cvt_pk_bf16_f32 v2, v8, v9
	v_cvt_pk_bf16_f32 v3, v10, v11
	global_store_dwordx4 v[16:17], v[0:3], off sc1
	s_nop 1
	v_cvt_pk_bf16_f32 v0, v4, v5
	v_lshl_add_u64 v[4:5], v[132:133], 0, v[18:19]
	v_cvt_pk_bf16_f32 v1, v6, v7
	v_cvt_pk_bf16_f32 v2, v20, v21
	v_cvt_pk_bf16_f32 v3, v22, v23
	global_store_dwordx4 v[4:5], v[0:3], off sc1
	s_andn2_b64 vcc, exec, s[10:11]
	s_mov_b64 s[10:11], -1
	s_cbranch_vccnz .LBB0_387

; __device__ __forceinline__ float sigmoid_f(float v) { return __builtin_amdgcn_rcpf(1.0f + __builtin_amdgcn_exp2f(-1.4426950408889634f * v)); }
; __device__ __forceinline__ float bf_lo(unsigned w) { return __uint_as_float(w << 16); }
; __device__ __forceinline__ float bf_hi(unsigned w) { return __uint_as_float(w & 0xffff0000u); }
; __device__ __forceinline__ u32x4 pack8(const f32x4 a, const f32x4 b) { u32x4 w; w.x = cvt_pk_bf16(a[0], a[1]); w.y = cvt_pk_bf16(a[2], a[3]); w.z = cvt_pk_bf16(b[0], b[1]); w.w = cvt_pk_bf16(b[2], b[3]); return w; }
; __device__ __forceinline__ float sumsq4(const f32x4 a) { return (a[0] * a[0] + a[1] * a[1]) + (a[2] * a[2] + a[3] * a[3]); }
;     __device__ __forceinline__ void operator()(f32x4 (&acc)[2][2][4][2], const Unit& u, int wr, int wc, int fr, int fq) const {
;         const int row0 = u.pm * BM + wr * 64 + fr, col0 = u.pn * BM + wc * 32 + 8 * fq;
;         f32x4 bv[2][2];
; #pragma unroll
;         for (int bj = 0; bj < 2; ++bj)
; #pragma unroll
;             for (int n = 0; n < 2; ++n) bv[bj][n] = *(const f32x4*)(bias + col0 + bj * HALF + 4 * n);
;         u32x4 zw[2][4][2];
; #pragma unroll
;         for (int ai = 0; ai < 2; ++ai)
; #pragma unroll
;             for (int m = 0; m < 4; ++m)
; #pragma unroll
;                 for (int bj = 0; bj < 2; ++bj) zw[ai][m][bj] = *(const u32x4*)(Z + (size_t)(row0 + ai * HALF + m * 16) * 1024 + col0 + bj * HALF);
; #pragma unroll
;         for (int ai = 0; ai < 2; ++ai)
; #pragma unroll
;             for (int m = 0; m < 4; ++m) { const int row = row0 + ai * HALF + m * 16; float q = 0.f;
; #pragma unroll
;                 for (int bj = 0; bj < 2; ++bj) { const u32x4 zb = zw[ai][m][bj];
;                     const f32x4 z0 = {bf_lo(zb.x), bf_hi(zb.x), bf_lo(zb.y), bf_hi(zb.y)}, z1 = {bf_lo(zb.z), bf_hi(zb.z), bf_lo(zb.w), bf_hi(zb.w)};
;                     const f32x4 a0 = acc[ai][bj][m][0] + bv[bj][0], a1 = acc[ai][bj][m][1] + bv[bj][1]; f32x4 y0, y1;
; #pragma unroll
;                     for (int e = 0; e < 4; ++e) { y0[e] = z0[e] * sigmoid_f(a0[e]); y1[e] = z1[e] * sigmoid_f(a1[e]); }
;                     *(u32x4*)(Y + (size_t)row * 2048 + col0 + bj * HALF) = pack8(y0, y1); q += sumsq4(y0) + sumsq4(y1); }
;                 q += __shfl_xor(q, 16); q += __shfl_xor(q, 32);
;                 if (fq == 0) atomicAdd(ssout + row, q); }
.LBB0_595:
	v_lshl_add_u32 v206, s58, 8, v235
	v_ashrrev_i32_e32 v207, 31, v206
	v_lshl_add_u64 v[68:69], v[206:207], 2, s[38:39]
	global_load_dwordx4 v[80:83], v[68:69], off
	global_load_dwordx4 v[76:79], v[68:69], off offset:16
	v_lshl_add_u32 v222, s56, 8, v233
	v_ashrrev_i32_e32 v223, 31, v222
	v_lshlrev_b64 v[224:225], 1, v[206:207]
	v_lshlrev_b64 v[64:65], 11, v[222:223]
	v_lshl_add_u64 v[88:89], s[12:13], 0, v[224:225]
	v_lshl_add_u64 v[90:91], v[88:89], 0, v[64:65]
	global_load_dwordx4 v[240:243], v[90:91], off
	global_load_dwordx4 v[64:67], v[68:69], off offset:528
	s_nop 0
	global_load_dwordx4 v[68:71], v[68:69], off offset:512
	v_or_b32_e32 v220, 16, v222
	v_or_b32_e32 v218, 32, v222
	v_or_b32_e32 v216, 48, v222
	v_add_u32_e32 v214, 0x80, v222
	v_add_u32_e32 v212, 0x90, v222
	v_add_u32_e32 v210, 0xa0, v222
	v_add_u32_e32 v208, 0xb0, v222
	v_ashrrev_i32_e32 v221, 31, v220
	v_ashrrev_i32_e32 v219, 31, v218
	v_ashrrev_i32_e32 v217, 31, v216
	v_ashrrev_i32_e32 v215, 31, v214
	v_ashrrev_i32_e32 v213, 31, v212
	v_ashrrev_i32_e32 v211, 31, v210
	v_ashrrev_i32_e32 v209, 31, v208
	v_lshlrev_b64 v[100:101], 11, v[220:221]
	v_lshlrev_b64 v[102:103], 11, v[218:219]
	v_lshlrev_b64 v[112:113], 11, v[216:217]
	v_lshlrev_b64 v[114:115], 11, v[214:215]
	v_lshlrev_b64 v[124:125], 11, v[212:213]
	v_lshlrev_b64 v[126:127], 11, v[210:211]
	v_lshlrev_b64 v[136:137], 11, v[208:209]
	v_lshl_add_u64 v[100:101], v[88:89], 0, v[100:101]
	v_lshl_add_u64 v[102:103], v[88:89], 0, v[102:103]
	v_lshl_add_u64 v[112:113], v[88:89], 0, v[112:113]
	v_lshl_add_u64 v[114:115], v[88:89], 0, v[114:115]
	v_lshl_add_u64 v[124:125], v[88:89], 0, v[124:125]
	v_lshl_add_u64 v[248:249], v[88:89], 0, v[126:127]
	v_lshl_add_u64 v[88:89], v[88:89], 0, v[136:137]
	global_load_dwordx4 v[244:247], v[90:91], off offset:256
	global_load_dwordx4 v[196:199], v[100:101], off
	global_load_dwordx4 v[192:195], v[100:101], off offset:256
	global_load_dwordx4 v[188:191], v[102:103], off
	global_load_dwordx4 v[184:187], v[102:103], off offset:256
	global_load_dwordx4 v[180:183], v[112:113], off
	global_load_dwordx4 v[176:179], v[112:113], off offset:256
	global_load_dwordx4 v[164:167], v[114:115], off
	global_load_dwordx4 v[160:163], v[114:115], off offset:256
	global_load_dwordx4 v[144:147], v[124:125], off
	global_load_dwordx4 v[136:139], v[124:125], off offset:256
	s_nop 0
	global_load_dwordx4 v[124:127], v[248:249], off
	global_load_dwordx4 v[112:115], v[248:249], off offset:256
	global_load_dwordx4 v[100:103], v[88:89], off
	s_nop 0
	global_load_dwordx4 v[88:91], v[88:89], off offset:256
	v_lshlrev_b64 v[226:227], 12, v[222:223]
	s_waitcnt vmcnt(0)
	v_add_f32_e32 v173, v173, v81
	v_add_f32_e32 v169, v169, v77
	v_mul_f32_e32 v173, 0xbfb8aa3b, v173
	v_mul_f32_e32 v169, 0xbfb8aa3b, v169
	v_exp_f32_e32 v173, v173
	v_exp_f32_e32 v169, v169
	v_add_f32_e32 v170, v170, v78
	v_add_f32_e32 v172, v172, v80
	v_add_f32_e32 v168, v168, v76
	v_mul_f32_e32 v170, 0xbfb8aa3b, v170
	v_add_f32_e32 v173, 1.0, v173
	v_add_f32_e32 v169, 1.0, v169
	v_mul_f32_e32 v172, 0xbfb8aa3b, v172
	v_mul_f32_e32 v168, 0xbfb8aa3b, v168
	v_exp_f32_e32 v170, v170
	v_rcp_f32_e32 v173, v173
	v_rcp_f32_e32 v169, v169
	v_exp_f32_e32 v172, v172
	v_exp_f32_e32 v168, v168
	v_and_b32_e32 v228, 0xffff0000, v240
	v_lshlrev_b32_e32 v248, 16, v242
	v_and_b32_e32 v242, 0xffff0000, v242
	v_add_f32_e32 v174, v174, v82
	v_mul_f32_e32 v173, v173, v228
	v_mul_f32_e32 v228, v169, v242
	v_add_f32_e32 v169, 1.0, v170
	v_add_f32_e32 v170, v175, v83
	v_mul_f32_e32 v174, 0xbfb8aa3b, v174
	v_add_f32_e32 v172, 1.0, v172
	v_add_f32_e32 v168, 1.0, v168
	v_mul_f32_e32 v170, 0xbfb8aa3b, v170
	v_exp_f32_e32 v174, v174
	v_rcp_f32_e32 v172, v172
	v_rcp_f32_e32 v168, v168
	v_exp_f32_e32 v170, v170
	v_add_f32_e32 v152, v152, v64
	v_lshlrev_b32_e32 v200, 16, v240
	v_mul_f32_e32 v152, 0xbfb8aa3b, v152
	v_mul_f32_e32 v172, v172, v200
	v_mul_f32_e32 v200, v168, v248
	v_add_f32_e32 v168, 1.0, v174
	v_add_f32_e32 v170, 1.0, v170
	v_exp_f32_e32 v152, v152
	v_rcp_f32_e32 v168, v168
	v_rcp_f32_e32 v170, v170
	v_add_f32_e32 v153, v153, v65
	v_lshlrev_b32_e32 v240, 16, v241
	v_and_b32_e32 v241, 0xffff0000, v241
	v_rcp_f32_e32 v169, v169
	v_add_f32_e32 v152, 1.0, v152
	v_mul_f32_e32 v153, 0xbfb8aa3b, v153
	v_mul_f32_e32 v174, v168, v240
	v_mul_f32_e32 v240, v170, v241
	v_cvt_pk_bf16_f32 v168, v172, v173
	v_mul_f32_e32 v173, v173, v173
	v_rcp_f32_e32 v152, v152
	v_exp_f32_e32 v153, v153
	v_fmac_f32_e32 v173, v172, v172
	v_mul_f32_e32 v172, v240, v240
	v_lshlrev_b32_e32 v249, 16, v243
	v_fmac_f32_e32 v172, v174, v174
	v_mul_f32_e32 v175, v169, v249
	v_cvt_pk_bf16_f32 v169, v174, v240
	v_cvt_pk_bf16_f32 v170, v200, v228
	v_add_f32_e32 v172, v173, v172
	v_mul_f32_e32 v173, v228, v228
	v_lshlrev_b32_e32 v228, 16, v246
	v_mul_f32_e32 v228, v152, v228
	v_add_f32_e32 v152, 1.0, v153
	v_add_f32_e32 v153, v158, v70
	v_add_f32_e32 v154, v154, v66
	v_mul_f32_e32 v153, 0xbfb8aa3b, v153
	v_mul_f32_e32 v154, 0xbfb8aa3b, v154
	v_add_f32_e32 v171, v171, v79
	v_rcp_f32_e32 v152, v152
	v_exp_f32_e32 v153, v153
	v_exp_f32_e32 v154, v154
	v_mul_f32_e32 v171, 0xbfb8aa3b, v171
	v_exp_f32_e32 v171, v171
	v_and_b32_e32 v240, 0xffff0000, v246
	v_add_f32_e32 v157, v157, v69
	v_mul_f32_e32 v158, v152, v240
	v_add_f32_e32 v152, 1.0, v153
	v_add_f32_e32 v153, 1.0, v154
	v_add_f32_e32 v154, v159, v71
	v_add_f32_e32 v156, v156, v68
	v_mul_f32_e32 v157, 0xbfb8aa3b, v157
	v_mul_f32_e32 v154, 0xbfb8aa3b, v154
	v_add_f32_e32 v171, 1.0, v171
	v_mul_f32_e32 v156, 0xbfb8aa3b, v156
	v_exp_f32_e32 v157, v157
	v_exp_f32_e32 v154, v154
	v_add_f32_e32 v155, v155, v67
	v_rcp_f32_e32 v171, v171
	v_exp_f32_e32 v156, v156
; __device__ __forceinline__ float sigmoid_f(float v) { return __builtin_amdgcn_rcpf(1.0f + __builtin_amdgcn_exp2f(-1.4426950408889634f * v)); }
; __device__ __forceinline__ float bf_lo(unsigned w) { return __uint_as_float(w << 16); }
; __device__ __forceinline__ float bf_hi(unsigned w) { return __uint_as_float(w & 0xffff0000u); }
; __device__ __forceinline__ u32x4 pack8(const f32x4 a, const f32x4 b) { u32x4 w; w.x = cvt_pk_bf16(a[0], a[1]); w.y = cvt_pk_bf16(a[2], a[3]); w.z = cvt_pk_bf16(b[0], b[1]); w.w = cvt_pk_bf16(b[2], b[3]); return w; }
; __device__ __forceinline__ float sumsq4(const f32x4 a) { return (a[0] * a[0] + a[1] * a[1]) + (a[2] * a[2] + a[3] * a[3]); }
;     __device__ __forceinline__ void operator()(f32x4 (&acc)[2][2][4][2], const Unit& u, int wr, int wc, int fr, int fq) const {
;     ...
;         for (int ai = 0; ai < 2; ++ai)
; #pragma unroll
;             for (int m = 0; m < 4; ++m) { const int row = row0 + ai * HALF + m * 16; float q = 0.f;
; #pragma unroll
;                 for (int bj = 0; bj < 2; ++bj) { const u32x4 zb = zw[ai][m][bj];
;                     const f32x4 z0 = {bf_lo(zb.x), bf_hi(zb.x), bf_lo(zb.y), bf_hi(zb.y)}, z1 = {bf_lo(zb.z), bf_hi(zb.z), bf_lo(zb.w), bf_hi(zb.w)};
;                     const f32x4 a0 = acc[ai][bj][m][0] + bv[bj][0], a1 = acc[ai][bj][m][1] + bv[bj][1]; f32x4 y0, y1;
; #pragma unroll
;                     for (int e = 0; e < 4; ++e) { y0[e] = z0[e] * sigmoid_f(a0[e]); y1[e] = z1[e] * sigmoid_f(a1[e]); }
;                     *(u32x4*)(Y + (size_t)row * 2048 + col0 + bj * HALF) = pack8(y0, y1); q += sumsq4(y0) + sumsq4(y1); }
;                 q += __shfl_xor(q, 16); q += __shfl_xor(q, 32);
;                 if (fq == 0) atomicAdd(ssout + row, q); }
	v_mul_f32_e32 v155, 0xbfb8aa3b, v155
	v_exp_f32_e32 v155, v155
	v_and_b32_e32 v243, 0xffff0000, v243
	v_add_f32_e32 v157, 1.0, v157
	v_add_f32_e32 v154, 1.0, v154
	v_mul_f32_e32 v241, v171, v243
	v_add_f32_e32 v156, 1.0, v156
	v_rcp_f32_e32 v157, v157
	v_rcp_f32_e32 v152, v152
	v_rcp_f32_e32 v154, v154
	v_mul_f32_e32 v174, v241, v241
	v_rcp_f32_e32 v156, v156
	v_rcp_f32_e32 v153, v153
	v_add_f32_e32 v155, 1.0, v155
	v_fmac_f32_e32 v173, v200, v200
	v_fmac_f32_e32 v174, v175, v175
	v_rcp_f32_e32 v155, v155
	v_cvt_pk_bf16_f32 v171, v175, v241
	v_add_f32_e32 v173, v173, v174
	v_and_b32_e32 v174, 0xffff0000, v244
	v_lshlrev_b32_e32 v175, 16, v245
	v_and_b32_e32 v200, 0xffff0000, v245
	v_add_f32_e32 v172, v172, v173
	v_lshlrev_b32_e32 v173, 16, v244
	v_lshlrev_b32_e32 v241, 16, v247
	v_mul_f32_e32 v157, v157, v174
	v_mul_f32_e32 v159, v152, v175
	v_mul_f32_e32 v175, v154, v200
	v_and_b32_e32 v242, 0xffff0000, v247
	v_mul_f32_e32 v156, v156, v173
	v_mul_f32_e32 v174, v153, v241
	v_mul_f32_e32 v152, v157, v157
	v_mul_f32_e32 v153, v175, v175
	v_mul_f32_e32 v200, v155, v242
	v_fmac_f32_e32 v152, v156, v156
	v_fmac_f32_e32 v153, v159, v159
	v_add_f32_e32 v152, v152, v153
	v_mul_f32_e32 v153, v158, v158
	v_mul_f32_e32 v154, v200, v200
	v_fmac_f32_e32 v153, v228, v228
	v_fmac_f32_e32 v154, v174, v174
	v_add_f32_e32 v153, v153, v154
	v_add_f32_e32 v152, v152, v153
	v_and_b32_e32 v154, 64, v239
	v_add_f32_e32 v153, v172, v152
	v_xor_b32_e32 v152, 16, v239
	v_add_u32_e32 v240, 64, v154
	v_cmp_lt_i32_e32 vcc, v152, v240
	v_lshl_add_u64 v[154:155], s[14:15], 0, v[226:227]
	v_lshl_add_u64 v[172:173], v[154:155], 0, v[224:225]
	v_cndmask_b32_e32 v152, v239, v152, vcc
	v_lshlrev_b32_e32 v152, 2, v152
	ds_bpermute_b32 v241, v152, v153
	global_store_dwordx4 v[172:173], v[168:171], off sc1
	v_cvt_pk_bf16_f32 v156, v156, v157
	v_cvt_pk_bf16_f32 v157, v159, v175
	v_cvt_pk_bf16_f32 v158, v228, v158
	s_waitcnt lgkmcnt(0)
	v_add_f32_e32 v154, v153, v241
	v_xor_b32_e32 v153, 32, v239
	v_cmp_lt_i32_e32 vcc, v153, v240
	v_cvt_pk_bf16_f32 v159, v174, v200
	global_store_dwordx4 v[172:173], v[156:159], off offset:256 sc1
	s_nop 0
	v_cndmask_b32_e32 v153, v239, v153, vcc
	v_lshlrev_b32_e32 v153, 2, v153
	ds_bpermute_b32 v155, v153, v154
	s_and_saveexec_b64 s[56:57], s[8:9]
	s_cbranch_execz .LBB0_597
	v_lshl_add_u64 v[156:157], v[222:223], 2, s[40:41]
	s_waitcnt lgkmcnt(0)
	v_add_f32_e32 v154, v154, v155
	global_atomic_add_f32 v[156:157], v154, off
.LBB0_597:
	s_or_b64 exec, exec, s[56:57]
	v_add_f32_e32 v148, v148, v80
	v_add_f32_e32 v140, v140, v76
	v_mul_f32_e32 v148, 0xbfb8aa3b, v148
	v_mul_f32_e32 v140, 0xbfb8aa3b, v140
	v_exp_f32_e32 v148, v148
	v_exp_f32_e32 v140, v140
	v_add_f32_e32 v141, v141, v77
	v_mul_f32_e32 v141, 0xbfb8aa3b, v141
	v_add_f32_e32 v148, 1.0, v148
	v_add_f32_e32 v140, 1.0, v140
	v_rcp_f32_e32 v148, v148
	v_rcp_f32_e32 v140, v140
	v_exp_f32_e32 v141, v141
	v_lshlrev_b32_e32 v156, 16, v196
	v_lshlrev_b32_e32 v168, 16, v198
	v_mul_f32_e32 v148, v148, v156
	v_mul_f32_e32 v156, v140, v168
	v_add_f32_e32 v140, 1.0, v141
	v_add_f32_e32 v141, v150, v82
	v_add_f32_e32 v142, v142, v78
	v_mul_f32_e32 v141, 0xbfb8aa3b, v141
	v_mul_f32_e32 v142, 0xbfb8aa3b, v142
	v_rcp_f32_e32 v140, v140
	v_exp_f32_e32 v141, v141
	v_exp_f32_e32 v142, v142
	v_and_b32_e32 v169, 0xffff0000, v198
	v_add_f32_e32 v149, v149, v81
	v_mul_f32_e32 v149, 0xbfb8aa3b, v149
	v_mul_f32_e32 v150, v140, v169
	v_add_f32_e32 v140, 1.0, v141
	v_add_f32_e32 v141, 1.0, v142
	v_add_f32_e32 v142, v151, v83
	v_exp_f32_e32 v149, v149
	v_mul_f32_e32 v142, 0xbfb8aa3b, v142
	v_exp_f32_e32 v142, v142
	v_add_f32_e32 v143, v143, v79
	v_mul_f32_e32 v143, 0xbfb8aa3b, v143
	v_exp_f32_e32 v143, v143
	v_add_f32_e32 v149, 1.0, v149
	v_rcp_f32_e32 v149, v149
	v_add_f32_e32 v142, 1.0, v142
	v_rcp_f32_e32 v140, v140
	v_rcp_f32_e32 v142, v142
	v_add_f32_e32 v132, v132, v68
	v_add_f32_e32 v128, v128, v64
	v_add_f32_e32 v143, 1.0, v143
	v_mul_f32_e32 v132, 0xbfb8aa3b, v132
	v_mul_f32_e32 v128, 0xbfb8aa3b, v128
	v_and_b32_e32 v157, 0xffff0000, v196
	v_rcp_f32_e32 v143, v143
	v_exp_f32_e32 v132, v132
	v_exp_f32_e32 v128, v128
	v_lshlrev_b32_e32 v158, 16, v197
	v_and_b32_e32 v159, 0xffff0000, v197
	v_mul_f32_e32 v149, v149, v157
	v_rcp_f32_e32 v141, v141
	v_mul_f32_e32 v151, v140, v158
	v_mul_f32_e32 v158, v142, v159
	v_cvt_pk_bf16_f32 v140, v148, v149
	v_mul_f32_e32 v149, v149, v149
	v_and_b32_e32 v171, 0xffff0000, v199
	v_fmac_f32_e32 v149, v148, v148
	v_mul_f32_e32 v148, v158, v158
	v_add_f32_e32 v129, v129, v65
	v_lshlrev_b32_e32 v170, 16, v199
	v_mul_f32_e32 v159, v143, v171
	v_fmac_f32_e32 v148, v151, v151
	v_add_f32_e32 v132, 1.0, v132
	v_add_f32_e32 v133, v133, v69
	v_add_f32_e32 v128, 1.0, v128
	v_mul_f32_e32 v129, 0xbfb8aa3b, v129
	v_mul_f32_e32 v157, v141, v170
	v_cvt_pk_bf16_f32 v141, v151, v158
	v_cvt_pk_bf16_f32 v142, v156, v150
	v_add_f32_e32 v148, v149, v148
	v_mul_f32_e32 v149, v150, v150
	v_mul_f32_e32 v150, v159, v159
	v_mul_f32_e32 v133, 0xbfb8aa3b, v133
	v_rcp_f32_e32 v132, v132
	v_rcp_f32_e32 v128, v128
	v_exp_f32_e32 v129, v129
	v_fmac_f32_e32 v149, v156, v156
	v_fmac_f32_e32 v150, v157, v157
	v_exp_f32_e32 v133, v133
	v_add_f32_e32 v149, v149, v150
	v_cvt_pk_bf16_f32 v143, v157, v159
	v_add_f32_e32 v148, v148, v149
	v_lshlrev_b32_e32 v149, 16, v192
	v_lshlrev_b32_e32 v157, 16, v194
	v_mul_f32_e32 v132, v132, v149
	v_mul_f32_e32 v149, v128, v157
	v_add_f32_e32 v128, 1.0, v129
	v_add_f32_e32 v129, v134, v70
	v_add_f32_e32 v130, v130, v66
	v_add_f32_e32 v133, 1.0, v133
	v_mul_f32_e32 v129, 0xbfb8aa3b, v129
	v_mul_f32_e32 v130, 0xbfb8aa3b, v130
	v_rcp_f32_e32 v133, v133
	v_rcp_f32_e32 v128, v128
	v_exp_f32_e32 v129, v129
	v_exp_f32_e32 v130, v130
	v_and_b32_e32 v150, 0xffff0000, v192
	v_and_b32_e32 v158, 0xffff0000, v194
	v_mul_f32_e32 v133, v133, v150
	v_mul_f32_e32 v150, v128, v158
	v_add_f32_e32 v128, 1.0, v129
	v_add_f32_e32 v129, 1.0, v130
	v_add_f32_e32 v130, v135, v71
	v_mul_f32_e32 v130, 0xbfb8aa3b, v130
	v_exp_f32_e32 v130, v130
	v_add_f32_e32 v131, v131, v67
	v_mul_f32_e32 v131, 0xbfb8aa3b, v131
	v_exp_f32_e32 v131, v131
	v_add_f32_e32 v130, 1.0, v130
	v_rcp_f32_e32 v130, v130
	v_rcp_f32_e32 v128, v128
	v_rcp_f32_e32 v129, v129
	v_add_f32_e32 v131, 1.0, v131
	v_rcp_f32_e32 v131, v131
	v_and_b32_e32 v156, 0xffff0000, v193
	v_lshlrev_b32_e32 v151, 16, v193
	v_lshlrev_b32_e32 v159, 16, v195
	v_mul_f32_e32 v156, v130, v156
	v_and_b32_e32 v168, 0xffff0000, v195
	v_mul_f32_e32 v151, v128, v151
	v_mul_f32_e32 v157, v129, v159
	v_mul_f32_e32 v128, v133, v133
	v_mul_f32_e32 v129, v156, v156
	v_mul_f32_e32 v158, v131, v168
	v_fmac_f32_e32 v128, v132, v132
	v_fmac_f32_e32 v129, v151, v151
	v_add_f32_e32 v128, v128, v129
	v_mul_f32_e32 v129, v150, v150
	v_mul_f32_e32 v130, v158, v158
	v_fmac_f32_e32 v129, v149, v149
	v_fmac_f32_e32 v130, v157, v157
	v_add_f32_e32 v129, v129, v130
	v_add_f32_e32 v128, v128, v129
	v_add_f32_e32 v131, v148, v128
	ds_bpermute_b32 v148, v152, v131
	s_waitcnt lgkmcnt(1)
; __device__ __forceinline__ float sigmoid_f(float v) { return __builtin_amdgcn_rcpf(1.0f + __builtin_amdgcn_exp2f(-1.4426950408889634f * v)); }
; __device__ __forceinline__ float bf_lo(unsigned w) { return __uint_as_float(w << 16); }
; __device__ __forceinline__ float bf_hi(unsigned w) { return __uint_as_float(w & 0xffff0000u); }
; __device__ __forceinline__ u32x4 pack8(const f32x4 a, const f32x4 b) { u32x4 w; w.x = cvt_pk_bf16(a[0], a[1]); w.y = cvt_pk_bf16(a[2], a[3]); w.z = cvt_pk_bf16(b[0], b[1]); w.w = cvt_pk_bf16(b[2], b[3]); return w; }
; __device__ __forceinline__ float sumsq4(const f32x4 a) { return (a[0] * a[0] + a[1] * a[1]) + (a[2] * a[2] + a[3] * a[3]); }
;     __device__ __forceinline__ void operator()(f32x4 (&acc)[2][2][4][2], const Unit& u, int wr, int wc, int fr, int fq) const {
;     ...
;         for (int ai = 0; ai < 2; ++ai)
; #pragma unroll
;             for (int m = 0; m < 4; ++m) { const int row = row0 + ai * HALF + m * 16; float q = 0.f;
; #pragma unroll
;                 for (int bj = 0; bj < 2; ++bj) { const u32x4 zb = zw[ai][m][bj];
;                     const f32x4 z0 = {bf_lo(zb.x), bf_hi(zb.x), bf_lo(zb.y), bf_hi(zb.y)}, z1 = {bf_lo(zb.z), bf_hi(zb.z), bf_lo(zb.w), bf_hi(zb.w)};
;                     const f32x4 a0 = acc[ai][bj][m][0] + bv[bj][0], a1 = acc[ai][bj][m][1] + bv[bj][1]; f32x4 y0, y1;
; #pragma unroll
;                     for (int e = 0; e < 4; ++e) { y0[e] = z0[e] * sigmoid_f(a0[e]); y1[e] = z1[e] * sigmoid_f(a1[e]); }
;                     *(u32x4*)(Y + (size_t)row * 2048 + col0 + bj * HALF) = pack8(y0, y1); q += sumsq4(y0) + sumsq4(y1); }
;                 q += __shfl_xor(q, 16); q += __shfl_xor(q, 32);
;                 if (fq == 0) atomicAdd(ssout + row, q); }
	v_lshlrev_b64 v[154:155], 12, v[220:221]
	v_lshl_add_u64 v[128:129], s[14:15], 0, v[154:155]
	v_lshl_add_u64 v[134:135], v[206:207], 1, v[128:129]
	global_store_dwordx4 v[134:135], v[140:143], off sc1
	s_waitcnt lgkmcnt(0)
	v_add_f32_e32 v128, v131, v148
	ds_bpermute_b32 v129, v153, v128
	v_cvt_pk_bf16_f32 v130, v132, v133
	v_cvt_pk_bf16_f32 v131, v151, v156
	v_cvt_pk_bf16_f32 v132, v149, v150
	v_cvt_pk_bf16_f32 v133, v157, v158
	global_store_dwordx4 v[134:135], v[130:133], off offset:256 sc1
	s_and_saveexec_b64 s[56:57], s[8:9]
	s_cbranch_execz .LBB0_599
	v_lshl_add_u64 v[130:131], v[220:221], 2, s[40:41]
	s_waitcnt lgkmcnt(0)
	v_add_f32_e32 v128, v128, v129
	global_atomic_add_f32 v[130:131], v128, off
.LBB0_599:
	s_or_b64 exec, exec, s[56:57]
	v_add_f32_e32 v120, v120, v80
	v_add_f32_e32 v116, v116, v76
	v_mul_f32_e32 v120, 0xbfb8aa3b, v120
	v_mul_f32_e32 v116, 0xbfb8aa3b, v116
	v_exp_f32_e32 v120, v120
	v_exp_f32_e32 v116, v116
	v_add_f32_e32 v117, v117, v77
	v_mul_f32_e32 v117, 0xbfb8aa3b, v117
	v_add_f32_e32 v120, 1.0, v120
	v_add_f32_e32 v116, 1.0, v116
	v_rcp_f32_e32 v120, v120
	v_rcp_f32_e32 v116, v116
	v_exp_f32_e32 v117, v117
	v_lshlrev_b32_e32 v130, 16, v188
	v_lshlrev_b32_e32 v134, 16, v190
	v_mul_f32_e32 v120, v120, v130
	v_mul_f32_e32 v130, v116, v134
	v_add_f32_e32 v116, 1.0, v117
	v_add_f32_e32 v117, v122, v82
	v_add_f32_e32 v118, v118, v78
	v_mul_f32_e32 v117, 0xbfb8aa3b, v117
	v_mul_f32_e32 v118, 0xbfb8aa3b, v118
	v_rcp_f32_e32 v116, v116
	v_exp_f32_e32 v117, v117
	v_exp_f32_e32 v118, v118
	v_and_b32_e32 v135, 0xffff0000, v190
	v_add_f32_e32 v121, v121, v81
	v_mul_f32_e32 v121, 0xbfb8aa3b, v121
	v_mul_f32_e32 v122, v116, v135
	v_add_f32_e32 v116, 1.0, v117
	v_add_f32_e32 v117, 1.0, v118
	v_add_f32_e32 v118, v123, v83
	v_exp_f32_e32 v121, v121
	v_mul_f32_e32 v118, 0xbfb8aa3b, v118
	v_exp_f32_e32 v118, v118
	v_add_f32_e32 v119, v119, v79
	v_mul_f32_e32 v119, 0xbfb8aa3b, v119
	v_exp_f32_e32 v119, v119
	v_add_f32_e32 v121, 1.0, v121
	v_rcp_f32_e32 v121, v121
	v_add_f32_e32 v118, 1.0, v118
	v_rcp_f32_e32 v116, v116
	v_rcp_f32_e32 v118, v118
	v_add_f32_e32 v108, v108, v68
	v_add_f32_e32 v104, v104, v64
	v_add_f32_e32 v119, 1.0, v119
	v_mul_f32_e32 v108, 0xbfb8aa3b, v108
	v_mul_f32_e32 v104, 0xbfb8aa3b, v104
	v_and_b32_e32 v131, 0xffff0000, v188
	v_rcp_f32_e32 v119, v119
	v_exp_f32_e32 v108, v108
	v_exp_f32_e32 v104, v104
	v_lshlrev_b32_e32 v132, 16, v189
	v_and_b32_e32 v133, 0xffff0000, v189
	v_mul_f32_e32 v121, v121, v131
	v_rcp_f32_e32 v117, v117
	v_mul_f32_e32 v123, v116, v132
	v_mul_f32_e32 v132, v118, v133
	v_cvt_pk_bf16_f32 v116, v120, v121
	v_mul_f32_e32 v121, v121, v121
	v_and_b32_e32 v141, 0xffff0000, v191
	v_fmac_f32_e32 v121, v120, v120
	v_mul_f32_e32 v120, v132, v132
	v_add_f32_e32 v105, v105, v65
	v_lshlrev_b32_e32 v140, 16, v191
	v_mul_f32_e32 v133, v119, v141
	v_fmac_f32_e32 v120, v123, v123
	v_add_f32_e32 v108, 1.0, v108
	v_add_f32_e32 v109, v109, v69
	v_add_f32_e32 v104, 1.0, v104
	v_mul_f32_e32 v105, 0xbfb8aa3b, v105
	v_mul_f32_e32 v131, v117, v140
	v_cvt_pk_bf16_f32 v117, v123, v132
	v_cvt_pk_bf16_f32 v118, v130, v122
	v_add_f32_e32 v120, v121, v120
	v_mul_f32_e32 v121, v122, v122
	v_mul_f32_e32 v122, v133, v133
	v_mul_f32_e32 v109, 0xbfb8aa3b, v109
	v_rcp_f32_e32 v108, v108
	v_rcp_f32_e32 v104, v104
	v_exp_f32_e32 v105, v105
	v_fmac_f32_e32 v121, v130, v130
	v_fmac_f32_e32 v122, v131, v131
	v_exp_f32_e32 v109, v109
	v_add_f32_e32 v121, v121, v122
	v_cvt_pk_bf16_f32 v119, v131, v133
	v_add_f32_e32 v120, v120, v121
	v_lshlrev_b32_e32 v121, 16, v184
	v_lshlrev_b32_e32 v131, 16, v186
	v_mul_f32_e32 v108, v108, v121
	v_mul_f32_e32 v121, v104, v131
	v_add_f32_e32 v104, 1.0, v105
	v_add_f32_e32 v105, v110, v70
	v_add_f32_e32 v106, v106, v66
	v_add_f32_e32 v109, 1.0, v109
	v_mul_f32_e32 v105, 0xbfb8aa3b, v105
	v_mul_f32_e32 v106, 0xbfb8aa3b, v106
	v_rcp_f32_e32 v109, v109
	v_rcp_f32_e32 v104, v104
	v_exp_f32_e32 v105, v105
	v_exp_f32_e32 v106, v106
	v_and_b32_e32 v122, 0xffff0000, v184
	v_and_b32_e32 v132, 0xffff0000, v186
	v_mul_f32_e32 v109, v109, v122
	v_mul_f32_e32 v122, v104, v132
	v_add_f32_e32 v104, 1.0, v105
	v_add_f32_e32 v105, 1.0, v106
	v_add_f32_e32 v106, v111, v71
	v_mul_f32_e32 v106, 0xbfb8aa3b, v106
	v_exp_f32_e32 v106, v106
	v_add_f32_e32 v107, v107, v67
	v_mul_f32_e32 v107, 0xbfb8aa3b, v107
	v_exp_f32_e32 v107, v107
	v_add_f32_e32 v106, 1.0, v106
	v_rcp_f32_e32 v106, v106
	v_rcp_f32_e32 v104, v104
	v_rcp_f32_e32 v105, v105
	v_add_f32_e32 v107, 1.0, v107
	v_rcp_f32_e32 v107, v107
	v_and_b32_e32 v130, 0xffff0000, v185
	v_lshlrev_b32_e32 v123, 16, v185
	v_lshlrev_b32_e32 v133, 16, v187
	v_mul_f32_e32 v130, v106, v130
	v_and_b32_e32 v134, 0xffff0000, v187
	v_mul_f32_e32 v123, v104, v123
	v_mul_f32_e32 v131, v105, v133
	v_mul_f32_e32 v104, v109, v109
	v_mul_f32_e32 v105, v130, v130
	v_mul_f32_e32 v132, v107, v134
	v_fmac_f32_e32 v104, v108, v108
	v_fmac_f32_e32 v105, v123, v123
	v_add_f32_e32 v104, v104, v105
	v_mul_f32_e32 v105, v122, v122
	v_mul_f32_e32 v106, v132, v132
	v_fmac_f32_e32 v105, v121, v121
	v_fmac_f32_e32 v106, v131, v131
	v_add_f32_e32 v105, v105, v106
	v_add_f32_e32 v104, v104, v105
	v_add_f32_e32 v107, v120, v104
	ds_bpermute_b32 v120, v152, v107
	s_waitcnt lgkmcnt(1)
	v_lshlrev_b64 v[128:129], 12, v[218:219]
	v_lshl_add_u64 v[104:105], s[14:15], 0, v[128:129]
	v_lshl_add_u64 v[110:111], v[206:207], 1, v[104:105]
	global_store_dwordx4 v[110:111], v[116:119], off sc1
	s_waitcnt lgkmcnt(0)
	v_add_f32_e32 v104, v107, v120
	ds_bpermute_b32 v105, v153, v104
	v_cvt_pk_bf16_f32 v106, v108, v109
	v_cvt_pk_bf16_f32 v107, v123, v130
	v_cvt_pk_bf16_f32 v108, v121, v122
	v_cvt_pk_bf16_f32 v109, v131, v132
	global_store_dwordx4 v[110:111], v[106:109], off offset:256 sc1
	s_and_saveexec_b64 s[56:57], s[8:9]
	s_cbranch_execz .LBB0_601
	v_lshl_add_u64 v[106:107], v[218:219], 2, s[40:41]
	s_waitcnt lgkmcnt(0)
	v_add_f32_e32 v104, v104, v105
	global_atomic_add_f32 v[106:107], v104, off
; __device__ __forceinline__ float sigmoid_f(float v) { return __builtin_amdgcn_rcpf(1.0f + __builtin_amdgcn_exp2f(-1.4426950408889634f * v)); }
; __device__ __forceinline__ float bf_lo(unsigned w) { return __uint_as_float(w << 16); }
; __device__ __forceinline__ float bf_hi(unsigned w) { return __uint_as_float(w & 0xffff0000u); }
; __device__ __forceinline__ u32x4 pack8(const f32x4 a, const f32x4 b) { u32x4 w; w.x = cvt_pk_bf16(a[0], a[1]); w.y = cvt_pk_bf16(a[2], a[3]); w.z = cvt_pk_bf16(b[0], b[1]); w.w = cvt_pk_bf16(b[2], b[3]); return w; }
; __device__ __forceinline__ float sumsq4(const f32x4 a) { return (a[0] * a[0] + a[1] * a[1]) + (a[2] * a[2] + a[3] * a[3]); }
;     __device__ __forceinline__ void operator()(f32x4 (&acc)[2][2][4][2], const Unit& u, int wr, int wc, int fr, int fq) const {
;     ...
;         for (int ai = 0; ai < 2; ++ai)
; #pragma unroll
;             for (int m = 0; m < 4; ++m) { const int row = row0 + ai * HALF + m * 16; float q = 0.f;
; #pragma unroll
;                 for (int bj = 0; bj < 2; ++bj) { const u32x4 zb = zw[ai][m][bj];
;                     const f32x4 z0 = {bf_lo(zb.x), bf_hi(zb.x), bf_lo(zb.y), bf_hi(zb.y)}, z1 = {bf_lo(zb.z), bf_hi(zb.z), bf_lo(zb.w), bf_hi(zb.w)};
;                     const f32x4 a0 = acc[ai][bj][m][0] + bv[bj][0], a1 = acc[ai][bj][m][1] + bv[bj][1]; f32x4 y0, y1;
; #pragma unroll
;                     for (int e = 0; e < 4; ++e) { y0[e] = z0[e] * sigmoid_f(a0[e]); y1[e] = z1[e] * sigmoid_f(a1[e]); }
;                     *(u32x4*)(Y + (size_t)row * 2048 + col0 + bj * HALF) = pack8(y0, y1); q += sumsq4(y0) + sumsq4(y1); }
;                 q += __shfl_xor(q, 16); q += __shfl_xor(q, 32);
;                 if (fq == 0) atomicAdd(ssout + row, q); }
.LBB0_601:
	s_or_b64 exec, exec, s[56:57]
	v_add_f32_e32 v96, v96, v80
	v_add_f32_e32 v92, v92, v76
	v_mul_f32_e32 v96, 0xbfb8aa3b, v96
	v_mul_f32_e32 v92, 0xbfb8aa3b, v92
	v_exp_f32_e32 v96, v96
	v_exp_f32_e32 v92, v92
	v_add_f32_e32 v93, v93, v77
	v_mul_f32_e32 v93, 0xbfb8aa3b, v93
	v_add_f32_e32 v96, 1.0, v96
	v_add_f32_e32 v92, 1.0, v92
	v_rcp_f32_e32 v96, v96
	v_rcp_f32_e32 v92, v92
	v_exp_f32_e32 v93, v93
	v_lshlrev_b32_e32 v106, 16, v180
	v_lshlrev_b32_e32 v110, 16, v182
	v_mul_f32_e32 v96, v96, v106
	v_mul_f32_e32 v106, v92, v110
	v_add_f32_e32 v92, 1.0, v93
	v_add_f32_e32 v93, v98, v82
	v_add_f32_e32 v94, v94, v78
	v_mul_f32_e32 v93, 0xbfb8aa3b, v93
	v_mul_f32_e32 v94, 0xbfb8aa3b, v94
	v_rcp_f32_e32 v92, v92
	v_exp_f32_e32 v93, v93
	v_exp_f32_e32 v94, v94
	v_and_b32_e32 v111, 0xffff0000, v182
	v_add_f32_e32 v97, v97, v81
	v_mul_f32_e32 v97, 0xbfb8aa3b, v97
	v_mul_f32_e32 v98, v92, v111
	v_add_f32_e32 v92, 1.0, v93
	v_add_f32_e32 v93, 1.0, v94
	v_add_f32_e32 v94, v99, v83
	v_exp_f32_e32 v97, v97
	v_mul_f32_e32 v94, 0xbfb8aa3b, v94
	v_exp_f32_e32 v94, v94
	v_add_f32_e32 v95, v95, v79
	v_mul_f32_e32 v95, 0xbfb8aa3b, v95
	v_exp_f32_e32 v95, v95
	v_add_f32_e32 v97, 1.0, v97
	v_rcp_f32_e32 v97, v97
	v_add_f32_e32 v94, 1.0, v94
	v_rcp_f32_e32 v92, v92
	v_rcp_f32_e32 v94, v94
	v_add_f32_e32 v84, v84, v68
	v_add_f32_e32 v72, v72, v64
	v_add_f32_e32 v95, 1.0, v95
	v_mul_f32_e32 v84, 0xbfb8aa3b, v84
	v_mul_f32_e32 v72, 0xbfb8aa3b, v72
	v_and_b32_e32 v107, 0xffff0000, v180
	v_rcp_f32_e32 v95, v95
	v_exp_f32_e32 v84, v84
	v_exp_f32_e32 v72, v72
	v_lshlrev_b32_e32 v108, 16, v181
	v_and_b32_e32 v109, 0xffff0000, v181
	v_mul_f32_e32 v97, v97, v107
	v_rcp_f32_e32 v93, v93
	v_mul_f32_e32 v99, v92, v108
	v_mul_f32_e32 v108, v94, v109
	v_cvt_pk_bf16_f32 v92, v96, v97
	v_mul_f32_e32 v97, v97, v97
	v_and_b32_e32 v117, 0xffff0000, v183
	v_fmac_f32_e32 v97, v96, v96
	v_mul_f32_e32 v96, v108, v108
	v_add_f32_e32 v73, v73, v65
	v_lshlrev_b32_e32 v116, 16, v183
	v_mul_f32_e32 v109, v95, v117
	v_fmac_f32_e32 v96, v99, v99
	v_add_f32_e32 v84, 1.0, v84
	v_add_f32_e32 v72, 1.0, v72
	v_mul_f32_e32 v73, 0xbfb8aa3b, v73
	v_mul_f32_e32 v107, v93, v116
	v_cvt_pk_bf16_f32 v93, v99, v108
	v_cvt_pk_bf16_f32 v94, v106, v98
	v_add_f32_e32 v96, v97, v96
	v_mul_f32_e32 v97, v98, v98
	v_mul_f32_e32 v98, v109, v109
	v_rcp_f32_e32 v84, v84
	v_rcp_f32_e32 v72, v72
	v_exp_f32_e32 v73, v73
	v_fmac_f32_e32 v97, v106, v106
	v_fmac_f32_e32 v98, v107, v107
	v_add_f32_e32 v97, v97, v98
	v_cvt_pk_bf16_f32 v95, v107, v109
	v_add_f32_e32 v96, v96, v97
	v_lshlrev_b32_e32 v97, 16, v176
	v_lshlrev_b32_e32 v107, 16, v178
	v_mul_f32_e32 v84, v84, v97
	v_mul_f32_e32 v97, v72, v107
	v_add_f32_e32 v72, 1.0, v73
	v_add_f32_e32 v73, v86, v70
	v_add_f32_e32 v74, v74, v66
	v_mul_f32_e32 v73, 0xbfb8aa3b, v73
	v_mul_f32_e32 v74, 0xbfb8aa3b, v74
	v_rcp_f32_e32 v72, v72
	v_exp_f32_e32 v73, v73
	v_exp_f32_e32 v74, v74
	v_and_b32_e32 v108, 0xffff0000, v178
	v_add_f32_e32 v85, v85, v69
	v_mul_f32_e32 v86, v72, v108
	v_add_f32_e32 v72, 1.0, v73
	v_add_f32_e32 v73, 1.0, v74
	v_add_f32_e32 v74, v87, v71
	v_mul_f32_e32 v85, 0xbfb8aa3b, v85
	v_mul_f32_e32 v74, 0xbfb8aa3b, v74
	v_exp_f32_e32 v85, v85
	v_exp_f32_e32 v74, v74
	v_add_f32_e32 v75, v75, v67
	v_mul_f32_e32 v75, 0xbfb8aa3b, v75
	v_exp_f32_e32 v75, v75
	v_add_f32_e32 v85, 1.0, v85
	v_add_f32_e32 v74, 1.0, v74
	v_rcp_f32_e32 v85, v85
	v_rcp_f32_e32 v72, v72
	v_rcp_f32_e32 v74, v74
	v_rcp_f32_e32 v73, v73
	v_add_f32_e32 v75, 1.0, v75
	v_rcp_f32_e32 v75, v75
	v_and_b32_e32 v98, 0xffff0000, v176
	v_lshlrev_b32_e32 v99, 16, v177
	v_and_b32_e32 v106, 0xffff0000, v177
	v_lshlrev_b32_e32 v109, 16, v179
	v_mul_f32_e32 v85, v85, v98
	v_mul_f32_e32 v87, v72, v99
	v_mul_f32_e32 v99, v74, v106
	v_and_b32_e32 v110, 0xffff0000, v179
	v_mul_f32_e32 v98, v73, v109
	v_mul_f32_e32 v72, v85, v85
	v_mul_f32_e32 v73, v99, v99
	v_mul_f32_e32 v106, v75, v110
	v_fmac_f32_e32 v72, v84, v84
	v_fmac_f32_e32 v73, v87, v87
	v_add_f32_e32 v72, v72, v73
	v_mul_f32_e32 v73, v86, v86
	v_mul_f32_e32 v74, v106, v106
	v_fmac_f32_e32 v73, v97, v97
	v_fmac_f32_e32 v74, v98, v98
	v_add_f32_e32 v73, v73, v74
	v_add_f32_e32 v72, v72, v73
	v_add_f32_e32 v96, v96, v72
	ds_bpermute_b32 v107, v152, v96
	s_waitcnt lgkmcnt(1)
	v_lshlrev_b64 v[104:105], 12, v[216:217]
	v_lshl_add_u64 v[72:73], s[14:15], 0, v[104:105]
	v_lshl_add_u64 v[74:75], v[206:207], 1, v[72:73]
	global_store_dwordx4 v[74:75], v[92:95], off sc1
	s_waitcnt lgkmcnt(0)
	v_add_f32_e32 v72, v96, v107
	ds_bpermute_b32 v73, v153, v72
	v_cvt_pk_bf16_f32 v84, v84, v85
	v_cvt_pk_bf16_f32 v85, v87, v99
	v_cvt_pk_bf16_f32 v86, v97, v86
	v_cvt_pk_bf16_f32 v87, v98, v106
	global_store_dwordx4 v[74:75], v[84:87], off offset:256 sc1
	s_and_saveexec_b64 s[56:57], s[8:9]
	s_cbranch_execz .LBB0_603
	v_lshl_add_u64 v[74:75], v[216:217], 2, s[40:41]
	s_waitcnt lgkmcnt(0)
	v_add_f32_e32 v72, v72, v73
	global_atomic_add_f32 v[74:75], v72, off
; __device__ __forceinline__ float sigmoid_f(float v) { return __builtin_amdgcn_rcpf(1.0f + __builtin_amdgcn_exp2f(-1.4426950408889634f * v)); }
; __device__ __forceinline__ float bf_lo(unsigned w) { return __uint_as_float(w << 16); }
; __device__ __forceinline__ float bf_hi(unsigned w) { return __uint_as_float(w & 0xffff0000u); }
; __device__ __forceinline__ u32x4 pack8(const f32x4 a, const f32x4 b) { u32x4 w; w.x = cvt_pk_bf16(a[0], a[1]); w.y = cvt_pk_bf16(a[2], a[3]); w.z = cvt_pk_bf16(b[0], b[1]); w.w = cvt_pk_bf16(b[2], b[3]); return w; }
; __device__ __forceinline__ float sumsq4(const f32x4 a) { return (a[0] * a[0] + a[1] * a[1]) + (a[2] * a[2] + a[3] * a[3]); }
;     __device__ __forceinline__ void operator()(f32x4 (&acc)[2][2][4][2], const Unit& u, int wr, int wc, int fr, int fq) const {
;     ...
;         for (int ai = 0; ai < 2; ++ai)
; #pragma unroll
;             for (int m = 0; m < 4; ++m) { const int row = row0 + ai * HALF + m * 16; float q = 0.f;
; #pragma unroll
;                 for (int bj = 0; bj < 2; ++bj) { const u32x4 zb = zw[ai][m][bj];
;                     const f32x4 z0 = {bf_lo(zb.x), bf_hi(zb.x), bf_lo(zb.y), bf_hi(zb.y)}, z1 = {bf_lo(zb.z), bf_hi(zb.z), bf_lo(zb.w), bf_hi(zb.w)};
;                     const f32x4 a0 = acc[ai][bj][m][0] + bv[bj][0], a1 = acc[ai][bj][m][1] + bv[bj][1]; f32x4 y0, y1;
; #pragma unroll
;                     for (int e = 0; e < 4; ++e) { y0[e] = z0[e] * sigmoid_f(a0[e]); y1[e] = z1[e] * sigmoid_f(a1[e]); }
;                     *(u32x4*)(Y + (size_t)row * 2048 + col0 + bj * HALF) = pack8(y0, y1); q += sumsq4(y0) + sumsq4(y1); }
;                 q += __shfl_xor(q, 16); q += __shfl_xor(q, 32);
;                 if (fq == 0) atomicAdd(ssout + row, q); }
.LBB0_603:
	s_or_b64 exec, exec, s[56:57]
	v_add_f32_e32 v60, v60, v80
	v_add_f32_e32 v56, v56, v76
	v_mul_f32_e32 v60, 0xbfb8aa3b, v60
	v_mul_f32_e32 v56, 0xbfb8aa3b, v56
	v_exp_f32_e32 v60, v60
	v_exp_f32_e32 v56, v56
	v_add_f32_e32 v57, v57, v77
	v_mul_f32_e32 v57, 0xbfb8aa3b, v57
	v_add_f32_e32 v60, 1.0, v60
	v_add_f32_e32 v56, 1.0, v56
	v_rcp_f32_e32 v60, v60
	v_rcp_f32_e32 v56, v56
	v_exp_f32_e32 v57, v57
	v_lshlrev_b32_e32 v74, 16, v164
	v_lshlrev_b32_e32 v86, 16, v166
	v_mul_f32_e32 v60, v60, v74
	v_mul_f32_e32 v74, v56, v86
	v_add_f32_e32 v56, 1.0, v57
	v_add_f32_e32 v57, v62, v82
	v_add_f32_e32 v58, v58, v78
	v_mul_f32_e32 v57, 0xbfb8aa3b, v57
	v_mul_f32_e32 v58, 0xbfb8aa3b, v58
	v_rcp_f32_e32 v56, v56
	v_exp_f32_e32 v57, v57
	v_exp_f32_e32 v58, v58
	v_and_b32_e32 v87, 0xffff0000, v166
	v_add_f32_e32 v61, v61, v81
	v_mul_f32_e32 v61, 0xbfb8aa3b, v61
	v_mul_f32_e32 v62, v56, v87
	v_add_f32_e32 v56, 1.0, v57
	v_add_f32_e32 v57, 1.0, v58
	v_add_f32_e32 v58, v63, v83
	v_exp_f32_e32 v61, v61
	v_mul_f32_e32 v58, 0xbfb8aa3b, v58
	v_exp_f32_e32 v58, v58
	v_add_f32_e32 v59, v59, v79
	v_mul_f32_e32 v59, 0xbfb8aa3b, v59
	v_exp_f32_e32 v59, v59
	v_add_f32_e32 v61, 1.0, v61
	v_rcp_f32_e32 v61, v61
	v_add_f32_e32 v58, 1.0, v58
	v_rcp_f32_e32 v56, v56
	v_rcp_f32_e32 v58, v58
	v_add_f32_e32 v52, v52, v68
	v_add_f32_e32 v48, v48, v64
	v_add_f32_e32 v59, 1.0, v59
	v_mul_f32_e32 v52, 0xbfb8aa3b, v52
	v_mul_f32_e32 v48, 0xbfb8aa3b, v48
	v_and_b32_e32 v75, 0xffff0000, v164
	v_rcp_f32_e32 v59, v59
	v_exp_f32_e32 v52, v52
	v_exp_f32_e32 v48, v48
	v_lshlrev_b32_e32 v84, 16, v165
	v_and_b32_e32 v85, 0xffff0000, v165
	v_mul_f32_e32 v61, v61, v75
	v_rcp_f32_e32 v57, v57
	v_mul_f32_e32 v63, v56, v84
	v_mul_f32_e32 v84, v58, v85
	v_cvt_pk_bf16_f32 v56, v60, v61
	v_mul_f32_e32 v61, v61, v61
	v_and_b32_e32 v93, 0xffff0000, v167
	v_fmac_f32_e32 v61, v60, v60
	v_mul_f32_e32 v60, v84, v84
	v_add_f32_e32 v49, v49, v65
	v_lshlrev_b32_e32 v92, 16, v167
	v_mul_f32_e32 v85, v59, v93
	v_fmac_f32_e32 v60, v63, v63
	v_add_f32_e32 v52, 1.0, v52
	v_add_f32_e32 v53, v53, v69
	v_add_f32_e32 v48, 1.0, v48
	v_mul_f32_e32 v49, 0xbfb8aa3b, v49
	v_mul_f32_e32 v75, v57, v92
	v_cvt_pk_bf16_f32 v57, v63, v84
	v_cvt_pk_bf16_f32 v58, v74, v62
	v_add_f32_e32 v60, v61, v60
	v_mul_f32_e32 v61, v62, v62
	v_mul_f32_e32 v62, v85, v85
	v_mul_f32_e32 v53, 0xbfb8aa3b, v53
	v_rcp_f32_e32 v52, v52
	v_rcp_f32_e32 v48, v48
	v_exp_f32_e32 v49, v49
	v_fmac_f32_e32 v61, v74, v74
	v_fmac_f32_e32 v62, v75, v75
	v_exp_f32_e32 v53, v53
	v_add_f32_e32 v61, v61, v62
	v_cvt_pk_bf16_f32 v59, v75, v85
	v_add_f32_e32 v60, v60, v61
	v_lshlrev_b32_e32 v61, 16, v160
	v_lshlrev_b32_e32 v75, 16, v162
	v_mul_f32_e32 v52, v52, v61
	v_mul_f32_e32 v61, v48, v75
	v_add_f32_e32 v48, 1.0, v49
	v_add_f32_e32 v49, v54, v70
	v_add_f32_e32 v50, v50, v66
	v_add_f32_e32 v53, 1.0, v53
	v_mul_f32_e32 v49, 0xbfb8aa3b, v49
	v_mul_f32_e32 v50, 0xbfb8aa3b, v50
	v_rcp_f32_e32 v53, v53
	v_rcp_f32_e32 v48, v48
	v_exp_f32_e32 v49, v49
	v_exp_f32_e32 v50, v50
	v_and_b32_e32 v62, 0xffff0000, v160
	v_and_b32_e32 v84, 0xffff0000, v162
	v_mul_f32_e32 v53, v53, v62
	v_mul_f32_e32 v62, v48, v84
	v_add_f32_e32 v48, 1.0, v49
	v_add_f32_e32 v49, 1.0, v50
	v_add_f32_e32 v50, v55, v71
	v_mul_f32_e32 v50, 0xbfb8aa3b, v50
	v_exp_f32_e32 v50, v50
	v_add_f32_e32 v51, v51, v67
	v_mul_f32_e32 v51, 0xbfb8aa3b, v51
	v_exp_f32_e32 v51, v51
	v_add_f32_e32 v50, 1.0, v50
	v_rcp_f32_e32 v50, v50
	v_rcp_f32_e32 v48, v48
	v_rcp_f32_e32 v49, v49
	v_add_f32_e32 v51, 1.0, v51
	v_rcp_f32_e32 v51, v51
	v_and_b32_e32 v74, 0xffff0000, v161
	v_lshlrev_b32_e32 v63, 16, v161
	v_lshlrev_b32_e32 v85, 16, v163
	v_mul_f32_e32 v74, v50, v74
	v_and_b32_e32 v86, 0xffff0000, v163
	v_mul_f32_e32 v63, v48, v63
	v_mul_f32_e32 v75, v49, v85
	v_mul_f32_e32 v48, v53, v53
	v_mul_f32_e32 v49, v74, v74
	v_mul_f32_e32 v84, v51, v86
	v_fmac_f32_e32 v48, v52, v52
	v_fmac_f32_e32 v49, v63, v63
	v_add_f32_e32 v48, v48, v49
	v_mul_f32_e32 v49, v62, v62
	v_mul_f32_e32 v50, v84, v84
	v_fmac_f32_e32 v49, v61, v61
	v_fmac_f32_e32 v50, v75, v75
	v_add_f32_e32 v49, v49, v50
	v_add_f32_e32 v48, v48, v49
	v_add_f32_e32 v51, v60, v48
	ds_bpermute_b32 v60, v152, v51
	s_waitcnt lgkmcnt(1)
	v_lshlrev_b64 v[72:73], 12, v[214:215]
	v_lshl_add_u64 v[48:49], s[14:15], 0, v[72:73]
	v_lshl_add_u64 v[54:55], v[206:207], 1, v[48:49]
	global_store_dwordx4 v[54:55], v[56:59], off sc1
	s_waitcnt lgkmcnt(0)
	v_add_f32_e32 v48, v51, v60
	ds_bpermute_b32 v49, v153, v48
	v_cvt_pk_bf16_f32 v50, v52, v53
	v_cvt_pk_bf16_f32 v51, v63, v74
	v_cvt_pk_bf16_f32 v52, v61, v62
	v_cvt_pk_bf16_f32 v53, v75, v84
	global_store_dwordx4 v[54:55], v[50:53], off offset:256 sc1
	s_and_saveexec_b64 s[56:57], s[8:9]
	s_cbranch_execz .LBB0_605
	v_lshl_add_u64 v[50:51], v[214:215], 2, s[40:41]
	s_waitcnt lgkmcnt(0)
	v_add_f32_e32 v48, v48, v49
	global_atomic_add_f32 v[50:51], v48, off
; __device__ __forceinline__ float sigmoid_f(float v) { return __builtin_amdgcn_rcpf(1.0f + __builtin_amdgcn_exp2f(-1.4426950408889634f * v)); }
; __device__ __forceinline__ float bf_lo(unsigned w) { return __uint_as_float(w << 16); }
; __device__ __forceinline__ float bf_hi(unsigned w) { return __uint_as_float(w & 0xffff0000u); }
; __device__ __forceinline__ u32x4 pack8(const f32x4 a, const f32x4 b) { u32x4 w; w.x = cvt_pk_bf16(a[0], a[1]); w.y = cvt_pk_bf16(a[2], a[3]); w.z = cvt_pk_bf16(b[0], b[1]); w.w = cvt_pk_bf16(b[2], b[3]); return w; }
; __device__ __forceinline__ float sumsq4(const f32x4 a) { return (a[0] * a[0] + a[1] * a[1]) + (a[2] * a[2] + a[3] * a[3]); }
;     __device__ __forceinline__ void operator()(f32x4 (&acc)[2][2][4][2], const Unit& u, int wr, int wc, int fr, int fq) const {
;     ...
;         for (int ai = 0; ai < 2; ++ai)
; #pragma unroll
;             for (int m = 0; m < 4; ++m) { const int row = row0 + ai * HALF + m * 16; float q = 0.f;
; #pragma unroll
;                 for (int bj = 0; bj < 2; ++bj) { const u32x4 zb = zw[ai][m][bj];
;                     const f32x4 z0 = {bf_lo(zb.x), bf_hi(zb.x), bf_lo(zb.y), bf_hi(zb.y)}, z1 = {bf_lo(zb.z), bf_hi(zb.z), bf_lo(zb.w), bf_hi(zb.w)};
;                     const f32x4 a0 = acc[ai][bj][m][0] + bv[bj][0], a1 = acc[ai][bj][m][1] + bv[bj][1]; f32x4 y0, y1;
; #pragma unroll
;                     for (int e = 0; e < 4; ++e) { y0[e] = z0[e] * sigmoid_f(a0[e]); y1[e] = z1[e] * sigmoid_f(a1[e]); }
;                     *(u32x4*)(Y + (size_t)row * 2048 + col0 + bj * HALF) = pack8(y0, y1); q += sumsq4(y0) + sumsq4(y1); }
;                 q += __shfl_xor(q, 16); q += __shfl_xor(q, 32);
;                 if (fq == 0) atomicAdd(ssout + row, q); }
.LBB0_605:
	s_or_b64 exec, exec, s[56:57]
	v_add_f32_e32 v44, v44, v80
	v_add_f32_e32 v40, v40, v76
	v_mul_f32_e32 v44, 0xbfb8aa3b, v44
	v_mul_f32_e32 v40, 0xbfb8aa3b, v40
	v_exp_f32_e32 v44, v44
	v_exp_f32_e32 v40, v40
	v_add_f32_e32 v41, v41, v77
	v_mul_f32_e32 v41, 0xbfb8aa3b, v41
	v_add_f32_e32 v44, 1.0, v44
	v_add_f32_e32 v40, 1.0, v40
	v_rcp_f32_e32 v44, v44
	v_rcp_f32_e32 v40, v40
	v_exp_f32_e32 v41, v41
	v_lshlrev_b32_e32 v50, 16, v144
	v_lshlrev_b32_e32 v54, 16, v146
	v_mul_f32_e32 v44, v44, v50
	v_mul_f32_e32 v50, v40, v54
	v_add_f32_e32 v40, 1.0, v41
	v_add_f32_e32 v41, v46, v82
	v_add_f32_e32 v42, v42, v78
	v_mul_f32_e32 v41, 0xbfb8aa3b, v41
	v_mul_f32_e32 v42, 0xbfb8aa3b, v42
	v_rcp_f32_e32 v40, v40
	v_exp_f32_e32 v41, v41
	v_exp_f32_e32 v42, v42
	v_and_b32_e32 v55, 0xffff0000, v146
	v_add_f32_e32 v45, v45, v81
	v_mul_f32_e32 v45, 0xbfb8aa3b, v45
	v_mul_f32_e32 v46, v40, v55
	v_add_f32_e32 v40, 1.0, v41
	v_add_f32_e32 v41, 1.0, v42
	v_add_f32_e32 v42, v47, v83
	v_exp_f32_e32 v45, v45
	v_mul_f32_e32 v42, 0xbfb8aa3b, v42
	v_exp_f32_e32 v42, v42
	v_add_f32_e32 v43, v43, v79
	v_mul_f32_e32 v43, 0xbfb8aa3b, v43
	v_exp_f32_e32 v43, v43
	v_add_f32_e32 v45, 1.0, v45
	v_rcp_f32_e32 v45, v45
	v_add_f32_e32 v42, 1.0, v42
	v_rcp_f32_e32 v40, v40
	v_rcp_f32_e32 v42, v42
	v_add_f32_e32 v36, v36, v68
	v_add_f32_e32 v32, v32, v64
	v_add_f32_e32 v43, 1.0, v43
	v_mul_f32_e32 v36, 0xbfb8aa3b, v36
	v_mul_f32_e32 v32, 0xbfb8aa3b, v32
	v_and_b32_e32 v51, 0xffff0000, v144
	v_rcp_f32_e32 v43, v43
	v_exp_f32_e32 v36, v36
	v_exp_f32_e32 v32, v32
	v_lshlrev_b32_e32 v52, 16, v145
	v_and_b32_e32 v53, 0xffff0000, v145
	v_mul_f32_e32 v45, v45, v51
	v_rcp_f32_e32 v41, v41
	v_mul_f32_e32 v47, v40, v52
	v_mul_f32_e32 v52, v42, v53
	v_cvt_pk_bf16_f32 v40, v44, v45
	v_mul_f32_e32 v45, v45, v45
	v_and_b32_e32 v57, 0xffff0000, v147
	v_fmac_f32_e32 v45, v44, v44
	v_mul_f32_e32 v44, v52, v52
	v_add_f32_e32 v33, v33, v65
	v_lshlrev_b32_e32 v56, 16, v147
	v_mul_f32_e32 v53, v43, v57
	v_fmac_f32_e32 v44, v47, v47
	v_add_f32_e32 v36, 1.0, v36
	v_add_f32_e32 v37, v37, v69
	v_add_f32_e32 v32, 1.0, v32
	v_mul_f32_e32 v33, 0xbfb8aa3b, v33
	v_mul_f32_e32 v51, v41, v56
	v_cvt_pk_bf16_f32 v41, v47, v52
	v_cvt_pk_bf16_f32 v42, v50, v46
	v_add_f32_e32 v44, v45, v44
	v_mul_f32_e32 v45, v46, v46
	v_mul_f32_e32 v46, v53, v53
	v_mul_f32_e32 v37, 0xbfb8aa3b, v37
	v_rcp_f32_e32 v36, v36
	v_rcp_f32_e32 v32, v32
	v_exp_f32_e32 v33, v33
	v_fmac_f32_e32 v45, v50, v50
	v_fmac_f32_e32 v46, v51, v51
	v_exp_f32_e32 v37, v37
	v_add_f32_e32 v45, v45, v46
	v_cvt_pk_bf16_f32 v43, v51, v53
	v_add_f32_e32 v44, v44, v45
	v_lshlrev_b32_e32 v45, 16, v136
	v_lshlrev_b32_e32 v51, 16, v138
	v_mul_f32_e32 v36, v36, v45
	v_mul_f32_e32 v45, v32, v51
	v_add_f32_e32 v32, 1.0, v33
	v_add_f32_e32 v33, v38, v70
	v_add_f32_e32 v34, v34, v66
	v_add_f32_e32 v37, 1.0, v37
	v_mul_f32_e32 v33, 0xbfb8aa3b, v33
	v_mul_f32_e32 v34, 0xbfb8aa3b, v34
	v_rcp_f32_e32 v37, v37
	v_rcp_f32_e32 v32, v32
	v_exp_f32_e32 v33, v33
	v_exp_f32_e32 v34, v34
	v_and_b32_e32 v46, 0xffff0000, v136
	v_and_b32_e32 v52, 0xffff0000, v138
	v_mul_f32_e32 v37, v37, v46
	v_mul_f32_e32 v46, v32, v52
	v_add_f32_e32 v32, 1.0, v33
	v_add_f32_e32 v33, 1.0, v34
	v_add_f32_e32 v34, v39, v71
	v_mul_f32_e32 v34, 0xbfb8aa3b, v34
	v_exp_f32_e32 v34, v34
	v_add_f32_e32 v35, v35, v67
	v_mul_f32_e32 v35, 0xbfb8aa3b, v35
	v_exp_f32_e32 v35, v35
	v_add_f32_e32 v34, 1.0, v34
	v_rcp_f32_e32 v34, v34
	v_rcp_f32_e32 v32, v32
	v_rcp_f32_e32 v33, v33
	v_add_f32_e32 v35, 1.0, v35
	v_rcp_f32_e32 v35, v35
	v_and_b32_e32 v50, 0xffff0000, v137
	v_lshlrev_b32_e32 v47, 16, v137
	v_lshlrev_b32_e32 v53, 16, v139
	v_mul_f32_e32 v50, v34, v50
	v_and_b32_e32 v54, 0xffff0000, v139
	v_mul_f32_e32 v47, v32, v47
	v_mul_f32_e32 v51, v33, v53
	v_mul_f32_e32 v32, v37, v37
	v_mul_f32_e32 v33, v50, v50
	v_mul_f32_e32 v52, v35, v54
	v_fmac_f32_e32 v32, v36, v36
	v_fmac_f32_e32 v33, v47, v47
	v_add_f32_e32 v32, v32, v33
	v_mul_f32_e32 v33, v46, v46
	v_mul_f32_e32 v34, v52, v52
	v_fmac_f32_e32 v33, v45, v45
	v_fmac_f32_e32 v34, v51, v51
	v_add_f32_e32 v33, v33, v34
	v_add_f32_e32 v32, v32, v33
	v_add_f32_e32 v35, v44, v32
	ds_bpermute_b32 v44, v152, v35
	s_waitcnt lgkmcnt(1)
	v_lshlrev_b64 v[48:49], 12, v[212:213]
	v_lshl_add_u64 v[32:33], s[14:15], 0, v[48:49]
	v_lshl_add_u64 v[38:39], v[206:207], 1, v[32:33]
	global_store_dwordx4 v[38:39], v[40:43], off sc1
	s_waitcnt lgkmcnt(0)
	v_add_f32_e32 v32, v35, v44
	ds_bpermute_b32 v33, v153, v32
	v_cvt_pk_bf16_f32 v34, v36, v37
	v_cvt_pk_bf16_f32 v35, v47, v50
	v_cvt_pk_bf16_f32 v36, v45, v46
	v_cvt_pk_bf16_f32 v37, v51, v52
	global_store_dwordx4 v[38:39], v[34:37], off offset:256 sc1
	s_and_saveexec_b64 s[56:57], s[8:9]
	s_cbranch_execz .LBB0_607
	v_lshl_add_u64 v[34:35], v[212:213], 2, s[40:41]
	s_waitcnt lgkmcnt(0)
	v_add_f32_e32 v32, v32, v33
	global_atomic_add_f32 v[34:35], v32, off
; __device__ __forceinline__ float sigmoid_f(float v) { return __builtin_amdgcn_rcpf(1.0f + __builtin_amdgcn_exp2f(-1.4426950408889634f * v)); }
; __device__ __forceinline__ float bf_lo(unsigned w) { return __uint_as_float(w << 16); }
; __device__ __forceinline__ float bf_hi(unsigned w) { return __uint_as_float(w & 0xffff0000u); }
; __device__ __forceinline__ u32x4 pack8(const f32x4 a, const f32x4 b) { u32x4 w; w.x = cvt_pk_bf16(a[0], a[1]); w.y = cvt_pk_bf16(a[2], a[3]); w.z = cvt_pk_bf16(b[0], b[1]); w.w = cvt_pk_bf16(b[2], b[3]); return w; }
; __device__ __forceinline__ float sumsq4(const f32x4 a) { return (a[0] * a[0] + a[1] * a[1]) + (a[2] * a[2] + a[3] * a[3]); }
;     __device__ __forceinline__ void operator()(f32x4 (&acc)[2][2][4][2], const Unit& u, int wr, int wc, int fr, int fq) const {
;     ...
;         for (int ai = 0; ai < 2; ++ai)
; #pragma unroll
;             for (int m = 0; m < 4; ++m) { const int row = row0 + ai * HALF + m * 16; float q = 0.f;
; #pragma unroll
;                 for (int bj = 0; bj < 2; ++bj) { const u32x4 zb = zw[ai][m][bj];
;                     const f32x4 z0 = {bf_lo(zb.x), bf_hi(zb.x), bf_lo(zb.y), bf_hi(zb.y)}, z1 = {bf_lo(zb.z), bf_hi(zb.z), bf_lo(zb.w), bf_hi(zb.w)};
;                     const f32x4 a0 = acc[ai][bj][m][0] + bv[bj][0], a1 = acc[ai][bj][m][1] + bv[bj][1]; f32x4 y0, y1;
; #pragma unroll
;                     for (int e = 0; e < 4; ++e) { y0[e] = z0[e] * sigmoid_f(a0[e]); y1[e] = z1[e] * sigmoid_f(a1[e]); }
;                     *(u32x4*)(Y + (size_t)row * 2048 + col0 + bj * HALF) = pack8(y0, y1); q += sumsq4(y0) + sumsq4(y1); }
;                 q += __shfl_xor(q, 16); q += __shfl_xor(q, 32);
;                 if (fq == 0) atomicAdd(ssout + row, q); }
.LBB0_607:
	s_or_b64 exec, exec, s[56:57]
	v_add_f32_e32 v28, v28, v80
	v_add_f32_e32 v24, v24, v76
	v_mul_f32_e32 v28, 0xbfb8aa3b, v28
	v_mul_f32_e32 v24, 0xbfb8aa3b, v24
	v_exp_f32_e32 v28, v28
	v_exp_f32_e32 v24, v24
	v_add_f32_e32 v25, v25, v77
	v_mul_f32_e32 v25, 0xbfb8aa3b, v25
	v_add_f32_e32 v28, 1.0, v28
	v_add_f32_e32 v24, 1.0, v24
	v_rcp_f32_e32 v28, v28
	v_rcp_f32_e32 v24, v24
	v_exp_f32_e32 v25, v25
	v_lshlrev_b32_e32 v34, 16, v124
	v_lshlrev_b32_e32 v38, 16, v126
	v_mul_f32_e32 v28, v28, v34
	v_mul_f32_e32 v34, v24, v38
	v_add_f32_e32 v24, 1.0, v25
	v_add_f32_e32 v25, v30, v82
	v_add_f32_e32 v26, v26, v78
	v_mul_f32_e32 v25, 0xbfb8aa3b, v25
	v_mul_f32_e32 v26, 0xbfb8aa3b, v26
	v_rcp_f32_e32 v24, v24
	v_exp_f32_e32 v25, v25
	v_exp_f32_e32 v26, v26
	v_and_b32_e32 v39, 0xffff0000, v126
	v_add_f32_e32 v29, v29, v81
	v_mul_f32_e32 v29, 0xbfb8aa3b, v29
	v_mul_f32_e32 v30, v24, v39
	v_add_f32_e32 v24, 1.0, v25
	v_add_f32_e32 v25, 1.0, v26
	v_add_f32_e32 v26, v31, v83
	v_exp_f32_e32 v29, v29
	v_mul_f32_e32 v26, 0xbfb8aa3b, v26
	v_exp_f32_e32 v26, v26
	v_add_f32_e32 v27, v27, v79
	v_mul_f32_e32 v27, 0xbfb8aa3b, v27
	v_exp_f32_e32 v27, v27
	v_add_f32_e32 v29, 1.0, v29
	v_rcp_f32_e32 v29, v29
	v_add_f32_e32 v26, 1.0, v26
	v_rcp_f32_e32 v24, v24
	v_rcp_f32_e32 v26, v26
	v_add_f32_e32 v20, v20, v68
	v_add_f32_e32 v16, v16, v64
	v_add_f32_e32 v27, 1.0, v27
	v_mul_f32_e32 v20, 0xbfb8aa3b, v20
	v_mul_f32_e32 v16, 0xbfb8aa3b, v16
	v_and_b32_e32 v35, 0xffff0000, v124
	v_rcp_f32_e32 v27, v27
	v_exp_f32_e32 v20, v20
	v_exp_f32_e32 v16, v16
	v_lshlrev_b32_e32 v36, 16, v125
	v_and_b32_e32 v37, 0xffff0000, v125
	v_mul_f32_e32 v29, v29, v35
	v_rcp_f32_e32 v25, v25
	v_mul_f32_e32 v31, v24, v36
	v_mul_f32_e32 v36, v26, v37
	v_cvt_pk_bf16_f32 v24, v28, v29
	v_mul_f32_e32 v29, v29, v29
	v_and_b32_e32 v41, 0xffff0000, v127
	v_fmac_f32_e32 v29, v28, v28
	v_mul_f32_e32 v28, v36, v36
	v_add_f32_e32 v17, v17, v65
	v_lshlrev_b32_e32 v40, 16, v127
	v_mul_f32_e32 v37, v27, v41
	v_fmac_f32_e32 v28, v31, v31
	v_add_f32_e32 v20, 1.0, v20
	v_add_f32_e32 v21, v21, v69
	v_add_f32_e32 v16, 1.0, v16
	v_mul_f32_e32 v17, 0xbfb8aa3b, v17
	v_mul_f32_e32 v35, v25, v40
	v_cvt_pk_bf16_f32 v25, v31, v36
	v_cvt_pk_bf16_f32 v26, v34, v30
	v_add_f32_e32 v28, v29, v28
	v_mul_f32_e32 v29, v30, v30
	v_mul_f32_e32 v30, v37, v37
	v_mul_f32_e32 v21, 0xbfb8aa3b, v21
	v_rcp_f32_e32 v20, v20
	v_rcp_f32_e32 v16, v16
	v_exp_f32_e32 v17, v17
	v_fmac_f32_e32 v29, v34, v34
	v_fmac_f32_e32 v30, v35, v35
	v_exp_f32_e32 v21, v21
	v_add_f32_e32 v29, v29, v30
	v_cvt_pk_bf16_f32 v27, v35, v37
	v_add_f32_e32 v28, v28, v29
	v_lshlrev_b32_e32 v29, 16, v112
	v_lshlrev_b32_e32 v35, 16, v114
	v_mul_f32_e32 v20, v20, v29
	v_mul_f32_e32 v29, v16, v35
	v_add_f32_e32 v16, 1.0, v17
	v_add_f32_e32 v17, v22, v70
	v_add_f32_e32 v18, v18, v66
	v_add_f32_e32 v21, 1.0, v21
	v_mul_f32_e32 v17, 0xbfb8aa3b, v17
	v_mul_f32_e32 v18, 0xbfb8aa3b, v18
	v_rcp_f32_e32 v21, v21
	v_rcp_f32_e32 v16, v16
	v_exp_f32_e32 v17, v17
	v_exp_f32_e32 v18, v18
	v_and_b32_e32 v30, 0xffff0000, v112
	v_and_b32_e32 v36, 0xffff0000, v114
	v_mul_f32_e32 v21, v21, v30
	v_mul_f32_e32 v30, v16, v36
	v_add_f32_e32 v16, 1.0, v17
	v_add_f32_e32 v17, 1.0, v18
	v_add_f32_e32 v18, v23, v71
	v_mul_f32_e32 v18, 0xbfb8aa3b, v18
	v_exp_f32_e32 v18, v18
	v_add_f32_e32 v19, v19, v67
	v_mul_f32_e32 v19, 0xbfb8aa3b, v19
	v_exp_f32_e32 v19, v19
	v_add_f32_e32 v18, 1.0, v18
	v_rcp_f32_e32 v18, v18
	v_rcp_f32_e32 v16, v16
	v_rcp_f32_e32 v17, v17
	v_add_f32_e32 v19, 1.0, v19
	v_rcp_f32_e32 v19, v19
	v_and_b32_e32 v34, 0xffff0000, v113
	v_lshlrev_b32_e32 v31, 16, v113
	v_lshlrev_b32_e32 v37, 16, v115
	v_mul_f32_e32 v34, v18, v34
	v_and_b32_e32 v38, 0xffff0000, v115
	v_mul_f32_e32 v31, v16, v31
	v_mul_f32_e32 v35, v17, v37
	v_mul_f32_e32 v16, v21, v21
	v_mul_f32_e32 v17, v34, v34
	v_mul_f32_e32 v36, v19, v38
	v_fmac_f32_e32 v16, v20, v20
	v_fmac_f32_e32 v17, v31, v31
	v_add_f32_e32 v16, v16, v17
	v_mul_f32_e32 v17, v30, v30
	v_mul_f32_e32 v18, v36, v36
	v_fmac_f32_e32 v17, v29, v29
	v_fmac_f32_e32 v18, v35, v35
	v_add_f32_e32 v17, v17, v18
	v_add_f32_e32 v16, v16, v17
	v_add_f32_e32 v19, v28, v16
	ds_bpermute_b32 v28, v152, v19
	s_waitcnt lgkmcnt(1)
	v_lshlrev_b64 v[32:33], 12, v[210:211]
	v_lshl_add_u64 v[16:17], s[14:15], 0, v[32:33]
	v_lshl_add_u64 v[22:23], v[206:207], 1, v[16:17]
	global_store_dwordx4 v[22:23], v[24:27], off sc1
	s_waitcnt lgkmcnt(0)
	v_add_f32_e32 v16, v19, v28
	ds_bpermute_b32 v17, v153, v16
	v_cvt_pk_bf16_f32 v18, v20, v21
	v_cvt_pk_bf16_f32 v19, v31, v34
	v_cvt_pk_bf16_f32 v20, v29, v30
	v_cvt_pk_bf16_f32 v21, v35, v36
	global_store_dwordx4 v[22:23], v[18:21], off offset:256 sc1
	s_and_saveexec_b64 s[56:57], s[8:9]
	s_cbranch_execz .LBB0_609
	v_lshl_add_u64 v[18:19], v[210:211], 2, s[40:41]
	s_waitcnt lgkmcnt(0)
	v_add_f32_e32 v16, v16, v17
	global_atomic_add_f32 v[18:19], v16, off
; __device__ __forceinline__ float sigmoid_f(float v) { return __builtin_amdgcn_rcpf(1.0f + __builtin_amdgcn_exp2f(-1.4426950408889634f * v)); }
; __device__ __forceinline__ float bf_lo(unsigned w) { return __uint_as_float(w << 16); }
; __device__ __forceinline__ float bf_hi(unsigned w) { return __uint_as_float(w & 0xffff0000u); }
; __device__ __forceinline__ u32x4 pack8(const f32x4 a, const f32x4 b) { u32x4 w; w.x = cvt_pk_bf16(a[0], a[1]); w.y = cvt_pk_bf16(a[2], a[3]); w.z = cvt_pk_bf16(b[0], b[1]); w.w = cvt_pk_bf16(b[2], b[3]); return w; }
; __device__ __forceinline__ float sumsq4(const f32x4 a) { return (a[0] * a[0] + a[1] * a[1]) + (a[2] * a[2] + a[3] * a[3]); }
;     __device__ __forceinline__ void operator()(f32x4 (&acc)[2][2][4][2], const Unit& u, int wr, int wc, int fr, int fq) const {
;     ...
;         for (int ai = 0; ai < 2; ++ai)
; #pragma unroll
;             for (int m = 0; m < 4; ++m) { const int row = row0 + ai * HALF + m * 16; float q = 0.f;
; #pragma unroll
;                 for (int bj = 0; bj < 2; ++bj) { const u32x4 zb = zw[ai][m][bj];
;                     const f32x4 z0 = {bf_lo(zb.x), bf_hi(zb.x), bf_lo(zb.y), bf_hi(zb.y)}, z1 = {bf_lo(zb.z), bf_hi(zb.z), bf_lo(zb.w), bf_hi(zb.w)};
;                     const f32x4 a0 = acc[ai][bj][m][0] + bv[bj][0], a1 = acc[ai][bj][m][1] + bv[bj][1]; f32x4 y0, y1;
; #pragma unroll
;                     for (int e = 0; e < 4; ++e) { y0[e] = z0[e] * sigmoid_f(a0[e]); y1[e] = z1[e] * sigmoid_f(a1[e]); }
;                     *(u32x4*)(Y + (size_t)row * 2048 + col0 + bj * HALF) = pack8(y0, y1); q += sumsq4(y0) + sumsq4(y1); }
;                 q += __shfl_xor(q, 16); q += __shfl_xor(q, 32);
;                 if (fq == 0) atomicAdd(ssout + row, q); }
.LBB0_609:
	s_or_b64 exec, exec, s[56:57]
	v_add_f32_e32 v12, v12, v80
	v_add_f32_e32 v8, v8, v76
	v_mul_f32_e32 v12, 0xbfb8aa3b, v12
	v_mul_f32_e32 v8, 0xbfb8aa3b, v8
	v_exp_f32_e32 v12, v12
	v_exp_f32_e32 v8, v8
	v_add_f32_e32 v9, v9, v77
	v_mul_f32_e32 v9, 0xbfb8aa3b, v9
	v_add_f32_e32 v12, 1.0, v12
	v_add_f32_e32 v8, 1.0, v8
	v_rcp_f32_e32 v12, v12
	v_rcp_f32_e32 v8, v8
	v_exp_f32_e32 v9, v9
	v_lshlrev_b32_e32 v18, 16, v100
	v_lshlrev_b32_e32 v22, 16, v102
	v_mul_f32_e32 v12, v12, v18
	v_mul_f32_e32 v18, v8, v22
	v_add_f32_e32 v8, 1.0, v9
	v_add_f32_e32 v9, v14, v82
	v_add_f32_e32 v10, v10, v78
	v_mul_f32_e32 v9, 0xbfb8aa3b, v9
	v_mul_f32_e32 v10, 0xbfb8aa3b, v10
	v_rcp_f32_e32 v8, v8
	v_exp_f32_e32 v9, v9
	v_exp_f32_e32 v10, v10
	v_and_b32_e32 v23, 0xffff0000, v102
	v_add_f32_e32 v13, v13, v81
	v_mul_f32_e32 v13, 0xbfb8aa3b, v13
	v_mul_f32_e32 v14, v8, v23
	v_add_f32_e32 v8, 1.0, v9
	v_add_f32_e32 v9, 1.0, v10
	v_add_f32_e32 v10, v15, v83
	v_exp_f32_e32 v13, v13
	v_mul_f32_e32 v10, 0xbfb8aa3b, v10
	v_exp_f32_e32 v10, v10
	v_add_f32_e32 v11, v11, v79
	v_mul_f32_e32 v11, 0xbfb8aa3b, v11
	v_exp_f32_e32 v11, v11
	v_add_f32_e32 v13, 1.0, v13
	v_rcp_f32_e32 v13, v13
	v_add_f32_e32 v10, 1.0, v10
	v_rcp_f32_e32 v8, v8
	v_rcp_f32_e32 v10, v10
	v_add_f32_e32 v4, v4, v68
	v_add_f32_e32 v0, v0, v64
	v_add_f32_e32 v11, 1.0, v11
	v_mul_f32_e32 v4, 0xbfb8aa3b, v4
	v_mul_f32_e32 v0, 0xbfb8aa3b, v0
	v_and_b32_e32 v19, 0xffff0000, v100
	v_rcp_f32_e32 v11, v11
	v_exp_f32_e32 v4, v4
	v_exp_f32_e32 v0, v0
	v_lshlrev_b32_e32 v20, 16, v101
	v_and_b32_e32 v21, 0xffff0000, v101
	v_mul_f32_e32 v13, v13, v19
	v_rcp_f32_e32 v9, v9
	v_mul_f32_e32 v15, v8, v20
	v_mul_f32_e32 v20, v10, v21
	v_cvt_pk_bf16_f32 v8, v12, v13
	v_mul_f32_e32 v13, v13, v13
	v_and_b32_e32 v25, 0xffff0000, v103
	v_fmac_f32_e32 v13, v12, v12
	v_mul_f32_e32 v12, v20, v20
	v_add_f32_e32 v1, v1, v65
	v_lshlrev_b32_e32 v24, 16, v103
	v_mul_f32_e32 v21, v11, v25
	v_fmac_f32_e32 v12, v15, v15
	v_add_f32_e32 v4, 1.0, v4
	v_add_f32_e32 v5, v5, v69
	v_add_f32_e32 v0, 1.0, v0
	v_mul_f32_e32 v1, 0xbfb8aa3b, v1
	v_mul_f32_e32 v19, v9, v24
	v_cvt_pk_bf16_f32 v9, v15, v20
	v_cvt_pk_bf16_f32 v10, v18, v14
	v_add_f32_e32 v12, v13, v12
	v_mul_f32_e32 v13, v14, v14
	v_mul_f32_e32 v14, v21, v21
	v_mul_f32_e32 v5, 0xbfb8aa3b, v5
	v_rcp_f32_e32 v4, v4
	v_rcp_f32_e32 v0, v0
	v_exp_f32_e32 v1, v1
	v_fmac_f32_e32 v13, v18, v18
	v_fmac_f32_e32 v14, v19, v19
	v_exp_f32_e32 v5, v5
	v_add_f32_e32 v13, v13, v14
	v_cvt_pk_bf16_f32 v11, v19, v21
	v_add_f32_e32 v12, v12, v13
	v_lshlrev_b32_e32 v13, 16, v88
	v_lshlrev_b32_e32 v19, 16, v90
	v_mul_f32_e32 v4, v4, v13
	v_mul_f32_e32 v13, v0, v19
	v_add_f32_e32 v0, 1.0, v1
	v_add_f32_e32 v1, v6, v70
	v_add_f32_e32 v2, v2, v66
	v_add_f32_e32 v5, 1.0, v5
	v_mul_f32_e32 v1, 0xbfb8aa3b, v1
	v_mul_f32_e32 v2, 0xbfb8aa3b, v2
	v_rcp_f32_e32 v5, v5
	v_rcp_f32_e32 v0, v0
	v_exp_f32_e32 v1, v1
	v_exp_f32_e32 v2, v2
	v_and_b32_e32 v14, 0xffff0000, v88
	v_and_b32_e32 v20, 0xffff0000, v90
	v_mul_f32_e32 v5, v5, v14
	v_mul_f32_e32 v14, v0, v20
	v_add_f32_e32 v0, 1.0, v1
	v_add_f32_e32 v1, 1.0, v2
	v_add_f32_e32 v2, v7, v71
	v_mul_f32_e32 v2, 0xbfb8aa3b, v2
	v_exp_f32_e32 v2, v2
	v_add_f32_e32 v3, v3, v67
	v_mul_f32_e32 v3, 0xbfb8aa3b, v3
	v_exp_f32_e32 v3, v3
	v_add_f32_e32 v2, 1.0, v2
	v_rcp_f32_e32 v2, v2
	v_rcp_f32_e32 v0, v0
	v_rcp_f32_e32 v1, v1
	v_add_f32_e32 v3, 1.0, v3
	v_rcp_f32_e32 v3, v3
	v_and_b32_e32 v18, 0xffff0000, v89
	v_lshlrev_b32_e32 v15, 16, v89
	v_lshlrev_b32_e32 v21, 16, v91
	v_mul_f32_e32 v18, v2, v18
	v_and_b32_e32 v22, 0xffff0000, v91
	v_mul_f32_e32 v15, v0, v15
	v_mul_f32_e32 v19, v1, v21
	v_mul_f32_e32 v0, v5, v5
	v_mul_f32_e32 v1, v18, v18
	v_mul_f32_e32 v20, v3, v22
	v_fmac_f32_e32 v0, v4, v4
	v_fmac_f32_e32 v1, v15, v15
	v_add_f32_e32 v0, v0, v1
	v_mul_f32_e32 v1, v14, v14
	v_mul_f32_e32 v2, v20, v20
	v_fmac_f32_e32 v1, v13, v13
	v_fmac_f32_e32 v2, v19, v19
	v_add_f32_e32 v1, v1, v2
	v_add_f32_e32 v0, v0, v1
	v_add_f32_e32 v3, v12, v0
	ds_bpermute_b32 v12, v152, v3
	s_waitcnt lgkmcnt(1)
	v_lshlrev_b64 v[16:17], 12, v[208:209]
	v_lshl_add_u64 v[0:1], s[14:15], 0, v[16:17]
	v_lshl_add_u64 v[6:7], v[206:207], 1, v[0:1]
	global_store_dwordx4 v[6:7], v[8:11], off sc1
	s_waitcnt lgkmcnt(0)
	v_add_f32_e32 v0, v3, v12
	ds_bpermute_b32 v1, v153, v0
	v_cvt_pk_bf16_f32 v2, v4, v5
	v_cvt_pk_bf16_f32 v3, v15, v18
	v_cvt_pk_bf16_f32 v4, v13, v14
	v_cvt_pk_bf16_f32 v5, v19, v20
	global_store_dwordx4 v[6:7], v[2:5], off offset:256 sc1
	s_and_saveexec_b64 s[56:57], s[8:9]
	s_cbranch_execz .LBB0_611
	v_lshl_add_u64 v[2:3], v[208:209], 2, s[40:41]
	s_waitcnt lgkmcnt(0)
	v_add_f32_e32 v0, v0, v1
	global_atomic_add_f32 v[2:3], v0, off

; __device__ __forceinline__ float bf_lo(unsigned w) { return __uint_as_float(w << 16); }
;     __device__ __forceinline__ void operator()(f32x4 (&acc)[2][2][4][2], const Unit& u_, int wr, int wc, int fr, int fq) const {
;         Unit u = u_; if constexpr (OPQ) { unsigned o1_ = ~0u; asm volatile("" : "+s"(u.pm), "+s"(u.pn), "+s"(o1_)); const int l_ = (int)__builtin_amdgcn_mbcnt_hi(o1_, __builtin_amdgcn_mbcnt_lo(o1_, 0u)); fr = l_ & 15; fq = l_ >> 4; }
;         if (MODE == 1 && u.kh == 0) { mid(acc, u, wr, fr); return; }
;         const int row0 = u.pm * BM + wr * 64 + fr, col0 = u.pn * BM + wc * 32 + 8 * fq;
;         u32x4 xw[2][4][2]; f32x4 xf[XF32 ? 16 : 1][2];
; #pragma unroll
;         for (int ai = 0; ai < 2; ++ai)
; #pragma unroll
;             for (int m = 0; m < 4; ++m)
; #pragma unroll
;                 for (int bj = 0; bj < 2; ++bj) { const size_t off = (size_t)(row0 + ai * HALF + m * 16) * 2048 + col0 + bj * HALF;
;                     if constexpr (XF32) { xf[(ai * 4 + m) * 2 + bj][0] = *(const f32x4*)(xin + off); xf[(ai * 4 + m) * 2 + bj][1] = *(const f32x4*)(xin + off + 4); }
;                     else if constexpr (BATCH) xw[ai][m][bj] = *(const u32x4*)(xb + off); }
; #pragma unroll
;         for (int ai = 0; ai < 2; ++ai)
; #pragma unroll
;             for (int m = 0; m < 4; ++m) {
;                 const int row = row0 + ai * HALF + m * 16; const size_t off = (size_t)row * 2048 + col0;
;                 float sc = alpha; if constexpr (MODE == 1) sc = rstd_of(ssb[row], 1.0f / 1024.0f);
;                 float q = 0.f;
; #pragma unroll
;                 for (int bj = 0; bj < 2; ++bj) {
;                     f32x4 x0, x1;
;                     if constexpr (XF32) { x0 = xf[(ai * 4 + m) * 2 + bj][0]; x1 = xf[(ai * 4 + m) * 2 + bj][1]; }
;                     else { const u32x4 w = BATCH ? xw[ai][m][bj] : *(const u32x4*)(xb + off + bj * HALF); x0 = (f32x4){bf_lo(w.x), bf_hi(w.x), bf_lo(w.y), bf_hi(w.y)}; x1 = (f32x4){bf_lo(w.z), bf_hi(w.z), bf_lo(w.w), bf_hi(w.w)}; }
;                     const f32x4 v0 = x0 + acc[ai][bj][m][0] * sc, v1 = x1 + acc[ai][bj][m][1] * sc;
;                     *(u32x4*)(xb + off + bj * HALF) = pack8(v0, v1);
;                     if (x8) { typedef unsigned u32x2 __attribute__((ext_vector_type(2))); u32x2 w8; w8.x = pack4_fp8(v0[0] * F8_X_SCALE, v0[1] * F8_X_SCALE, v0[2] * F8_X_SCALE, v0[3] * F8_X_SCALE);
.LBB0_689:
	s_mov_b32 s13, -1
	s_cmp_lg_u32 s11, 0
	s_cselect_b64 s[62:63], -1, 0
	v_mbcnt_lo_u32_b32 v0, s13, 0
	s_lshl_b32 s11, s12, 8
	v_mbcnt_hi_u32_b32 v160, s13, v0
	s_add_i32 s11, s11, s94
	v_and_or_b32 v2, v160, 15, s11
	s_and_b64 vcc, exec, s[62:63]
	v_ashrrev_i32_e32 v3, 31, v2
	s_cbranch_vccz .LBB0_745
	v_lshrrev_b32_e32 v0, 1, v160
	s_lshl_b32 s10, s10, 8
	v_and_b32_e32 v0, 56, v0
	s_or_b32 s10, s10, s91
	v_add_u32_e32 v136, s10, v0
	v_ashrrev_i32_e32 v137, 31, v136
	v_lshlrev_b64 v[138:139], 11, v[2:3]
	v_lshl_add_u64 v[150:151], v[138:139], 0, v[136:137]
	v_lshl_add_u64 v[138:139], v[2:3], 2, s[48:49]
	global_load_dword v0, v[138:139], off
	v_lshl_add_u64 v[140:141], v[150:151], 1, s[28:29]
	global_load_dwordx4 v[142:145], v[140:141], off
	v_cndmask_b32_e64 v146, 0, 1, s[52:53]
	v_cmp_ne_u32_e64 s[10:11], 1, v146
	s_andn2_b64 vcc, exec, s[52:53]
	v_lshl_add_u64 v[150:151], s[38:39], 0, v[150:151]
	s_waitcnt vmcnt(0)
	v_fmamk_f32 v0, v0, 0x3a800000, v168
	v_rsq_f32_e32 v152, v0
	v_lshlrev_b32_e32 v148, 16, v142
	v_and_b32_e32 v149, 0xffff0000, v142
	v_lshlrev_b32_e32 v142, 16, v143
	v_and_b32_e32 v143, 0xffff0000, v143
	v_lshlrev_b32_e32 v154, 16, v144
	v_and_b32_e32 v155, 0xffff0000, v144
	v_lshlrev_b32_e32 v144, 16, v145
	v_and_b32_e32 v145, 0xffff0000, v145
	v_pk_fma_f32 v[146:147], v[130:131], v[152:153], v[142:143] op_sel_hi:[1,0,1]
	v_pk_fma_f32 v[148:149], v[128:129], v[152:153], v[148:149] op_sel_hi:[1,0,1]
	v_pk_fma_f32 v[142:143], v[126:127], v[152:153], v[144:145] op_sel_hi:[1,0,1]
	v_pk_fma_f32 v[144:145], v[124:125], v[152:153], v[154:155] op_sel_hi:[1,0,1]
	v_cvt_pk_bf16_f32 v154, v148, v149
	v_cvt_pk_bf16_f32 v155, v146, v147
	s_nop 0
	v_cvt_pk_bf16_f32 v156, v144, v145
	v_cvt_pk_bf16_f32 v157, v142, v143
	global_store_dwordx4 v[140:141], v[154:157], off sc1
	s_cbranch_vccnz .LBB0_692
	v_mul_f32_e32 v0, 0x41800000, v148
	v_mul_f32_e32 v153, 0x41800000, v149
	v_med3_f32 v0, v0, s75, v169
	v_med3_f32 v153, v153, s75, v169
	v_mov_b32_e32 v154, v1
	v_cvt_pk_fp8_f32 v154, v0, v153
	v_mul_f32_e32 v155, 0x41800000, v146
	v_mul_f32_e32 v0, 0x41800000, v147
	v_med3_f32 v153, v155, s75, v169
	v_med3_f32 v0, v0, s75, v169
	v_cvt_pk_fp8_f32 v154, v153, v0 op_sel:[0,0,1]
	v_mul_f32_e32 v0, 0x41800000, v144
	v_mul_f32_e32 v153, 0x41800000, v145
	v_med3_f32 v0, v0, s75, v169
	v_med3_f32 v153, v153, s75, v169
	v_mov_b32_e32 v155, v1
	v_cvt_pk_fp8_f32 v155, v0, v153
	v_mul_f32_e32 v156, 0x41800000, v142
	v_mul_f32_e32 v0, 0x41800000, v143
	v_med3_f32 v153, v156, s75, v169
	v_med3_f32 v0, v0, s75, v169
	v_cvt_pk_fp8_f32 v155, v153, v0 op_sel:[0,0,1]
	global_store_dwordx2 v[150:151], v[154:155], off
.LBB0_692:
	global_load_dwordx4 v[154:157], v[140:141], off offset:256
	v_mov_b32_e32 v153, v152
	v_mov_b32_e32 v172, v152
	v_mov_b32_e32 v173, v152
	s_and_b64 vcc, exec, s[10:11]
	s_waitcnt vmcnt(0)
	v_lshlrev_b32_e32 v158, 16, v154
	v_and_b32_e32 v159, 0xffff0000, v154
	v_lshlrev_b32_e32 v154, 16, v155
	v_and_b32_e32 v155, 0xffff0000, v155
	v_lshlrev_b32_e32 v174, 16, v156
	v_and_b32_e32 v175, 0xffff0000, v156
	v_lshlrev_b32_e32 v156, 16, v157
	v_and_b32_e32 v157, 0xffff0000, v157
	v_pk_fma_f32 v[154:155], v[94:95], v[172:173], v[154:155]
	v_pk_fma_f32 v[158:159], v[92:93], v[152:153], v[158:159]
	v_pk_fma_f32 v[156:157], v[86:87], v[172:173], v[156:157]
	v_pk_fma_f32 v[152:153], v[84:85], v[152:153], v[174:175]
	v_cvt_pk_bf16_f32 v172, v158, v159
	v_cvt_pk_bf16_f32 v173, v154, v155
	s_nop 0
	v_cvt_pk_bf16_f32 v174, v152, v153
	v_cvt_pk_bf16_f32 v175, v156, v157
	global_store_dwordx4 v[140:141], v[172:175], off offset:256 sc1
	s_cbranch_vccnz .LBB0_694
	v_mul_f32_e32 v0, 0x41800000, v158
	v_mul_f32_e32 v140, 0x41800000, v159
	v_med3_f32 v0, v0, s75, v169
	v_med3_f32 v161, v140, s75, v169
	v_mov_b32_e32 v140, v1
	v_cvt_pk_fp8_f32 v140, v0, v161
	v_mul_f32_e32 v141, 0x41800000, v154
	v_mul_f32_e32 v0, 0x41800000, v155
	v_med3_f32 v141, v141, s75, v169
	v_med3_f32 v0, v0, s75, v169
	v_cvt_pk_fp8_f32 v140, v141, v0 op_sel:[0,0,1]
	v_mul_f32_e32 v0, 0x41800000, v152
	v_mul_f32_e32 v141, 0x41800000, v153
	v_med3_f32 v0, v0, s75, v169
	v_med3_f32 v171, v141, s75, v169
	v_mov_b32_e32 v141, v1
	v_cvt_pk_fp8_f32 v141, v0, v171
	v_mul_f32_e32 v161, 0x41800000, v156
	v_mul_f32_e32 v0, 0x41800000, v157
	v_med3_f32 v161, v161, s75, v169
	v_med3_f32 v0, v0, s75, v169
	v_cvt_pk_fp8_f32 v141, v161, v0 op_sel:[0,0,1]
	global_store_dwordx2 v[150:151], v[140:141], off offset:128

; __device__ __forceinline__ float rstd_of(float ss, float inv_n) { return __builtin_amdgcn_rsqf(ss * inv_n + 1e-6f); }
; __device__ __forceinline__ float bf_lo(unsigned w) { return __uint_as_float(w << 16); }
; __device__ __forceinline__ float bf_hi(unsigned w) { return __uint_as_float(w & 0xffff0000u); }
; __device__ __forceinline__ u32x4 pack8(const f32x4 a, const f32x4 b) { u32x4 w; w.x = cvt_pk_bf16(a[0], a[1]); w.y = cvt_pk_bf16(a[2], a[3]); w.z = cvt_pk_bf16(b[0], b[1]); w.w = cvt_pk_bf16(b[2], b[3]); return w; }
; __device__ __forceinline__ float sumsq4(const f32x4 a) { return (a[0] * a[0] + a[1] * a[1]) + (a[2] * a[2] + a[3] * a[3]); }
;     __device__ __forceinline__ void operator()(f32x4 (&acc)[2][2][4][2], const Unit& u_, int wr, int wc, int fr, int fq) const {
;     ...
;             for (int m = 0; m < 4; ++m) {
;                 const int row = row0 + ai * HALF + m * 16; const size_t off = (size_t)row * 2048 + col0;
;                 float sc = alpha; if constexpr (MODE == 1) sc = rstd_of(ssb[row], 1.0f / 1024.0f);
;                 float q = 0.f;
; #pragma unroll
;                 for (int bj = 0; bj < 2; ++bj) {
;                     f32x4 x0, x1;
;                     if constexpr (XF32) { x0 = xf[(ai * 4 + m) * 2 + bj][0]; x1 = xf[(ai * 4 + m) * 2 + bj][1]; }
;                     else { const u32x4 w = BATCH ? xw[ai][m][bj] : *(const u32x4*)(xb + off + bj * HALF); x0 = (f32x4){bf_lo(w.x), bf_hi(w.x), bf_lo(w.y), bf_hi(w.y)}; x1 = (f32x4){bf_lo(w.z), bf_hi(w.z), bf_lo(w.w), bf_hi(w.w)}; }
;                     const f32x4 v0 = x0 + acc[ai][bj][m][0] * sc, v1 = x1 + acc[ai][bj][m][1] * sc;
;                     *(u32x4*)(xb + off + bj * HALF) = pack8(v0, v1);
;                     if (x8) { typedef unsigned u32x2 __attribute__((ext_vector_type(2))); u32x2 w8; w8.x = pack4_fp8(v0[0] * F8_X_SCALE, v0[1] * F8_X_SCALE, v0[2] * F8_X_SCALE, v0[3] * F8_X_SCALE);
;                         w8.y = pack4_fp8(v1[0] * F8_X_SCALE, v1[1] * F8_X_SCALE, v1[2] * F8_X_SCALE, v1[3] * F8_X_SCALE); *(u32x2*)(x8 + off + bj * HALF) = w8; }
;                     q += sumsq4(v0) + sumsq4(v1);
.LBB0_696:
	s_or_b64 exec, exec, s[64:65]
	v_or_b32_e32 v140, 16, v2
	s_waitcnt lgkmcnt(0)
	v_ashrrev_i32_e32 v141, 31, v140
	v_lshlrev_b64 v[142:143], 11, v[140:141]
	v_lshl_add_u64 v[152:153], v[142:143], 0, v[136:137]
	v_lshl_add_u64 v[142:143], v[140:141], 2, s[48:49]
	global_load_dword v148, v[142:143], off
	v_lshl_add_u64 v[142:143], v[152:153], 1, s[28:29]
	global_load_dwordx4 v[144:147], v[142:143], off
	s_and_b64 vcc, exec, s[10:11]
	v_lshl_add_u64 v[152:153], s[38:39], 0, v[152:153]
	s_waitcnt vmcnt(1)
	v_fmamk_f32 v148, v148, 0x3a800000, v168
	v_rsq_f32_e32 v154, v148
	s_waitcnt vmcnt(0)
	v_lshlrev_b32_e32 v150, 16, v144
	v_and_b32_e32 v151, 0xffff0000, v144
	v_lshlrev_b32_e32 v144, 16, v145
	v_and_b32_e32 v145, 0xffff0000, v145
	v_lshlrev_b32_e32 v156, 16, v146
	v_and_b32_e32 v157, 0xffff0000, v146
	v_lshlrev_b32_e32 v146, 16, v147
	v_and_b32_e32 v147, 0xffff0000, v147
	v_pk_fma_f32 v[148:149], v[122:123], v[154:155], v[144:145] op_sel_hi:[1,0,1]
	v_pk_fma_f32 v[150:151], v[120:121], v[154:155], v[150:151] op_sel_hi:[1,0,1]
	v_pk_fma_f32 v[144:145], v[118:119], v[154:155], v[146:147] op_sel_hi:[1,0,1]
	v_pk_fma_f32 v[146:147], v[116:117], v[154:155], v[156:157] op_sel_hi:[1,0,1]
	v_cvt_pk_bf16_f32 v156, v150, v151
	v_cvt_pk_bf16_f32 v157, v148, v149
	s_nop 0
	v_cvt_pk_bf16_f32 v158, v146, v147
	v_cvt_pk_bf16_f32 v159, v144, v145
	global_store_dwordx4 v[142:143], v[156:159], off sc1
	s_cbranch_vccnz .LBB0_698
	v_mul_f32_e32 v155, 0x41800000, v150
	v_mul_f32_e32 v156, 0x41800000, v151
	v_med3_f32 v155, v155, s75, v169
	v_med3_f32 v158, v156, s75, v169
	v_mov_b32_e32 v156, v1
	v_cvt_pk_fp8_f32 v156, v155, v158
	v_mul_f32_e32 v157, 0x41800000, v148
	v_mul_f32_e32 v155, 0x41800000, v149
	v_med3_f32 v157, v157, s75, v169
	v_med3_f32 v155, v155, s75, v169
	v_cvt_pk_fp8_f32 v156, v157, v155 op_sel:[0,0,1]
	v_mul_f32_e32 v155, 0x41800000, v146
	v_mul_f32_e32 v157, 0x41800000, v147
	v_med3_f32 v155, v155, s75, v169
	v_med3_f32 v159, v157, s75, v169
	v_mov_b32_e32 v157, v1
	v_cvt_pk_fp8_f32 v157, v155, v159
	v_mul_f32_e32 v158, 0x41800000, v144
	v_mul_f32_e32 v155, 0x41800000, v145
	v_med3_f32 v158, v158, s75, v169
	v_med3_f32 v155, v155, s75, v169
	v_cvt_pk_fp8_f32 v157, v158, v155 op_sel:[0,0,1]
	global_store_dwordx2 v[152:153], v[156:157], off
.LBB0_698:
	global_load_dwordx4 v[156:159], v[142:143], off offset:256
	v_mov_b32_e32 v155, v154
	v_mov_b32_e32 v172, v154
	v_mov_b32_e32 v173, v154
	s_and_b64 vcc, exec, s[10:11]
	s_waitcnt vmcnt(0)
	v_lshlrev_b32_e32 v160, 16, v156
	v_and_b32_e32 v161, 0xffff0000, v156
	v_lshlrev_b32_e32 v156, 16, v157
	v_and_b32_e32 v157, 0xffff0000, v157
	v_lshlrev_b32_e32 v174, 16, v158
	v_and_b32_e32 v175, 0xffff0000, v158
	v_lshlrev_b32_e32 v158, 16, v159
	v_and_b32_e32 v159, 0xffff0000, v159
	v_pk_fma_f32 v[156:157], v[78:79], v[172:173], v[156:157]
	v_pk_fma_f32 v[160:161], v[76:77], v[154:155], v[160:161]
	v_pk_fma_f32 v[158:159], v[70:71], v[172:173], v[158:159]
	v_pk_fma_f32 v[154:155], v[68:69], v[154:155], v[174:175]
	v_cvt_pk_bf16_f32 v172, v160, v161
	v_cvt_pk_bf16_f32 v173, v156, v157
	s_nop 0
	v_cvt_pk_bf16_f32 v174, v154, v155
	v_cvt_pk_bf16_f32 v175, v158, v159
	global_store_dwordx4 v[142:143], v[172:175], off offset:256 sc1
	s_cbranch_vccnz .LBB0_700
	v_mul_f32_e32 v142, 0x41800000, v160
	v_mul_f32_e32 v143, 0x41800000, v161
	v_med3_f32 v173, v142, s75, v169
	v_med3_f32 v143, v143, s75, v169
	v_mov_b32_e32 v142, v1
	v_cvt_pk_fp8_f32 v142, v173, v143
	v_mul_f32_e32 v172, 0x41800000, v156
	v_mul_f32_e32 v143, 0x41800000, v157
	v_med3_f32 v172, v172, s75, v169
	v_med3_f32 v143, v143, s75, v169
	v_cvt_pk_fp8_f32 v142, v172, v143 op_sel:[0,0,1]
	v_mul_f32_e32 v143, 0x41800000, v154
	v_mul_f32_e32 v172, 0x41800000, v155
	v_med3_f32 v174, v143, s75, v169
	v_med3_f32 v172, v172, s75, v169
	v_mov_b32_e32 v143, v1
	v_cvt_pk_fp8_f32 v143, v174, v172
	v_mul_f32_e32 v173, 0x41800000, v158
	v_mul_f32_e32 v172, 0x41800000, v159
	v_med3_f32 v173, v173, s75, v169
	v_med3_f32 v172, v172, s75, v169
	v_cvt_pk_fp8_f32 v143, v173, v172 op_sel:[0,0,1]
	global_store_dwordx2 v[152:153], v[142:143], off offset:128

; __device__ __forceinline__ float rstd_of(float ss, float inv_n) { return __builtin_amdgcn_rsqf(ss * inv_n + 1e-6f); }
; __device__ __forceinline__ float bf_lo(unsigned w) { return __uint_as_float(w << 16); }
; __device__ __forceinline__ float bf_hi(unsigned w) { return __uint_as_float(w & 0xffff0000u); }
; __device__ __forceinline__ u32x4 pack8(const f32x4 a, const f32x4 b) { u32x4 w; w.x = cvt_pk_bf16(a[0], a[1]); w.y = cvt_pk_bf16(a[2], a[3]); w.z = cvt_pk_bf16(b[0], b[1]); w.w = cvt_pk_bf16(b[2], b[3]); return w; }
; __device__ __forceinline__ float sumsq4(const f32x4 a) { return (a[0] * a[0] + a[1] * a[1]) + (a[2] * a[2] + a[3] * a[3]); }
;     __device__ __forceinline__ void operator()(f32x4 (&acc)[2][2][4][2], const Unit& u_, int wr, int wc, int fr, int fq) const {
;     ...
;             for (int m = 0; m < 4; ++m) {
;                 const int row = row0 + ai * HALF + m * 16; const size_t off = (size_t)row * 2048 + col0;
;                 float sc = alpha; if constexpr (MODE == 1) sc = rstd_of(ssb[row], 1.0f / 1024.0f);
;                 float q = 0.f;
; #pragma unroll
;                 for (int bj = 0; bj < 2; ++bj) {
;                     f32x4 x0, x1;
;                     if constexpr (XF32) { x0 = xf[(ai * 4 + m) * 2 + bj][0]; x1 = xf[(ai * 4 + m) * 2 + bj][1]; }
;                     else { const u32x4 w = BATCH ? xw[ai][m][bj] : *(const u32x4*)(xb + off + bj * HALF); x0 = (f32x4){bf_lo(w.x), bf_hi(w.x), bf_lo(w.y), bf_hi(w.y)}; x1 = (f32x4){bf_lo(w.z), bf_hi(w.z), bf_lo(w.w), bf_hi(w.w)}; }
;                     const f32x4 v0 = x0 + acc[ai][bj][m][0] * sc, v1 = x1 + acc[ai][bj][m][1] * sc;
;                     *(u32x4*)(xb + off + bj * HALF) = pack8(v0, v1);
;                     if (x8) { typedef unsigned u32x2 __attribute__((ext_vector_type(2))); u32x2 w8; w8.x = pack4_fp8(v0[0] * F8_X_SCALE, v0[1] * F8_X_SCALE, v0[2] * F8_X_SCALE, v0[3] * F8_X_SCALE);
;                         w8.y = pack4_fp8(v1[0] * F8_X_SCALE, v1[1] * F8_X_SCALE, v1[2] * F8_X_SCALE, v1[3] * F8_X_SCALE); *(u32x2*)(x8 + off + bj * HALF) = w8; }
;                     q += sumsq4(v0) + sumsq4(v1);
.LBB0_702:
	s_or_b64 exec, exec, s[64:65]
	v_or_b32_e32 v140, 32, v2
	v_ashrrev_i32_e32 v141, 31, v140
	s_waitcnt lgkmcnt(0)
	v_lshlrev_b64 v[142:143], 11, v[140:141]
	v_lshl_add_u64 v[152:153], v[142:143], 0, v[136:137]
	v_lshl_add_u64 v[142:143], v[140:141], 2, s[48:49]
	global_load_dword v148, v[142:143], off
	v_lshl_add_u64 v[142:143], v[152:153], 1, s[28:29]
	global_load_dwordx4 v[144:147], v[142:143], off
	s_and_b64 vcc, exec, s[10:11]
	v_lshl_add_u64 v[152:153], s[38:39], 0, v[152:153]
	s_waitcnt vmcnt(1)
	v_fmamk_f32 v148, v148, 0x3a800000, v168
	v_rsq_f32_e32 v154, v148
	s_waitcnt vmcnt(0)
	v_lshlrev_b32_e32 v150, 16, v144
	v_and_b32_e32 v151, 0xffff0000, v144
	v_lshlrev_b32_e32 v144, 16, v145
	v_and_b32_e32 v145, 0xffff0000, v145
	v_lshlrev_b32_e32 v156, 16, v146
	v_and_b32_e32 v157, 0xffff0000, v146
	v_lshlrev_b32_e32 v146, 16, v147
	v_and_b32_e32 v147, 0xffff0000, v147
	v_pk_fma_f32 v[148:149], v[114:115], v[154:155], v[144:145] op_sel_hi:[1,0,1]
	v_pk_fma_f32 v[150:151], v[112:113], v[154:155], v[150:151] op_sel_hi:[1,0,1]
	v_pk_fma_f32 v[144:145], v[110:111], v[154:155], v[146:147] op_sel_hi:[1,0,1]
	v_pk_fma_f32 v[146:147], v[108:109], v[154:155], v[156:157] op_sel_hi:[1,0,1]
	v_cvt_pk_bf16_f32 v156, v150, v151
	v_cvt_pk_bf16_f32 v157, v148, v149
	s_nop 0
	v_cvt_pk_bf16_f32 v158, v146, v147
	v_cvt_pk_bf16_f32 v159, v144, v145
	global_store_dwordx4 v[142:143], v[156:159], off sc1
	s_cbranch_vccnz .LBB0_704
	v_mul_f32_e32 v155, 0x41800000, v150
	v_mul_f32_e32 v156, 0x41800000, v151
	v_med3_f32 v155, v155, s75, v169
	v_med3_f32 v158, v156, s75, v169
	v_mov_b32_e32 v156, v1
	v_cvt_pk_fp8_f32 v156, v155, v158
	v_mul_f32_e32 v157, 0x41800000, v148
	v_mul_f32_e32 v155, 0x41800000, v149
	v_med3_f32 v157, v157, s75, v169
	v_med3_f32 v155, v155, s75, v169
	v_cvt_pk_fp8_f32 v156, v157, v155 op_sel:[0,0,1]
	v_mul_f32_e32 v155, 0x41800000, v146
	v_mul_f32_e32 v157, 0x41800000, v147
	v_med3_f32 v155, v155, s75, v169
	v_med3_f32 v159, v157, s75, v169
	v_mov_b32_e32 v157, v1
	v_cvt_pk_fp8_f32 v157, v155, v159
	v_mul_f32_e32 v158, 0x41800000, v144
	v_mul_f32_e32 v155, 0x41800000, v145
	v_med3_f32 v158, v158, s75, v169
	v_med3_f32 v155, v155, s75, v169
	v_cvt_pk_fp8_f32 v157, v158, v155 op_sel:[0,0,1]
	global_store_dwordx2 v[152:153], v[156:157], off
.LBB0_704:
	global_load_dwordx4 v[156:159], v[142:143], off offset:256
	v_mov_b32_e32 v155, v154
	v_mov_b32_e32 v172, v154
	v_mov_b32_e32 v173, v154
	s_and_b64 vcc, exec, s[10:11]
	s_waitcnt vmcnt(0)
	v_lshlrev_b32_e32 v160, 16, v156
	v_and_b32_e32 v161, 0xffff0000, v156
	v_lshlrev_b32_e32 v156, 16, v157
	v_and_b32_e32 v157, 0xffff0000, v157
	v_lshlrev_b32_e32 v174, 16, v158
	v_and_b32_e32 v175, 0xffff0000, v158
	v_lshlrev_b32_e32 v158, 16, v159
	v_and_b32_e32 v159, 0xffff0000, v159
	v_pk_fma_f32 v[156:157], v[62:63], v[172:173], v[156:157]
	v_pk_fma_f32 v[160:161], v[60:61], v[154:155], v[160:161]
	v_pk_fma_f32 v[158:159], v[54:55], v[172:173], v[158:159]
	v_pk_fma_f32 v[154:155], v[52:53], v[154:155], v[174:175]
	v_cvt_pk_bf16_f32 v172, v160, v161
	v_cvt_pk_bf16_f32 v173, v156, v157
	s_nop 0
	v_cvt_pk_bf16_f32 v174, v154, v155
	v_cvt_pk_bf16_f32 v175, v158, v159
	global_store_dwordx4 v[142:143], v[172:175], off offset:256 sc1
	s_cbranch_vccnz .LBB0_706
	v_mul_f32_e32 v142, 0x41800000, v160
	v_mul_f32_e32 v143, 0x41800000, v161
	v_med3_f32 v173, v142, s75, v169
	v_med3_f32 v143, v143, s75, v169
	v_mov_b32_e32 v142, v1
	v_cvt_pk_fp8_f32 v142, v173, v143
	v_mul_f32_e32 v172, 0x41800000, v156
	v_mul_f32_e32 v143, 0x41800000, v157
	v_med3_f32 v172, v172, s75, v169
	v_med3_f32 v143, v143, s75, v169
	v_cvt_pk_fp8_f32 v142, v172, v143 op_sel:[0,0,1]
	v_mul_f32_e32 v143, 0x41800000, v154
	v_mul_f32_e32 v172, 0x41800000, v155
	v_med3_f32 v174, v143, s75, v169
	v_med3_f32 v172, v172, s75, v169
	v_mov_b32_e32 v143, v1
	v_cvt_pk_fp8_f32 v143, v174, v172
	v_mul_f32_e32 v173, 0x41800000, v158
	v_mul_f32_e32 v172, 0x41800000, v159
	v_med3_f32 v173, v173, s75, v169
	v_med3_f32 v172, v172, s75, v169
	v_cvt_pk_fp8_f32 v143, v173, v172 op_sel:[0,0,1]
	global_store_dwordx2 v[152:153], v[142:143], off offset:128

; __device__ __forceinline__ float rstd_of(float ss, float inv_n) { return __builtin_amdgcn_rsqf(ss * inv_n + 1e-6f); }
; __device__ __forceinline__ float bf_lo(unsigned w) { return __uint_as_float(w << 16); }
; __device__ __forceinline__ float bf_hi(unsigned w) { return __uint_as_float(w & 0xffff0000u); }
; __device__ __forceinline__ u32x4 pack8(const f32x4 a, const f32x4 b) { u32x4 w; w.x = cvt_pk_bf16(a[0], a[1]); w.y = cvt_pk_bf16(a[2], a[3]); w.z = cvt_pk_bf16(b[0], b[1]); w.w = cvt_pk_bf16(b[2], b[3]); return w; }
; __device__ __forceinline__ float sumsq4(const f32x4 a) { return (a[0] * a[0] + a[1] * a[1]) + (a[2] * a[2] + a[3] * a[3]); }
;     __device__ __forceinline__ void operator()(f32x4 (&acc)[2][2][4][2], const Unit& u_, int wr, int wc, int fr, int fq) const {
;     ...
;             for (int m = 0; m < 4; ++m) {
;                 const int row = row0 + ai * HALF + m * 16; const size_t off = (size_t)row * 2048 + col0;
;                 float sc = alpha; if constexpr (MODE == 1) sc = rstd_of(ssb[row], 1.0f / 1024.0f);
;                 float q = 0.f;
; #pragma unroll
;                 for (int bj = 0; bj < 2; ++bj) {
;                     f32x4 x0, x1;
;                     if constexpr (XF32) { x0 = xf[(ai * 4 + m) * 2 + bj][0]; x1 = xf[(ai * 4 + m) * 2 + bj][1]; }
;                     else { const u32x4 w = BATCH ? xw[ai][m][bj] : *(const u32x4*)(xb + off + bj * HALF); x0 = (f32x4){bf_lo(w.x), bf_hi(w.x), bf_lo(w.y), bf_hi(w.y)}; x1 = (f32x4){bf_lo(w.z), bf_hi(w.z), bf_lo(w.w), bf_hi(w.w)}; }
;                     const f32x4 v0 = x0 + acc[ai][bj][m][0] * sc, v1 = x1 + acc[ai][bj][m][1] * sc;
;                     *(u32x4*)(xb + off + bj * HALF) = pack8(v0, v1);
;                     if (x8) { typedef unsigned u32x2 __attribute__((ext_vector_type(2))); u32x2 w8; w8.x = pack4_fp8(v0[0] * F8_X_SCALE, v0[1] * F8_X_SCALE, v0[2] * F8_X_SCALE, v0[3] * F8_X_SCALE);
;                         w8.y = pack4_fp8(v1[0] * F8_X_SCALE, v1[1] * F8_X_SCALE, v1[2] * F8_X_SCALE, v1[3] * F8_X_SCALE); *(u32x2*)(x8 + off + bj * HALF) = w8; }
;                     q += sumsq4(v0) + sumsq4(v1);
.LBB0_708:
	s_or_b64 exec, exec, s[64:65]
	v_or_b32_e32 v140, 48, v2
	v_ashrrev_i32_e32 v141, 31, v140
	s_waitcnt lgkmcnt(0)
	v_lshlrev_b64 v[142:143], 11, v[140:141]
	v_lshl_add_u64 v[152:153], v[142:143], 0, v[136:137]
	v_lshl_add_u64 v[142:143], v[140:141], 2, s[48:49]
	global_load_dword v148, v[142:143], off
	v_lshl_add_u64 v[142:143], v[152:153], 1, s[28:29]
	global_load_dwordx4 v[144:147], v[142:143], off
	s_and_b64 vcc, exec, s[10:11]
	v_lshl_add_u64 v[152:153], s[38:39], 0, v[152:153]
	s_waitcnt vmcnt(1)
	v_fmamk_f32 v148, v148, 0x3a800000, v168
	v_rsq_f32_e32 v154, v148
	s_waitcnt vmcnt(0)
	v_lshlrev_b32_e32 v150, 16, v144
	v_and_b32_e32 v151, 0xffff0000, v144
	v_lshlrev_b32_e32 v144, 16, v145
	v_and_b32_e32 v145, 0xffff0000, v145
	v_lshlrev_b32_e32 v156, 16, v146
	v_and_b32_e32 v157, 0xffff0000, v146
	v_lshlrev_b32_e32 v146, 16, v147
	v_and_b32_e32 v147, 0xffff0000, v147
	v_pk_fma_f32 v[148:149], v[106:107], v[154:155], v[144:145] op_sel_hi:[1,0,1]
	v_pk_fma_f32 v[150:151], v[104:105], v[154:155], v[150:151] op_sel_hi:[1,0,1]
	v_pk_fma_f32 v[144:145], v[102:103], v[154:155], v[146:147] op_sel_hi:[1,0,1]
	v_pk_fma_f32 v[146:147], v[100:101], v[154:155], v[156:157] op_sel_hi:[1,0,1]
	v_cvt_pk_bf16_f32 v156, v150, v151
	v_cvt_pk_bf16_f32 v157, v148, v149
	s_nop 0
	v_cvt_pk_bf16_f32 v158, v146, v147
	v_cvt_pk_bf16_f32 v159, v144, v145
	global_store_dwordx4 v[142:143], v[156:159], off sc1
	s_cbranch_vccnz .LBB0_710
	v_mul_f32_e32 v155, 0x41800000, v150
	v_mul_f32_e32 v156, 0x41800000, v151
	v_med3_f32 v155, v155, s75, v169
	v_med3_f32 v158, v156, s75, v169
	v_mov_b32_e32 v156, v1
	v_cvt_pk_fp8_f32 v156, v155, v158
	v_mul_f32_e32 v157, 0x41800000, v148
	v_mul_f32_e32 v155, 0x41800000, v149
	v_med3_f32 v157, v157, s75, v169
	v_med3_f32 v155, v155, s75, v169
	v_cvt_pk_fp8_f32 v156, v157, v155 op_sel:[0,0,1]
	v_mul_f32_e32 v155, 0x41800000, v146
	v_mul_f32_e32 v157, 0x41800000, v147
	v_med3_f32 v155, v155, s75, v169
	v_med3_f32 v159, v157, s75, v169
	v_mov_b32_e32 v157, v1
	v_cvt_pk_fp8_f32 v157, v155, v159
	v_mul_f32_e32 v158, 0x41800000, v144
	v_mul_f32_e32 v155, 0x41800000, v145
	v_med3_f32 v158, v158, s75, v169
	v_med3_f32 v155, v155, s75, v169
	v_cvt_pk_fp8_f32 v157, v158, v155 op_sel:[0,0,1]
	global_store_dwordx2 v[152:153], v[156:157], off
.LBB0_710:
	global_load_dwordx4 v[156:159], v[142:143], off offset:256
	v_mov_b32_e32 v155, v154
	v_mov_b32_e32 v172, v154
	v_mov_b32_e32 v173, v154
	s_and_b64 vcc, exec, s[10:11]
	s_waitcnt vmcnt(0)
	v_lshlrev_b32_e32 v160, 16, v156
	v_and_b32_e32 v161, 0xffff0000, v156
	v_lshlrev_b32_e32 v156, 16, v157
	v_and_b32_e32 v157, 0xffff0000, v157
	v_lshlrev_b32_e32 v174, 16, v158
	v_and_b32_e32 v175, 0xffff0000, v158
	v_lshlrev_b32_e32 v158, 16, v159
	v_and_b32_e32 v159, 0xffff0000, v159
	v_pk_fma_f32 v[156:157], v[46:47], v[172:173], v[156:157]
	v_pk_fma_f32 v[160:161], v[44:45], v[154:155], v[160:161]
	v_pk_fma_f32 v[158:159], v[38:39], v[172:173], v[158:159]
	v_pk_fma_f32 v[154:155], v[36:37], v[154:155], v[174:175]
	v_cvt_pk_bf16_f32 v172, v160, v161
	v_cvt_pk_bf16_f32 v173, v156, v157
	s_nop 0
	v_cvt_pk_bf16_f32 v174, v154, v155
	v_cvt_pk_bf16_f32 v175, v158, v159
	global_store_dwordx4 v[142:143], v[172:175], off offset:256 sc1
	s_cbranch_vccnz .LBB0_712
	v_mul_f32_e32 v142, 0x41800000, v160
	v_mul_f32_e32 v143, 0x41800000, v161
	v_med3_f32 v173, v142, s75, v169
	v_med3_f32 v143, v143, s75, v169
	v_mov_b32_e32 v142, v1
	v_cvt_pk_fp8_f32 v142, v173, v143
	v_mul_f32_e32 v172, 0x41800000, v156
	v_mul_f32_e32 v143, 0x41800000, v157
	v_med3_f32 v172, v172, s75, v169
	v_med3_f32 v143, v143, s75, v169
	v_cvt_pk_fp8_f32 v142, v172, v143 op_sel:[0,0,1]
	v_mul_f32_e32 v143, 0x41800000, v154
	v_mul_f32_e32 v172, 0x41800000, v155
	v_med3_f32 v174, v143, s75, v169
	v_med3_f32 v172, v172, s75, v169
	v_mov_b32_e32 v143, v1
	v_cvt_pk_fp8_f32 v143, v174, v172
	v_mul_f32_e32 v173, 0x41800000, v158
	v_mul_f32_e32 v172, 0x41800000, v159
	v_med3_f32 v173, v173, s75, v169
	v_med3_f32 v172, v172, s75, v169
	v_cvt_pk_fp8_f32 v143, v173, v172 op_sel:[0,0,1]
	global_store_dwordx2 v[152:153], v[142:143], off offset:128

; __device__ __forceinline__ float rstd_of(float ss, float inv_n) { return __builtin_amdgcn_rsqf(ss * inv_n + 1e-6f); }
; __device__ __forceinline__ float bf_lo(unsigned w) { return __uint_as_float(w << 16); }
; __device__ __forceinline__ float bf_hi(unsigned w) { return __uint_as_float(w & 0xffff0000u); }
; __device__ __forceinline__ u32x4 pack8(const f32x4 a, const f32x4 b) { u32x4 w; w.x = cvt_pk_bf16(a[0], a[1]); w.y = cvt_pk_bf16(a[2], a[3]); w.z = cvt_pk_bf16(b[0], b[1]); w.w = cvt_pk_bf16(b[2], b[3]); return w; }
; __device__ __forceinline__ float sumsq4(const f32x4 a) { return (a[0] * a[0] + a[1] * a[1]) + (a[2] * a[2] + a[3] * a[3]); }
;     __device__ __forceinline__ void operator()(f32x4 (&acc)[2][2][4][2], const Unit& u_, int wr, int wc, int fr, int fq) const {
;     ...
;             for (int m = 0; m < 4; ++m) {
;                 const int row = row0 + ai * HALF + m * 16; const size_t off = (size_t)row * 2048 + col0;
;                 float sc = alpha; if constexpr (MODE == 1) sc = rstd_of(ssb[row], 1.0f / 1024.0f);
;                 float q = 0.f;
; #pragma unroll
;                 for (int bj = 0; bj < 2; ++bj) {
;                     f32x4 x0, x1;
;                     if constexpr (XF32) { x0 = xf[(ai * 4 + m) * 2 + bj][0]; x1 = xf[(ai * 4 + m) * 2 + bj][1]; }
;                     else { const u32x4 w = BATCH ? xw[ai][m][bj] : *(const u32x4*)(xb + off + bj * HALF); x0 = (f32x4){bf_lo(w.x), bf_hi(w.x), bf_lo(w.y), bf_hi(w.y)}; x1 = (f32x4){bf_lo(w.z), bf_hi(w.z), bf_lo(w.w), bf_hi(w.w)}; }
;                     const f32x4 v0 = x0 + acc[ai][bj][m][0] * sc, v1 = x1 + acc[ai][bj][m][1] * sc;
;                     *(u32x4*)(xb + off + bj * HALF) = pack8(v0, v1);
;                     if (x8) { typedef unsigned u32x2 __attribute__((ext_vector_type(2))); u32x2 w8; w8.x = pack4_fp8(v0[0] * F8_X_SCALE, v0[1] * F8_X_SCALE, v0[2] * F8_X_SCALE, v0[3] * F8_X_SCALE);
;                         w8.y = pack4_fp8(v1[0] * F8_X_SCALE, v1[1] * F8_X_SCALE, v1[2] * F8_X_SCALE, v1[3] * F8_X_SCALE); *(u32x2*)(x8 + off + bj * HALF) = w8; }
;                     q += sumsq4(v0) + sumsq4(v1);
.LBB0_714:
	s_or_b64 exec, exec, s[64:65]
	v_add_u32_e32 v140, 0x80, v2
	v_ashrrev_i32_e32 v141, 31, v140
	global_load_dword v148, v[138:139], off offset:512
	s_waitcnt lgkmcnt(0)
	v_lshlrev_b64 v[142:143], 11, v[140:141]
	v_lshl_add_u64 v[152:153], v[142:143], 0, v[136:137]
	v_lshl_add_u64 v[142:143], v[152:153], 1, s[28:29]
	global_load_dwordx4 v[144:147], v[142:143], off
	s_and_b64 vcc, exec, s[10:11]
	v_lshl_add_u64 v[152:153], s[38:39], 0, v[152:153]
	s_waitcnt vmcnt(1)
	v_fmamk_f32 v148, v148, 0x3a800000, v168
	v_rsq_f32_e32 v154, v148
	s_waitcnt vmcnt(0)
	v_lshlrev_b32_e32 v150, 16, v144
	v_and_b32_e32 v151, 0xffff0000, v144
	v_lshlrev_b32_e32 v144, 16, v145
	v_and_b32_e32 v145, 0xffff0000, v145
	v_lshlrev_b32_e32 v156, 16, v146
	v_and_b32_e32 v157, 0xffff0000, v146
	v_lshlrev_b32_e32 v146, 16, v147
	v_and_b32_e32 v147, 0xffff0000, v147
	v_pk_fma_f32 v[148:149], v[98:99], v[154:155], v[144:145] op_sel_hi:[1,0,1]
	v_pk_fma_f32 v[150:151], v[96:97], v[154:155], v[150:151] op_sel_hi:[1,0,1]
	v_pk_fma_f32 v[144:145], v[90:91], v[154:155], v[146:147] op_sel_hi:[1,0,1]
	v_pk_fma_f32 v[146:147], v[88:89], v[154:155], v[156:157] op_sel_hi:[1,0,1]
	v_cvt_pk_bf16_f32 v156, v150, v151
	v_cvt_pk_bf16_f32 v157, v148, v149
	s_nop 0
	v_cvt_pk_bf16_f32 v158, v146, v147
	v_cvt_pk_bf16_f32 v159, v144, v145
	global_store_dwordx4 v[142:143], v[156:159], off sc1
	s_cbranch_vccnz .LBB0_716
	v_mul_f32_e32 v155, 0x41800000, v150
	v_mul_f32_e32 v156, 0x41800000, v151
	v_med3_f32 v155, v155, s75, v169
	v_med3_f32 v158, v156, s75, v169
	v_mov_b32_e32 v156, v1
	v_cvt_pk_fp8_f32 v156, v155, v158
	v_mul_f32_e32 v157, 0x41800000, v148
	v_mul_f32_e32 v155, 0x41800000, v149
	v_med3_f32 v157, v157, s75, v169
	v_med3_f32 v155, v155, s75, v169
	v_cvt_pk_fp8_f32 v156, v157, v155 op_sel:[0,0,1]
	v_mul_f32_e32 v155, 0x41800000, v146
	v_mul_f32_e32 v157, 0x41800000, v147
	v_med3_f32 v155, v155, s75, v169
	v_med3_f32 v159, v157, s75, v169
	v_mov_b32_e32 v157, v1
	v_cvt_pk_fp8_f32 v157, v155, v159
	v_mul_f32_e32 v158, 0x41800000, v144
	v_mul_f32_e32 v155, 0x41800000, v145
	v_med3_f32 v158, v158, s75, v169
	v_med3_f32 v155, v155, s75, v169
	v_cvt_pk_fp8_f32 v157, v158, v155 op_sel:[0,0,1]
	global_store_dwordx2 v[152:153], v[156:157], off
.LBB0_716:
	global_load_dwordx4 v[156:159], v[142:143], off offset:256
	v_mov_b32_e32 v155, v154
	v_mov_b32_e32 v172, v154
	v_mov_b32_e32 v173, v154
	s_and_b64 vcc, exec, s[10:11]
	s_waitcnt vmcnt(0)
	v_lshlrev_b32_e32 v160, 16, v156
	v_and_b32_e32 v161, 0xffff0000, v156
	v_lshlrev_b32_e32 v156, 16, v157
	v_and_b32_e32 v157, 0xffff0000, v157
	v_lshlrev_b32_e32 v174, 16, v158
	v_and_b32_e32 v175, 0xffff0000, v158
	v_lshlrev_b32_e32 v158, 16, v159
	v_and_b32_e32 v159, 0xffff0000, v159
	v_pk_fma_f32 v[156:157], v[34:35], v[172:173], v[156:157]
	v_pk_fma_f32 v[160:161], v[32:33], v[154:155], v[160:161]
	v_pk_fma_f32 v[158:159], v[30:31], v[172:173], v[158:159]
	v_pk_fma_f32 v[154:155], v[28:29], v[154:155], v[174:175]
	v_cvt_pk_bf16_f32 v172, v160, v161
	v_cvt_pk_bf16_f32 v173, v156, v157
	s_nop 0
	v_cvt_pk_bf16_f32 v174, v154, v155
	v_cvt_pk_bf16_f32 v175, v158, v159
	global_store_dwordx4 v[142:143], v[172:175], off offset:256 sc1
	s_cbranch_vccnz .LBB0_718
	v_mul_f32_e32 v142, 0x41800000, v160
	v_mul_f32_e32 v143, 0x41800000, v161
	v_med3_f32 v173, v142, s75, v169
	v_med3_f32 v143, v143, s75, v169
	v_mov_b32_e32 v142, v1
	v_cvt_pk_fp8_f32 v142, v173, v143
	v_mul_f32_e32 v172, 0x41800000, v156
	v_mul_f32_e32 v143, 0x41800000, v157
	v_med3_f32 v172, v172, s75, v169
	v_med3_f32 v143, v143, s75, v169
	v_cvt_pk_fp8_f32 v142, v172, v143 op_sel:[0,0,1]
	v_mul_f32_e32 v143, 0x41800000, v154
	v_mul_f32_e32 v172, 0x41800000, v155
	v_med3_f32 v174, v143, s75, v169
	v_med3_f32 v172, v172, s75, v169
	v_mov_b32_e32 v143, v1
	v_cvt_pk_fp8_f32 v143, v174, v172
	v_mul_f32_e32 v173, 0x41800000, v158
	v_mul_f32_e32 v172, 0x41800000, v159
	v_med3_f32 v173, v173, s75, v169
	v_med3_f32 v172, v172, s75, v169
	v_cvt_pk_fp8_f32 v143, v173, v172 op_sel:[0,0,1]
	global_store_dwordx2 v[152:153], v[142:143], off offset:128

; __device__ __forceinline__ float rstd_of(float ss, float inv_n) { return __builtin_amdgcn_rsqf(ss * inv_n + 1e-6f); }
; __device__ __forceinline__ float bf_lo(unsigned w) { return __uint_as_float(w << 16); }
; __device__ __forceinline__ float bf_hi(unsigned w) { return __uint_as_float(w & 0xffff0000u); }
; __device__ __forceinline__ u32x4 pack8(const f32x4 a, const f32x4 b) { u32x4 w; w.x = cvt_pk_bf16(a[0], a[1]); w.y = cvt_pk_bf16(a[2], a[3]); w.z = cvt_pk_bf16(b[0], b[1]); w.w = cvt_pk_bf16(b[2], b[3]); return w; }
; __device__ __forceinline__ float sumsq4(const f32x4 a) { return (a[0] * a[0] + a[1] * a[1]) + (a[2] * a[2] + a[3] * a[3]); }
;     __device__ __forceinline__ void operator()(f32x4 (&acc)[2][2][4][2], const Unit& u_, int wr, int wc, int fr, int fq) const {
;     ...
;             for (int m = 0; m < 4; ++m) {
;                 const int row = row0 + ai * HALF + m * 16; const size_t off = (size_t)row * 2048 + col0;
;                 float sc = alpha; if constexpr (MODE == 1) sc = rstd_of(ssb[row], 1.0f / 1024.0f);
;                 float q = 0.f;
; #pragma unroll
;                 for (int bj = 0; bj < 2; ++bj) {
;                     f32x4 x0, x1;
;                     if constexpr (XF32) { x0 = xf[(ai * 4 + m) * 2 + bj][0]; x1 = xf[(ai * 4 + m) * 2 + bj][1]; }
;                     else { const u32x4 w = BATCH ? xw[ai][m][bj] : *(const u32x4*)(xb + off + bj * HALF); x0 = (f32x4){bf_lo(w.x), bf_hi(w.x), bf_lo(w.y), bf_hi(w.y)}; x1 = (f32x4){bf_lo(w.z), bf_hi(w.z), bf_lo(w.w), bf_hi(w.w)}; }
;                     const f32x4 v0 = x0 + acc[ai][bj][m][0] * sc, v1 = x1 + acc[ai][bj][m][1] * sc;
;                     *(u32x4*)(xb + off + bj * HALF) = pack8(v0, v1);
;                     if (x8) { typedef unsigned u32x2 __attribute__((ext_vector_type(2))); u32x2 w8; w8.x = pack4_fp8(v0[0] * F8_X_SCALE, v0[1] * F8_X_SCALE, v0[2] * F8_X_SCALE, v0[3] * F8_X_SCALE);
;                         w8.y = pack4_fp8(v1[0] * F8_X_SCALE, v1[1] * F8_X_SCALE, v1[2] * F8_X_SCALE, v1[3] * F8_X_SCALE); *(u32x2*)(x8 + off + bj * HALF) = w8; }
;                     q += sumsq4(v0) + sumsq4(v1);
.LBB0_720:
	s_or_b64 exec, exec, s[64:65]
	v_add_u32_e32 v140, 0x90, v2
	v_ashrrev_i32_e32 v141, 31, v140
	global_load_dword v148, v[138:139], off offset:576
	s_waitcnt lgkmcnt(0)
	v_lshlrev_b64 v[142:143], 11, v[140:141]
	v_lshl_add_u64 v[152:153], v[142:143], 0, v[136:137]
	v_lshl_add_u64 v[142:143], v[152:153], 1, s[28:29]
	global_load_dwordx4 v[144:147], v[142:143], off
	s_and_b64 vcc, exec, s[10:11]
	v_lshl_add_u64 v[152:153], s[38:39], 0, v[152:153]
	s_waitcnt vmcnt(1)
	v_fmamk_f32 v148, v148, 0x3a800000, v168
	v_rsq_f32_e32 v154, v148
	s_waitcnt vmcnt(0)
	v_lshlrev_b32_e32 v150, 16, v144
	v_and_b32_e32 v151, 0xffff0000, v144
	v_lshlrev_b32_e32 v144, 16, v145
	v_and_b32_e32 v145, 0xffff0000, v145
	v_lshlrev_b32_e32 v156, 16, v146
	v_and_b32_e32 v157, 0xffff0000, v146
	v_lshlrev_b32_e32 v146, 16, v147
	v_and_b32_e32 v147, 0xffff0000, v147
	v_pk_fma_f32 v[148:149], v[82:83], v[154:155], v[144:145] op_sel_hi:[1,0,1]
	v_pk_fma_f32 v[150:151], v[80:81], v[154:155], v[150:151] op_sel_hi:[1,0,1]
	v_pk_fma_f32 v[144:145], v[74:75], v[154:155], v[146:147] op_sel_hi:[1,0,1]
	v_pk_fma_f32 v[146:147], v[72:73], v[154:155], v[156:157] op_sel_hi:[1,0,1]
	v_cvt_pk_bf16_f32 v156, v150, v151
	v_cvt_pk_bf16_f32 v157, v148, v149
	s_nop 0
	v_cvt_pk_bf16_f32 v158, v146, v147
	v_cvt_pk_bf16_f32 v159, v144, v145
	global_store_dwordx4 v[142:143], v[156:159], off sc1
	s_cbranch_vccnz .LBB0_722
	v_mul_f32_e32 v155, 0x41800000, v150
	v_mul_f32_e32 v156, 0x41800000, v151
	v_med3_f32 v155, v155, s75, v169
	v_med3_f32 v158, v156, s75, v169
	v_mov_b32_e32 v156, v1
	v_cvt_pk_fp8_f32 v156, v155, v158
	v_mul_f32_e32 v157, 0x41800000, v148
	v_mul_f32_e32 v155, 0x41800000, v149
	v_med3_f32 v157, v157, s75, v169
	v_med3_f32 v155, v155, s75, v169
	v_cvt_pk_fp8_f32 v156, v157, v155 op_sel:[0,0,1]
	v_mul_f32_e32 v155, 0x41800000, v146
	v_mul_f32_e32 v157, 0x41800000, v147
	v_med3_f32 v155, v155, s75, v169
	v_med3_f32 v159, v157, s75, v169
	v_mov_b32_e32 v157, v1
	v_cvt_pk_fp8_f32 v157, v155, v159
	v_mul_f32_e32 v158, 0x41800000, v144
	v_mul_f32_e32 v155, 0x41800000, v145
	v_med3_f32 v158, v158, s75, v169
	v_med3_f32 v155, v155, s75, v169
	v_cvt_pk_fp8_f32 v157, v158, v155 op_sel:[0,0,1]
	global_store_dwordx2 v[152:153], v[156:157], off
.LBB0_722:
	global_load_dwordx4 v[156:159], v[142:143], off offset:256
	v_mov_b32_e32 v155, v154
	v_mov_b32_e32 v172, v154
	v_mov_b32_e32 v173, v154
	s_and_b64 vcc, exec, s[10:11]
	s_waitcnt vmcnt(0)
	v_lshlrev_b32_e32 v160, 16, v156
	v_and_b32_e32 v161, 0xffff0000, v156
	v_lshlrev_b32_e32 v156, 16, v157
	v_and_b32_e32 v157, 0xffff0000, v157
	v_lshlrev_b32_e32 v174, 16, v158
	v_and_b32_e32 v175, 0xffff0000, v158
	v_lshlrev_b32_e32 v158, 16, v159
	v_and_b32_e32 v159, 0xffff0000, v159
	v_pk_fma_f32 v[156:157], v[26:27], v[172:173], v[156:157]
	v_pk_fma_f32 v[160:161], v[24:25], v[154:155], v[160:161]
	v_pk_fma_f32 v[158:159], v[22:23], v[172:173], v[158:159]
	v_pk_fma_f32 v[154:155], v[20:21], v[154:155], v[174:175]
	v_cvt_pk_bf16_f32 v172, v160, v161
	v_cvt_pk_bf16_f32 v173, v156, v157
	s_nop 0
	v_cvt_pk_bf16_f32 v174, v154, v155
	v_cvt_pk_bf16_f32 v175, v158, v159
	global_store_dwordx4 v[142:143], v[172:175], off offset:256 sc1
	s_cbranch_vccnz .LBB0_724
	v_mul_f32_e32 v142, 0x41800000, v160
	v_mul_f32_e32 v143, 0x41800000, v161
	v_med3_f32 v173, v142, s75, v169
	v_med3_f32 v143, v143, s75, v169
	v_mov_b32_e32 v142, v1
	v_cvt_pk_fp8_f32 v142, v173, v143
	v_mul_f32_e32 v172, 0x41800000, v156
	v_mul_f32_e32 v143, 0x41800000, v157
	v_med3_f32 v172, v172, s75, v169
	v_med3_f32 v143, v143, s75, v169
	v_cvt_pk_fp8_f32 v142, v172, v143 op_sel:[0,0,1]
	v_mul_f32_e32 v143, 0x41800000, v154
	v_mul_f32_e32 v172, 0x41800000, v155
	v_med3_f32 v174, v143, s75, v169
	v_med3_f32 v172, v172, s75, v169
	v_mov_b32_e32 v143, v1
	v_cvt_pk_fp8_f32 v143, v174, v172
	v_mul_f32_e32 v173, 0x41800000, v158
	v_mul_f32_e32 v172, 0x41800000, v159
	v_med3_f32 v173, v173, s75, v169
	v_med3_f32 v172, v172, s75, v169
	v_cvt_pk_fp8_f32 v143, v173, v172 op_sel:[0,0,1]
	global_store_dwordx2 v[152:153], v[142:143], off offset:128

; __device__ __forceinline__ float rstd_of(float ss, float inv_n) { return __builtin_amdgcn_rsqf(ss * inv_n + 1e-6f); }
; __device__ __forceinline__ float bf_lo(unsigned w) { return __uint_as_float(w << 16); }
; __device__ __forceinline__ float bf_hi(unsigned w) { return __uint_as_float(w & 0xffff0000u); }
; __device__ __forceinline__ u32x4 pack8(const f32x4 a, const f32x4 b) { u32x4 w; w.x = cvt_pk_bf16(a[0], a[1]); w.y = cvt_pk_bf16(a[2], a[3]); w.z = cvt_pk_bf16(b[0], b[1]); w.w = cvt_pk_bf16(b[2], b[3]); return w; }
; __device__ __forceinline__ float sumsq4(const f32x4 a) { return (a[0] * a[0] + a[1] * a[1]) + (a[2] * a[2] + a[3] * a[3]); }
;     __device__ __forceinline__ void operator()(f32x4 (&acc)[2][2][4][2], const Unit& u_, int wr, int wc, int fr, int fq) const {
;     ...
;             for (int m = 0; m < 4; ++m) {
;                 const int row = row0 + ai * HALF + m * 16; const size_t off = (size_t)row * 2048 + col0;
;                 float sc = alpha; if constexpr (MODE == 1) sc = rstd_of(ssb[row], 1.0f / 1024.0f);
;                 float q = 0.f;
; #pragma unroll
;                 for (int bj = 0; bj < 2; ++bj) {
;                     f32x4 x0, x1;
;                     if constexpr (XF32) { x0 = xf[(ai * 4 + m) * 2 + bj][0]; x1 = xf[(ai * 4 + m) * 2 + bj][1]; }
;                     else { const u32x4 w = BATCH ? xw[ai][m][bj] : *(const u32x4*)(xb + off + bj * HALF); x0 = (f32x4){bf_lo(w.x), bf_hi(w.x), bf_lo(w.y), bf_hi(w.y)}; x1 = (f32x4){bf_lo(w.z), bf_hi(w.z), bf_lo(w.w), bf_hi(w.w)}; }
;                     const f32x4 v0 = x0 + acc[ai][bj][m][0] * sc, v1 = x1 + acc[ai][bj][m][1] * sc;
;                     *(u32x4*)(xb + off + bj * HALF) = pack8(v0, v1);
;                     if (x8) { typedef unsigned u32x2 __attribute__((ext_vector_type(2))); u32x2 w8; w8.x = pack4_fp8(v0[0] * F8_X_SCALE, v0[1] * F8_X_SCALE, v0[2] * F8_X_SCALE, v0[3] * F8_X_SCALE);
;                         w8.y = pack4_fp8(v1[0] * F8_X_SCALE, v1[1] * F8_X_SCALE, v1[2] * F8_X_SCALE, v1[3] * F8_X_SCALE); *(u32x2*)(x8 + off + bj * HALF) = w8; }
;                     q += sumsq4(v0) + sumsq4(v1);
.LBB0_726:
	s_or_b64 exec, exec, s[64:65]
	v_add_u32_e32 v140, 0xa0, v2
	v_ashrrev_i32_e32 v141, 31, v140
	global_load_dword v148, v[138:139], off offset:640
	s_waitcnt lgkmcnt(0)
	v_lshlrev_b64 v[142:143], 11, v[140:141]
	v_lshl_add_u64 v[152:153], v[142:143], 0, v[136:137]
	v_lshl_add_u64 v[142:143], v[152:153], 1, s[28:29]
	global_load_dwordx4 v[144:147], v[142:143], off
	s_and_b64 vcc, exec, s[10:11]
	v_lshl_add_u64 v[152:153], s[38:39], 0, v[152:153]
	s_waitcnt vmcnt(1)
	v_fmamk_f32 v148, v148, 0x3a800000, v168
	v_rsq_f32_e32 v154, v148
	s_waitcnt vmcnt(0)
	v_lshlrev_b32_e32 v150, 16, v144
	v_and_b32_e32 v151, 0xffff0000, v144
	v_lshlrev_b32_e32 v144, 16, v145
	v_and_b32_e32 v145, 0xffff0000, v145
	v_lshlrev_b32_e32 v156, 16, v146
	v_and_b32_e32 v157, 0xffff0000, v146
	v_lshlrev_b32_e32 v146, 16, v147
	v_and_b32_e32 v147, 0xffff0000, v147
	v_pk_fma_f32 v[148:149], v[66:67], v[154:155], v[144:145] op_sel_hi:[1,0,1]
	v_pk_fma_f32 v[150:151], v[64:65], v[154:155], v[150:151] op_sel_hi:[1,0,1]
	v_pk_fma_f32 v[144:145], v[58:59], v[154:155], v[146:147] op_sel_hi:[1,0,1]
	v_pk_fma_f32 v[146:147], v[56:57], v[154:155], v[156:157] op_sel_hi:[1,0,1]
	v_cvt_pk_bf16_f32 v156, v150, v151
	v_cvt_pk_bf16_f32 v157, v148, v149
	s_nop 0
	v_cvt_pk_bf16_f32 v158, v146, v147
	v_cvt_pk_bf16_f32 v159, v144, v145
	global_store_dwordx4 v[142:143], v[156:159], off sc1
	s_cbranch_vccnz .LBB0_728
	v_mul_f32_e32 v155, 0x41800000, v150
	v_mul_f32_e32 v156, 0x41800000, v151
	v_med3_f32 v155, v155, s75, v169
	v_med3_f32 v158, v156, s75, v169
	v_mov_b32_e32 v156, v1
	v_cvt_pk_fp8_f32 v156, v155, v158
	v_mul_f32_e32 v157, 0x41800000, v148
	v_mul_f32_e32 v155, 0x41800000, v149
	v_med3_f32 v157, v157, s75, v169
	v_med3_f32 v155, v155, s75, v169
	v_cvt_pk_fp8_f32 v156, v157, v155 op_sel:[0,0,1]
	v_mul_f32_e32 v155, 0x41800000, v146
	v_mul_f32_e32 v157, 0x41800000, v147
	v_med3_f32 v155, v155, s75, v169
	v_med3_f32 v159, v157, s75, v169
	v_mov_b32_e32 v157, v1
	v_cvt_pk_fp8_f32 v157, v155, v159
	v_mul_f32_e32 v158, 0x41800000, v144
	v_mul_f32_e32 v155, 0x41800000, v145
	v_med3_f32 v158, v158, s75, v169
	v_med3_f32 v155, v155, s75, v169
	v_cvt_pk_fp8_f32 v157, v158, v155 op_sel:[0,0,1]
	global_store_dwordx2 v[152:153], v[156:157], off
.LBB0_728:
	global_load_dwordx4 v[156:159], v[142:143], off offset:256
	v_mov_b32_e32 v155, v154
	v_mov_b32_e32 v172, v154
	v_mov_b32_e32 v173, v154
	s_and_b64 vcc, exec, s[10:11]
	s_waitcnt vmcnt(0)
	v_lshlrev_b32_e32 v160, 16, v156
	v_and_b32_e32 v161, 0xffff0000, v156
	v_lshlrev_b32_e32 v156, 16, v157
	v_and_b32_e32 v157, 0xffff0000, v157
	v_lshlrev_b32_e32 v174, 16, v158
	v_and_b32_e32 v175, 0xffff0000, v158
	v_lshlrev_b32_e32 v158, 16, v159
	v_and_b32_e32 v159, 0xffff0000, v159
	v_pk_fma_f32 v[156:157], v[18:19], v[172:173], v[156:157]
	v_pk_fma_f32 v[160:161], v[16:17], v[154:155], v[160:161]
	v_pk_fma_f32 v[158:159], v[14:15], v[172:173], v[158:159]
	v_pk_fma_f32 v[154:155], v[12:13], v[154:155], v[174:175]
	v_cvt_pk_bf16_f32 v172, v160, v161
	v_cvt_pk_bf16_f32 v173, v156, v157
	s_nop 0
	v_cvt_pk_bf16_f32 v174, v154, v155
	v_cvt_pk_bf16_f32 v175, v158, v159
	global_store_dwordx4 v[142:143], v[172:175], off offset:256 sc1
	s_cbranch_vccnz .LBB0_730
	v_mul_f32_e32 v142, 0x41800000, v160
	v_mul_f32_e32 v143, 0x41800000, v161
	v_med3_f32 v173, v142, s75, v169
	v_med3_f32 v143, v143, s75, v169
	v_mov_b32_e32 v142, v1
	v_cvt_pk_fp8_f32 v142, v173, v143
	v_mul_f32_e32 v172, 0x41800000, v156
	v_mul_f32_e32 v143, 0x41800000, v157
	v_med3_f32 v172, v172, s75, v169
	v_med3_f32 v143, v143, s75, v169
	v_cvt_pk_fp8_f32 v142, v172, v143 op_sel:[0,0,1]
	v_mul_f32_e32 v143, 0x41800000, v154
	v_mul_f32_e32 v172, 0x41800000, v155
	v_med3_f32 v174, v143, s75, v169
	v_med3_f32 v172, v172, s75, v169
	v_mov_b32_e32 v143, v1
	v_cvt_pk_fp8_f32 v143, v174, v172
	v_mul_f32_e32 v173, 0x41800000, v158
	v_mul_f32_e32 v172, 0x41800000, v159
	v_med3_f32 v173, v173, s75, v169
	v_med3_f32 v172, v172, s75, v169
	v_cvt_pk_fp8_f32 v143, v173, v172 op_sel:[0,0,1]
	global_store_dwordx2 v[152:153], v[142:143], off offset:128

; __device__ __forceinline__ float rstd_of(float ss, float inv_n) { return __builtin_amdgcn_rsqf(ss * inv_n + 1e-6f); }
; __device__ __forceinline__ float bf_lo(unsigned w) { return __uint_as_float(w << 16); }
; __device__ __forceinline__ float bf_hi(unsigned w) { return __uint_as_float(w & 0xffff0000u); }
; __device__ __forceinline__ u32x4 pack8(const f32x4 a, const f32x4 b) { u32x4 w; w.x = cvt_pk_bf16(a[0], a[1]); w.y = cvt_pk_bf16(a[2], a[3]); w.z = cvt_pk_bf16(b[0], b[1]); w.w = cvt_pk_bf16(b[2], b[3]); return w; }
; __device__ __forceinline__ float sumsq4(const f32x4 a) { return (a[0] * a[0] + a[1] * a[1]) + (a[2] * a[2] + a[3] * a[3]); }
;     __device__ __forceinline__ void operator()(f32x4 (&acc)[2][2][4][2], const Unit& u_, int wr, int wc, int fr, int fq) const {
;     ...
;             for (int m = 0; m < 4; ++m) {
;                 const int row = row0 + ai * HALF + m * 16; const size_t off = (size_t)row * 2048 + col0;
;                 float sc = alpha; if constexpr (MODE == 1) sc = rstd_of(ssb[row], 1.0f / 1024.0f);
;                 float q = 0.f;
; #pragma unroll
;                 for (int bj = 0; bj < 2; ++bj) {
;                     f32x4 x0, x1;
;                     if constexpr (XF32) { x0 = xf[(ai * 4 + m) * 2 + bj][0]; x1 = xf[(ai * 4 + m) * 2 + bj][1]; }
;                     else { const u32x4 w = BATCH ? xw[ai][m][bj] : *(const u32x4*)(xb + off + bj * HALF); x0 = (f32x4){bf_lo(w.x), bf_hi(w.x), bf_lo(w.y), bf_hi(w.y)}; x1 = (f32x4){bf_lo(w.z), bf_hi(w.z), bf_lo(w.w), bf_hi(w.w)}; }
;                     const f32x4 v0 = x0 + acc[ai][bj][m][0] * sc, v1 = x1 + acc[ai][bj][m][1] * sc;
;                     *(u32x4*)(xb + off + bj * HALF) = pack8(v0, v1);
;                     if (x8) { typedef unsigned u32x2 __attribute__((ext_vector_type(2))); u32x2 w8; w8.x = pack4_fp8(v0[0] * F8_X_SCALE, v0[1] * F8_X_SCALE, v0[2] * F8_X_SCALE, v0[3] * F8_X_SCALE);
;                         w8.y = pack4_fp8(v1[0] * F8_X_SCALE, v1[1] * F8_X_SCALE, v1[2] * F8_X_SCALE, v1[3] * F8_X_SCALE); *(u32x2*)(x8 + off + bj * HALF) = w8; }
;                     q += sumsq4(v0) + sumsq4(v1);
.LBB0_732:
	s_or_b64 exec, exec, s[64:65]
	v_add_u32_e32 v140, 0xb0, v2
	v_ashrrev_i32_e32 v141, 31, v140
	global_load_dword v138, v[138:139], off offset:704
	s_waitcnt lgkmcnt(0)
	v_lshlrev_b64 v[142:143], 11, v[140:141]
	v_lshl_add_u64 v[148:149], v[142:143], 0, v[136:137]
	v_lshl_add_u64 v[136:137], v[148:149], 1, s[28:29]
	global_load_dwordx4 v[142:145], v[136:137], off
	s_and_b64 vcc, exec, s[10:11]
	v_lshl_add_u64 v[148:149], s[38:39], 0, v[148:149]
	s_waitcnt vmcnt(1)
	v_fmamk_f32 v138, v138, 0x3a800000, v168
	v_rsq_f32_e32 v150, v138
	s_waitcnt vmcnt(0)
	v_lshlrev_b32_e32 v138, 16, v142
	v_and_b32_e32 v139, 0xffff0000, v142
	v_lshlrev_b32_e32 v142, 16, v143
	v_and_b32_e32 v143, 0xffff0000, v143
	v_lshlrev_b32_e32 v152, 16, v144
	v_and_b32_e32 v153, 0xffff0000, v144
	v_lshlrev_b32_e32 v154, 16, v145
	v_and_b32_e32 v155, 0xffff0000, v145
	v_pk_fma_f32 v[144:145], v[50:51], v[150:151], v[142:143] op_sel_hi:[1,0,1]
	v_pk_fma_f32 v[146:147], v[48:49], v[150:151], v[138:139] op_sel_hi:[1,0,1]
	v_pk_fma_f32 v[138:139], v[42:43], v[150:151], v[154:155] op_sel_hi:[1,0,1]
	v_pk_fma_f32 v[142:143], v[40:41], v[150:151], v[152:153] op_sel_hi:[1,0,1]
	v_cvt_pk_bf16_f32 v152, v146, v147
	v_cvt_pk_bf16_f32 v153, v144, v145
	s_nop 0
	v_cvt_pk_bf16_f32 v154, v142, v143
	v_cvt_pk_bf16_f32 v155, v138, v139
	global_store_dwordx4 v[136:137], v[152:155], off sc1
	s_cbranch_vccnz .LBB0_734
	v_mul_f32_e32 v151, 0x41800000, v146
	v_mul_f32_e32 v152, 0x41800000, v147
	v_med3_f32 v151, v151, s75, v169
	v_med3_f32 v154, v152, s75, v169
	v_mov_b32_e32 v152, v1
	v_cvt_pk_fp8_f32 v152, v151, v154
	v_mul_f32_e32 v153, 0x41800000, v144
	v_mul_f32_e32 v151, 0x41800000, v145
	v_med3_f32 v153, v153, s75, v169
	v_med3_f32 v151, v151, s75, v169
	v_cvt_pk_fp8_f32 v152, v153, v151 op_sel:[0,0,1]
	v_mul_f32_e32 v151, 0x41800000, v142
	v_mul_f32_e32 v153, 0x41800000, v143
	v_med3_f32 v151, v151, s75, v169
	v_med3_f32 v155, v153, s75, v169
	v_mov_b32_e32 v153, v1
	v_cvt_pk_fp8_f32 v153, v151, v155
	v_mul_f32_e32 v154, 0x41800000, v138
	v_mul_f32_e32 v151, 0x41800000, v139
	v_med3_f32 v154, v154, s75, v169
	v_med3_f32 v151, v151, s75, v169
	v_cvt_pk_fp8_f32 v153, v154, v151 op_sel:[0,0,1]
	global_store_dwordx2 v[148:149], v[152:153], off
.LBB0_734:
	global_load_dwordx4 v[152:155], v[136:137], off offset:256
	v_mov_b32_e32 v151, v150
	v_mov_b32_e32 v158, v150
	v_mov_b32_e32 v159, v150
	s_and_b64 vcc, exec, s[10:11]
	s_waitcnt vmcnt(0)
	v_lshlrev_b32_e32 v156, 16, v152
	v_and_b32_e32 v157, 0xffff0000, v152
	v_lshlrev_b32_e32 v152, 16, v153
	v_and_b32_e32 v153, 0xffff0000, v153
	v_lshlrev_b32_e32 v160, 16, v154
	v_and_b32_e32 v161, 0xffff0000, v154
	v_lshlrev_b32_e32 v154, 16, v155
	v_and_b32_e32 v155, 0xffff0000, v155
	v_pk_fma_f32 v[152:153], v[10:11], v[158:159], v[152:153]
	v_pk_fma_f32 v[156:157], v[8:9], v[150:151], v[156:157]
	v_pk_fma_f32 v[154:155], v[6:7], v[158:159], v[154:155]
	v_pk_fma_f32 v[150:151], v[4:5], v[150:151], v[160:161]
	v_cvt_pk_bf16_f32 v158, v156, v157
	v_cvt_pk_bf16_f32 v159, v152, v153
	s_nop 0
	v_cvt_pk_bf16_f32 v160, v150, v151
	v_cvt_pk_bf16_f32 v161, v154, v155
	global_store_dwordx4 v[136:137], v[158:161], off offset:256 sc1
	s_cbranch_vccnz .LBB0_736
	v_mul_f32_e32 v136, 0x41800000, v156
	v_mul_f32_e32 v137, 0x41800000, v157
	v_med3_f32 v159, v136, s75, v169
	v_med3_f32 v137, v137, s75, v169
	v_mov_b32_e32 v136, v1
	v_cvt_pk_fp8_f32 v136, v159, v137
	v_mul_f32_e32 v158, 0x41800000, v152
	v_mul_f32_e32 v137, 0x41800000, v153
	v_med3_f32 v158, v158, s75, v169
	v_med3_f32 v137, v137, s75, v169
	v_cvt_pk_fp8_f32 v136, v158, v137 op_sel:[0,0,1]
	v_mul_f32_e32 v137, 0x41800000, v150
	v_mul_f32_e32 v158, 0x41800000, v151
	v_med3_f32 v160, v137, s75, v169
	v_med3_f32 v158, v158, s75, v169
	v_mov_b32_e32 v137, v1
	v_cvt_pk_fp8_f32 v137, v160, v158
	v_mul_f32_e32 v159, 0x41800000, v154
	v_mul_f32_e32 v158, 0x41800000, v155
	v_med3_f32 v159, v159, s75, v169
	v_med3_f32 v158, v158, s75, v169
	v_cvt_pk_fp8_f32 v137, v159, v158 op_sel:[0,0,1]
	global_store_dwordx2 v[148:149], v[136:137], off offset:128

; __device__ __forceinline__ float rstd_of(float ss, float inv_n) { return __builtin_amdgcn_rsqf(ss * inv_n + 1e-6f); }
; __device__ __forceinline__ float sigmoid_f(float v) { return __builtin_amdgcn_rcpf(1.0f + __builtin_amdgcn_exp2f(-1.4426950408889634f * v)); }
; __device__ __forceinline__ u32x4 pack8(const f32x4 a, const f32x4 b) { u32x4 w; w.x = cvt_pk_bf16(a[0], a[1]); w.y = cvt_pk_bf16(a[2], a[3]); w.z = cvt_pk_bf16(b[0], b[1]); w.w = cvt_pk_bf16(b[2], b[3]); return w; }
;     __device__ __forceinline__ void operator()(f32x4 (&acc)[2][2][4][2], const Unit& u_, int wr, int wc, int fr, int fq) const {
;     ...
;         const int row0 = u.pm * BM + wr * 64 + fr, col0 = u.pn * HALF + wc * 32 + 8 * fq;
; #pragma unroll
;         for (int ai = 0; ai < 2; ++ai)
; #pragma unroll
;             for (int m = 0; m < 4; ++m) {
;                 const int row = row0 + ai * HALF + m * 16; const float r = rstd_of(sl[u.par * 256 + ai * HALF + wr * 64 + m * 16 + fr], 1.0f / 2048.0f) * ascale;
;                 f32x4 o[2];
; #pragma unroll
;                 for (int n = 0; n < 2; ++n) { const f32x4 g = acc[ai][0][m][n] * r, uu = acc[ai][1][m][n] * r;
; #pragma unroll
;                     for (int e = 0; e < 4; ++e) o[n][e] = g[e] * uu[e] * sigmoid_f(g[e]); }
;                 if constexpr (F8OUT) {
;                     typedef unsigned u32x2 __attribute__((ext_vector_type(2))); u32x2 w8; w8.x = pack4_fp8(o[0][0] * F8_ACT_SCALE, o[0][1] * F8_ACT_SCALE, o[0][2] * F8_ACT_SCALE, o[0][3] * F8_ACT_SCALE);
;                     w8.y = pack4_fp8(o[1][0] * F8_ACT_SCALE, o[1][1] * F8_ACT_SCALE, o[1][2] * F8_ACT_SCALE, o[1][3] * F8_ACT_SCALE);
;                     *(u32x2*)((unsigned char*)O + (((size_t)u.pm * (ldo / 128) + (col0 >> 7)) * BM + (ai * HALF + wr * 64 + m * 16 + fr)) * 128 + (col0 & 127)) = w8;
;                 } else
;                 *(u32x4*)(O + (((size_t)u.pm * (ldo / 64) + (col0 >> 6)) * BM + (ai * HALF + wr * 64 + m * 16 + fr)) * 64 + (col0 & 63)) = pack8(o[0], o[1]);
.LBB0_815:
	s_lshl_b32 s11, s65, 10
	v_mbcnt_lo_u32_b32 v168, -1, 0
	v_mbcnt_hi_u32_b32 v168, -1, v168
	s_add_i32 s11, s53, s11
	v_and_b32_e32 v169, 15, v168
	v_lshl_add_u32 v166, v169, 2, s11
	ds_read_b32 v172, v166
	ds_read_b32 v173, v166 offset:64
	ds_read_b32 v174, v166 offset:128
	ds_read_b32 v175, v166 offset:192
	ds_read_b32 v176, v166 offset:512
	ds_read_b32 v177, v166 offset:576
	ds_read_b32 v178, v166 offset:640
	ds_read_b32 v179, v166 offset:704
	s_lshl_b32 s10, s52, 7
	v_lshrrev_b32_e32 v168, 1, v168
	s_or_b32 s10, s10, s91
	v_and_b32_e32 v168, 56, v168
	v_add_u32_e32 v167, s10, v168
	s_andn2_b64 vcc, exec, s[8:9]
	s_mov_b64 s[8:9], -1
	v_or_b32_e32 v170, s94, v169
	v_mov_b32_e32 v171, 0
	v_ashrrev_i32_e32 v168, 6, v167
	v_ashrrev_i32_e32 v169, 31, v168
	v_mad_i64_i32 v[180:181], s[10:11], s50, v146, v[168:169]
	v_lshlrev_b64 v[170:171], 7, v[170:171]
	v_lshlrev_b64 v[180:181], 15, v[180:181]
	v_and_b32_e32 v168, 56, v167
	v_lshl_add_u64 v[180:181], s[34:35], 0, v[180:181]
	v_lshlrev_b32_e32 v168, 1, v168
	v_mov_b32_e32 v169, 0
	v_lshl_add_u64 v[180:181], v[180:181], 0, v[170:171]
	v_mov_b32_e32 v182, 1.0
	v_lshl_add_u64 v[180:181], v[180:181], 0, v[168:169]
	s_mov_b64 s[10:11], 0x1000
	v_lshl_add_u64 v[202:203], v[180:181], 0, s[10:11]
	s_mov_b64 s[10:11], 0x5000
	v_lshl_add_u64 v[204:205], v[180:181], 0, s[10:11]
	s_waitcnt lgkmcnt(0)
	v_fmamk_f32 v184, v172, 0x3a000000, v145
	v_rsq_f32_e32 v184, v184
	s_nop 0
	v_mul_f32_e32 v184, 0x3a800000, v184
	v_mul_f32_e32 v186, 0xbfb8aa3b, v184
	v_mul_f32_e32 v188, v184, v184
	v_pk_mul_f32 v[190:191], v[124:125], v[186:187] op_sel_hi:[1,0]
	v_pk_mul_f32 v[192:193], v[126:127], v[186:187] op_sel_hi:[1,0]
	v_pk_mul_f32 v[124:125], v[124:125], v[120:121]
	v_exp_f32_e32 v190, v190
	v_exp_f32_e32 v191, v191
	v_exp_f32_e32 v192, v192
	v_exp_f32_e32 v193, v193
	v_pk_mul_f32 v[126:127], v[126:127], v[122:123]
	v_pk_add_f32 v[190:191], v[190:191], v[182:183] op_sel_hi:[1,0]
	v_pk_add_f32 v[192:193], v[192:193], v[182:183] op_sel_hi:[1,0]
	v_pk_mul_f32 v[124:125], v[124:125], v[188:189] op_sel_hi:[1,0]
	v_rcp_f32_e32 v190, v190
	v_rcp_f32_e32 v191, v191
	v_rcp_f32_e32 v192, v192
	v_rcp_f32_e32 v193, v193
	v_pk_mul_f32 v[126:127], v[126:127], v[188:189] op_sel_hi:[1,0]
	v_pk_mul_f32 v[124:125], v[124:125], v[190:191]
	v_pk_mul_f32 v[126:127], v[126:127], v[192:193]
	v_pk_mul_f32 v[190:191], v[116:117], v[186:187] op_sel_hi:[1,0]
	v_pk_mul_f32 v[192:193], v[118:119], v[186:187] op_sel_hi:[1,0]
	v_pk_mul_f32 v[116:117], v[116:117], v[112:113]
	v_exp_f32_e32 v190, v190
	v_exp_f32_e32 v191, v191
	v_exp_f32_e32 v192, v192
	v_exp_f32_e32 v193, v193
	v_pk_mul_f32 v[118:119], v[118:119], v[114:115]
	v_pk_add_f32 v[190:191], v[190:191], v[182:183] op_sel_hi:[1,0]
	v_pk_add_f32 v[192:193], v[192:193], v[182:183] op_sel_hi:[1,0]
	v_pk_mul_f32 v[116:117], v[116:117], v[188:189] op_sel_hi:[1,0]
	v_rcp_f32_e32 v190, v190
	v_rcp_f32_e32 v191, v191
	v_rcp_f32_e32 v192, v192
	v_rcp_f32_e32 v193, v193
	v_pk_mul_f32 v[118:119], v[118:119], v[188:189] op_sel_hi:[1,0]
	v_pk_mul_f32 v[116:117], v[116:117], v[190:191]
	v_pk_mul_f32 v[118:119], v[118:119], v[192:193]
	v_cvt_pk_bf16_f32 v194, v124, v125
	v_cvt_pk_bf16_f32 v195, v126, v127
	v_cvt_pk_bf16_f32 v196, v116, v117
	v_cvt_pk_bf16_f32 v197, v118, v119
	global_store_dwordx4 v[202:203], v[194:197], off offset:-4096 sc1
	v_fmamk_f32 v184, v173, 0x3a000000, v145
	v_rsq_f32_e32 v184, v184
	s_nop 0
	v_mul_f32_e32 v184, 0x3a800000, v184
	v_mul_f32_e32 v186, 0xbfb8aa3b, v184
	v_mul_f32_e32 v188, v184, v184
	v_pk_mul_f32 v[190:191], v[108:109], v[186:187] op_sel_hi:[1,0]
	v_pk_mul_f32 v[192:193], v[110:111], v[186:187] op_sel_hi:[1,0]
	v_pk_mul_f32 v[108:109], v[108:109], v[104:105]
	v_exp_f32_e32 v190, v190
	v_exp_f32_e32 v191, v191
	v_exp_f32_e32 v192, v192
	v_exp_f32_e32 v193, v193
	v_pk_mul_f32 v[110:111], v[110:111], v[106:107]
	v_pk_add_f32 v[190:191], v[190:191], v[182:183] op_sel_hi:[1,0]
	v_pk_add_f32 v[192:193], v[192:193], v[182:183] op_sel_hi:[1,0]
	v_pk_mul_f32 v[108:109], v[108:109], v[188:189] op_sel_hi:[1,0]
	v_rcp_f32_e32 v190, v190
	v_rcp_f32_e32 v191, v191
	v_rcp_f32_e32 v192, v192
	v_rcp_f32_e32 v193, v193
	v_pk_mul_f32 v[110:111], v[110:111], v[188:189] op_sel_hi:[1,0]
	v_pk_mul_f32 v[108:109], v[108:109], v[190:191]
	v_pk_mul_f32 v[110:111], v[110:111], v[192:193]
	v_pk_mul_f32 v[190:191], v[100:101], v[186:187] op_sel_hi:[1,0]
	v_pk_mul_f32 v[192:193], v[102:103], v[186:187] op_sel_hi:[1,0]
	v_pk_mul_f32 v[100:101], v[100:101], v[96:97]
	v_exp_f32_e32 v190, v190
	v_exp_f32_e32 v191, v191
	v_exp_f32_e32 v192, v192
	v_exp_f32_e32 v193, v193
	v_pk_mul_f32 v[102:103], v[102:103], v[98:99]
	v_pk_add_f32 v[190:191], v[190:191], v[182:183] op_sel_hi:[1,0]
	v_pk_add_f32 v[192:193], v[192:193], v[182:183] op_sel_hi:[1,0]
	v_pk_mul_f32 v[100:101], v[100:101], v[188:189] op_sel_hi:[1,0]
	v_rcp_f32_e32 v190, v190
	v_rcp_f32_e32 v191, v191
	v_rcp_f32_e32 v192, v192
	v_rcp_f32_e32 v193, v193
	v_pk_mul_f32 v[102:103], v[102:103], v[188:189] op_sel_hi:[1,0]
	v_pk_mul_f32 v[100:101], v[100:101], v[190:191]
	v_pk_mul_f32 v[102:103], v[102:103], v[192:193]
	v_cvt_pk_bf16_f32 v198, v108, v109
	v_cvt_pk_bf16_f32 v199, v110, v111
	v_cvt_pk_bf16_f32 v200, v100, v101
	v_cvt_pk_bf16_f32 v201, v102, v103
	global_store_dwordx4 v[202:203], v[198:201], off offset:-2048 sc1
	v_fmamk_f32 v184, v174, 0x3a000000, v145
	v_rsq_f32_e32 v184, v184
	s_nop 0
	v_mul_f32_e32 v184, 0x3a800000, v184
	v_mul_f32_e32 v186, 0xbfb8aa3b, v184
	v_mul_f32_e32 v188, v184, v184
	v_pk_mul_f32 v[190:191], v[92:93], v[186:187] op_sel_hi:[1,0]
	v_pk_mul_f32 v[192:193], v[94:95], v[186:187] op_sel_hi:[1,0]
; __device__ __forceinline__ float rstd_of(float ss, float inv_n) { return __builtin_amdgcn_rsqf(ss * inv_n + 1e-6f); }
; __device__ __forceinline__ float sigmoid_f(float v) { return __builtin_amdgcn_rcpf(1.0f + __builtin_amdgcn_exp2f(-1.4426950408889634f * v)); }
; __device__ __forceinline__ u32x4 pack8(const f32x4 a, const f32x4 b) { u32x4 w; w.x = cvt_pk_bf16(a[0], a[1]); w.y = cvt_pk_bf16(a[2], a[3]); w.z = cvt_pk_bf16(b[0], b[1]); w.w = cvt_pk_bf16(b[2], b[3]); return w; }
;     __device__ __forceinline__ void operator()(f32x4 (&acc)[2][2][4][2], const Unit& u_, int wr, int wc, int fr, int fq) const {
;     ...
;             for (int m = 0; m < 4; ++m) {
;                 const int row = row0 + ai * HALF + m * 16; const float r = rstd_of(sl[u.par * 256 + ai * HALF + wr * 64 + m * 16 + fr], 1.0f / 2048.0f) * ascale;
;                 f32x4 o[2];
; #pragma unroll
;                 for (int n = 0; n < 2; ++n) { const f32x4 g = acc[ai][0][m][n] * r, uu = acc[ai][1][m][n] * r;
; #pragma unroll
;                     for (int e = 0; e < 4; ++e) o[n][e] = g[e] * uu[e] * sigmoid_f(g[e]); }
;                 if constexpr (F8OUT) {
;                     typedef unsigned u32x2 __attribute__((ext_vector_type(2))); u32x2 w8; w8.x = pack4_fp8(o[0][0] * F8_ACT_SCALE, o[0][1] * F8_ACT_SCALE, o[0][2] * F8_ACT_SCALE, o[0][3] * F8_ACT_SCALE);
;                     w8.y = pack4_fp8(o[1][0] * F8_ACT_SCALE, o[1][1] * F8_ACT_SCALE, o[1][2] * F8_ACT_SCALE, o[1][3] * F8_ACT_SCALE);
;                     *(u32x2*)((unsigned char*)O + (((size_t)u.pm * (ldo / 128) + (col0 >> 7)) * BM + (ai * HALF + wr * 64 + m * 16 + fr)) * 128 + (col0 & 127)) = w8;
;                 } else
;                 *(u32x4*)(O + (((size_t)u.pm * (ldo / 64) + (col0 >> 6)) * BM + (ai * HALF + wr * 64 + m * 16 + fr)) * 64 + (col0 & 63)) = pack8(o[0], o[1]);
	v_pk_mul_f32 v[92:93], v[92:93], v[88:89]
	v_exp_f32_e32 v190, v190
	v_exp_f32_e32 v191, v191
	v_exp_f32_e32 v192, v192
	v_exp_f32_e32 v193, v193
	v_pk_mul_f32 v[94:95], v[94:95], v[90:91]
	v_pk_add_f32 v[190:191], v[190:191], v[182:183] op_sel_hi:[1,0]
	v_pk_add_f32 v[192:193], v[192:193], v[182:183] op_sel_hi:[1,0]
	v_pk_mul_f32 v[92:93], v[92:93], v[188:189] op_sel_hi:[1,0]
	v_rcp_f32_e32 v190, v190
	v_rcp_f32_e32 v191, v191
	v_rcp_f32_e32 v192, v192
	v_rcp_f32_e32 v193, v193
	v_pk_mul_f32 v[94:95], v[94:95], v[188:189] op_sel_hi:[1,0]
	v_pk_mul_f32 v[92:93], v[92:93], v[190:191]
	v_pk_mul_f32 v[94:95], v[94:95], v[192:193]
	v_pk_mul_f32 v[190:191], v[84:85], v[186:187] op_sel_hi:[1,0]
	v_pk_mul_f32 v[192:193], v[86:87], v[186:187] op_sel_hi:[1,0]
	v_pk_mul_f32 v[84:85], v[84:85], v[80:81]
	v_exp_f32_e32 v190, v190
	v_exp_f32_e32 v191, v191
	v_exp_f32_e32 v192, v192
	v_exp_f32_e32 v193, v193
	v_pk_mul_f32 v[86:87], v[86:87], v[82:83]
	v_pk_add_f32 v[190:191], v[190:191], v[182:183] op_sel_hi:[1,0]
	v_pk_add_f32 v[192:193], v[192:193], v[182:183] op_sel_hi:[1,0]
	v_pk_mul_f32 v[84:85], v[84:85], v[188:189] op_sel_hi:[1,0]
	v_rcp_f32_e32 v190, v190
	v_rcp_f32_e32 v191, v191
	v_rcp_f32_e32 v192, v192
	v_rcp_f32_e32 v193, v193
	v_pk_mul_f32 v[86:87], v[86:87], v[188:189] op_sel_hi:[1,0]
	v_pk_mul_f32 v[84:85], v[84:85], v[190:191]
	v_pk_mul_f32 v[86:87], v[86:87], v[192:193]
	v_cvt_pk_bf16_f32 v194, v92, v93
	v_cvt_pk_bf16_f32 v195, v94, v95
	v_cvt_pk_bf16_f32 v196, v84, v85
	v_cvt_pk_bf16_f32 v197, v86, v87
	global_store_dwordx4 v[202:203], v[194:197], off offset:0 sc1
	v_fmamk_f32 v184, v175, 0x3a000000, v145
	v_rsq_f32_e32 v184, v184
	s_nop 0
	v_mul_f32_e32 v184, 0x3a800000, v184
	v_mul_f32_e32 v186, 0xbfb8aa3b, v184
	v_mul_f32_e32 v188, v184, v184
	v_pk_mul_f32 v[190:191], v[76:77], v[186:187] op_sel_hi:[1,0]
	v_pk_mul_f32 v[192:193], v[78:79], v[186:187] op_sel_hi:[1,0]
	v_pk_mul_f32 v[76:77], v[76:77], v[72:73]
	v_exp_f32_e32 v190, v190
	v_exp_f32_e32 v191, v191
	v_exp_f32_e32 v192, v192
	v_exp_f32_e32 v193, v193
	v_pk_mul_f32 v[78:79], v[78:79], v[74:75]
	v_pk_add_f32 v[190:191], v[190:191], v[182:183] op_sel_hi:[1,0]
	v_pk_add_f32 v[192:193], v[192:193], v[182:183] op_sel_hi:[1,0]
	v_pk_mul_f32 v[76:77], v[76:77], v[188:189] op_sel_hi:[1,0]
	v_rcp_f32_e32 v190, v190
	v_rcp_f32_e32 v191, v191
	v_rcp_f32_e32 v192, v192
	v_rcp_f32_e32 v193, v193
	v_pk_mul_f32 v[78:79], v[78:79], v[188:189] op_sel_hi:[1,0]
	v_pk_mul_f32 v[76:77], v[76:77], v[190:191]
	v_pk_mul_f32 v[78:79], v[78:79], v[192:193]
	v_pk_mul_f32 v[190:191], v[68:69], v[186:187] op_sel_hi:[1,0]
	v_pk_mul_f32 v[192:193], v[70:71], v[186:187] op_sel_hi:[1,0]
	v_pk_mul_f32 v[68:69], v[68:69], v[64:65]
	v_exp_f32_e32 v190, v190
	v_exp_f32_e32 v191, v191
	v_exp_f32_e32 v192, v192
	v_exp_f32_e32 v193, v193
	v_pk_mul_f32 v[70:71], v[70:71], v[66:67]
	v_pk_add_f32 v[190:191], v[190:191], v[182:183] op_sel_hi:[1,0]
	v_pk_add_f32 v[192:193], v[192:193], v[182:183] op_sel_hi:[1,0]
	v_pk_mul_f32 v[68:69], v[68:69], v[188:189] op_sel_hi:[1,0]
	v_rcp_f32_e32 v190, v190
	v_rcp_f32_e32 v191, v191
	v_rcp_f32_e32 v192, v192
	v_rcp_f32_e32 v193, v193
	v_pk_mul_f32 v[70:71], v[70:71], v[188:189] op_sel_hi:[1,0]
	v_pk_mul_f32 v[68:69], v[68:69], v[190:191]
	v_pk_mul_f32 v[70:71], v[70:71], v[192:193]
	v_cvt_pk_bf16_f32 v198, v76, v77
	v_cvt_pk_bf16_f32 v199, v78, v79
	v_cvt_pk_bf16_f32 v200, v68, v69
	v_cvt_pk_bf16_f32 v201, v70, v71
	global_store_dwordx4 v[202:203], v[198:201], off offset:2048 sc1
	v_fmamk_f32 v184, v176, 0x3a000000, v145
	v_rsq_f32_e32 v184, v184
	s_nop 0
	v_mul_f32_e32 v184, 0x3a800000, v184
	v_mul_f32_e32 v186, 0xbfb8aa3b, v184
	v_mul_f32_e32 v188, v184, v184
	v_pk_mul_f32 v[190:191], v[60:61], v[186:187] op_sel_hi:[1,0]
	v_pk_mul_f32 v[192:193], v[62:63], v[186:187] op_sel_hi:[1,0]
	v_pk_mul_f32 v[60:61], v[60:61], v[56:57]
	v_exp_f32_e32 v190, v190
	v_exp_f32_e32 v191, v191
	v_exp_f32_e32 v192, v192
	v_exp_f32_e32 v193, v193
	v_pk_mul_f32 v[62:63], v[62:63], v[58:59]
	v_pk_add_f32 v[190:191], v[190:191], v[182:183] op_sel_hi:[1,0]
	v_pk_add_f32 v[192:193], v[192:193], v[182:183] op_sel_hi:[1,0]
	v_pk_mul_f32 v[60:61], v[60:61], v[188:189] op_sel_hi:[1,0]
	v_rcp_f32_e32 v190, v190
	v_rcp_f32_e32 v191, v191
	v_rcp_f32_e32 v192, v192
	v_rcp_f32_e32 v193, v193
	v_pk_mul_f32 v[62:63], v[62:63], v[188:189] op_sel_hi:[1,0]
	v_pk_mul_f32 v[60:61], v[60:61], v[190:191]
	v_pk_mul_f32 v[62:63], v[62:63], v[192:193]
	v_pk_mul_f32 v[190:191], v[52:53], v[186:187] op_sel_hi:[1,0]
	v_pk_mul_f32 v[192:193], v[54:55], v[186:187] op_sel_hi:[1,0]
	v_pk_mul_f32 v[52:53], v[52:53], v[48:49]
	v_exp_f32_e32 v190, v190
	v_exp_f32_e32 v191, v191
	v_exp_f32_e32 v192, v192
	v_exp_f32_e32 v193, v193
	v_pk_mul_f32 v[54:55], v[54:55], v[50:51]
	v_pk_add_f32 v[190:191], v[190:191], v[182:183] op_sel_hi:[1,0]
	v_pk_add_f32 v[192:193], v[192:193], v[182:183] op_sel_hi:[1,0]
	v_pk_mul_f32 v[52:53], v[52:53], v[188:189] op_sel_hi:[1,0]
	v_rcp_f32_e32 v190, v190
	v_rcp_f32_e32 v191, v191
	v_rcp_f32_e32 v192, v192
	v_rcp_f32_e32 v193, v193
	v_pk_mul_f32 v[54:55], v[54:55], v[188:189] op_sel_hi:[1,0]
	v_pk_mul_f32 v[52:53], v[52:53], v[190:191]
	v_pk_mul_f32 v[54:55], v[54:55], v[192:193]
	v_cvt_pk_bf16_f32 v194, v60, v61
	v_cvt_pk_bf16_f32 v195, v62, v63
	v_cvt_pk_bf16_f32 v196, v52, v53
	v_cvt_pk_bf16_f32 v197, v54, v55
	global_store_dwordx4 v[204:205], v[194:197], off offset:-4096 sc1
	v_fmamk_f32 v184, v177, 0x3a000000, v145
	v_rsq_f32_e32 v184, v184
	s_nop 0
	v_mul_f32_e32 v184, 0x3a800000, v184
	v_mul_f32_e32 v186, 0xbfb8aa3b, v184
	v_mul_f32_e32 v188, v184, v184
; __device__ __forceinline__ float rstd_of(float ss, float inv_n) { return __builtin_amdgcn_rsqf(ss * inv_n + 1e-6f); }
; #define PG8_BAR __builtin_amdgcn_s_barrier()
;     __device__ __forceinline__ void operator()(f32x4 (&acc)[2][2][4][2], const Unit& u_, int wr, int wc, int fr, int fq) const {
;     ...
;             for (int m = 0; m < 4; ++m) {
;                 const int row = row0 + ai * HALF + m * 16; const float r = rstd_of(sl[u.par * 256 + ai * HALF + wr * 64 + m * 16 + fr], 1.0f / 2048.0f) * ascale;
;                 f32x4 o[2];
; #pragma unroll
;                 for (int n = 0; n < 2; ++n) { const f32x4 g = acc[ai][0][m][n] * r, uu = acc[ai][1][m][n] * r;
; #pragma unroll
;                     for (int e = 0; e < 4; ++e) o[n][e] = g[e] * uu[e] * sigmoid_f(g[e]); }
;                 if constexpr (F8OUT) {
;                     typedef unsigned u32x2 __attribute__((ext_vector_type(2))); u32x2 w8; w8.x = pack4_fp8(o[0][0] * F8_ACT_SCALE, o[0][1] * F8_ACT_SCALE, o[0][2] * F8_ACT_SCALE, o[0][3] * F8_ACT_SCALE);
;                     w8.y = pack4_fp8(o[1][0] * F8_ACT_SCALE, o[1][1] * F8_ACT_SCALE, o[1][2] * F8_ACT_SCALE, o[1][3] * F8_ACT_SCALE);
;                     *(u32x2*)((unsigned char*)O + (((size_t)u.pm * (ldo / 128) + (col0 >> 7)) * BM + (ai * HALF + wr * 64 + m * 16 + fr)) * 128 + (col0 & 127)) = w8;
;                 } else
;                 *(u32x4*)(O + (((size_t)u.pm * (ldo / 64) + (col0 >> 6)) * BM + (ai * HALF + wr * 64 + m * 16 + fr)) * 64 + (col0 & 63)) = pack8(o[0], o[1]);
; template <class Epi, class Sched, bool ALIGN_EPI = false, bool SP2 = false, bool ABLK = false, bool F8 = false>
; __device__ __forceinline__ void gemm_phase(PG8_LAS unsigned char* lds, const Gemm g, const Sched& S, const Epi& E, const int wave_s) {
;     ...
;         if constexpr (ALIGN_EPI) { if (wr == 0) PG8_BAR; }
;         if constexpr (!Epi::AFTER_DRAIN) { E(acc, cur, wr, wc, fr, fq); S.done(cur); }
;         if (!has_next) break;
;         if (!(Epi::MID && cur.kh == 0))
; #pragma unroll
;         for (int a = 0; a < 2; ++a)
; #pragma unroll
;             for (int b = 0; b < 2; ++b)
; #pragma unroll
;                 for (int m = 0; m < 4; ++m)
; #pragma unroll
;                     for (int n = 0; n < 2; ++n) acc[a][b][m][n] = (f32x4){0.f, 0.f, 0.f, 0.f};
;         cur = nxt; cA = nA; cB = nB; ++ui;
;         if constexpr (ALIGN_EPI) { if (wr == 1) PG8_BAR; }
	v_pk_mul_f32 v[190:191], v[44:45], v[186:187] op_sel_hi:[1,0]
	v_pk_mul_f32 v[192:193], v[46:47], v[186:187] op_sel_hi:[1,0]
	v_pk_mul_f32 v[44:45], v[44:45], v[40:41]
	v_exp_f32_e32 v190, v190
	v_exp_f32_e32 v191, v191
	v_exp_f32_e32 v192, v192
	v_exp_f32_e32 v193, v193
	v_pk_mul_f32 v[46:47], v[46:47], v[42:43]
	v_pk_add_f32 v[190:191], v[190:191], v[182:183] op_sel_hi:[1,0]
	v_pk_add_f32 v[192:193], v[192:193], v[182:183] op_sel_hi:[1,0]
	v_pk_mul_f32 v[44:45], v[44:45], v[188:189] op_sel_hi:[1,0]
	v_rcp_f32_e32 v190, v190
	v_rcp_f32_e32 v191, v191
	v_rcp_f32_e32 v192, v192
	v_rcp_f32_e32 v193, v193
	v_pk_mul_f32 v[46:47], v[46:47], v[188:189] op_sel_hi:[1,0]
	v_pk_mul_f32 v[44:45], v[44:45], v[190:191]
	v_pk_mul_f32 v[46:47], v[46:47], v[192:193]
	v_pk_mul_f32 v[190:191], v[36:37], v[186:187] op_sel_hi:[1,0]
	v_pk_mul_f32 v[192:193], v[38:39], v[186:187] op_sel_hi:[1,0]
	v_pk_mul_f32 v[36:37], v[36:37], v[32:33]
	v_exp_f32_e32 v190, v190
	v_exp_f32_e32 v191, v191
	v_exp_f32_e32 v192, v192
	v_exp_f32_e32 v193, v193
	v_pk_mul_f32 v[38:39], v[38:39], v[34:35]
	v_pk_add_f32 v[190:191], v[190:191], v[182:183] op_sel_hi:[1,0]
	v_pk_add_f32 v[192:193], v[192:193], v[182:183] op_sel_hi:[1,0]
	v_pk_mul_f32 v[36:37], v[36:37], v[188:189] op_sel_hi:[1,0]
	v_rcp_f32_e32 v190, v190
	v_rcp_f32_e32 v191, v191
	v_rcp_f32_e32 v192, v192
	v_rcp_f32_e32 v193, v193
	v_pk_mul_f32 v[38:39], v[38:39], v[188:189] op_sel_hi:[1,0]
	v_pk_mul_f32 v[36:37], v[36:37], v[190:191]
	v_pk_mul_f32 v[38:39], v[38:39], v[192:193]
	v_cvt_pk_bf16_f32 v198, v44, v45
	v_cvt_pk_bf16_f32 v199, v46, v47
	v_cvt_pk_bf16_f32 v200, v36, v37
	v_cvt_pk_bf16_f32 v201, v38, v39
	global_store_dwordx4 v[204:205], v[198:201], off offset:-2048 sc1
	v_fmamk_f32 v184, v178, 0x3a000000, v145
	v_rsq_f32_e32 v184, v184
	s_nop 0
	v_mul_f32_e32 v184, 0x3a800000, v184
	v_mul_f32_e32 v186, 0xbfb8aa3b, v184
	v_mul_f32_e32 v188, v184, v184
	v_pk_mul_f32 v[190:191], v[28:29], v[186:187] op_sel_hi:[1,0]
	v_pk_mul_f32 v[192:193], v[30:31], v[186:187] op_sel_hi:[1,0]
	v_pk_mul_f32 v[28:29], v[28:29], v[24:25]
	v_exp_f32_e32 v190, v190
	v_exp_f32_e32 v191, v191
	v_exp_f32_e32 v192, v192
	v_exp_f32_e32 v193, v193
	v_pk_mul_f32 v[30:31], v[30:31], v[26:27]
	v_pk_add_f32 v[190:191], v[190:191], v[182:183] op_sel_hi:[1,0]
	v_pk_add_f32 v[192:193], v[192:193], v[182:183] op_sel_hi:[1,0]
	v_pk_mul_f32 v[28:29], v[28:29], v[188:189] op_sel_hi:[1,0]
	v_rcp_f32_e32 v190, v190
	v_rcp_f32_e32 v191, v191
	v_rcp_f32_e32 v192, v192
	v_rcp_f32_e32 v193, v193
	v_pk_mul_f32 v[30:31], v[30:31], v[188:189] op_sel_hi:[1,0]
	v_pk_mul_f32 v[28:29], v[28:29], v[190:191]
	v_pk_mul_f32 v[30:31], v[30:31], v[192:193]
	v_pk_mul_f32 v[190:191], v[20:21], v[186:187] op_sel_hi:[1,0]
	v_pk_mul_f32 v[192:193], v[22:23], v[186:187] op_sel_hi:[1,0]
	v_pk_mul_f32 v[20:21], v[20:21], v[16:17]
	v_exp_f32_e32 v190, v190
	v_exp_f32_e32 v191, v191
	v_exp_f32_e32 v192, v192
	v_exp_f32_e32 v193, v193
	v_pk_mul_f32 v[22:23], v[22:23], v[18:19]
	v_pk_add_f32 v[190:191], v[190:191], v[182:183] op_sel_hi:[1,0]
	v_pk_add_f32 v[192:193], v[192:193], v[182:183] op_sel_hi:[1,0]
	v_pk_mul_f32 v[20:21], v[20:21], v[188:189] op_sel_hi:[1,0]
	v_rcp_f32_e32 v190, v190
	v_rcp_f32_e32 v191, v191
	v_rcp_f32_e32 v192, v192
	v_rcp_f32_e32 v193, v193
	v_pk_mul_f32 v[22:23], v[22:23], v[188:189] op_sel_hi:[1,0]
	v_pk_mul_f32 v[20:21], v[20:21], v[190:191]
	v_pk_mul_f32 v[22:23], v[22:23], v[192:193]
	v_cvt_pk_bf16_f32 v194, v28, v29
	v_cvt_pk_bf16_f32 v195, v30, v31
	v_cvt_pk_bf16_f32 v196, v20, v21
	v_cvt_pk_bf16_f32 v197, v22, v23
	global_store_dwordx4 v[204:205], v[194:197], off offset:0 sc1
	v_fmamk_f32 v184, v179, 0x3a000000, v145
	v_rsq_f32_e32 v184, v184
	s_nop 0
	v_mul_f32_e32 v184, 0x3a800000, v184
	v_mul_f32_e32 v186, 0xbfb8aa3b, v184
	v_mul_f32_e32 v188, v184, v184
	v_pk_mul_f32 v[190:191], v[12:13], v[186:187] op_sel_hi:[1,0]
	v_pk_mul_f32 v[192:193], v[14:15], v[186:187] op_sel_hi:[1,0]
	v_pk_mul_f32 v[12:13], v[12:13], v[8:9]
	v_exp_f32_e32 v190, v190
	v_exp_f32_e32 v191, v191
	v_exp_f32_e32 v192, v192
	v_exp_f32_e32 v193, v193
	v_pk_mul_f32 v[14:15], v[14:15], v[10:11]
	v_pk_add_f32 v[190:191], v[190:191], v[182:183] op_sel_hi:[1,0]
	v_pk_add_f32 v[192:193], v[192:193], v[182:183] op_sel_hi:[1,0]
	v_pk_mul_f32 v[12:13], v[12:13], v[188:189] op_sel_hi:[1,0]
	v_rcp_f32_e32 v190, v190
	v_rcp_f32_e32 v191, v191
	v_rcp_f32_e32 v192, v192
	v_rcp_f32_e32 v193, v193
	v_pk_mul_f32 v[14:15], v[14:15], v[188:189] op_sel_hi:[1,0]
	v_pk_mul_f32 v[12:13], v[12:13], v[190:191]
	v_pk_mul_f32 v[14:15], v[14:15], v[192:193]
	v_pk_mul_f32 v[190:191], v[4:5], v[186:187] op_sel_hi:[1,0]
	v_pk_mul_f32 v[192:193], v[6:7], v[186:187] op_sel_hi:[1,0]
	v_pk_mul_f32 v[4:5], v[4:5], v[0:1]
	v_exp_f32_e32 v190, v190
	v_exp_f32_e32 v191, v191
	v_exp_f32_e32 v192, v192
	v_exp_f32_e32 v193, v193
	v_pk_mul_f32 v[6:7], v[6:7], v[2:3]
	v_pk_add_f32 v[190:191], v[190:191], v[182:183] op_sel_hi:[1,0]
	v_pk_add_f32 v[192:193], v[192:193], v[182:183] op_sel_hi:[1,0]
	v_pk_mul_f32 v[4:5], v[4:5], v[188:189] op_sel_hi:[1,0]
	v_rcp_f32_e32 v190, v190
	v_rcp_f32_e32 v191, v191
	v_rcp_f32_e32 v192, v192
	v_rcp_f32_e32 v193, v193
	v_pk_mul_f32 v[6:7], v[6:7], v[188:189] op_sel_hi:[1,0]
	v_pk_mul_f32 v[4:5], v[4:5], v[190:191]
	v_pk_mul_f32 v[6:7], v[6:7], v[192:193]
	v_cvt_pk_bf16_f32 v198, v12, v13
	v_cvt_pk_bf16_f32 v199, v14, v15
	v_cvt_pk_bf16_f32 v200, v4, v5
	v_cvt_pk_bf16_f32 v201, v6, v7
	global_store_dwordx4 v[204:205], v[198:201], off offset:2048 sc1
	s_cbranch_vccnz .LBB0_806
	s_and_b64 vcc, exec, s[16:17]
	s_cbranch_vccnz .LBB0_805
	s_barrier
	s_branch .LBB0_805

;     __device__ __forceinline__ void operator()(f32x4 (&acc)[2][2][4][2], const Unit& u_, int wr, int wc, int fr, int fq) const {
;     ...
;         const int row0 = u.pm * BM + wr * 64 + fr, col0 = u.pn * BM + wc * 32 + 8 * fq;
;         u32x4 xw[2][4][2]; f32x4 xf[XF32 ? 16 : 1][2];
; #pragma unroll
;         for (int ai = 0; ai < 2; ++ai)
; #pragma unroll
;             for (int m = 0; m < 4; ++m)
; #pragma unroll
;                 for (int bj = 0; bj < 2; ++bj) { const size_t off = (size_t)(row0 + ai * HALF + m * 16) * 2048 + col0 + bj * HALF;
;                     if constexpr (XF32) { xf[(ai * 4 + m) * 2 + bj][0] = *(const f32x4*)(xin + off); xf[(ai * 4 + m) * 2 + bj][1] = *(const f32x4*)(xin + off + 4); }
;                     else if constexpr (BATCH) xw[ai][m][bj] = *(const u32x4*)(xb + off); }
; #pragma unroll
;         for (int ai = 0; ai < 2; ++ai)
; #pragma unroll
;             for (int m = 0; m < 4; ++m) {
;                 const int row = row0 + ai * HALF + m * 16; const size_t off = (size_t)row * 2048 + col0;
;                 float sc = alpha; if constexpr (MODE == 1) sc = rstd_of(ssb[row], 1.0f / 1024.0f);
;                 float q = 0.f;
; #pragma unroll
;                 for (int bj = 0; bj < 2; ++bj) {
;                     f32x4 x0, x1;
;                     if constexpr (XF32) { x0 = xf[(ai * 4 + m) * 2 + bj][0]; x1 = xf[(ai * 4 + m) * 2 + bj][1]; }
;                     else { const u32x4 w = BATCH ? xw[ai][m][bj] : *(const u32x4*)(xb + off + bj * HALF); x0 = (f32x4){bf_lo(w.x), bf_hi(w.x), bf_lo(w.y), bf_hi(w.y)}; x1 = (f32x4){bf_lo(w.z), bf_hi(w.z), bf_lo(w.w), bf_hi(w.w)}; }
;                     const f32x4 v0 = x0 + acc[ai][bj][m][0] * sc, v1 = x1 + acc[ai][bj][m][1] * sc;
;                     *(u32x4*)(xb + off + bj * HALF) = pack8(v0, v1);
;                     if (x8) { typedef unsigned u32x2 __attribute__((ext_vector_type(2))); u32x2 w8; w8.x = pack4_fp8(v0[0] * F8_X_SCALE, v0[1] * F8_X_SCALE, v0[2] * F8_X_SCALE, v0[3] * F8_X_SCALE);
;                         w8.y = pack4_fp8(v1[0] * F8_X_SCALE, v1[1] * F8_X_SCALE, v1[2] * F8_X_SCALE, v1[3] * F8_X_SCALE); *(u32x2*)(x8 + off + bj * HALF) = w8; }
;                     q += sumsq4(v0) + sumsq4(v1);
;                 }
;                 q += __shfl_xor(q, 16); q += __shfl_xor(q, 32);
;                 if (fq == 0 && ssout) atomicAdd(ssout + row, q);
.LBB0_897:
	v_lshl_add_u32 v190, s59, 8, v229
	v_lshl_add_u32 v220, s58, 8, v226
	v_ashrrev_i32_e32 v191, 31, v190
	v_lshlrev_b64 v[242:243], 1, v[190:191]
	v_ashrrev_i32_e32 v221, 31, v220
	v_lshl_add_u64 v[104:105], s[28:29], 0, v[242:243]
	v_lshlrev_b64 v[244:245], 12, v[220:221]
	v_lshl_add_u64 v[106:107], v[104:105], 0, v[244:245]
	global_load_dwordx4 v[234:237], v[106:107], off
	global_load_dwordx4 v[238:241], v[106:107], off offset:256
	v_or_b32_e32 v216, 16, v220
	v_or_b32_e32 v212, 32, v220
	v_or_b32_e32 v208, 48, v220
	v_add_u32_e32 v204, 0x80, v220
	v_add_u32_e32 v200, 0x90, v220
	v_add_u32_e32 v196, 0xa0, v220
	v_add_u32_e32 v192, 0xb0, v220
	v_ashrrev_i32_e32 v217, 31, v216
	v_ashrrev_i32_e32 v213, 31, v212
	v_ashrrev_i32_e32 v209, 31, v208
	v_ashrrev_i32_e32 v205, 31, v204
	v_ashrrev_i32_e32 v201, 31, v200
	v_ashrrev_i32_e32 v197, 31, v196
	v_ashrrev_i32_e32 v193, 31, v192
	v_lshlrev_b64 v[218:219], 12, v[216:217]
	v_lshlrev_b64 v[214:215], 12, v[212:213]
	v_lshlrev_b64 v[210:211], 12, v[208:209]
	v_lshlrev_b64 v[206:207], 12, v[204:205]
	v_lshlrev_b64 v[202:203], 12, v[200:201]
	v_lshlrev_b64 v[198:199], 12, v[196:197]
	v_lshlrev_b64 v[194:195], 12, v[192:193]
	v_lshl_add_u64 v[106:107], v[104:105], 0, v[218:219]
	v_lshl_add_u64 v[116:117], v[104:105], 0, v[214:215]
	v_lshl_add_u64 v[118:119], v[104:105], 0, v[210:211]
	v_lshl_add_u64 v[128:129], v[104:105], 0, v[206:207]
	v_lshl_add_u64 v[130:131], v[104:105], 0, v[202:203]
	v_lshl_add_u64 v[246:247], v[104:105], 0, v[198:199]
	v_lshl_add_u64 v[104:105], v[104:105], 0, v[194:195]
	global_load_dwordx4 v[180:183], v[106:107], off
	global_load_dwordx4 v[176:179], v[106:107], off offset:256
	global_load_dwordx4 v[172:175], v[116:117], off
	global_load_dwordx4 v[168:171], v[116:117], off offset:256
	global_load_dwordx4 v[164:167], v[118:119], off
	global_load_dwordx4 v[160:163], v[118:119], off offset:256
	global_load_dwordx4 v[156:159], v[128:129], off
	global_load_dwordx4 v[152:155], v[128:129], off offset:256
	global_load_dwordx4 v[148:151], v[130:131], off
	global_load_dwordx4 v[144:147], v[130:131], off offset:256
	global_load_dwordx4 v[140:143], v[246:247], off
	s_nop 0
	global_load_dwordx4 v[128:131], v[246:247], off offset:256
	global_load_dwordx4 v[116:119], v[104:105], off
	s_nop 0
	global_load_dwordx4 v[104:107], v[104:105], off offset:256
	s_waitcnt vmcnt(0)
	v_lshlrev_b32_e32 v246, 16, v234
	v_and_b32_e32 v247, 0xffff0000, v234
	v_lshlrev_b32_e32 v234, 16, v235
	v_and_b32_e32 v235, 0xffff0000, v235
	v_lshlrev_b32_e32 v248, 16, v236
	v_and_b32_e32 v249, 0xffff0000, v236
	v_lshlrev_b32_e32 v236, 16, v237
	v_and_b32_e32 v237, 0xffff0000, v237
	v_lshlrev_b32_e32 v250, 16, v238
	v_and_b32_e32 v251, 0xffff0000, v238
	v_lshlrev_b32_e32 v238, 16, v239
	v_and_b32_e32 v239, 0xffff0000, v239
	v_lshlrev_b32_e32 v252, 16, v240
	v_and_b32_e32 v253, 0xffff0000, v240
	v_lshlrev_b32_e32 v240, 16, v241
	v_and_b32_e32 v241, 0xffff0000, v241
	v_pk_fma_f32 v[138:139], v[138:139], 0.5, v[234:235] op_sel_hi:[1,0,1]
	v_pk_fma_f32 v[136:137], v[136:137], 0.5, v[246:247] op_sel_hi:[1,0,1]
	v_pk_fma_f32 v[134:135], v[134:135], 0.5, v[236:237] op_sel_hi:[1,0,1]
	v_pk_fma_f32 v[132:133], v[132:133], 0.5, v[248:249] op_sel_hi:[1,0,1]
	v_pk_fma_f32 v[126:127], v[126:127], 0.5, v[238:239] op_sel_hi:[1,0,1]
	v_pk_fma_f32 v[234:235], v[124:125], 0.5, v[250:251] op_sel_hi:[1,0,1]
	v_pk_fma_f32 v[236:237], v[122:123], 0.5, v[240:241] op_sel_hi:[1,0,1]
	v_pk_fma_f32 v[238:239], v[120:121], 0.5, v[252:253] op_sel_hi:[1,0,1]
	v_cvt_pk_bf16_f32 v122, v136, v137
	v_cvt_pk_bf16_f32 v123, v138, v139
	v_cvt_pk_bf16_f32 v124, v132, v133
	v_cvt_pk_bf16_f32 v125, v134, v135
	v_mul_f32_e32 v120, v137, v137
	v_mul_f32_e32 v121, v139, v139
	v_mul_f32_e32 v133, v133, v133
	v_mul_f32_e32 v135, v135, v135
	v_fmac_f32_e32 v120, v136, v136
	v_fmac_f32_e32 v121, v138, v138
	v_fmac_f32_e32 v133, v132, v132
	v_fmac_f32_e32 v135, v134, v134
	v_add_f32_e32 v120, v120, v121
	v_add_f32_e32 v121, v133, v135
	v_add_f32_e32 v120, v120, v121
	v_mul_f32_e32 v121, v235, v235
	v_mul_f32_e32 v132, v127, v127
	v_fmac_f32_e32 v121, v234, v234
	v_fmac_f32_e32 v132, v126, v126
	v_add_f32_e32 v121, v121, v132
	v_mul_f32_e32 v132, v239, v239
	v_mul_f32_e32 v133, v237, v237
	v_fmac_f32_e32 v132, v238, v238
	v_fmac_f32_e32 v133, v236, v236
	v_add_f32_e32 v132, v132, v133
	v_add_f32_e32 v121, v121, v132
	v_and_b32_e32 v132, 64, v233
	v_add_f32_e32 v121, v120, v121
	v_xor_b32_e32 v120, 16, v233
	v_add_u32_e32 v134, 64, v132
	v_cmp_lt_i32_e32 vcc, v120, v134
	v_lshl_add_u64 v[132:133], s[28:29], 0, v[244:245]
	v_lshl_add_u64 v[132:133], v[132:133], 0, v[242:243]
	v_cndmask_b32_e32 v120, v233, v120, vcc
	v_lshlrev_b32_e32 v120, 2, v120
	ds_bpermute_b32 v135, v120, v121
	global_store_dwordx4 v[132:133], v[122:125], off sc1
	s_nop 1
	v_cvt_pk_bf16_f32 v124, v234, v235
	s_waitcnt lgkmcnt(0)
	v_add_f32_e32 v122, v121, v135
	v_xor_b32_e32 v121, 32, v233
	v_cmp_lt_i32_e32 vcc, v121, v134
	v_cvt_pk_bf16_f32 v125, v126, v127
	v_cvt_pk_bf16_f32 v126, v238, v239
	v_cvt_pk_bf16_f32 v127, v236, v237
	global_store_dwordx4 v[132:133], v[124:127], off offset:256 sc1
	s_nop 0
	v_cndmask_b32_e32 v121, v233, v121, vcc
	v_lshlrev_b32_e32 v121, 2, v121
	ds_bpermute_b32 v123, v121, v122
	s_and_saveexec_b64 s[44:45], s[8:9]
	s_cbranch_execz .LBB0_899
	s_waitcnt lgkmcnt(0)
	v_add_f32_e32 v124, v122, v123
	v_lshl_add_u64 v[122:123], v[220:221], 2, s[38:39]
	global_atomic_add_f32 v[122:123], v124, off
; __device__ __forceinline__ float rstd_of(float ss, float inv_n) { return __builtin_amdgcn_rsqf(ss * inv_n + 1e-6f); }
; __device__ __forceinline__ float bf_lo(unsigned w) { return __uint_as_float(w << 16); }
; __device__ __forceinline__ float bf_hi(unsigned w) { return __uint_as_float(w & 0xffff0000u); }
; __device__ __forceinline__ u32x4 pack8(const f32x4 a, const f32x4 b) { u32x4 w; w.x = cvt_pk_bf16(a[0], a[1]); w.y = cvt_pk_bf16(a[2], a[3]); w.z = cvt_pk_bf16(b[0], b[1]); w.w = cvt_pk_bf16(b[2], b[3]); return w; }
; __device__ __forceinline__ float sumsq4(const f32x4 a) { return (a[0] * a[0] + a[1] * a[1]) + (a[2] * a[2] + a[3] * a[3]); }
;     __device__ __forceinline__ void operator()(f32x4 (&acc)[2][2][4][2], const Unit& u_, int wr, int wc, int fr, int fq) const {
;     ...
;         for (int ai = 0; ai < 2; ++ai)
; #pragma unroll
;             for (int m = 0; m < 4; ++m) {
;                 const int row = row0 + ai * HALF + m * 16; const size_t off = (size_t)row * 2048 + col0;
;                 float sc = alpha; if constexpr (MODE == 1) sc = rstd_of(ssb[row], 1.0f / 1024.0f);
;                 float q = 0.f;
; #pragma unroll
;                 for (int bj = 0; bj < 2; ++bj) {
;                     f32x4 x0, x1;
;                     if constexpr (XF32) { x0 = xf[(ai * 4 + m) * 2 + bj][0]; x1 = xf[(ai * 4 + m) * 2 + bj][1]; }
;                     else { const u32x4 w = BATCH ? xw[ai][m][bj] : *(const u32x4*)(xb + off + bj * HALF); x0 = (f32x4){bf_lo(w.x), bf_hi(w.x), bf_lo(w.y), bf_hi(w.y)}; x1 = (f32x4){bf_lo(w.z), bf_hi(w.z), bf_lo(w.w), bf_hi(w.w)}; }
;                     const f32x4 v0 = x0 + acc[ai][bj][m][0] * sc, v1 = x1 + acc[ai][bj][m][1] * sc;
;                     *(u32x4*)(xb + off + bj * HALF) = pack8(v0, v1);
;                     if (x8) { typedef unsigned u32x2 __attribute__((ext_vector_type(2))); u32x2 w8; w8.x = pack4_fp8(v0[0] * F8_X_SCALE, v0[1] * F8_X_SCALE, v0[2] * F8_X_SCALE, v0[3] * F8_X_SCALE);
;                         w8.y = pack4_fp8(v1[0] * F8_X_SCALE, v1[1] * F8_X_SCALE, v1[2] * F8_X_SCALE, v1[3] * F8_X_SCALE); *(u32x2*)(x8 + off + bj * HALF) = w8; }
;                     q += sumsq4(v0) + sumsq4(v1);
;                 }
;                 q += __shfl_xor(q, 16); q += __shfl_xor(q, 32);
;                 if (fq == 0 && ssout) atomicAdd(ssout + row, q);
.LBB0_899:
	s_or_b64 exec, exec, s[44:45]
	v_lshlrev_b32_e32 v122, 16, v180
	s_waitcnt lgkmcnt(0)
	v_and_b32_e32 v123, 0xffff0000, v180
	v_lshlrev_b32_e32 v124, 16, v181
	v_and_b32_e32 v125, 0xffff0000, v181
	v_lshlrev_b32_e32 v126, 16, v182
	v_and_b32_e32 v127, 0xffff0000, v182
	v_pk_fma_f32 v[112:113], v[112:113], 0.5, v[122:123] op_sel_hi:[1,0,1]
	v_pk_fma_f32 v[114:115], v[114:115], 0.5, v[124:125] op_sel_hi:[1,0,1]
	v_pk_fma_f32 v[124:125], v[108:109], 0.5, v[126:127] op_sel_hi:[1,0,1]
	v_cvt_pk_bf16_f32 v108, v112, v113
	v_mul_f32_e32 v113, v113, v113
	v_lshlrev_b32_e32 v132, 16, v183
	v_and_b32_e32 v133, 0xffff0000, v183
	v_fmac_f32_e32 v113, v112, v112
	v_mul_f32_e32 v112, v115, v115
	v_pk_fma_f32 v[122:123], v[110:111], 0.5, v[132:133] op_sel_hi:[1,0,1]
	v_fmac_f32_e32 v112, v114, v114
	v_cvt_pk_bf16_f32 v109, v114, v115
	v_add_f32_e32 v112, v113, v112
	v_mul_f32_e32 v113, v125, v125
	v_mul_f32_e32 v114, v123, v123
	v_fmac_f32_e32 v113, v124, v124
	v_fmac_f32_e32 v114, v122, v122
	v_add_f32_e32 v113, v113, v114
	v_add_f32_e32 v126, v112, v113
	v_lshlrev_b32_e32 v112, 16, v176
	v_and_b32_e32 v113, 0xffff0000, v176
	v_lshlrev_b32_e32 v114, 16, v177
	v_and_b32_e32 v115, 0xffff0000, v177
	v_cvt_pk_bf16_f32 v110, v124, v125
	v_cvt_pk_bf16_f32 v111, v122, v123
	v_lshlrev_b32_e32 v122, 16, v178
	v_and_b32_e32 v123, 0xffff0000, v178
	v_pk_fma_f32 v[102:103], v[102:103], 0.5, v[114:115] op_sel_hi:[1,0,1]
	v_pk_fma_f32 v[100:101], v[100:101], 0.5, v[112:113] op_sel_hi:[1,0,1]
	v_lshlrev_b32_e32 v124, 16, v179
	v_and_b32_e32 v125, 0xffff0000, v179
	v_pk_fma_f32 v[114:115], v[96:97], 0.5, v[122:123] op_sel_hi:[1,0,1]
	v_mul_f32_e32 v96, v101, v101
	v_mul_f32_e32 v97, v103, v103
	v_pk_fma_f32 v[112:113], v[98:99], 0.5, v[124:125] op_sel_hi:[1,0,1]
	v_fmac_f32_e32 v96, v100, v100
	v_fmac_f32_e32 v97, v102, v102
	v_add_f32_e32 v96, v96, v97
	v_mul_f32_e32 v97, v115, v115
	v_mul_f32_e32 v98, v113, v113
	v_fmac_f32_e32 v97, v114, v114
	v_fmac_f32_e32 v98, v112, v112
	v_add_f32_e32 v97, v97, v98
	v_add_f32_e32 v96, v96, v97
	v_add_f32_e32 v99, v126, v96
	ds_bpermute_b32 v124, v120, v99
	v_lshl_add_u64 v[96:97], s[28:29], 0, v[218:219]
	v_lshl_add_u64 v[122:123], v[190:191], 1, v[96:97]
	global_store_dwordx4 v[122:123], v[108:111], off sc1
	v_cvt_pk_bf16_f32 v98, v100, v101
	s_waitcnt lgkmcnt(0)
	v_add_f32_e32 v96, v99, v124
	ds_bpermute_b32 v97, v121, v96
	v_cvt_pk_bf16_f32 v99, v102, v103
	v_cvt_pk_bf16_f32 v100, v114, v115
	v_cvt_pk_bf16_f32 v101, v112, v113
	global_store_dwordx4 v[122:123], v[98:101], off offset:256 sc1
	s_and_saveexec_b64 s[44:45], s[8:9]
	s_cbranch_execz .LBB0_901
	s_waitcnt lgkmcnt(0)
	v_add_f32_e32 v98, v96, v97
	v_lshl_add_u64 v[96:97], v[216:217], 2, s[38:39]
	global_atomic_add_f32 v[96:97], v98, off
.LBB0_901:
	s_or_b64 exec, exec, s[44:45]
	v_lshlrev_b32_e32 v96, 16, v172
	s_waitcnt lgkmcnt(0)
	v_and_b32_e32 v97, 0xffff0000, v172
	v_lshlrev_b32_e32 v98, 16, v173
	v_and_b32_e32 v99, 0xffff0000, v173
	v_lshlrev_b32_e32 v100, 16, v174
	v_and_b32_e32 v101, 0xffff0000, v174
	v_pk_fma_f32 v[92:93], v[92:93], 0.5, v[96:97] op_sel_hi:[1,0,1]
	v_pk_fma_f32 v[94:95], v[94:95], 0.5, v[98:99] op_sel_hi:[1,0,1]
	v_pk_fma_f32 v[98:99], v[88:89], 0.5, v[100:101] op_sel_hi:[1,0,1]
	v_cvt_pk_bf16_f32 v88, v92, v93
	v_mul_f32_e32 v93, v93, v93
	v_lshlrev_b32_e32 v102, 16, v175
	v_and_b32_e32 v103, 0xffff0000, v175
	v_fmac_f32_e32 v93, v92, v92
	v_mul_f32_e32 v92, v95, v95
	v_pk_fma_f32 v[96:97], v[90:91], 0.5, v[102:103] op_sel_hi:[1,0,1]
	v_fmac_f32_e32 v92, v94, v94
	v_cvt_pk_bf16_f32 v89, v94, v95
	v_add_f32_e32 v92, v93, v92
	v_mul_f32_e32 v93, v99, v99
	v_mul_f32_e32 v94, v97, v97
	v_fmac_f32_e32 v93, v98, v98
	v_fmac_f32_e32 v94, v96, v96
	v_add_f32_e32 v93, v93, v94
	v_add_f32_e32 v100, v92, v93
	v_lshlrev_b32_e32 v92, 16, v168
	v_and_b32_e32 v93, 0xffff0000, v168
	v_lshlrev_b32_e32 v94, 16, v169
	v_and_b32_e32 v95, 0xffff0000, v169
	v_cvt_pk_bf16_f32 v90, v98, v99
	v_cvt_pk_bf16_f32 v91, v96, v97
	v_lshlrev_b32_e32 v96, 16, v170
	v_and_b32_e32 v97, 0xffff0000, v170
	v_pk_fma_f32 v[86:87], v[86:87], 0.5, v[94:95] op_sel_hi:[1,0,1]
	v_pk_fma_f32 v[84:85], v[84:85], 0.5, v[92:93] op_sel_hi:[1,0,1]
	v_lshlrev_b32_e32 v98, 16, v171
	v_and_b32_e32 v99, 0xffff0000, v171
	v_pk_fma_f32 v[94:95], v[80:81], 0.5, v[96:97] op_sel_hi:[1,0,1]
	v_mul_f32_e32 v80, v85, v85
	v_mul_f32_e32 v81, v87, v87
	v_pk_fma_f32 v[92:93], v[82:83], 0.5, v[98:99] op_sel_hi:[1,0,1]
	v_fmac_f32_e32 v80, v84, v84
	v_fmac_f32_e32 v81, v86, v86
	v_add_f32_e32 v80, v80, v81
	v_mul_f32_e32 v81, v95, v95
	v_mul_f32_e32 v82, v93, v93
	v_fmac_f32_e32 v81, v94, v94
	v_fmac_f32_e32 v82, v92, v92
	v_add_f32_e32 v81, v81, v82
	v_add_f32_e32 v80, v80, v81
	v_add_f32_e32 v83, v100, v80
	ds_bpermute_b32 v98, v120, v83
	v_lshl_add_u64 v[80:81], s[28:29], 0, v[214:215]
	v_lshl_add_u64 v[96:97], v[190:191], 1, v[80:81]
	global_store_dwordx4 v[96:97], v[88:91], off sc1
	v_cvt_pk_bf16_f32 v82, v84, v85
	s_waitcnt lgkmcnt(0)
	v_add_f32_e32 v80, v83, v98
	ds_bpermute_b32 v81, v121, v80
	v_cvt_pk_bf16_f32 v83, v86, v87
	v_cvt_pk_bf16_f32 v84, v94, v95
	v_cvt_pk_bf16_f32 v85, v92, v93
	global_store_dwordx4 v[96:97], v[82:85], off offset:256 sc1
	s_and_saveexec_b64 s[44:45], s[8:9]
	s_cbranch_execz .LBB0_903
	s_waitcnt lgkmcnt(0)
	v_add_f32_e32 v82, v80, v81
	v_lshl_add_u64 v[80:81], v[212:213], 2, s[38:39]
	global_atomic_add_f32 v[80:81], v82, off
; __device__ __forceinline__ float rstd_of(float ss, float inv_n) { return __builtin_amdgcn_rsqf(ss * inv_n + 1e-6f); }
; __device__ __forceinline__ float bf_lo(unsigned w) { return __uint_as_float(w << 16); }
; __device__ __forceinline__ float bf_hi(unsigned w) { return __uint_as_float(w & 0xffff0000u); }
; __device__ __forceinline__ u32x4 pack8(const f32x4 a, const f32x4 b) { u32x4 w; w.x = cvt_pk_bf16(a[0], a[1]); w.y = cvt_pk_bf16(a[2], a[3]); w.z = cvt_pk_bf16(b[0], b[1]); w.w = cvt_pk_bf16(b[2], b[3]); return w; }
; __device__ __forceinline__ float sumsq4(const f32x4 a) { return (a[0] * a[0] + a[1] * a[1]) + (a[2] * a[2] + a[3] * a[3]); }
;     __device__ __forceinline__ void operator()(f32x4 (&acc)[2][2][4][2], const Unit& u_, int wr, int wc, int fr, int fq) const {
;     ...
;         for (int ai = 0; ai < 2; ++ai)
; #pragma unroll
;             for (int m = 0; m < 4; ++m) {
;                 const int row = row0 + ai * HALF + m * 16; const size_t off = (size_t)row * 2048 + col0;
;                 float sc = alpha; if constexpr (MODE == 1) sc = rstd_of(ssb[row], 1.0f / 1024.0f);
;                 float q = 0.f;
; #pragma unroll
;                 for (int bj = 0; bj < 2; ++bj) {
;                     f32x4 x0, x1;
;                     if constexpr (XF32) { x0 = xf[(ai * 4 + m) * 2 + bj][0]; x1 = xf[(ai * 4 + m) * 2 + bj][1]; }
;                     else { const u32x4 w = BATCH ? xw[ai][m][bj] : *(const u32x4*)(xb + off + bj * HALF); x0 = (f32x4){bf_lo(w.x), bf_hi(w.x), bf_lo(w.y), bf_hi(w.y)}; x1 = (f32x4){bf_lo(w.z), bf_hi(w.z), bf_lo(w.w), bf_hi(w.w)}; }
;                     const f32x4 v0 = x0 + acc[ai][bj][m][0] * sc, v1 = x1 + acc[ai][bj][m][1] * sc;
;                     *(u32x4*)(xb + off + bj * HALF) = pack8(v0, v1);
;                     if (x8) { typedef unsigned u32x2 __attribute__((ext_vector_type(2))); u32x2 w8; w8.x = pack4_fp8(v0[0] * F8_X_SCALE, v0[1] * F8_X_SCALE, v0[2] * F8_X_SCALE, v0[3] * F8_X_SCALE);
;                         w8.y = pack4_fp8(v1[0] * F8_X_SCALE, v1[1] * F8_X_SCALE, v1[2] * F8_X_SCALE, v1[3] * F8_X_SCALE); *(u32x2*)(x8 + off + bj * HALF) = w8; }
;                     q += sumsq4(v0) + sumsq4(v1);
;                 }
;                 q += __shfl_xor(q, 16); q += __shfl_xor(q, 32);
;                 if (fq == 0 && ssout) atomicAdd(ssout + row, q);
.LBB0_903:
	s_or_b64 exec, exec, s[44:45]
	v_lshlrev_b32_e32 v80, 16, v164
	s_waitcnt lgkmcnt(0)
	v_and_b32_e32 v81, 0xffff0000, v164
	v_lshlrev_b32_e32 v82, 16, v165
	v_and_b32_e32 v83, 0xffff0000, v165
	v_lshlrev_b32_e32 v84, 16, v166
	v_and_b32_e32 v85, 0xffff0000, v166
	v_pk_fma_f32 v[76:77], v[76:77], 0.5, v[80:81] op_sel_hi:[1,0,1]
	v_pk_fma_f32 v[78:79], v[78:79], 0.5, v[82:83] op_sel_hi:[1,0,1]
	v_pk_fma_f32 v[82:83], v[72:73], 0.5, v[84:85] op_sel_hi:[1,0,1]
	v_cvt_pk_bf16_f32 v72, v76, v77
	v_mul_f32_e32 v77, v77, v77
	v_lshlrev_b32_e32 v86, 16, v167
	v_and_b32_e32 v87, 0xffff0000, v167
	v_fmac_f32_e32 v77, v76, v76
	v_mul_f32_e32 v76, v79, v79
	v_pk_fma_f32 v[80:81], v[74:75], 0.5, v[86:87] op_sel_hi:[1,0,1]
	v_fmac_f32_e32 v76, v78, v78
	v_cvt_pk_bf16_f32 v73, v78, v79
	v_add_f32_e32 v76, v77, v76
	v_mul_f32_e32 v77, v83, v83
	v_mul_f32_e32 v78, v81, v81
	v_fmac_f32_e32 v77, v82, v82
	v_fmac_f32_e32 v78, v80, v80
	v_add_f32_e32 v77, v77, v78
	v_add_f32_e32 v84, v76, v77
	v_lshlrev_b32_e32 v76, 16, v160
	v_and_b32_e32 v77, 0xffff0000, v160
	v_lshlrev_b32_e32 v78, 16, v161
	v_and_b32_e32 v79, 0xffff0000, v161
	v_cvt_pk_bf16_f32 v74, v82, v83
	v_cvt_pk_bf16_f32 v75, v80, v81
	v_lshlrev_b32_e32 v80, 16, v162
	v_and_b32_e32 v81, 0xffff0000, v162
	v_pk_fma_f32 v[70:71], v[70:71], 0.5, v[78:79] op_sel_hi:[1,0,1]
	v_pk_fma_f32 v[68:69], v[68:69], 0.5, v[76:77] op_sel_hi:[1,0,1]
	v_lshlrev_b32_e32 v82, 16, v163
	v_and_b32_e32 v83, 0xffff0000, v163
	v_pk_fma_f32 v[78:79], v[64:65], 0.5, v[80:81] op_sel_hi:[1,0,1]
	v_mul_f32_e32 v64, v69, v69
	v_mul_f32_e32 v65, v71, v71
	v_pk_fma_f32 v[76:77], v[66:67], 0.5, v[82:83] op_sel_hi:[1,0,1]
	v_fmac_f32_e32 v64, v68, v68
	v_fmac_f32_e32 v65, v70, v70
	v_add_f32_e32 v64, v64, v65
	v_mul_f32_e32 v65, v79, v79
	v_mul_f32_e32 v66, v77, v77
	v_fmac_f32_e32 v65, v78, v78
	v_fmac_f32_e32 v66, v76, v76
	v_add_f32_e32 v65, v65, v66
	v_add_f32_e32 v64, v64, v65
	v_add_f32_e32 v67, v84, v64
	ds_bpermute_b32 v82, v120, v67
	v_lshl_add_u64 v[64:65], s[28:29], 0, v[210:211]
	v_lshl_add_u64 v[80:81], v[190:191], 1, v[64:65]
	global_store_dwordx4 v[80:81], v[72:75], off sc1
	v_cvt_pk_bf16_f32 v66, v68, v69
	s_waitcnt lgkmcnt(0)
	v_add_f32_e32 v64, v67, v82
	ds_bpermute_b32 v65, v121, v64
	v_cvt_pk_bf16_f32 v67, v70, v71
	v_cvt_pk_bf16_f32 v68, v78, v79
	v_cvt_pk_bf16_f32 v69, v76, v77
	global_store_dwordx4 v[80:81], v[66:69], off offset:256 sc1
	s_and_saveexec_b64 s[44:45], s[8:9]
	s_cbranch_execz .LBB0_905
	s_waitcnt lgkmcnt(0)
	v_add_f32_e32 v66, v64, v65
	v_lshl_add_u64 v[64:65], v[208:209], 2, s[38:39]
	global_atomic_add_f32 v[64:65], v66, off
.LBB0_905:
	s_or_b64 exec, exec, s[44:45]
	v_lshlrev_b32_e32 v64, 16, v156
	s_waitcnt lgkmcnt(0)
	v_and_b32_e32 v65, 0xffff0000, v156
	v_lshlrev_b32_e32 v66, 16, v157
	v_and_b32_e32 v67, 0xffff0000, v157
	v_lshlrev_b32_e32 v68, 16, v158
	v_and_b32_e32 v69, 0xffff0000, v158
	v_pk_fma_f32 v[60:61], v[60:61], 0.5, v[64:65] op_sel_hi:[1,0,1]
	v_pk_fma_f32 v[62:63], v[62:63], 0.5, v[66:67] op_sel_hi:[1,0,1]
	v_pk_fma_f32 v[66:67], v[56:57], 0.5, v[68:69] op_sel_hi:[1,0,1]
	v_cvt_pk_bf16_f32 v56, v60, v61
	v_mul_f32_e32 v61, v61, v61
	v_lshlrev_b32_e32 v70, 16, v159
	v_and_b32_e32 v71, 0xffff0000, v159
	v_fmac_f32_e32 v61, v60, v60
	v_mul_f32_e32 v60, v63, v63
	v_pk_fma_f32 v[64:65], v[58:59], 0.5, v[70:71] op_sel_hi:[1,0,1]
	v_fmac_f32_e32 v60, v62, v62
	v_cvt_pk_bf16_f32 v57, v62, v63
	v_add_f32_e32 v60, v61, v60
	v_mul_f32_e32 v61, v67, v67
	v_mul_f32_e32 v62, v65, v65
	v_fmac_f32_e32 v61, v66, v66
	v_fmac_f32_e32 v62, v64, v64
	v_add_f32_e32 v61, v61, v62
	v_add_f32_e32 v68, v60, v61
	v_lshlrev_b32_e32 v60, 16, v152
	v_and_b32_e32 v61, 0xffff0000, v152
	v_lshlrev_b32_e32 v62, 16, v153
	v_and_b32_e32 v63, 0xffff0000, v153
	v_cvt_pk_bf16_f32 v58, v66, v67
	v_cvt_pk_bf16_f32 v59, v64, v65
	v_lshlrev_b32_e32 v64, 16, v154
	v_and_b32_e32 v65, 0xffff0000, v154
	v_pk_fma_f32 v[54:55], v[54:55], 0.5, v[62:63] op_sel_hi:[1,0,1]
	v_pk_fma_f32 v[52:53], v[52:53], 0.5, v[60:61] op_sel_hi:[1,0,1]
	v_lshlrev_b32_e32 v66, 16, v155
	v_and_b32_e32 v67, 0xffff0000, v155
	v_pk_fma_f32 v[62:63], v[48:49], 0.5, v[64:65] op_sel_hi:[1,0,1]
	v_mul_f32_e32 v48, v53, v53
	v_mul_f32_e32 v49, v55, v55
	v_pk_fma_f32 v[60:61], v[50:51], 0.5, v[66:67] op_sel_hi:[1,0,1]
	v_fmac_f32_e32 v48, v52, v52
	v_fmac_f32_e32 v49, v54, v54
	v_add_f32_e32 v48, v48, v49
	v_mul_f32_e32 v49, v63, v63
	v_mul_f32_e32 v50, v61, v61
	v_fmac_f32_e32 v49, v62, v62
	v_fmac_f32_e32 v50, v60, v60
	v_add_f32_e32 v49, v49, v50
	v_add_f32_e32 v48, v48, v49
	v_add_f32_e32 v51, v68, v48
	ds_bpermute_b32 v66, v120, v51
	v_lshl_add_u64 v[48:49], s[28:29], 0, v[206:207]
	v_lshl_add_u64 v[64:65], v[190:191], 1, v[48:49]
	global_store_dwordx4 v[64:65], v[56:59], off sc1
	v_cvt_pk_bf16_f32 v50, v52, v53
	s_waitcnt lgkmcnt(0)
	v_add_f32_e32 v48, v51, v66
	ds_bpermute_b32 v49, v121, v48
	v_cvt_pk_bf16_f32 v51, v54, v55
	v_cvt_pk_bf16_f32 v52, v62, v63
	v_cvt_pk_bf16_f32 v53, v60, v61
	global_store_dwordx4 v[64:65], v[50:53], off offset:256 sc1
	s_and_saveexec_b64 s[44:45], s[8:9]
	s_cbranch_execz .LBB0_907
	s_waitcnt lgkmcnt(0)
	v_add_f32_e32 v50, v48, v49
	v_lshl_add_u64 v[48:49], v[204:205], 2, s[38:39]
	global_atomic_add_f32 v[48:49], v50, off
; __device__ __forceinline__ float rstd_of(float ss, float inv_n) { return __builtin_amdgcn_rsqf(ss * inv_n + 1e-6f); }
; __device__ __forceinline__ float bf_lo(unsigned w) { return __uint_as_float(w << 16); }
; __device__ __forceinline__ float bf_hi(unsigned w) { return __uint_as_float(w & 0xffff0000u); }
; __device__ __forceinline__ u32x4 pack8(const f32x4 a, const f32x4 b) { u32x4 w; w.x = cvt_pk_bf16(a[0], a[1]); w.y = cvt_pk_bf16(a[2], a[3]); w.z = cvt_pk_bf16(b[0], b[1]); w.w = cvt_pk_bf16(b[2], b[3]); return w; }
; __device__ __forceinline__ float sumsq4(const f32x4 a) { return (a[0] * a[0] + a[1] * a[1]) + (a[2] * a[2] + a[3] * a[3]); }
;     __device__ __forceinline__ void operator()(f32x4 (&acc)[2][2][4][2], const Unit& u_, int wr, int wc, int fr, int fq) const {
;     ...
;         for (int ai = 0; ai < 2; ++ai)
; #pragma unroll
;             for (int m = 0; m < 4; ++m) {
;                 const int row = row0 + ai * HALF + m * 16; const size_t off = (size_t)row * 2048 + col0;
;                 float sc = alpha; if constexpr (MODE == 1) sc = rstd_of(ssb[row], 1.0f / 1024.0f);
;                 float q = 0.f;
; #pragma unroll
;                 for (int bj = 0; bj < 2; ++bj) {
;                     f32x4 x0, x1;
;                     if constexpr (XF32) { x0 = xf[(ai * 4 + m) * 2 + bj][0]; x1 = xf[(ai * 4 + m) * 2 + bj][1]; }
;                     else { const u32x4 w = BATCH ? xw[ai][m][bj] : *(const u32x4*)(xb + off + bj * HALF); x0 = (f32x4){bf_lo(w.x), bf_hi(w.x), bf_lo(w.y), bf_hi(w.y)}; x1 = (f32x4){bf_lo(w.z), bf_hi(w.z), bf_lo(w.w), bf_hi(w.w)}; }
;                     const f32x4 v0 = x0 + acc[ai][bj][m][0] * sc, v1 = x1 + acc[ai][bj][m][1] * sc;
;                     *(u32x4*)(xb + off + bj * HALF) = pack8(v0, v1);
;                     if (x8) { typedef unsigned u32x2 __attribute__((ext_vector_type(2))); u32x2 w8; w8.x = pack4_fp8(v0[0] * F8_X_SCALE, v0[1] * F8_X_SCALE, v0[2] * F8_X_SCALE, v0[3] * F8_X_SCALE);
;                         w8.y = pack4_fp8(v1[0] * F8_X_SCALE, v1[1] * F8_X_SCALE, v1[2] * F8_X_SCALE, v1[3] * F8_X_SCALE); *(u32x2*)(x8 + off + bj * HALF) = w8; }
;                     q += sumsq4(v0) + sumsq4(v1);
;                 }
;                 q += __shfl_xor(q, 16); q += __shfl_xor(q, 32);
;                 if (fq == 0 && ssout) atomicAdd(ssout + row, q);
.LBB0_907:
	s_or_b64 exec, exec, s[44:45]
	v_lshlrev_b32_e32 v48, 16, v148
	s_waitcnt lgkmcnt(0)
	v_and_b32_e32 v49, 0xffff0000, v148
	v_lshlrev_b32_e32 v50, 16, v149
	v_and_b32_e32 v51, 0xffff0000, v149
	v_lshlrev_b32_e32 v52, 16, v150
	v_and_b32_e32 v53, 0xffff0000, v150
	v_pk_fma_f32 v[44:45], v[44:45], 0.5, v[48:49] op_sel_hi:[1,0,1]
	v_pk_fma_f32 v[46:47], v[46:47], 0.5, v[50:51] op_sel_hi:[1,0,1]
	v_pk_fma_f32 v[50:51], v[40:41], 0.5, v[52:53] op_sel_hi:[1,0,1]
	v_cvt_pk_bf16_f32 v40, v44, v45
	v_mul_f32_e32 v45, v45, v45
	v_lshlrev_b32_e32 v54, 16, v151
	v_and_b32_e32 v55, 0xffff0000, v151
	v_fmac_f32_e32 v45, v44, v44
	v_mul_f32_e32 v44, v47, v47
	v_pk_fma_f32 v[48:49], v[42:43], 0.5, v[54:55] op_sel_hi:[1,0,1]
	v_fmac_f32_e32 v44, v46, v46
	v_cvt_pk_bf16_f32 v41, v46, v47
	v_add_f32_e32 v44, v45, v44
	v_mul_f32_e32 v45, v51, v51
	v_mul_f32_e32 v46, v49, v49
	v_fmac_f32_e32 v45, v50, v50
	v_fmac_f32_e32 v46, v48, v48
	v_add_f32_e32 v45, v45, v46
	v_add_f32_e32 v52, v44, v45
	v_lshlrev_b32_e32 v44, 16, v144
	v_and_b32_e32 v45, 0xffff0000, v144
	v_lshlrev_b32_e32 v46, 16, v145
	v_and_b32_e32 v47, 0xffff0000, v145
	v_cvt_pk_bf16_f32 v42, v50, v51
	v_cvt_pk_bf16_f32 v43, v48, v49
	v_lshlrev_b32_e32 v48, 16, v146
	v_and_b32_e32 v49, 0xffff0000, v146
	v_pk_fma_f32 v[38:39], v[38:39], 0.5, v[46:47] op_sel_hi:[1,0,1]
	v_pk_fma_f32 v[36:37], v[36:37], 0.5, v[44:45] op_sel_hi:[1,0,1]
	v_lshlrev_b32_e32 v50, 16, v147
	v_and_b32_e32 v51, 0xffff0000, v147
	v_pk_fma_f32 v[46:47], v[32:33], 0.5, v[48:49] op_sel_hi:[1,0,1]
	v_mul_f32_e32 v32, v37, v37
	v_mul_f32_e32 v33, v39, v39
	v_pk_fma_f32 v[44:45], v[34:35], 0.5, v[50:51] op_sel_hi:[1,0,1]
	v_fmac_f32_e32 v32, v36, v36
	v_fmac_f32_e32 v33, v38, v38
	v_add_f32_e32 v32, v32, v33
	v_mul_f32_e32 v33, v47, v47
	v_mul_f32_e32 v34, v45, v45
	v_fmac_f32_e32 v33, v46, v46
	v_fmac_f32_e32 v34, v44, v44
	v_add_f32_e32 v33, v33, v34
	v_add_f32_e32 v32, v32, v33
	v_add_f32_e32 v35, v52, v32
	ds_bpermute_b32 v50, v120, v35
	v_lshl_add_u64 v[32:33], s[28:29], 0, v[202:203]
	v_lshl_add_u64 v[48:49], v[190:191], 1, v[32:33]
	global_store_dwordx4 v[48:49], v[40:43], off sc1
	v_cvt_pk_bf16_f32 v34, v36, v37
	s_waitcnt lgkmcnt(0)
	v_add_f32_e32 v32, v35, v50
	ds_bpermute_b32 v33, v121, v32
	v_cvt_pk_bf16_f32 v35, v38, v39
	v_cvt_pk_bf16_f32 v36, v46, v47
	v_cvt_pk_bf16_f32 v37, v44, v45
	global_store_dwordx4 v[48:49], v[34:37], off offset:256 sc1
	s_and_saveexec_b64 s[44:45], s[8:9]
	s_cbranch_execz .LBB0_909
	s_waitcnt lgkmcnt(0)
	v_add_f32_e32 v34, v32, v33
	v_lshl_add_u64 v[32:33], v[200:201], 2, s[38:39]
	global_atomic_add_f32 v[32:33], v34, off
; __device__ __forceinline__ float rstd_of(float ss, float inv_n) { return __builtin_amdgcn_rsqf(ss * inv_n + 1e-6f); }
; __device__ __forceinline__ float bf_lo(unsigned w) { return __uint_as_float(w << 16); }
; __device__ __forceinline__ float bf_hi(unsigned w) { return __uint_as_float(w & 0xffff0000u); }
; __device__ __forceinline__ u32x4 pack8(const f32x4 a, const f32x4 b) { u32x4 w; w.x = cvt_pk_bf16(a[0], a[1]); w.y = cvt_pk_bf16(a[2], a[3]); w.z = cvt_pk_bf16(b[0], b[1]); w.w = cvt_pk_bf16(b[2], b[3]); return w; }
; __device__ __forceinline__ float sumsq4(const f32x4 a) { return (a[0] * a[0] + a[1] * a[1]) + (a[2] * a[2] + a[3] * a[3]); }
;     __device__ __forceinline__ void operator()(f32x4 (&acc)[2][2][4][2], const Unit& u_, int wr, int wc, int fr, int fq) const {
;     ...
;         for (int ai = 0; ai < 2; ++ai)
; #pragma unroll
;             for (int m = 0; m < 4; ++m) {
;                 const int row = row0 + ai * HALF + m * 16; const size_t off = (size_t)row * 2048 + col0;
;                 float sc = alpha; if constexpr (MODE == 1) sc = rstd_of(ssb[row], 1.0f / 1024.0f);
;                 float q = 0.f;
; #pragma unroll
;                 for (int bj = 0; bj < 2; ++bj) {
;                     f32x4 x0, x1;
;                     if constexpr (XF32) { x0 = xf[(ai * 4 + m) * 2 + bj][0]; x1 = xf[(ai * 4 + m) * 2 + bj][1]; }
;                     else { const u32x4 w = BATCH ? xw[ai][m][bj] : *(const u32x4*)(xb + off + bj * HALF); x0 = (f32x4){bf_lo(w.x), bf_hi(w.x), bf_lo(w.y), bf_hi(w.y)}; x1 = (f32x4){bf_lo(w.z), bf_hi(w.z), bf_lo(w.w), bf_hi(w.w)}; }
;                     const f32x4 v0 = x0 + acc[ai][bj][m][0] * sc, v1 = x1 + acc[ai][bj][m][1] * sc;
;                     *(u32x4*)(xb + off + bj * HALF) = pack8(v0, v1);
;                     if (x8) { typedef unsigned u32x2 __attribute__((ext_vector_type(2))); u32x2 w8; w8.x = pack4_fp8(v0[0] * F8_X_SCALE, v0[1] * F8_X_SCALE, v0[2] * F8_X_SCALE, v0[3] * F8_X_SCALE);
;                         w8.y = pack4_fp8(v1[0] * F8_X_SCALE, v1[1] * F8_X_SCALE, v1[2] * F8_X_SCALE, v1[3] * F8_X_SCALE); *(u32x2*)(x8 + off + bj * HALF) = w8; }
;                     q += sumsq4(v0) + sumsq4(v1);
;                 }
;                 q += __shfl_xor(q, 16); q += __shfl_xor(q, 32);
;                 if (fq == 0 && ssout) atomicAdd(ssout + row, q);
.LBB0_909:
	s_or_b64 exec, exec, s[44:45]
	v_lshlrev_b32_e32 v32, 16, v140
	s_waitcnt lgkmcnt(0)
	v_and_b32_e32 v33, 0xffff0000, v140
	v_lshlrev_b32_e32 v34, 16, v141
	v_and_b32_e32 v35, 0xffff0000, v141
	v_lshlrev_b32_e32 v36, 16, v142
	v_and_b32_e32 v37, 0xffff0000, v142
	v_pk_fma_f32 v[28:29], v[28:29], 0.5, v[32:33] op_sel_hi:[1,0,1]
	v_pk_fma_f32 v[30:31], v[30:31], 0.5, v[34:35] op_sel_hi:[1,0,1]
	v_pk_fma_f32 v[34:35], v[24:25], 0.5, v[36:37] op_sel_hi:[1,0,1]
	v_cvt_pk_bf16_f32 v24, v28, v29
	v_mul_f32_e32 v29, v29, v29
	v_lshlrev_b32_e32 v38, 16, v143
	v_and_b32_e32 v39, 0xffff0000, v143
	v_fmac_f32_e32 v29, v28, v28
	v_mul_f32_e32 v28, v31, v31
	v_pk_fma_f32 v[32:33], v[26:27], 0.5, v[38:39] op_sel_hi:[1,0,1]
	v_fmac_f32_e32 v28, v30, v30
	v_cvt_pk_bf16_f32 v25, v30, v31
	v_add_f32_e32 v28, v29, v28
	v_mul_f32_e32 v29, v35, v35
	v_mul_f32_e32 v30, v33, v33
	v_fmac_f32_e32 v29, v34, v34
	v_fmac_f32_e32 v30, v32, v32
	v_add_f32_e32 v29, v29, v30
	v_add_f32_e32 v36, v28, v29
	v_lshlrev_b32_e32 v28, 16, v128
	v_and_b32_e32 v29, 0xffff0000, v128
	v_lshlrev_b32_e32 v30, 16, v129
	v_and_b32_e32 v31, 0xffff0000, v129
	v_cvt_pk_bf16_f32 v26, v34, v35
	v_cvt_pk_bf16_f32 v27, v32, v33
	v_lshlrev_b32_e32 v32, 16, v130
	v_and_b32_e32 v33, 0xffff0000, v130
	v_pk_fma_f32 v[22:23], v[22:23], 0.5, v[30:31] op_sel_hi:[1,0,1]
	v_pk_fma_f32 v[20:21], v[20:21], 0.5, v[28:29] op_sel_hi:[1,0,1]
	v_lshlrev_b32_e32 v34, 16, v131
	v_and_b32_e32 v35, 0xffff0000, v131
	v_pk_fma_f32 v[30:31], v[16:17], 0.5, v[32:33] op_sel_hi:[1,0,1]
	v_mul_f32_e32 v16, v21, v21
	v_mul_f32_e32 v17, v23, v23
	v_pk_fma_f32 v[28:29], v[18:19], 0.5, v[34:35] op_sel_hi:[1,0,1]
	v_fmac_f32_e32 v16, v20, v20
	v_fmac_f32_e32 v17, v22, v22
	v_add_f32_e32 v16, v16, v17
	v_mul_f32_e32 v17, v31, v31
	v_mul_f32_e32 v18, v29, v29
	v_fmac_f32_e32 v17, v30, v30
	v_fmac_f32_e32 v18, v28, v28
	v_add_f32_e32 v17, v17, v18
	v_add_f32_e32 v16, v16, v17
	v_add_f32_e32 v19, v36, v16
	ds_bpermute_b32 v34, v120, v19
	v_lshl_add_u64 v[16:17], s[28:29], 0, v[198:199]
	v_lshl_add_u64 v[32:33], v[190:191], 1, v[16:17]
	global_store_dwordx4 v[32:33], v[24:27], off sc1
	v_cvt_pk_bf16_f32 v18, v20, v21
	s_waitcnt lgkmcnt(0)
	v_add_f32_e32 v16, v19, v34
	ds_bpermute_b32 v17, v121, v16
	v_cvt_pk_bf16_f32 v19, v22, v23
	v_cvt_pk_bf16_f32 v20, v30, v31
	v_cvt_pk_bf16_f32 v21, v28, v29
	global_store_dwordx4 v[32:33], v[18:21], off offset:256 sc1
	s_and_saveexec_b64 s[44:45], s[8:9]
	s_cbranch_execz .LBB0_911
	s_waitcnt lgkmcnt(0)
	v_add_f32_e32 v18, v16, v17
	v_lshl_add_u64 v[16:17], v[196:197], 2, s[38:39]
	global_atomic_add_f32 v[16:17], v18, off
.LBB0_911:
	s_or_b64 exec, exec, s[44:45]
	v_lshlrev_b32_e32 v16, 16, v116
	s_waitcnt lgkmcnt(0)
	v_and_b32_e32 v17, 0xffff0000, v116
	v_lshlrev_b32_e32 v18, 16, v117
	v_and_b32_e32 v19, 0xffff0000, v117
	v_lshlrev_b32_e32 v20, 16, v118
	v_and_b32_e32 v21, 0xffff0000, v118
	v_pk_fma_f32 v[12:13], v[12:13], 0.5, v[16:17] op_sel_hi:[1,0,1]
	v_pk_fma_f32 v[14:15], v[14:15], 0.5, v[18:19] op_sel_hi:[1,0,1]
	v_pk_fma_f32 v[18:19], v[8:9], 0.5, v[20:21] op_sel_hi:[1,0,1]
	v_cvt_pk_bf16_f32 v8, v12, v13
	v_mul_f32_e32 v13, v13, v13
	v_lshlrev_b32_e32 v22, 16, v119
	v_and_b32_e32 v23, 0xffff0000, v119
	v_fmac_f32_e32 v13, v12, v12
	v_mul_f32_e32 v12, v15, v15
	v_pk_fma_f32 v[16:17], v[10:11], 0.5, v[22:23] op_sel_hi:[1,0,1]
	v_fmac_f32_e32 v12, v14, v14
	v_cvt_pk_bf16_f32 v9, v14, v15
	v_add_f32_e32 v12, v13, v12
	v_mul_f32_e32 v13, v19, v19
	v_mul_f32_e32 v14, v17, v17
	v_fmac_f32_e32 v13, v18, v18
	v_fmac_f32_e32 v14, v16, v16
	v_add_f32_e32 v13, v13, v14
	v_add_f32_e32 v20, v12, v13
	v_lshlrev_b32_e32 v12, 16, v104
	v_and_b32_e32 v13, 0xffff0000, v104
	v_lshlrev_b32_e32 v14, 16, v105
	v_and_b32_e32 v15, 0xffff0000, v105
	v_cvt_pk_bf16_f32 v10, v18, v19
	v_cvt_pk_bf16_f32 v11, v16, v17
	v_lshlrev_b32_e32 v16, 16, v106
	v_and_b32_e32 v17, 0xffff0000, v106
	v_pk_fma_f32 v[6:7], v[6:7], 0.5, v[14:15] op_sel_hi:[1,0,1]
	v_pk_fma_f32 v[4:5], v[4:5], 0.5, v[12:13] op_sel_hi:[1,0,1]
	v_lshlrev_b32_e32 v18, 16, v107
	v_and_b32_e32 v19, 0xffff0000, v107
	v_pk_fma_f32 v[14:15], v[0:1], 0.5, v[16:17] op_sel_hi:[1,0,1]
	v_mul_f32_e32 v0, v5, v5
	v_mul_f32_e32 v1, v7, v7
	v_pk_fma_f32 v[12:13], v[2:3], 0.5, v[18:19] op_sel_hi:[1,0,1]
	v_fmac_f32_e32 v0, v4, v4
	v_fmac_f32_e32 v1, v6, v6
	v_add_f32_e32 v0, v0, v1
	v_mul_f32_e32 v1, v15, v15
	v_mul_f32_e32 v2, v13, v13
	v_fmac_f32_e32 v1, v14, v14
	v_fmac_f32_e32 v2, v12, v12
	v_add_f32_e32 v1, v1, v2
	v_add_f32_e32 v0, v0, v1
	v_add_f32_e32 v3, v20, v0
	ds_bpermute_b32 v18, v120, v3
	v_lshl_add_u64 v[0:1], s[28:29], 0, v[194:195]
	v_lshl_add_u64 v[16:17], v[190:191], 1, v[0:1]
	global_store_dwordx4 v[16:17], v[8:11], off sc1
	v_cvt_pk_bf16_f32 v2, v4, v5
	s_waitcnt lgkmcnt(0)
	v_add_f32_e32 v0, v3, v18
	ds_bpermute_b32 v1, v121, v0
	v_cvt_pk_bf16_f32 v3, v6, v7
	v_cvt_pk_bf16_f32 v4, v14, v15
	v_cvt_pk_bf16_f32 v5, v12, v13
	global_store_dwordx4 v[16:17], v[2:5], off offset:256 sc1
	s_and_saveexec_b64 s[44:45], s[8:9]
	s_cbranch_execz .LBB0_913
	s_waitcnt lgkmcnt(0)
	v_add_f32_e32 v2, v0, v1
	v_lshl_add_u64 v[0:1], v[192:193], 2, s[38:39]
	global_atomic_add_f32 v[0:1], v2, off

; __device__ __forceinline__ float rstd_of(float ss, float inv_n) { return __builtin_amdgcn_rsqf(ss * inv_n + 1e-6f); }
; __device__ __forceinline__ float sigmoid_f(float v) { return __builtin_amdgcn_rcpf(1.0f + __builtin_amdgcn_exp2f(-1.4426950408889634f * v)); }
; __device__ __forceinline__ float bf_lo(unsigned w) { return __uint_as_float(w << 16); }
; __device__ __forceinline__ float bf_hi(unsigned w) { return __uint_as_float(w & 0xffff0000u); }
;     __device__ __forceinline__ void operator()(f32x4 (&acc)[2][2][4][2], const Unit& u, int wr, int wc, int fr, int fq) const {
;         const int row0 = u.pm * BM + wr * 64 + fr, col0 = u.pn * BM + wc * 32 + 8 * fq;
;         u32x4 pw[2][4][2];
; #pragma unroll
;         for (int ai = 0; ai < 2; ++ai)
; #pragma unroll
;             for (int m = 0; m < 4; ++m)
; #pragma unroll
;                 for (int bj = 0; bj < 2; ++bj) pw[ai][m][bj] = *(const u32x4*)(PP + (size_t)(row0 + ai * HALF + m * 16) * 2048 + col0 + bj * HALF);
; #pragma unroll
;         for (int ai = 0; ai < 2; ++ai)
; #pragma unroll
;             for (int m = 0; m < 4; ++m) { const int row = row0 + ai * HALF + m * 16; const float r = rstd_of(ss[row], 1.0f / 2048.0f); float q = 0.f;
; #pragma unroll
;                 for (int bj = 0; bj < 2; ++bj) { const u32x4 pb = pw[ai][m][bj];
;                     const f32x4 p0 = {bf_lo(pb.x), bf_hi(pb.x), bf_lo(pb.y), bf_hi(pb.y)}, p1 = {bf_lo(pb.z), bf_hi(pb.z), bf_lo(pb.w), bf_hi(pb.w)};
;                     const f32x4 a0 = acc[ai][bj][m][0] * r, a1 = acc[ai][bj][m][1] * r; f32x4 y0, y1;
; #pragma unroll
;                     for (int e = 0; e < 4; ++e) { y0[e] = p0[e] * sigmoid_f(a0[e]); y1[e] = p1[e] * sigmoid_f(a1[e]); }
.LBB0_1013:
	v_lshl_add_u32 v190, s48, 8, v235
	v_lshl_add_u32 v222, s46, 8, v233
	v_ashrrev_i32_e32 v191, 31, v190
	v_lshlrev_b64 v[224:225], 1, v[190:191]
	v_ashrrev_i32_e32 v223, 31, v222
	v_lshl_add_u64 v[64:65], s[14:15], 0, v[224:225]
	v_lshlrev_b64 v[226:227], 12, v[222:223]
	v_lshl_add_u64 v[196:197], v[222:223], 2, s[38:39]
	v_lshl_add_u64 v[66:67], v[64:65], 0, v[226:227]
	global_load_dword v184, v[196:197], off
	global_load_dwordx4 v[240:243], v[66:67], off
	v_or_b32_e32 v218, 16, v222
	v_or_b32_e32 v214, 32, v222
	v_or_b32_e32 v210, 48, v222
	v_add_u32_e32 v206, 0x80, v222
	v_add_u32_e32 v202, 0x90, v222
	v_add_u32_e32 v198, 0xa0, v222
	v_add_u32_e32 v192, 0xb0, v222
	v_ashrrev_i32_e32 v219, 31, v218
	v_ashrrev_i32_e32 v215, 31, v214
	v_ashrrev_i32_e32 v211, 31, v210
	v_ashrrev_i32_e32 v207, 31, v206
	v_ashrrev_i32_e32 v203, 31, v202
	v_ashrrev_i32_e32 v199, 31, v198
	v_ashrrev_i32_e32 v193, 31, v192
	v_lshlrev_b64 v[220:221], 12, v[218:219]
	v_lshlrev_b64 v[216:217], 12, v[214:215]
	v_lshlrev_b64 v[212:213], 12, v[210:211]
	v_lshlrev_b64 v[208:209], 12, v[206:207]
	v_lshlrev_b64 v[204:205], 12, v[202:203]
	v_lshlrev_b64 v[200:201], 12, v[198:199]
	v_lshlrev_b64 v[194:195], 12, v[192:193]
	v_lshl_add_u64 v[68:69], v[64:65], 0, v[220:221]
	v_lshl_add_u64 v[70:71], v[64:65], 0, v[216:217]
	v_lshl_add_u64 v[88:89], v[64:65], 0, v[212:213]
	v_lshl_add_u64 v[90:91], v[64:65], 0, v[208:209]
	v_lshl_add_u64 v[92:93], v[64:65], 0, v[204:205]
	v_lshl_add_u64 v[248:249], v[64:65], 0, v[200:201]
	v_lshl_add_u64 v[64:65], v[64:65], 0, v[194:195]
	global_load_dwordx4 v[244:247], v[66:67], off offset:256
	global_load_dwordx4 v[180:183], v[68:69], off
	global_load_dwordx4 v[176:179], v[68:69], off offset:256
	global_load_dwordx4 v[172:175], v[70:71], off
	global_load_dwordx4 v[168:171], v[70:71], off offset:256
	global_load_dwordx4 v[164:167], v[88:89], off
	global_load_dwordx4 v[152:155], v[88:89], off offset:256
	global_load_dwordx4 v[140:143], v[90:91], off
	global_load_dwordx4 v[136:139], v[90:91], off offset:256
	global_load_dwordx4 v[116:119], v[92:93], off
	global_load_dwordx4 v[112:115], v[92:93], off offset:256
	s_nop 0
	global_load_dwordx4 v[92:95], v[248:249], off
	global_load_dwordx4 v[88:91], v[248:249], off offset:256
	global_load_dwordx4 v[68:71], v[64:65], off
	s_nop 0
	global_load_dwordx4 v[64:67], v[64:65], off offset:256
	s_waitcnt vmcnt(0)
	v_fmamk_f32 v184, v184, 0x3a000000, v239
	v_rsq_f32_e32 v184, v184
	v_lshlrev_b32_e32 v248, 16, v240
	v_lshlrev_b32_e32 v250, 16, v242
	v_and_b32_e32 v240, 0xffff0000, v240
	v_mul_f32_e32 v160, v160, v184
	v_mul_f32_e32 v156, v156, v184
	v_mul_f32_e32 v160, 0xbfb8aa3b, v160
	v_mul_f32_e32 v156, 0xbfb8aa3b, v156
	v_exp_f32_e32 v160, v160
	v_exp_f32_e32 v156, v156
	v_mul_f32_e32 v161, v161, v184
	v_mul_f32_e32 v157, v157, v184
	v_mul_f32_e32 v161, 0xbfb8aa3b, v161
	v_mul_f32_e32 v157, 0xbfb8aa3b, v157
	v_exp_f32_e32 v161, v161
	v_exp_f32_e32 v157, v157
	v_add_f32_e32 v160, 1.0, v160
	v_add_f32_e32 v156, 1.0, v156
	v_rcp_f32_e32 v160, v160
	v_rcp_f32_e32 v156, v156
	v_mul_f32_e32 v158, v158, v184
	v_mul_f32_e32 v163, v163, v184
	v_mul_f32_e32 v159, v159, v184
	v_mul_f32_e32 v158, 0xbfb8aa3b, v158
	v_mul_f32_e32 v162, v162, v184
	v_mul_f32_e32 v163, 0xbfb8aa3b, v163
	v_mul_f32_e32 v159, 0xbfb8aa3b, v159
	v_exp_f32_e32 v158, v158
	v_add_f32_e32 v161, 1.0, v161
	v_add_f32_e32 v157, 1.0, v157
	v_mul_f32_e32 v162, 0xbfb8aa3b, v162
	v_exp_f32_e32 v163, v163
	v_rcp_f32_e32 v161, v161
	v_rcp_f32_e32 v157, v157
	v_mul_f32_e32 v160, v160, v248
	v_mul_f32_e32 v248, v156, v250
	v_exp_f32_e32 v156, v159
	v_mul_f32_e32 v144, v144, v184
	v_exp_f32_e32 v162, v162
	v_mul_f32_e32 v144, 0xbfb8aa3b, v144
	v_exp_f32_e32 v144, v144
	v_and_b32_e32 v242, 0xffff0000, v242
	v_add_f32_e32 v158, 1.0, v158
	v_mul_f32_e32 v161, v161, v240
	v_mul_f32_e32 v240, v157, v242
	v_rcp_f32_e32 v157, v158
	v_add_f32_e32 v158, 1.0, v163
	v_add_f32_e32 v156, 1.0, v156
	v_add_f32_e32 v162, 1.0, v162
	v_rcp_f32_e32 v158, v158
	v_rcp_f32_e32 v156, v156
	v_mul_f32_e32 v145, v145, v184
	v_rcp_f32_e32 v162, v162
	v_add_f32_e32 v144, 1.0, v144
	v_mul_f32_e32 v145, 0xbfb8aa3b, v145
	v_rcp_f32_e32 v144, v144
	v_exp_f32_e32 v145, v145
	v_lshlrev_b32_e32 v249, 16, v241
	v_and_b32_e32 v241, 0xffff0000, v241
	v_lshlrev_b32_e32 v251, 16, v243
	v_and_b32_e32 v243, 0xffff0000, v243
	v_mul_f32_e32 v241, v158, v241
	v_mul_f32_e32 v242, v156, v243
	v_cvt_pk_bf16_f32 v156, v160, v161
	v_mul_f32_e32 v161, v161, v161
	v_mul_f32_e32 v162, v162, v249
	v_mul_f32_e32 v163, v157, v251
	v_cvt_pk_bf16_f32 v157, v162, v241
	v_fmac_f32_e32 v161, v160, v160
	v_mul_f32_e32 v160, v241, v241
	v_lshlrev_b32_e32 v241, 16, v246
	v_mul_f32_e32 v241, v144, v241
	v_add_f32_e32 v144, 1.0, v145
	v_mul_f32_e32 v145, v150, v184
	v_mul_f32_e32 v146, v146, v184
	v_mul_f32_e32 v145, 0xbfb8aa3b, v145
	v_mul_f32_e32 v146, 0xbfb8aa3b, v146
	v_rcp_f32_e32 v144, v144
	v_exp_f32_e32 v145, v145
	v_exp_f32_e32 v146, v146
	v_cvt_pk_bf16_f32 v158, v248, v240
	v_cvt_pk_bf16_f32 v159, v163, v242
	v_fmac_f32_e32 v160, v162, v162
	v_mul_f32_e32 v162, v242, v242
	v_and_b32_e32 v242, 0xffff0000, v246
	v_mul_f32_e32 v149, v149, v184
	v_mul_f32_e32 v150, v144, v242
	v_add_f32_e32 v144, 1.0, v145
	v_add_f32_e32 v145, 1.0, v146
	v_mul_f32_e32 v146, v151, v184
	v_mul_f32_e32 v148, v148, v184
	v_mul_f32_e32 v149, 0xbfb8aa3b, v149
	v_mul_f32_e32 v146, 0xbfb8aa3b, v146
	v_mul_f32_e32 v148, 0xbfb8aa3b, v148
	v_exp_f32_e32 v149, v149
	v_exp_f32_e32 v146, v146
	v_mul_f32_e32 v147, v147, v184
	v_exp_f32_e32 v148, v148
	v_mul_f32_e32 v147, 0xbfb8aa3b, v147
	v_exp_f32_e32 v147, v147
	v_add_f32_e32 v149, 1.0, v149
; __device__ __forceinline__ float rstd_of(float ss, float inv_n) { return __builtin_amdgcn_rsqf(ss * inv_n + 1e-6f); }
; __device__ __forceinline__ float sigmoid_f(float v) { return __builtin_amdgcn_rcpf(1.0f + __builtin_amdgcn_exp2f(-1.4426950408889634f * v)); }
; __device__ __forceinline__ float bf_lo(unsigned w) { return __uint_as_float(w << 16); }
; __device__ __forceinline__ float bf_hi(unsigned w) { return __uint_as_float(w & 0xffff0000u); }
; __device__ __forceinline__ u32x4 pack8(const f32x4 a, const f32x4 b) { u32x4 w; w.x = cvt_pk_bf16(a[0], a[1]); w.y = cvt_pk_bf16(a[2], a[3]); w.z = cvt_pk_bf16(b[0], b[1]); w.w = cvt_pk_bf16(b[2], b[3]); return w; }
; __device__ __forceinline__ float sumsq4(const f32x4 a) { return (a[0] * a[0] + a[1] * a[1]) + (a[2] * a[2] + a[3] * a[3]); }
;     __device__ __forceinline__ void operator()(f32x4 (&acc)[2][2][4][2], const Unit& u, int wr, int wc, int fr, int fq) const {
;     ...
;         for (int ai = 0; ai < 2; ++ai)
; #pragma unroll
;             for (int m = 0; m < 4; ++m) { const int row = row0 + ai * HALF + m * 16; const float r = rstd_of(ss[row], 1.0f / 2048.0f); float q = 0.f;
; #pragma unroll
;                 for (int bj = 0; bj < 2; ++bj) { const u32x4 pb = pw[ai][m][bj];
;                     const f32x4 p0 = {bf_lo(pb.x), bf_hi(pb.x), bf_lo(pb.y), bf_hi(pb.y)}, p1 = {bf_lo(pb.z), bf_hi(pb.z), bf_lo(pb.w), bf_hi(pb.w)};
;                     const f32x4 a0 = acc[ai][bj][m][0] * r, a1 = acc[ai][bj][m][1] * r; f32x4 y0, y1;
; #pragma unroll
;                     for (int e = 0; e < 4; ++e) { y0[e] = p0[e] * sigmoid_f(a0[e]); y1[e] = p1[e] * sigmoid_f(a1[e]); }
;                     *(u32x4*)(E + (size_t)row * 2048 + col0 + bj * HALF) = pack8(y0, y1); q += sumsq4(y0) + sumsq4(y1); }
;                 q += __shfl_xor(q, 16); q += __shfl_xor(q, 32);
;                 if (fq == 0) atomicAdd(ssout + row, q); }
	v_add_f32_e32 v146, 1.0, v146
	v_add_f32_e32 v148, 1.0, v148
	v_rcp_f32_e32 v149, v149
	v_rcp_f32_e32 v144, v144
	v_rcp_f32_e32 v146, v146
	v_add_f32_e32 v160, v161, v160
	v_mul_f32_e32 v161, v240, v240
	v_rcp_f32_e32 v148, v148
	v_rcp_f32_e32 v145, v145
	v_add_f32_e32 v147, 1.0, v147
	v_fmac_f32_e32 v161, v248, v248
	v_fmac_f32_e32 v162, v163, v163
	v_rcp_f32_e32 v147, v147
	v_add_f32_e32 v161, v161, v162
	v_and_b32_e32 v162, 0xffff0000, v244
	v_lshlrev_b32_e32 v163, 16, v245
	v_and_b32_e32 v240, 0xffff0000, v245
	v_add_f32_e32 v160, v160, v161
	v_lshlrev_b32_e32 v161, 16, v244
	v_lshlrev_b32_e32 v243, 16, v247
	v_mul_f32_e32 v149, v149, v162
	v_mul_f32_e32 v151, v144, v163
	v_mul_f32_e32 v163, v146, v240
	v_and_b32_e32 v244, 0xffff0000, v247
	v_mul_f32_e32 v148, v148, v161
	v_mul_f32_e32 v162, v145, v243
	v_mul_f32_e32 v144, v149, v149
	v_mul_f32_e32 v145, v163, v163
	v_mul_f32_e32 v184, v147, v244
	v_fmac_f32_e32 v144, v148, v148
	v_fmac_f32_e32 v145, v151, v151
	v_add_f32_e32 v144, v144, v145
	v_mul_f32_e32 v145, v150, v150
	v_mul_f32_e32 v146, v184, v184
	v_fmac_f32_e32 v145, v241, v241
	v_fmac_f32_e32 v146, v162, v162
	v_add_f32_e32 v145, v145, v146
	v_add_f32_e32 v144, v144, v145
	v_and_b32_e32 v146, 64, v228
	v_add_f32_e32 v145, v160, v144
	v_xor_b32_e32 v144, 16, v228
	v_add_u32_e32 v240, 64, v146
	v_cmp_lt_i32_e32 vcc, v144, v240
	v_lshl_add_u64 v[146:147], s[34:35], 0, v[226:227]
	v_lshl_add_u64 v[160:161], v[146:147], 0, v[224:225]
	v_cndmask_b32_e32 v144, v228, v144, vcc
	v_lshlrev_b32_e32 v144, 2, v144
	ds_bpermute_b32 v242, v144, v145
	global_store_dwordx4 v[160:161], v[156:159], off sc1
	v_cvt_pk_bf16_f32 v148, v148, v149
	v_cvt_pk_bf16_f32 v149, v151, v163
	v_cvt_pk_bf16_f32 v150, v241, v150
	s_waitcnt lgkmcnt(0)
	v_add_f32_e32 v146, v145, v242
	v_xor_b32_e32 v145, 32, v228
	v_cmp_lt_i32_e32 vcc, v145, v240
	v_cvt_pk_bf16_f32 v151, v162, v184
	global_store_dwordx4 v[160:161], v[148:151], off offset:256 sc1
	s_nop 0
	v_cndmask_b32_e32 v145, v228, v145, vcc
	v_lshlrev_b32_e32 v145, 2, v145
	ds_bpermute_b32 v147, v145, v146
	s_and_saveexec_b64 s[46:47], s[4:5]
	s_cbranch_execz .LBB0_1015
	v_lshl_add_u64 v[148:149], v[222:223], 2, s[8:9]
	s_waitcnt lgkmcnt(0)
	v_add_f32_e32 v146, v146, v147
	global_atomic_add_f32 v[148:149], v146, off
.LBB0_1015:
	s_or_b64 exec, exec, s[46:47]
	s_waitcnt lgkmcnt(0)
	v_lshl_add_u64 v[146:147], v[218:219], 2, s[38:39]
	global_load_dword v146, v[146:147], off
	v_and_b32_e32 v148, 0xffff0000, v180
	v_and_b32_e32 v150, 0xffff0000, v181
	v_and_b32_e32 v156, 0xffff0000, v182
	v_and_b32_e32 v158, 0xffff0000, v183
	v_lshlrev_b32_e32 v147, 16, v180
	v_lshlrev_b32_e32 v149, 16, v181
	v_lshlrev_b32_e32 v151, 16, v182
	v_lshlrev_b32_e32 v157, 16, v183
	v_lshlrev_b32_e32 v163, 16, v178
	v_lshlrev_b32_e32 v159, 16, v176
	v_and_b32_e32 v160, 0xffff0000, v176
	v_and_b32_e32 v176, 0xffff0000, v178
	v_and_b32_e32 v162, 0xffff0000, v177
	v_lshlrev_b32_e32 v161, 16, v177
	v_lshlrev_b32_e32 v177, 16, v179
	v_and_b32_e32 v178, 0xffff0000, v179
	s_waitcnt vmcnt(0)
	v_fmamk_f32 v146, v146, 0x3a000000, v239
	v_rsq_f32_e32 v146, v146
	s_nop 0
	v_mul_f32_e32 v133, v133, v146
	v_mul_f32_e32 v129, v129, v146
	v_mul_f32_e32 v135, v135, v146
	v_mul_f32_e32 v131, v131, v146
	v_mul_f32_e32 v132, v132, v146
	v_mul_f32_e32 v128, v128, v146
	v_mul_f32_e32 v134, v134, v146
	v_mul_f32_e32 v130, v130, v146
	v_mul_f32_e32 v133, 0xbfb8aa3b, v133
	v_mul_f32_e32 v129, 0xbfb8aa3b, v129
	v_mul_f32_e32 v135, 0xbfb8aa3b, v135
	v_mul_f32_e32 v131, 0xbfb8aa3b, v131
	v_mul_f32_e32 v132, 0xbfb8aa3b, v132
	v_mul_f32_e32 v128, 0xbfb8aa3b, v128
	v_mul_f32_e32 v134, 0xbfb8aa3b, v134
	v_mul_f32_e32 v130, 0xbfb8aa3b, v130
	v_exp_f32_e32 v133, v133
	v_exp_f32_e32 v129, v129
	v_exp_f32_e32 v135, v135
	v_exp_f32_e32 v131, v131
	v_exp_f32_e32 v132, v132
	v_exp_f32_e32 v128, v128
	v_exp_f32_e32 v134, v134
	v_exp_f32_e32 v130, v130
	v_mul_f32_e32 v120, v120, v146
	v_mul_f32_e32 v120, 0xbfb8aa3b, v120
	v_exp_f32_e32 v120, v120
	v_add_f32_e32 v133, 1.0, v133
	v_add_f32_e32 v129, 1.0, v129
	v_add_f32_e32 v135, 1.0, v135
	v_add_f32_e32 v131, 1.0, v131
	v_add_f32_e32 v132, 1.0, v132
	v_add_f32_e32 v128, 1.0, v128
	v_add_f32_e32 v134, 1.0, v134
	v_add_f32_e32 v130, 1.0, v130
	v_rcp_f32_e32 v133, v133
	v_rcp_f32_e32 v129, v129
	v_rcp_f32_e32 v135, v135
	v_rcp_f32_e32 v131, v131
	v_rcp_f32_e32 v132, v132
	v_rcp_f32_e32 v128, v128
	v_rcp_f32_e32 v134, v134
	v_rcp_f32_e32 v130, v130
	v_mul_f32_e32 v121, v121, v146
	v_mul_f32_e32 v121, 0xbfb8aa3b, v121
	v_add_f32_e32 v120, 1.0, v120
	v_exp_f32_e32 v121, v121
	v_rcp_f32_e32 v120, v120
	v_mul_f32_e32 v133, v133, v148
	v_mul_f32_e32 v148, v129, v156
	v_mul_f32_e32 v135, v135, v150
	v_mul_f32_e32 v150, v131, v158
	v_mul_f32_e32 v132, v132, v147
	v_mul_f32_e32 v147, v128, v151
	v_mul_f32_e32 v134, v134, v149
	v_mul_f32_e32 v149, v130, v157
	v_cvt_pk_bf16_f32 v128, v132, v133
	v_cvt_pk_bf16_f32 v129, v134, v135
	v_cvt_pk_bf16_f32 v130, v147, v148
	v_cvt_pk_bf16_f32 v131, v149, v150
	v_mul_f32_e32 v133, v133, v133
	v_mul_f32_e32 v135, v135, v135
	v_mul_f32_e32 v148, v148, v148
	v_mul_f32_e32 v150, v150, v150
	v_fmac_f32_e32 v133, v132, v132
	v_fmac_f32_e32 v135, v134, v134
	v_fmac_f32_e32 v148, v147, v147
	v_fmac_f32_e32 v150, v149, v149
	v_add_f32_e32 v132, v133, v135
	v_add_f32_e32 v133, v148, v150
	v_add_f32_e32 v132, v132, v133
	v_mul_f32_e32 v133, v120, v163
	v_add_f32_e32 v120, 1.0, v121
	v_mul_f32_e32 v121, v126, v146
	v_mul_f32_e32 v122, v122, v146
	v_mul_f32_e32 v121, 0xbfb8aa3b, v121
	v_mul_f32_e32 v122, 0xbfb8aa3b, v122
	v_rcp_f32_e32 v120, v120
	v_exp_f32_e32 v121, v121
	v_exp_f32_e32 v122, v122
; __device__ __forceinline__ float rstd_of(float ss, float inv_n) { return __builtin_amdgcn_rsqf(ss * inv_n + 1e-6f); }
; __device__ __forceinline__ float sigmoid_f(float v) { return __builtin_amdgcn_rcpf(1.0f + __builtin_amdgcn_exp2f(-1.4426950408889634f * v)); }
; __device__ __forceinline__ float bf_lo(unsigned w) { return __uint_as_float(w << 16); }
; __device__ __forceinline__ float bf_hi(unsigned w) { return __uint_as_float(w & 0xffff0000u); }
; __device__ __forceinline__ u32x4 pack8(const f32x4 a, const f32x4 b) { u32x4 w; w.x = cvt_pk_bf16(a[0], a[1]); w.y = cvt_pk_bf16(a[2], a[3]); w.z = cvt_pk_bf16(b[0], b[1]); w.w = cvt_pk_bf16(b[2], b[3]); return w; }
; __device__ __forceinline__ float sumsq4(const f32x4 a) { return (a[0] * a[0] + a[1] * a[1]) + (a[2] * a[2] + a[3] * a[3]); }
;     __device__ __forceinline__ void operator()(f32x4 (&acc)[2][2][4][2], const Unit& u, int wr, int wc, int fr, int fq) const {
;     ...
;         for (int ai = 0; ai < 2; ++ai)
; #pragma unroll
;             for (int m = 0; m < 4; ++m) { const int row = row0 + ai * HALF + m * 16; const float r = rstd_of(ss[row], 1.0f / 2048.0f); float q = 0.f;
; #pragma unroll
;                 for (int bj = 0; bj < 2; ++bj) { const u32x4 pb = pw[ai][m][bj];
;                     const f32x4 p0 = {bf_lo(pb.x), bf_hi(pb.x), bf_lo(pb.y), bf_hi(pb.y)}, p1 = {bf_lo(pb.z), bf_hi(pb.z), bf_lo(pb.w), bf_hi(pb.w)};
;                     const f32x4 a0 = acc[ai][bj][m][0] * r, a1 = acc[ai][bj][m][1] * r; f32x4 y0, y1;
; #pragma unroll
;                     for (int e = 0; e < 4; ++e) { y0[e] = p0[e] * sigmoid_f(a0[e]); y1[e] = p1[e] * sigmoid_f(a1[e]); }
;                     *(u32x4*)(E + (size_t)row * 2048 + col0 + bj * HALF) = pack8(y0, y1); q += sumsq4(y0) + sumsq4(y1); }
;                 q += __shfl_xor(q, 16); q += __shfl_xor(q, 32);
;                 if (fq == 0) atomicAdd(ssout + row, q); }
	v_mul_f32_e32 v125, v125, v146
	v_mul_f32_e32 v134, v120, v176
	v_add_f32_e32 v120, 1.0, v121
	v_add_f32_e32 v121, 1.0, v122
	v_mul_f32_e32 v122, v127, v146
	v_mul_f32_e32 v124, v124, v146
	v_mul_f32_e32 v125, 0xbfb8aa3b, v125
	v_mul_f32_e32 v122, 0xbfb8aa3b, v122
	v_mul_f32_e32 v124, 0xbfb8aa3b, v124
	v_exp_f32_e32 v125, v125
	v_exp_f32_e32 v122, v122
	v_mul_f32_e32 v123, v123, v146
	v_exp_f32_e32 v124, v124
	v_mul_f32_e32 v123, 0xbfb8aa3b, v123
	v_exp_f32_e32 v123, v123
	v_add_f32_e32 v125, 1.0, v125
	v_add_f32_e32 v122, 1.0, v122
	v_add_f32_e32 v124, 1.0, v124
	v_rcp_f32_e32 v125, v125
	v_rcp_f32_e32 v122, v122
	v_rcp_f32_e32 v124, v124
	v_rcp_f32_e32 v120, v120
	v_rcp_f32_e32 v121, v121
	v_add_f32_e32 v123, 1.0, v123
	v_rcp_f32_e32 v123, v123
	v_mul_f32_e32 v125, v125, v160
	v_mul_f32_e32 v147, v122, v162
	v_mul_f32_e32 v124, v124, v159
	v_mul_f32_e32 v135, v120, v161
	v_mul_f32_e32 v146, v121, v177
	v_mul_f32_e32 v120, v125, v125
	v_mul_f32_e32 v121, v147, v147
	v_mul_f32_e32 v148, v123, v178
	v_fmac_f32_e32 v120, v124, v124
	v_fmac_f32_e32 v121, v135, v135
	v_add_f32_e32 v120, v120, v121
	v_mul_f32_e32 v121, v134, v134
	v_mul_f32_e32 v122, v148, v148
	v_fmac_f32_e32 v121, v133, v133
	v_fmac_f32_e32 v122, v146, v146
	v_add_f32_e32 v121, v121, v122
	v_add_f32_e32 v120, v120, v121
	v_add_f32_e32 v123, v132, v120
	ds_bpermute_b32 v132, v144, v123
	v_lshl_add_u64 v[120:121], s[34:35], 0, v[220:221]
	v_lshl_add_u64 v[126:127], v[190:191], 1, v[120:121]
	global_store_dwordx4 v[126:127], v[128:131], off sc1
	v_cvt_pk_bf16_f32 v122, v124, v125
	s_waitcnt lgkmcnt(0)
	v_add_f32_e32 v120, v123, v132
	ds_bpermute_b32 v121, v145, v120
	v_cvt_pk_bf16_f32 v123, v135, v147
	v_cvt_pk_bf16_f32 v124, v133, v134
	v_cvt_pk_bf16_f32 v125, v146, v148
	global_store_dwordx4 v[126:127], v[122:125], off offset:256 sc1
	s_and_saveexec_b64 s[46:47], s[4:5]
	s_cbranch_execz .LBB0_1017
	v_lshl_add_u64 v[122:123], v[218:219], 2, s[8:9]
	s_waitcnt lgkmcnt(0)
	v_add_f32_e32 v120, v120, v121
	global_atomic_add_f32 v[122:123], v120, off
.LBB0_1017:
	s_or_b64 exec, exec, s[46:47]
	s_waitcnt lgkmcnt(0)
	v_lshl_add_u64 v[120:121], v[214:215], 2, s[38:39]
	global_load_dword v120, v[120:121], off
	v_and_b32_e32 v122, 0xffff0000, v172
	v_and_b32_e32 v124, 0xffff0000, v173
	v_and_b32_e32 v126, 0xffff0000, v174
	v_and_b32_e32 v128, 0xffff0000, v175
	v_lshlrev_b32_e32 v121, 16, v172
	v_lshlrev_b32_e32 v123, 16, v173
	v_lshlrev_b32_e32 v125, 16, v174
	v_lshlrev_b32_e32 v127, 16, v175
	v_lshlrev_b32_e32 v133, 16, v170
	v_and_b32_e32 v134, 0xffff0000, v170
	v_and_b32_e32 v130, 0xffff0000, v168
	v_and_b32_e32 v132, 0xffff0000, v169
	v_lshlrev_b32_e32 v129, 16, v168
	v_lshlrev_b32_e32 v131, 16, v169
	v_lshlrev_b32_e32 v135, 16, v171
	v_and_b32_e32 v146, 0xffff0000, v171
	s_waitcnt vmcnt(0)
	v_fmamk_f32 v120, v120, 0x3a000000, v239
	v_rsq_f32_e32 v120, v120
	s_nop 0
	v_mul_f32_e32 v109, v109, v120
	v_mul_f32_e32 v105, v105, v120
	v_mul_f32_e32 v111, v111, v120
	v_mul_f32_e32 v107, v107, v120
	v_mul_f32_e32 v108, v108, v120
	v_mul_f32_e32 v104, v104, v120
	v_mul_f32_e32 v110, v110, v120
	v_mul_f32_e32 v106, v106, v120
	v_mul_f32_e32 v109, 0xbfb8aa3b, v109
	v_mul_f32_e32 v105, 0xbfb8aa3b, v105
	v_mul_f32_e32 v111, 0xbfb8aa3b, v111
	v_mul_f32_e32 v107, 0xbfb8aa3b, v107
	v_mul_f32_e32 v108, 0xbfb8aa3b, v108
	v_mul_f32_e32 v104, 0xbfb8aa3b, v104
	v_mul_f32_e32 v110, 0xbfb8aa3b, v110
	v_mul_f32_e32 v106, 0xbfb8aa3b, v106
	v_exp_f32_e32 v109, v109
	v_exp_f32_e32 v105, v105
	v_exp_f32_e32 v111, v111
	v_exp_f32_e32 v107, v107
	v_exp_f32_e32 v108, v108
	v_exp_f32_e32 v104, v104
	v_exp_f32_e32 v110, v110
	v_exp_f32_e32 v106, v106
	v_mul_f32_e32 v96, v96, v120
	v_mul_f32_e32 v96, 0xbfb8aa3b, v96
	v_exp_f32_e32 v96, v96
	v_add_f32_e32 v109, 1.0, v109
	v_add_f32_e32 v105, 1.0, v105
	v_add_f32_e32 v111, 1.0, v111
	v_add_f32_e32 v107, 1.0, v107
	v_add_f32_e32 v108, 1.0, v108
	v_add_f32_e32 v104, 1.0, v104
	v_add_f32_e32 v110, 1.0, v110
	v_add_f32_e32 v106, 1.0, v106
	v_rcp_f32_e32 v109, v109
	v_rcp_f32_e32 v105, v105
	v_rcp_f32_e32 v111, v111
	v_rcp_f32_e32 v107, v107
	v_rcp_f32_e32 v108, v108
	v_rcp_f32_e32 v104, v104
	v_rcp_f32_e32 v110, v110
	v_rcp_f32_e32 v106, v106
	v_mul_f32_e32 v97, v97, v120
	v_mul_f32_e32 v97, 0xbfb8aa3b, v97
	v_add_f32_e32 v96, 1.0, v96
	v_exp_f32_e32 v97, v97
	v_rcp_f32_e32 v96, v96
	v_mul_f32_e32 v109, v109, v122
	v_mul_f32_e32 v122, v105, v126
	v_mul_f32_e32 v111, v111, v124
	v_mul_f32_e32 v124, v107, v128
	v_mul_f32_e32 v108, v108, v121
	v_mul_f32_e32 v121, v104, v125
	v_mul_f32_e32 v110, v110, v123
	v_mul_f32_e32 v123, v106, v127
	v_cvt_pk_bf16_f32 v104, v108, v109
	v_cvt_pk_bf16_f32 v105, v110, v111
	v_cvt_pk_bf16_f32 v106, v121, v122
	v_cvt_pk_bf16_f32 v107, v123, v124
	v_mul_f32_e32 v109, v109, v109
	v_mul_f32_e32 v111, v111, v111
	v_mul_f32_e32 v122, v122, v122
	v_mul_f32_e32 v124, v124, v124
	v_fmac_f32_e32 v109, v108, v108
	v_fmac_f32_e32 v111, v110, v110
	v_fmac_f32_e32 v122, v121, v121
	v_fmac_f32_e32 v124, v123, v123
	v_add_f32_e32 v108, v109, v111
	v_add_f32_e32 v109, v122, v124
	v_add_f32_e32 v108, v108, v109
	v_mul_f32_e32 v109, v96, v133
	v_add_f32_e32 v96, 1.0, v97
	v_mul_f32_e32 v97, v102, v120
	v_mul_f32_e32 v98, v98, v120
	v_mul_f32_e32 v97, 0xbfb8aa3b, v97
	v_mul_f32_e32 v98, 0xbfb8aa3b, v98
	v_rcp_f32_e32 v96, v96
	v_exp_f32_e32 v97, v97
	v_exp_f32_e32 v98, v98
	v_mul_f32_e32 v101, v101, v120
	v_mul_f32_e32 v110, v96, v134
	v_add_f32_e32 v96, 1.0, v97
	v_add_f32_e32 v97, 1.0, v98
	v_mul_f32_e32 v98, v103, v120
	v_mul_f32_e32 v100, v100, v120
	v_mul_f32_e32 v101, 0xbfb8aa3b, v101
	v_mul_f32_e32 v98, 0xbfb8aa3b, v98
	v_mul_f32_e32 v100, 0xbfb8aa3b, v100
	v_exp_f32_e32 v101, v101
	v_exp_f32_e32 v98, v98
	v_mul_f32_e32 v99, v99, v120
	v_exp_f32_e32 v100, v100
	v_mul_f32_e32 v99, 0xbfb8aa3b, v99
	v_exp_f32_e32 v99, v99
	v_add_f32_e32 v101, 1.0, v101
	v_add_f32_e32 v98, 1.0, v98
	v_add_f32_e32 v100, 1.0, v100
	v_rcp_f32_e32 v101, v101
	v_rcp_f32_e32 v98, v98
	v_rcp_f32_e32 v100, v100
	v_rcp_f32_e32 v96, v96
	v_rcp_f32_e32 v97, v97
	v_add_f32_e32 v99, 1.0, v99
	v_rcp_f32_e32 v99, v99
	v_mul_f32_e32 v101, v101, v130
	v_mul_f32_e32 v121, v98, v132
	v_mul_f32_e32 v100, v100, v129
	v_mul_f32_e32 v111, v96, v131
	v_mul_f32_e32 v120, v97, v135
	v_mul_f32_e32 v96, v101, v101
	v_mul_f32_e32 v97, v121, v121
	v_mul_f32_e32 v122, v99, v146
	v_fmac_f32_e32 v96, v100, v100
	v_fmac_f32_e32 v97, v111, v111
	v_add_f32_e32 v96, v96, v97
	v_mul_f32_e32 v97, v110, v110
	v_mul_f32_e32 v98, v122, v122
	v_fmac_f32_e32 v97, v109, v109
	v_fmac_f32_e32 v98, v120, v120
	v_add_f32_e32 v97, v97, v98
	v_add_f32_e32 v96, v96, v97
	v_add_f32_e32 v99, v108, v96
	ds_bpermute_b32 v108, v144, v99
	v_lshl_add_u64 v[96:97], s[34:35], 0, v[216:217]
	v_lshl_add_u64 v[102:103], v[190:191], 1, v[96:97]
	global_store_dwordx4 v[102:103], v[104:107], off sc1
	v_cvt_pk_bf16_f32 v98, v100, v101
	s_waitcnt lgkmcnt(0)
; __device__ __forceinline__ float rstd_of(float ss, float inv_n) { return __builtin_amdgcn_rsqf(ss * inv_n + 1e-6f); }
; __device__ __forceinline__ float sigmoid_f(float v) { return __builtin_amdgcn_rcpf(1.0f + __builtin_amdgcn_exp2f(-1.4426950408889634f * v)); }
; __device__ __forceinline__ float bf_lo(unsigned w) { return __uint_as_float(w << 16); }
; __device__ __forceinline__ float bf_hi(unsigned w) { return __uint_as_float(w & 0xffff0000u); }
; __device__ __forceinline__ u32x4 pack8(const f32x4 a, const f32x4 b) { u32x4 w; w.x = cvt_pk_bf16(a[0], a[1]); w.y = cvt_pk_bf16(a[2], a[3]); w.z = cvt_pk_bf16(b[0], b[1]); w.w = cvt_pk_bf16(b[2], b[3]); return w; }
; __device__ __forceinline__ float sumsq4(const f32x4 a) { return (a[0] * a[0] + a[1] * a[1]) + (a[2] * a[2] + a[3] * a[3]); }
;     __device__ __forceinline__ void operator()(f32x4 (&acc)[2][2][4][2], const Unit& u, int wr, int wc, int fr, int fq) const {
;     ...
;         for (int ai = 0; ai < 2; ++ai)
; #pragma unroll
;             for (int m = 0; m < 4; ++m) { const int row = row0 + ai * HALF + m * 16; const float r = rstd_of(ss[row], 1.0f / 2048.0f); float q = 0.f;
; #pragma unroll
;                 for (int bj = 0; bj < 2; ++bj) { const u32x4 pb = pw[ai][m][bj];
;                     const f32x4 p0 = {bf_lo(pb.x), bf_hi(pb.x), bf_lo(pb.y), bf_hi(pb.y)}, p1 = {bf_lo(pb.z), bf_hi(pb.z), bf_lo(pb.w), bf_hi(pb.w)};
;                     const f32x4 a0 = acc[ai][bj][m][0] * r, a1 = acc[ai][bj][m][1] * r; f32x4 y0, y1;
; #pragma unroll
;                     for (int e = 0; e < 4; ++e) { y0[e] = p0[e] * sigmoid_f(a0[e]); y1[e] = p1[e] * sigmoid_f(a1[e]); }
;                     *(u32x4*)(E + (size_t)row * 2048 + col0 + bj * HALF) = pack8(y0, y1); q += sumsq4(y0) + sumsq4(y1); }
;                 q += __shfl_xor(q, 16); q += __shfl_xor(q, 32);
;                 if (fq == 0) atomicAdd(ssout + row, q); }
	v_add_f32_e32 v96, v99, v108
	ds_bpermute_b32 v97, v145, v96
	v_cvt_pk_bf16_f32 v99, v111, v121
	v_cvt_pk_bf16_f32 v100, v109, v110
	v_cvt_pk_bf16_f32 v101, v120, v122
	global_store_dwordx4 v[102:103], v[98:101], off offset:256 sc1
	s_and_saveexec_b64 s[46:47], s[4:5]
	s_cbranch_execz .LBB0_1019
	v_lshl_add_u64 v[98:99], v[214:215], 2, s[8:9]
	s_waitcnt lgkmcnt(0)
	v_add_f32_e32 v96, v96, v97
	global_atomic_add_f32 v[98:99], v96, off
.LBB0_1019:
	s_or_b64 exec, exec, s[46:47]
	s_waitcnt lgkmcnt(0)
	v_lshl_add_u64 v[96:97], v[210:211], 2, s[38:39]
	global_load_dword v96, v[96:97], off
	v_and_b32_e32 v98, 0xffff0000, v164
	v_and_b32_e32 v100, 0xffff0000, v165
	v_and_b32_e32 v102, 0xffff0000, v166
	v_and_b32_e32 v104, 0xffff0000, v167
	v_lshlrev_b32_e32 v97, 16, v164
	v_lshlrev_b32_e32 v99, 16, v165
	v_lshlrev_b32_e32 v101, 16, v166
	v_lshlrev_b32_e32 v103, 16, v167
	v_lshlrev_b32_e32 v109, 16, v154
	v_and_b32_e32 v110, 0xffff0000, v154
	v_and_b32_e32 v106, 0xffff0000, v152
	v_and_b32_e32 v108, 0xffff0000, v153
	v_lshlrev_b32_e32 v105, 16, v152
	v_lshlrev_b32_e32 v107, 16, v153
	v_lshlrev_b32_e32 v111, 16, v155
	v_and_b32_e32 v120, 0xffff0000, v155
	s_waitcnt vmcnt(0)
	v_fmamk_f32 v96, v96, 0x3a000000, v239
	v_rsq_f32_e32 v96, v96
	s_nop 0
	v_mul_f32_e32 v85, v85, v96
	v_mul_f32_e32 v81, v81, v96
	v_mul_f32_e32 v87, v87, v96
	v_mul_f32_e32 v83, v83, v96
	v_mul_f32_e32 v84, v84, v96
	v_mul_f32_e32 v80, v80, v96
	v_mul_f32_e32 v86, v86, v96
	v_mul_f32_e32 v82, v82, v96
	v_mul_f32_e32 v85, 0xbfb8aa3b, v85
	v_mul_f32_e32 v81, 0xbfb8aa3b, v81
	v_mul_f32_e32 v87, 0xbfb8aa3b, v87
	v_mul_f32_e32 v83, 0xbfb8aa3b, v83
	v_mul_f32_e32 v84, 0xbfb8aa3b, v84
	v_mul_f32_e32 v80, 0xbfb8aa3b, v80
	v_mul_f32_e32 v86, 0xbfb8aa3b, v86
	v_mul_f32_e32 v82, 0xbfb8aa3b, v82
	v_exp_f32_e32 v85, v85
	v_exp_f32_e32 v81, v81
	v_exp_f32_e32 v87, v87
	v_exp_f32_e32 v83, v83
	v_exp_f32_e32 v84, v84
	v_exp_f32_e32 v80, v80
	v_exp_f32_e32 v86, v86
	v_exp_f32_e32 v82, v82
	v_mul_f32_e32 v72, v72, v96
	v_mul_f32_e32 v72, 0xbfb8aa3b, v72
	v_exp_f32_e32 v72, v72
	v_add_f32_e32 v85, 1.0, v85
	v_add_f32_e32 v81, 1.0, v81
	v_add_f32_e32 v87, 1.0, v87
	v_add_f32_e32 v83, 1.0, v83
	v_add_f32_e32 v84, 1.0, v84
	v_add_f32_e32 v80, 1.0, v80
	v_add_f32_e32 v86, 1.0, v86
	v_add_f32_e32 v82, 1.0, v82
	v_rcp_f32_e32 v85, v85
	v_rcp_f32_e32 v81, v81
	v_rcp_f32_e32 v87, v87
	v_rcp_f32_e32 v83, v83
	v_rcp_f32_e32 v84, v84
	v_rcp_f32_e32 v80, v80
	v_rcp_f32_e32 v86, v86
	v_rcp_f32_e32 v82, v82
	v_mul_f32_e32 v73, v73, v96
	v_mul_f32_e32 v73, 0xbfb8aa3b, v73
	v_add_f32_e32 v72, 1.0, v72
	v_exp_f32_e32 v73, v73
	v_rcp_f32_e32 v72, v72
	v_mul_f32_e32 v85, v85, v98
	v_mul_f32_e32 v98, v81, v102
	v_mul_f32_e32 v87, v87, v100
	v_mul_f32_e32 v100, v83, v104
	v_mul_f32_e32 v84, v84, v97
	v_mul_f32_e32 v97, v80, v101
	v_mul_f32_e32 v86, v86, v99
	v_mul_f32_e32 v99, v82, v103
	v_cvt_pk_bf16_f32 v80, v84, v85
	v_cvt_pk_bf16_f32 v81, v86, v87
	v_cvt_pk_bf16_f32 v82, v97, v98
	v_cvt_pk_bf16_f32 v83, v99, v100
	v_mul_f32_e32 v85, v85, v85
	v_mul_f32_e32 v87, v87, v87
	v_mul_f32_e32 v98, v98, v98
	v_mul_f32_e32 v100, v100, v100
	v_fmac_f32_e32 v85, v84, v84
	v_fmac_f32_e32 v87, v86, v86
	v_fmac_f32_e32 v98, v97, v97
	v_fmac_f32_e32 v100, v99, v99
	v_add_f32_e32 v84, v85, v87
	v_add_f32_e32 v85, v98, v100
	v_add_f32_e32 v84, v84, v85
	v_mul_f32_e32 v85, v72, v109
	v_add_f32_e32 v72, 1.0, v73
	v_mul_f32_e32 v73, v78, v96
	v_mul_f32_e32 v74, v74, v96
	v_mul_f32_e32 v73, 0xbfb8aa3b, v73
	v_mul_f32_e32 v74, 0xbfb8aa3b, v74
	v_rcp_f32_e32 v72, v72
	v_exp_f32_e32 v73, v73
	v_exp_f32_e32 v74, v74
	v_mul_f32_e32 v77, v77, v96
	v_mul_f32_e32 v86, v72, v110
	v_add_f32_e32 v72, 1.0, v73
	v_add_f32_e32 v73, 1.0, v74
	v_mul_f32_e32 v74, v79, v96
	v_mul_f32_e32 v76, v76, v96
	v_mul_f32_e32 v77, 0xbfb8aa3b, v77
	v_mul_f32_e32 v74, 0xbfb8aa3b, v74
	v_mul_f32_e32 v76, 0xbfb8aa3b, v76
	v_exp_f32_e32 v77, v77
	v_exp_f32_e32 v74, v74
	v_mul_f32_e32 v75, v75, v96
	v_exp_f32_e32 v76, v76
	v_mul_f32_e32 v75, 0xbfb8aa3b, v75
	v_exp_f32_e32 v75, v75
	v_add_f32_e32 v77, 1.0, v77
	v_add_f32_e32 v74, 1.0, v74
	v_add_f32_e32 v76, 1.0, v76
	v_rcp_f32_e32 v77, v77
	v_rcp_f32_e32 v74, v74
	v_rcp_f32_e32 v76, v76
	v_rcp_f32_e32 v72, v72
	v_rcp_f32_e32 v73, v73
	v_add_f32_e32 v75, 1.0, v75
	v_rcp_f32_e32 v75, v75
	v_mul_f32_e32 v77, v77, v106
	v_mul_f32_e32 v97, v74, v108
	v_mul_f32_e32 v76, v76, v105
	v_mul_f32_e32 v87, v72, v107
	v_mul_f32_e32 v96, v73, v111
	v_mul_f32_e32 v72, v77, v77
	v_mul_f32_e32 v73, v97, v97
	v_mul_f32_e32 v98, v75, v120
	v_fmac_f32_e32 v72, v76, v76
	v_fmac_f32_e32 v73, v87, v87
	v_add_f32_e32 v72, v72, v73
	v_mul_f32_e32 v73, v86, v86
	v_mul_f32_e32 v74, v98, v98
	v_fmac_f32_e32 v73, v85, v85
	v_fmac_f32_e32 v74, v96, v96
	v_add_f32_e32 v73, v73, v74
	v_add_f32_e32 v72, v72, v73
	v_add_f32_e32 v75, v84, v72
	ds_bpermute_b32 v84, v144, v75
	v_lshl_add_u64 v[72:73], s[34:35], 0, v[212:213]
	v_lshl_add_u64 v[78:79], v[190:191], 1, v[72:73]
	global_store_dwordx4 v[78:79], v[80:83], off sc1
	v_cvt_pk_bf16_f32 v74, v76, v77
	s_waitcnt lgkmcnt(0)
	v_add_f32_e32 v72, v75, v84
	ds_bpermute_b32 v73, v145, v72
	v_cvt_pk_bf16_f32 v75, v87, v97
	v_cvt_pk_bf16_f32 v76, v85, v86
	v_cvt_pk_bf16_f32 v77, v96, v98
	global_store_dwordx4 v[78:79], v[74:77], off offset:256 sc1
	s_and_saveexec_b64 s[46:47], s[4:5]
	s_cbranch_execz .LBB0_1021
	v_lshl_add_u64 v[74:75], v[210:211], 2, s[8:9]
	s_waitcnt lgkmcnt(0)
	v_add_f32_e32 v72, v72, v73
	global_atomic_add_f32 v[74:75], v72, off
; __device__ __forceinline__ float rstd_of(float ss, float inv_n) { return __builtin_amdgcn_rsqf(ss * inv_n + 1e-6f); }
; __device__ __forceinline__ float sigmoid_f(float v) { return __builtin_amdgcn_rcpf(1.0f + __builtin_amdgcn_exp2f(-1.4426950408889634f * v)); }
; __device__ __forceinline__ float bf_lo(unsigned w) { return __uint_as_float(w << 16); }
; __device__ __forceinline__ float bf_hi(unsigned w) { return __uint_as_float(w & 0xffff0000u); }
; __device__ __forceinline__ u32x4 pack8(const f32x4 a, const f32x4 b) { u32x4 w; w.x = cvt_pk_bf16(a[0], a[1]); w.y = cvt_pk_bf16(a[2], a[3]); w.z = cvt_pk_bf16(b[0], b[1]); w.w = cvt_pk_bf16(b[2], b[3]); return w; }
; __device__ __forceinline__ float sumsq4(const f32x4 a) { return (a[0] * a[0] + a[1] * a[1]) + (a[2] * a[2] + a[3] * a[3]); }
;     __device__ __forceinline__ void operator()(f32x4 (&acc)[2][2][4][2], const Unit& u, int wr, int wc, int fr, int fq) const {
;     ...
;         for (int ai = 0; ai < 2; ++ai)
; #pragma unroll
;             for (int m = 0; m < 4; ++m) { const int row = row0 + ai * HALF + m * 16; const float r = rstd_of(ss[row], 1.0f / 2048.0f); float q = 0.f;
; #pragma unroll
;                 for (int bj = 0; bj < 2; ++bj) { const u32x4 pb = pw[ai][m][bj];
;                     const f32x4 p0 = {bf_lo(pb.x), bf_hi(pb.x), bf_lo(pb.y), bf_hi(pb.y)}, p1 = {bf_lo(pb.z), bf_hi(pb.z), bf_lo(pb.w), bf_hi(pb.w)};
;                     const f32x4 a0 = acc[ai][bj][m][0] * r, a1 = acc[ai][bj][m][1] * r; f32x4 y0, y1;
; #pragma unroll
;                     for (int e = 0; e < 4; ++e) { y0[e] = p0[e] * sigmoid_f(a0[e]); y1[e] = p1[e] * sigmoid_f(a1[e]); }
;                     *(u32x4*)(E + (size_t)row * 2048 + col0 + bj * HALF) = pack8(y0, y1); q += sumsq4(y0) + sumsq4(y1); }
;                 q += __shfl_xor(q, 16); q += __shfl_xor(q, 32);
;                 if (fq == 0) atomicAdd(ssout + row, q); }
.LBB0_1021:
	s_or_b64 exec, exec, s[46:47]
	global_load_dword v72, v[196:197], off offset:512
	v_and_b32_e32 v74, 0xffff0000, v140
	v_and_b32_e32 v76, 0xffff0000, v141
	v_and_b32_e32 v78, 0xffff0000, v142
	v_and_b32_e32 v80, 0xffff0000, v143
	s_waitcnt lgkmcnt(0)
	v_lshlrev_b32_e32 v73, 16, v140
	v_lshlrev_b32_e32 v75, 16, v141
	v_lshlrev_b32_e32 v77, 16, v142
	v_lshlrev_b32_e32 v79, 16, v143
	v_lshlrev_b32_e32 v85, 16, v138
	v_and_b32_e32 v86, 0xffff0000, v138
	v_and_b32_e32 v82, 0xffff0000, v136
	v_and_b32_e32 v84, 0xffff0000, v137
	v_lshlrev_b32_e32 v81, 16, v136
	v_lshlrev_b32_e32 v83, 16, v137
	v_lshlrev_b32_e32 v87, 16, v139
	v_and_b32_e32 v96, 0xffff0000, v139
	s_waitcnt vmcnt(0)
	v_fmamk_f32 v72, v72, 0x3a000000, v239
	v_rsq_f32_e32 v72, v72
	s_nop 0
	v_mul_f32_e32 v61, v61, v72
	v_mul_f32_e32 v57, v57, v72
	v_mul_f32_e32 v63, v63, v72
	v_mul_f32_e32 v59, v59, v72
	v_mul_f32_e32 v60, v60, v72
	v_mul_f32_e32 v56, v56, v72
	v_mul_f32_e32 v62, v62, v72
	v_mul_f32_e32 v58, v58, v72
	v_mul_f32_e32 v61, 0xbfb8aa3b, v61
	v_mul_f32_e32 v57, 0xbfb8aa3b, v57
	v_mul_f32_e32 v63, 0xbfb8aa3b, v63
	v_mul_f32_e32 v59, 0xbfb8aa3b, v59
	v_mul_f32_e32 v60, 0xbfb8aa3b, v60
	v_mul_f32_e32 v56, 0xbfb8aa3b, v56
	v_mul_f32_e32 v62, 0xbfb8aa3b, v62
	v_mul_f32_e32 v58, 0xbfb8aa3b, v58
	v_exp_f32_e32 v61, v61
	v_exp_f32_e32 v57, v57
	v_exp_f32_e32 v63, v63
	v_exp_f32_e32 v59, v59
	v_exp_f32_e32 v60, v60
	v_exp_f32_e32 v56, v56
	v_exp_f32_e32 v62, v62
	v_exp_f32_e32 v58, v58
	v_mul_f32_e32 v48, v48, v72
	v_mul_f32_e32 v48, 0xbfb8aa3b, v48
	v_exp_f32_e32 v48, v48
	v_add_f32_e32 v61, 1.0, v61
	v_add_f32_e32 v57, 1.0, v57
	v_add_f32_e32 v63, 1.0, v63
	v_add_f32_e32 v59, 1.0, v59
	v_add_f32_e32 v60, 1.0, v60
	v_add_f32_e32 v56, 1.0, v56
	v_add_f32_e32 v62, 1.0, v62
	v_add_f32_e32 v58, 1.0, v58
	v_rcp_f32_e32 v61, v61
	v_rcp_f32_e32 v57, v57
	v_rcp_f32_e32 v63, v63
	v_rcp_f32_e32 v59, v59
	v_rcp_f32_e32 v60, v60
	v_rcp_f32_e32 v56, v56
	v_rcp_f32_e32 v62, v62
	v_rcp_f32_e32 v58, v58
	v_mul_f32_e32 v49, v49, v72
	v_mul_f32_e32 v49, 0xbfb8aa3b, v49
	v_add_f32_e32 v48, 1.0, v48
	v_exp_f32_e32 v49, v49
	v_rcp_f32_e32 v48, v48
	v_mul_f32_e32 v61, v61, v74
	v_mul_f32_e32 v74, v57, v78
	v_mul_f32_e32 v63, v63, v76
	v_mul_f32_e32 v76, v59, v80
	v_mul_f32_e32 v60, v60, v73
	v_mul_f32_e32 v73, v56, v77
	v_mul_f32_e32 v62, v62, v75
	v_mul_f32_e32 v75, v58, v79
	v_cvt_pk_bf16_f32 v56, v60, v61
	v_cvt_pk_bf16_f32 v57, v62, v63
	v_cvt_pk_bf16_f32 v58, v73, v74
	v_cvt_pk_bf16_f32 v59, v75, v76
	v_mul_f32_e32 v61, v61, v61
	v_mul_f32_e32 v63, v63, v63
	v_mul_f32_e32 v74, v74, v74
	v_mul_f32_e32 v76, v76, v76
	v_fmac_f32_e32 v61, v60, v60
	v_fmac_f32_e32 v63, v62, v62
	v_fmac_f32_e32 v74, v73, v73
	v_fmac_f32_e32 v76, v75, v75
	v_add_f32_e32 v60, v61, v63
	v_add_f32_e32 v61, v74, v76
	v_add_f32_e32 v60, v60, v61
	v_mul_f32_e32 v61, v48, v85
	v_add_f32_e32 v48, 1.0, v49
	v_mul_f32_e32 v49, v54, v72
	v_mul_f32_e32 v50, v50, v72
	v_mul_f32_e32 v49, 0xbfb8aa3b, v49
	v_mul_f32_e32 v50, 0xbfb8aa3b, v50
	v_rcp_f32_e32 v48, v48
	v_exp_f32_e32 v49, v49
	v_exp_f32_e32 v50, v50
	v_mul_f32_e32 v53, v53, v72
	v_mul_f32_e32 v62, v48, v86
	v_add_f32_e32 v48, 1.0, v49
	v_add_f32_e32 v49, 1.0, v50
	v_mul_f32_e32 v50, v55, v72
	v_mul_f32_e32 v52, v52, v72
	v_mul_f32_e32 v53, 0xbfb8aa3b, v53
	v_mul_f32_e32 v50, 0xbfb8aa3b, v50
	v_mul_f32_e32 v52, 0xbfb8aa3b, v52
	v_exp_f32_e32 v53, v53
	v_exp_f32_e32 v50, v50
	v_mul_f32_e32 v51, v51, v72
	v_exp_f32_e32 v52, v52
	v_mul_f32_e32 v51, 0xbfb8aa3b, v51
	v_exp_f32_e32 v51, v51
	v_add_f32_e32 v53, 1.0, v53
	v_add_f32_e32 v50, 1.0, v50
	v_add_f32_e32 v52, 1.0, v52
	v_rcp_f32_e32 v53, v53
	v_rcp_f32_e32 v50, v50
	v_rcp_f32_e32 v52, v52
	v_rcp_f32_e32 v48, v48
	v_rcp_f32_e32 v49, v49
	v_add_f32_e32 v51, 1.0, v51
	v_rcp_f32_e32 v51, v51
	v_mul_f32_e32 v53, v53, v82
	v_mul_f32_e32 v73, v50, v84
	v_mul_f32_e32 v52, v52, v81
	v_mul_f32_e32 v63, v48, v83
	v_mul_f32_e32 v72, v49, v87
	v_mul_f32_e32 v48, v53, v53
	v_mul_f32_e32 v49, v73, v73
	v_mul_f32_e32 v74, v51, v96
	v_fmac_f32_e32 v48, v52, v52
	v_fmac_f32_e32 v49, v63, v63
	v_add_f32_e32 v48, v48, v49
	v_mul_f32_e32 v49, v62, v62
	v_mul_f32_e32 v50, v74, v74
	v_fmac_f32_e32 v49, v61, v61
	v_fmac_f32_e32 v50, v72, v72
	v_add_f32_e32 v49, v49, v50
	v_add_f32_e32 v48, v48, v49
	v_add_f32_e32 v51, v60, v48
	ds_bpermute_b32 v60, v144, v51
	v_lshl_add_u64 v[48:49], s[34:35], 0, v[208:209]
	v_lshl_add_u64 v[54:55], v[190:191], 1, v[48:49]
	global_store_dwordx4 v[54:55], v[56:59], off sc1
	v_cvt_pk_bf16_f32 v50, v52, v53
	s_waitcnt lgkmcnt(0)
	v_add_f32_e32 v48, v51, v60
	ds_bpermute_b32 v49, v145, v48
	v_cvt_pk_bf16_f32 v51, v63, v73
	v_cvt_pk_bf16_f32 v52, v61, v62
	v_cvt_pk_bf16_f32 v53, v72, v74
	global_store_dwordx4 v[54:55], v[50:53], off offset:256 sc1
	s_and_saveexec_b64 s[46:47], s[4:5]
	s_cbranch_execz .LBB0_1023
	v_lshl_add_u64 v[50:51], v[206:207], 2, s[8:9]
	s_waitcnt lgkmcnt(0)
	v_add_f32_e32 v48, v48, v49
	global_atomic_add_f32 v[50:51], v48, off
; __device__ __forceinline__ float rstd_of(float ss, float inv_n) { return __builtin_amdgcn_rsqf(ss * inv_n + 1e-6f); }
; __device__ __forceinline__ float sigmoid_f(float v) { return __builtin_amdgcn_rcpf(1.0f + __builtin_amdgcn_exp2f(-1.4426950408889634f * v)); }
; __device__ __forceinline__ float bf_lo(unsigned w) { return __uint_as_float(w << 16); }
; __device__ __forceinline__ float bf_hi(unsigned w) { return __uint_as_float(w & 0xffff0000u); }
; __device__ __forceinline__ u32x4 pack8(const f32x4 a, const f32x4 b) { u32x4 w; w.x = cvt_pk_bf16(a[0], a[1]); w.y = cvt_pk_bf16(a[2], a[3]); w.z = cvt_pk_bf16(b[0], b[1]); w.w = cvt_pk_bf16(b[2], b[3]); return w; }
; __device__ __forceinline__ float sumsq4(const f32x4 a) { return (a[0] * a[0] + a[1] * a[1]) + (a[2] * a[2] + a[3] * a[3]); }
;     __device__ __forceinline__ void operator()(f32x4 (&acc)[2][2][4][2], const Unit& u, int wr, int wc, int fr, int fq) const {
;     ...
;         for (int ai = 0; ai < 2; ++ai)
; #pragma unroll
;             for (int m = 0; m < 4; ++m) { const int row = row0 + ai * HALF + m * 16; const float r = rstd_of(ss[row], 1.0f / 2048.0f); float q = 0.f;
; #pragma unroll
;                 for (int bj = 0; bj < 2; ++bj) { const u32x4 pb = pw[ai][m][bj];
;                     const f32x4 p0 = {bf_lo(pb.x), bf_hi(pb.x), bf_lo(pb.y), bf_hi(pb.y)}, p1 = {bf_lo(pb.z), bf_hi(pb.z), bf_lo(pb.w), bf_hi(pb.w)};
;                     const f32x4 a0 = acc[ai][bj][m][0] * r, a1 = acc[ai][bj][m][1] * r; f32x4 y0, y1;
; #pragma unroll
;                     for (int e = 0; e < 4; ++e) { y0[e] = p0[e] * sigmoid_f(a0[e]); y1[e] = p1[e] * sigmoid_f(a1[e]); }
;                     *(u32x4*)(E + (size_t)row * 2048 + col0 + bj * HALF) = pack8(y0, y1); q += sumsq4(y0) + sumsq4(y1); }
;                 q += __shfl_xor(q, 16); q += __shfl_xor(q, 32);
;                 if (fq == 0) atomicAdd(ssout + row, q); }
.LBB0_1023:
	s_or_b64 exec, exec, s[46:47]
	global_load_dword v48, v[196:197], off offset:576
	v_and_b32_e32 v50, 0xffff0000, v116
	v_and_b32_e32 v52, 0xffff0000, v117
	v_and_b32_e32 v54, 0xffff0000, v118
	v_and_b32_e32 v56, 0xffff0000, v119
	s_waitcnt lgkmcnt(0)
	v_lshlrev_b32_e32 v49, 16, v116
	v_lshlrev_b32_e32 v51, 16, v117
	v_lshlrev_b32_e32 v53, 16, v118
	v_lshlrev_b32_e32 v55, 16, v119
	v_lshlrev_b32_e32 v61, 16, v114
	v_and_b32_e32 v62, 0xffff0000, v114
	v_and_b32_e32 v58, 0xffff0000, v112
	v_and_b32_e32 v60, 0xffff0000, v113
	v_lshlrev_b32_e32 v57, 16, v112
	v_lshlrev_b32_e32 v59, 16, v113
	v_lshlrev_b32_e32 v63, 16, v115
	v_and_b32_e32 v72, 0xffff0000, v115
	s_waitcnt vmcnt(0)
	v_fmamk_f32 v48, v48, 0x3a000000, v239
	v_rsq_f32_e32 v48, v48
	s_nop 0
	v_mul_f32_e32 v45, v45, v48
	v_mul_f32_e32 v41, v41, v48
	v_mul_f32_e32 v47, v47, v48
	v_mul_f32_e32 v43, v43, v48
	v_mul_f32_e32 v44, v44, v48
	v_mul_f32_e32 v40, v40, v48
	v_mul_f32_e32 v46, v46, v48
	v_mul_f32_e32 v42, v42, v48
	v_mul_f32_e32 v45, 0xbfb8aa3b, v45
	v_mul_f32_e32 v41, 0xbfb8aa3b, v41
	v_mul_f32_e32 v47, 0xbfb8aa3b, v47
	v_mul_f32_e32 v43, 0xbfb8aa3b, v43
	v_mul_f32_e32 v44, 0xbfb8aa3b, v44
	v_mul_f32_e32 v40, 0xbfb8aa3b, v40
	v_mul_f32_e32 v46, 0xbfb8aa3b, v46
	v_mul_f32_e32 v42, 0xbfb8aa3b, v42
	v_exp_f32_e32 v45, v45
	v_exp_f32_e32 v41, v41
	v_exp_f32_e32 v47, v47
	v_exp_f32_e32 v43, v43
	v_exp_f32_e32 v44, v44
	v_exp_f32_e32 v40, v40
	v_exp_f32_e32 v46, v46
	v_exp_f32_e32 v42, v42
	v_mul_f32_e32 v32, v32, v48
	v_mul_f32_e32 v32, 0xbfb8aa3b, v32
	v_exp_f32_e32 v32, v32
	v_add_f32_e32 v45, 1.0, v45
	v_add_f32_e32 v41, 1.0, v41
	v_add_f32_e32 v47, 1.0, v47
	v_add_f32_e32 v43, 1.0, v43
	v_add_f32_e32 v44, 1.0, v44
	v_add_f32_e32 v40, 1.0, v40
	v_add_f32_e32 v46, 1.0, v46
	v_add_f32_e32 v42, 1.0, v42
	v_rcp_f32_e32 v45, v45
	v_rcp_f32_e32 v41, v41
	v_rcp_f32_e32 v47, v47
	v_rcp_f32_e32 v43, v43
	v_rcp_f32_e32 v44, v44
	v_rcp_f32_e32 v40, v40
	v_rcp_f32_e32 v46, v46
	v_rcp_f32_e32 v42, v42
	v_mul_f32_e32 v33, v33, v48
	v_mul_f32_e32 v33, 0xbfb8aa3b, v33
	v_add_f32_e32 v32, 1.0, v32
	v_exp_f32_e32 v33, v33
	v_rcp_f32_e32 v32, v32
	v_mul_f32_e32 v45, v45, v50
	v_mul_f32_e32 v50, v41, v54
	v_mul_f32_e32 v47, v47, v52
	v_mul_f32_e32 v52, v43, v56
	v_mul_f32_e32 v44, v44, v49
	v_mul_f32_e32 v49, v40, v53
	v_mul_f32_e32 v46, v46, v51
	v_mul_f32_e32 v51, v42, v55
	v_cvt_pk_bf16_f32 v40, v44, v45
	v_cvt_pk_bf16_f32 v41, v46, v47
	v_cvt_pk_bf16_f32 v42, v49, v50
	v_cvt_pk_bf16_f32 v43, v51, v52
	v_mul_f32_e32 v45, v45, v45
	v_mul_f32_e32 v47, v47, v47
	v_mul_f32_e32 v50, v50, v50
	v_mul_f32_e32 v52, v52, v52
	v_fmac_f32_e32 v45, v44, v44
	v_fmac_f32_e32 v47, v46, v46
	v_fmac_f32_e32 v50, v49, v49
	v_fmac_f32_e32 v52, v51, v51
	v_add_f32_e32 v44, v45, v47
	v_add_f32_e32 v45, v50, v52
	v_add_f32_e32 v44, v44, v45
	v_mul_f32_e32 v45, v32, v61
	v_add_f32_e32 v32, 1.0, v33
	v_mul_f32_e32 v33, v38, v48
	v_mul_f32_e32 v34, v34, v48
	v_mul_f32_e32 v33, 0xbfb8aa3b, v33
	v_mul_f32_e32 v34, 0xbfb8aa3b, v34
	v_rcp_f32_e32 v32, v32
	v_exp_f32_e32 v33, v33
	v_exp_f32_e32 v34, v34
	v_mul_f32_e32 v37, v37, v48
	v_mul_f32_e32 v46, v32, v62
	v_add_f32_e32 v32, 1.0, v33
	v_add_f32_e32 v33, 1.0, v34
	v_mul_f32_e32 v34, v39, v48
	v_mul_f32_e32 v36, v36, v48
	v_mul_f32_e32 v37, 0xbfb8aa3b, v37
	v_mul_f32_e32 v34, 0xbfb8aa3b, v34
	v_mul_f32_e32 v36, 0xbfb8aa3b, v36
	v_exp_f32_e32 v37, v37
	v_exp_f32_e32 v34, v34
	v_mul_f32_e32 v35, v35, v48
	v_exp_f32_e32 v36, v36
	v_mul_f32_e32 v35, 0xbfb8aa3b, v35
	v_exp_f32_e32 v35, v35
	v_add_f32_e32 v37, 1.0, v37
	v_add_f32_e32 v34, 1.0, v34
	v_add_f32_e32 v36, 1.0, v36
	v_rcp_f32_e32 v37, v37
	v_rcp_f32_e32 v34, v34
	v_rcp_f32_e32 v36, v36
	v_rcp_f32_e32 v32, v32
	v_rcp_f32_e32 v33, v33
	v_add_f32_e32 v35, 1.0, v35
	v_rcp_f32_e32 v35, v35
	v_mul_f32_e32 v37, v37, v58
	v_mul_f32_e32 v49, v34, v60
	v_mul_f32_e32 v36, v36, v57
	v_mul_f32_e32 v47, v32, v59
	v_mul_f32_e32 v48, v33, v63
	v_mul_f32_e32 v32, v37, v37
	v_mul_f32_e32 v33, v49, v49
	v_mul_f32_e32 v50, v35, v72
	v_fmac_f32_e32 v32, v36, v36
	v_fmac_f32_e32 v33, v47, v47
	v_add_f32_e32 v32, v32, v33
	v_mul_f32_e32 v33, v46, v46
	v_mul_f32_e32 v34, v50, v50
	v_fmac_f32_e32 v33, v45, v45
	v_fmac_f32_e32 v34, v48, v48
	v_add_f32_e32 v33, v33, v34
	v_add_f32_e32 v32, v32, v33
	v_add_f32_e32 v35, v44, v32
	ds_bpermute_b32 v44, v144, v35
	v_lshl_add_u64 v[32:33], s[34:35], 0, v[204:205]
	v_lshl_add_u64 v[38:39], v[190:191], 1, v[32:33]
	global_store_dwordx4 v[38:39], v[40:43], off sc1
	v_cvt_pk_bf16_f32 v34, v36, v37
	s_waitcnt lgkmcnt(0)
	v_add_f32_e32 v32, v35, v44
	ds_bpermute_b32 v33, v145, v32
	v_cvt_pk_bf16_f32 v35, v47, v49
	v_cvt_pk_bf16_f32 v36, v45, v46
	v_cvt_pk_bf16_f32 v37, v48, v50
	global_store_dwordx4 v[38:39], v[34:37], off offset:256 sc1
	s_and_saveexec_b64 s[46:47], s[4:5]
	s_cbranch_execz .LBB0_1025
	v_lshl_add_u64 v[34:35], v[202:203], 2, s[8:9]
	s_waitcnt lgkmcnt(0)
	v_add_f32_e32 v32, v32, v33
	global_atomic_add_f32 v[34:35], v32, off
; __device__ __forceinline__ float rstd_of(float ss, float inv_n) { return __builtin_amdgcn_rsqf(ss * inv_n + 1e-6f); }
; __device__ __forceinline__ float sigmoid_f(float v) { return __builtin_amdgcn_rcpf(1.0f + __builtin_amdgcn_exp2f(-1.4426950408889634f * v)); }
; __device__ __forceinline__ float bf_lo(unsigned w) { return __uint_as_float(w << 16); }
; __device__ __forceinline__ float bf_hi(unsigned w) { return __uint_as_float(w & 0xffff0000u); }
; __device__ __forceinline__ u32x4 pack8(const f32x4 a, const f32x4 b) { u32x4 w; w.x = cvt_pk_bf16(a[0], a[1]); w.y = cvt_pk_bf16(a[2], a[3]); w.z = cvt_pk_bf16(b[0], b[1]); w.w = cvt_pk_bf16(b[2], b[3]); return w; }
; __device__ __forceinline__ float sumsq4(const f32x4 a) { return (a[0] * a[0] + a[1] * a[1]) + (a[2] * a[2] + a[3] * a[3]); }
;     __device__ __forceinline__ void operator()(f32x4 (&acc)[2][2][4][2], const Unit& u, int wr, int wc, int fr, int fq) const {
;     ...
;         for (int ai = 0; ai < 2; ++ai)
; #pragma unroll
;             for (int m = 0; m < 4; ++m) { const int row = row0 + ai * HALF + m * 16; const float r = rstd_of(ss[row], 1.0f / 2048.0f); float q = 0.f;
; #pragma unroll
;                 for (int bj = 0; bj < 2; ++bj) { const u32x4 pb = pw[ai][m][bj];
;                     const f32x4 p0 = {bf_lo(pb.x), bf_hi(pb.x), bf_lo(pb.y), bf_hi(pb.y)}, p1 = {bf_lo(pb.z), bf_hi(pb.z), bf_lo(pb.w), bf_hi(pb.w)};
;                     const f32x4 a0 = acc[ai][bj][m][0] * r, a1 = acc[ai][bj][m][1] * r; f32x4 y0, y1;
; #pragma unroll
;                     for (int e = 0; e < 4; ++e) { y0[e] = p0[e] * sigmoid_f(a0[e]); y1[e] = p1[e] * sigmoid_f(a1[e]); }
;                     *(u32x4*)(E + (size_t)row * 2048 + col0 + bj * HALF) = pack8(y0, y1); q += sumsq4(y0) + sumsq4(y1); }
;                 q += __shfl_xor(q, 16); q += __shfl_xor(q, 32);
;                 if (fq == 0) atomicAdd(ssout + row, q); }
.LBB0_1025:
	s_or_b64 exec, exec, s[46:47]
	global_load_dword v32, v[196:197], off offset:640
	v_and_b32_e32 v34, 0xffff0000, v92
	v_and_b32_e32 v36, 0xffff0000, v93
	v_and_b32_e32 v38, 0xffff0000, v94
	v_and_b32_e32 v40, 0xffff0000, v95
	s_waitcnt lgkmcnt(0)
	v_lshlrev_b32_e32 v33, 16, v92
	v_lshlrev_b32_e32 v35, 16, v93
	v_lshlrev_b32_e32 v37, 16, v94
	v_lshlrev_b32_e32 v39, 16, v95
	v_lshlrev_b32_e32 v45, 16, v90
	v_and_b32_e32 v46, 0xffff0000, v90
	v_and_b32_e32 v42, 0xffff0000, v88
	v_and_b32_e32 v44, 0xffff0000, v89
	v_lshlrev_b32_e32 v41, 16, v88
	v_lshlrev_b32_e32 v43, 16, v89
	v_lshlrev_b32_e32 v47, 16, v91
	v_and_b32_e32 v48, 0xffff0000, v91
	s_waitcnt vmcnt(0)
	v_fmamk_f32 v32, v32, 0x3a000000, v239
	v_rsq_f32_e32 v32, v32
	s_nop 0
	v_mul_f32_e32 v29, v29, v32
	v_mul_f32_e32 v25, v25, v32
	v_mul_f32_e32 v31, v31, v32
	v_mul_f32_e32 v27, v27, v32
	v_mul_f32_e32 v28, v28, v32
	v_mul_f32_e32 v24, v24, v32
	v_mul_f32_e32 v30, v30, v32
	v_mul_f32_e32 v26, v26, v32
	v_mul_f32_e32 v29, 0xbfb8aa3b, v29
	v_mul_f32_e32 v25, 0xbfb8aa3b, v25
	v_mul_f32_e32 v31, 0xbfb8aa3b, v31
	v_mul_f32_e32 v27, 0xbfb8aa3b, v27
	v_mul_f32_e32 v28, 0xbfb8aa3b, v28
	v_mul_f32_e32 v24, 0xbfb8aa3b, v24
	v_mul_f32_e32 v30, 0xbfb8aa3b, v30
	v_mul_f32_e32 v26, 0xbfb8aa3b, v26
	v_exp_f32_e32 v29, v29
	v_exp_f32_e32 v25, v25
	v_exp_f32_e32 v31, v31
	v_exp_f32_e32 v27, v27
	v_exp_f32_e32 v28, v28
	v_exp_f32_e32 v24, v24
	v_exp_f32_e32 v30, v30
	v_exp_f32_e32 v26, v26
	v_mul_f32_e32 v16, v16, v32
	v_mul_f32_e32 v16, 0xbfb8aa3b, v16
	v_exp_f32_e32 v16, v16
	v_add_f32_e32 v29, 1.0, v29
	v_add_f32_e32 v25, 1.0, v25
	v_add_f32_e32 v31, 1.0, v31
	v_add_f32_e32 v27, 1.0, v27
	v_add_f32_e32 v28, 1.0, v28
	v_add_f32_e32 v24, 1.0, v24
	v_add_f32_e32 v30, 1.0, v30
	v_add_f32_e32 v26, 1.0, v26
	v_rcp_f32_e32 v29, v29
	v_rcp_f32_e32 v25, v25
	v_rcp_f32_e32 v31, v31
	v_rcp_f32_e32 v27, v27
	v_rcp_f32_e32 v28, v28
	v_rcp_f32_e32 v24, v24
	v_rcp_f32_e32 v30, v30
	v_rcp_f32_e32 v26, v26
	v_mul_f32_e32 v17, v17, v32
	v_mul_f32_e32 v17, 0xbfb8aa3b, v17
	v_add_f32_e32 v16, 1.0, v16
	v_exp_f32_e32 v17, v17
	v_rcp_f32_e32 v16, v16
	v_mul_f32_e32 v29, v29, v34
	v_mul_f32_e32 v34, v25, v38
	v_mul_f32_e32 v31, v31, v36
	v_mul_f32_e32 v36, v27, v40
	v_mul_f32_e32 v28, v28, v33
	v_mul_f32_e32 v33, v24, v37
	v_mul_f32_e32 v30, v30, v35
	v_mul_f32_e32 v35, v26, v39
	v_cvt_pk_bf16_f32 v24, v28, v29
	v_cvt_pk_bf16_f32 v25, v30, v31
	v_cvt_pk_bf16_f32 v26, v33, v34
	v_cvt_pk_bf16_f32 v27, v35, v36
	v_mul_f32_e32 v29, v29, v29
	v_mul_f32_e32 v31, v31, v31
	v_mul_f32_e32 v34, v34, v34
	v_mul_f32_e32 v36, v36, v36
	v_fmac_f32_e32 v29, v28, v28
	v_fmac_f32_e32 v31, v30, v30
	v_fmac_f32_e32 v34, v33, v33
	v_fmac_f32_e32 v36, v35, v35
	v_add_f32_e32 v28, v29, v31
	v_add_f32_e32 v29, v34, v36
	v_add_f32_e32 v28, v28, v29
	v_mul_f32_e32 v29, v16, v45
	v_add_f32_e32 v16, 1.0, v17
	v_mul_f32_e32 v17, v22, v32
	v_mul_f32_e32 v18, v18, v32
	v_mul_f32_e32 v17, 0xbfb8aa3b, v17
	v_mul_f32_e32 v18, 0xbfb8aa3b, v18
	v_rcp_f32_e32 v16, v16
	v_exp_f32_e32 v17, v17
	v_exp_f32_e32 v18, v18
	v_mul_f32_e32 v21, v21, v32
	v_mul_f32_e32 v30, v16, v46
	v_add_f32_e32 v16, 1.0, v17
	v_add_f32_e32 v17, 1.0, v18
	v_mul_f32_e32 v18, v23, v32
	v_mul_f32_e32 v20, v20, v32
	v_mul_f32_e32 v21, 0xbfb8aa3b, v21
	v_mul_f32_e32 v18, 0xbfb8aa3b, v18
	v_mul_f32_e32 v20, 0xbfb8aa3b, v20
	v_exp_f32_e32 v21, v21
	v_exp_f32_e32 v18, v18
	v_mul_f32_e32 v19, v19, v32
	v_exp_f32_e32 v20, v20
	v_mul_f32_e32 v19, 0xbfb8aa3b, v19
	v_exp_f32_e32 v19, v19
	v_add_f32_e32 v21, 1.0, v21
	v_add_f32_e32 v18, 1.0, v18
	v_add_f32_e32 v20, 1.0, v20
	v_rcp_f32_e32 v21, v21
	v_rcp_f32_e32 v18, v18
	v_rcp_f32_e32 v20, v20
	v_rcp_f32_e32 v16, v16
	v_rcp_f32_e32 v17, v17
	v_add_f32_e32 v19, 1.0, v19
	v_rcp_f32_e32 v19, v19
	v_mul_f32_e32 v21, v21, v42
	v_mul_f32_e32 v33, v18, v44
	v_mul_f32_e32 v20, v20, v41
	v_mul_f32_e32 v31, v16, v43
	v_mul_f32_e32 v32, v17, v47
	v_mul_f32_e32 v16, v21, v21
	v_mul_f32_e32 v17, v33, v33
	v_mul_f32_e32 v34, v19, v48
	v_fmac_f32_e32 v16, v20, v20
	v_fmac_f32_e32 v17, v31, v31
	v_add_f32_e32 v16, v16, v17
	v_mul_f32_e32 v17, v30, v30
	v_mul_f32_e32 v18, v34, v34
	v_fmac_f32_e32 v17, v29, v29
	v_fmac_f32_e32 v18, v32, v32
	v_add_f32_e32 v17, v17, v18
	v_add_f32_e32 v16, v16, v17
	v_add_f32_e32 v19, v28, v16
	ds_bpermute_b32 v28, v144, v19
	v_lshl_add_u64 v[16:17], s[34:35], 0, v[200:201]
	v_lshl_add_u64 v[22:23], v[190:191], 1, v[16:17]
	global_store_dwordx4 v[22:23], v[24:27], off sc1
	v_cvt_pk_bf16_f32 v18, v20, v21
	s_waitcnt lgkmcnt(0)
	v_add_f32_e32 v16, v19, v28
	ds_bpermute_b32 v17, v145, v16
	v_cvt_pk_bf16_f32 v19, v31, v33
	v_cvt_pk_bf16_f32 v20, v29, v30
	v_cvt_pk_bf16_f32 v21, v32, v34
	global_store_dwordx4 v[22:23], v[18:21], off offset:256 sc1
	s_and_saveexec_b64 s[46:47], s[4:5]
	s_cbranch_execz .LBB0_1027
	v_lshl_add_u64 v[18:19], v[198:199], 2, s[8:9]
	s_waitcnt lgkmcnt(0)
	v_add_f32_e32 v16, v16, v17
	global_atomic_add_f32 v[18:19], v16, off
; __device__ __forceinline__ float rstd_of(float ss, float inv_n) { return __builtin_amdgcn_rsqf(ss * inv_n + 1e-6f); }
; __device__ __forceinline__ float sigmoid_f(float v) { return __builtin_amdgcn_rcpf(1.0f + __builtin_amdgcn_exp2f(-1.4426950408889634f * v)); }
; __device__ __forceinline__ float bf_lo(unsigned w) { return __uint_as_float(w << 16); }
; __device__ __forceinline__ float bf_hi(unsigned w) { return __uint_as_float(w & 0xffff0000u); }
; __device__ __forceinline__ u32x4 pack8(const f32x4 a, const f32x4 b) { u32x4 w; w.x = cvt_pk_bf16(a[0], a[1]); w.y = cvt_pk_bf16(a[2], a[3]); w.z = cvt_pk_bf16(b[0], b[1]); w.w = cvt_pk_bf16(b[2], b[3]); return w; }
; __device__ __forceinline__ float sumsq4(const f32x4 a) { return (a[0] * a[0] + a[1] * a[1]) + (a[2] * a[2] + a[3] * a[3]); }
;     __device__ __forceinline__ void operator()(f32x4 (&acc)[2][2][4][2], const Unit& u, int wr, int wc, int fr, int fq) const {
;     ...
;         for (int ai = 0; ai < 2; ++ai)
; #pragma unroll
;             for (int m = 0; m < 4; ++m) { const int row = row0 + ai * HALF + m * 16; const float r = rstd_of(ss[row], 1.0f / 2048.0f); float q = 0.f;
; #pragma unroll
;                 for (int bj = 0; bj < 2; ++bj) { const u32x4 pb = pw[ai][m][bj];
;                     const f32x4 p0 = {bf_lo(pb.x), bf_hi(pb.x), bf_lo(pb.y), bf_hi(pb.y)}, p1 = {bf_lo(pb.z), bf_hi(pb.z), bf_lo(pb.w), bf_hi(pb.w)};
;                     const f32x4 a0 = acc[ai][bj][m][0] * r, a1 = acc[ai][bj][m][1] * r; f32x4 y0, y1;
; #pragma unroll
;                     for (int e = 0; e < 4; ++e) { y0[e] = p0[e] * sigmoid_f(a0[e]); y1[e] = p1[e] * sigmoid_f(a1[e]); }
;                     *(u32x4*)(E + (size_t)row * 2048 + col0 + bj * HALF) = pack8(y0, y1); q += sumsq4(y0) + sumsq4(y1); }
;                 q += __shfl_xor(q, 16); q += __shfl_xor(q, 32);
;                 if (fq == 0) atomicAdd(ssout + row, q); }
.LBB0_1027:
	s_or_b64 exec, exec, s[46:47]
	global_load_dword v16, v[196:197], off offset:704
	v_and_b32_e32 v18, 0xffff0000, v68
	v_and_b32_e32 v20, 0xffff0000, v69
	v_and_b32_e32 v22, 0xffff0000, v70
	v_and_b32_e32 v24, 0xffff0000, v71
	s_waitcnt lgkmcnt(0)
	v_lshlrev_b32_e32 v17, 16, v68
	v_lshlrev_b32_e32 v19, 16, v69
	v_lshlrev_b32_e32 v21, 16, v70
	v_lshlrev_b32_e32 v23, 16, v71
	v_lshlrev_b32_e32 v29, 16, v66
	v_and_b32_e32 v30, 0xffff0000, v66
	v_and_b32_e32 v26, 0xffff0000, v64
	v_and_b32_e32 v28, 0xffff0000, v65
	v_lshlrev_b32_e32 v25, 16, v64
	v_lshlrev_b32_e32 v27, 16, v65
	v_lshlrev_b32_e32 v31, 16, v67
	v_and_b32_e32 v32, 0xffff0000, v67
	s_waitcnt vmcnt(0)
	v_fmamk_f32 v16, v16, 0x3a000000, v239
	v_rsq_f32_e32 v16, v16
	s_nop 0
	v_mul_f32_e32 v13, v13, v16
	v_mul_f32_e32 v9, v9, v16
	v_mul_f32_e32 v15, v15, v16
	v_mul_f32_e32 v11, v11, v16
	v_mul_f32_e32 v12, v12, v16
	v_mul_f32_e32 v8, v8, v16
	v_mul_f32_e32 v14, v14, v16
	v_mul_f32_e32 v10, v10, v16
	v_mul_f32_e32 v13, 0xbfb8aa3b, v13
	v_mul_f32_e32 v9, 0xbfb8aa3b, v9
	v_mul_f32_e32 v15, 0xbfb8aa3b, v15
	v_mul_f32_e32 v11, 0xbfb8aa3b, v11
	v_mul_f32_e32 v12, 0xbfb8aa3b, v12
	v_mul_f32_e32 v8, 0xbfb8aa3b, v8
	v_mul_f32_e32 v14, 0xbfb8aa3b, v14
	v_mul_f32_e32 v10, 0xbfb8aa3b, v10
	v_exp_f32_e32 v13, v13
	v_exp_f32_e32 v9, v9
	v_exp_f32_e32 v15, v15
	v_exp_f32_e32 v11, v11
	v_exp_f32_e32 v12, v12
	v_exp_f32_e32 v8, v8
	v_exp_f32_e32 v14, v14
	v_exp_f32_e32 v10, v10
	v_mul_f32_e32 v0, v0, v16
	v_mul_f32_e32 v0, 0xbfb8aa3b, v0
	v_exp_f32_e32 v0, v0
	v_add_f32_e32 v13, 1.0, v13
	v_add_f32_e32 v9, 1.0, v9
	v_add_f32_e32 v15, 1.0, v15
	v_add_f32_e32 v11, 1.0, v11
	v_add_f32_e32 v12, 1.0, v12
	v_add_f32_e32 v8, 1.0, v8
	v_add_f32_e32 v14, 1.0, v14
	v_add_f32_e32 v10, 1.0, v10
	v_rcp_f32_e32 v13, v13
	v_rcp_f32_e32 v9, v9
	v_rcp_f32_e32 v15, v15
	v_rcp_f32_e32 v11, v11
	v_rcp_f32_e32 v12, v12
	v_rcp_f32_e32 v8, v8
	v_rcp_f32_e32 v14, v14
	v_rcp_f32_e32 v10, v10
	v_mul_f32_e32 v1, v1, v16
	v_mul_f32_e32 v1, 0xbfb8aa3b, v1
	v_add_f32_e32 v0, 1.0, v0
	v_exp_f32_e32 v1, v1
	v_rcp_f32_e32 v0, v0
	v_mul_f32_e32 v13, v13, v18
	v_mul_f32_e32 v18, v9, v22
	v_mul_f32_e32 v15, v15, v20
	v_mul_f32_e32 v20, v11, v24
	v_mul_f32_e32 v12, v12, v17
	v_mul_f32_e32 v17, v8, v21
	v_mul_f32_e32 v14, v14, v19
	v_mul_f32_e32 v19, v10, v23
	v_cvt_pk_bf16_f32 v8, v12, v13
	v_cvt_pk_bf16_f32 v9, v14, v15
	v_cvt_pk_bf16_f32 v10, v17, v18
	v_cvt_pk_bf16_f32 v11, v19, v20
	v_mul_f32_e32 v13, v13, v13
	v_mul_f32_e32 v15, v15, v15
	v_mul_f32_e32 v18, v18, v18
	v_mul_f32_e32 v20, v20, v20
	v_fmac_f32_e32 v13, v12, v12
	v_fmac_f32_e32 v15, v14, v14
	v_fmac_f32_e32 v18, v17, v17
	v_fmac_f32_e32 v20, v19, v19
	v_add_f32_e32 v12, v13, v15
	v_add_f32_e32 v13, v18, v20
	v_add_f32_e32 v12, v12, v13
	v_mul_f32_e32 v13, v0, v29
	v_add_f32_e32 v0, 1.0, v1
	v_mul_f32_e32 v1, v6, v16
	v_mul_f32_e32 v2, v2, v16
	v_mul_f32_e32 v1, 0xbfb8aa3b, v1
	v_mul_f32_e32 v2, 0xbfb8aa3b, v2
	v_rcp_f32_e32 v0, v0
	v_exp_f32_e32 v1, v1
	v_exp_f32_e32 v2, v2
	v_mul_f32_e32 v5, v5, v16
	v_mul_f32_e32 v14, v0, v30
	v_add_f32_e32 v0, 1.0, v1
	v_add_f32_e32 v1, 1.0, v2
	v_mul_f32_e32 v2, v7, v16
	v_mul_f32_e32 v4, v4, v16
	v_mul_f32_e32 v5, 0xbfb8aa3b, v5
	v_mul_f32_e32 v2, 0xbfb8aa3b, v2
	v_mul_f32_e32 v4, 0xbfb8aa3b, v4
	v_exp_f32_e32 v5, v5
	v_exp_f32_e32 v2, v2
	v_mul_f32_e32 v3, v3, v16
	v_exp_f32_e32 v4, v4
	v_mul_f32_e32 v3, 0xbfb8aa3b, v3
	v_exp_f32_e32 v3, v3
	v_add_f32_e32 v5, 1.0, v5
	v_add_f32_e32 v2, 1.0, v2
	v_add_f32_e32 v4, 1.0, v4
	v_rcp_f32_e32 v5, v5
	v_rcp_f32_e32 v2, v2
	v_rcp_f32_e32 v4, v4
	v_rcp_f32_e32 v0, v0
	v_rcp_f32_e32 v1, v1
	v_add_f32_e32 v3, 1.0, v3
	v_rcp_f32_e32 v3, v3
	v_mul_f32_e32 v5, v5, v26
	v_mul_f32_e32 v17, v2, v28
	v_mul_f32_e32 v4, v4, v25
	v_mul_f32_e32 v15, v0, v27
	v_mul_f32_e32 v16, v1, v31
	v_mul_f32_e32 v0, v5, v5
	v_mul_f32_e32 v1, v17, v17
	v_mul_f32_e32 v18, v3, v32
	v_fmac_f32_e32 v0, v4, v4
	v_fmac_f32_e32 v1, v15, v15
	v_add_f32_e32 v0, v0, v1
	v_mul_f32_e32 v1, v14, v14
	v_mul_f32_e32 v2, v18, v18
	v_fmac_f32_e32 v1, v13, v13
	v_fmac_f32_e32 v2, v16, v16
	v_add_f32_e32 v1, v1, v2
	v_add_f32_e32 v0, v0, v1
	v_add_f32_e32 v3, v12, v0
	ds_bpermute_b32 v12, v144, v3
	v_lshl_add_u64 v[0:1], s[34:35], 0, v[194:195]
	v_lshl_add_u64 v[6:7], v[190:191], 1, v[0:1]
	global_store_dwordx4 v[6:7], v[8:11], off sc1
	v_cvt_pk_bf16_f32 v2, v4, v5
	s_waitcnt lgkmcnt(0)
	v_add_f32_e32 v0, v3, v12
	ds_bpermute_b32 v1, v145, v0
	v_cvt_pk_bf16_f32 v3, v15, v17
	v_cvt_pk_bf16_f32 v4, v13, v14
	v_cvt_pk_bf16_f32 v5, v16, v18
	global_store_dwordx4 v[6:7], v[2:5], off offset:256 sc1
	s_and_saveexec_b64 s[46:47], s[4:5]
	s_cbranch_execz .LBB0_1029
	v_lshl_add_u64 v[2:3], v[192:193], 2, s[8:9]
	s_waitcnt lgkmcnt(0)
	v_add_f32_e32 v0, v0, v1
	global_atomic_add_f32 v[2:3], v0, off
